# on top of v20: load-interval address prefixes hoisted into the LATE gaps (from the 9th MFMA) of the preceding MFMA run
# speedup vs baseline: 1.0025x; 1.0025x over previous
; #define PG8_STAGE(bufoff, gbase) do { _Pragma("unroll") for (int _i = 0; _i < 2; ++_i) \
;         __builtin_amdgcn_global_load_lds((const unsigned*)((const char*)(gbase) + voff[_i]), (LAS unsigned*)(lds + (bufoff) + ldsw + _i * 8192), 16, 0, 0); } while (0)
; #define PG8_LDA(dst, b, h) do { _Pragma("unroll") for (int m = 0; m < 4; ++m) _Pragma("unroll") for (int k = 0; k < 2; ++k) dst[m][k] = *(const LAS bf16x8*)(lds + PG8_SA(b, h) + aoff + m * 2048 + k * 1024); } while (0)
; #define PG8_LDB(dst, b, h) do { _Pragma("unroll") for (int n = 0; n < 2; ++n) _Pragma("unroll") for (int k = 0; k < 2; ++k) dst[n][k] = *(const LAS bf16x8*)(lds + PG8_SB(b, h) + boff + n * 2048 + k * 1024); } while (0)
; #define PG8_MMA(ai, bj, At, Bt) do { __builtin_amdgcn_s_setprio(1); _Pragma("unroll") for (int m = 0; m < 4; ++m) _Pragma("unroll") for (int n = 0; n < 2; ++n) _Pragma("unroll") for (int k = 0; k < 2; ++k) \
;         acc[ai][bj][m][n] = __builtin_amdgcn_mfma_f32_16x16x32_bf16(Bt[n][k], At[m][k], acc[ai][bj][m][n], 0, 0, 0); __builtin_amdgcn_s_setprio(0); } while (0)
; #define PG8_WAIT_V(n) asm volatile("s_waitcnt vmcnt(" #n ")" ::: "memory")
; #define PG8_WAIT_L(n) asm volatile("s_waitcnt lgkmcnt(" #n ")" ::: "memory")
; #define PG8_BAR __builtin_amdgcn_s_barrier()
; #define PG8_SCHED __builtin_amdgcn_sched_barrier(0)
; template <class Epi>
; DI void gemm_phase(LAS unsigned char* lds, const Gemm g, const StaticOrder& S, const Epi& E) {
;     ...
;             PG8_LDB(B0, 0, 0); PG8_SCHED; PG8_LDA(At, 0, 0); PG8_STAGE(PG8_SA(1, 1), a1 + hstep);
;             PG8_WAIT_L(8); PG8_BAR; PG8_WAIT_L(0); PG8_MMA(0, 0, At, B0); PG8_BAR; PG8_SCHED;
;             PG8_LDB(B1, 0, 1); PG8_STAGE(PG8_SB(0, 0), b2);
;             PG8_BAR; PG8_WAIT_L(0); PG8_MMA(0, 1, At, B1); PG8_BAR;
;             PG8_LDA(At, 0, 1); PG8_STAGE(PG8_SA(0, 0), a2);
;             PG8_BAR; PG8_WAIT_L(0); PG8_MMA(1, 0, At, B0); PG8_BAR; PG8_SCHED;
;             PG8_STAGE(PG8_SB(0, 1), b2 + hstep);
;             PG8_WAIT_V(6); PG8_BAR; PG8_MMA(1, 1, At, B1); PG8_BAR;
.LBB0_37:
	s_add_u32 s20, s18, 0xfff80080
	s_addc_u32 s21, s19, -1
	s_add_i32 s39, 0, 0x10000
	v_add_u32_e32 v150, s39, v135
	ds_read_b128 v[138:141], v150
	ds_read_b128 v[142:145], v150 offset:1024
	ds_read_b128 v[146:149], v150 offset:2048
	ds_read_b128 v[150:153], v150 offset:3072
	s_cmp_eq_u32 s38, 28
	s_cselect_b32 s23, s4, s21
	s_cselect_b32 s22, s5, s20
	s_cselect_b32 s21, s9, s37
	s_cselect_b32 s20, s11, s33
	v_lshl_add_u64 v[154:155], s[18:19], 0, v[130:131]
	s_add_i32 m0, s28, 0xc000
	ds_read_b128 v[186:189], v137
	ds_read_b128 v[190:193], v137 offset:1024
	ds_read_b128 v[194:197], v137 offset:2048
	ds_read_b128 v[198:201], v137 offset:3072
	ds_read_b128 v[202:205], v137 offset:4096
	ds_read_b128 v[206:209], v137 offset:5120
	ds_read_b128 v[210:213], v137 offset:6144
	ds_read_b128 v[214:217], v137 offset:7168
	global_load_lds_dwordx4 v[154:155], off
	v_lshl_add_u64 v[154:155], s[18:19], 0, v[132:133]
	s_add_i32 m0, s28, 0xe000
	s_nop 0
	global_load_lds_dwordx4 v[154:155], off
	s_waitcnt lgkmcnt(8)
	s_setprio 1
	s_barrier
	s_waitcnt lgkmcnt(0)
	v_mfma_f32_16x16x32_bf16 v[124:127], v[138:141], v[186:189], v[124:127]
	v_mfma_f32_16x16x32_bf16 v[120:123], v[146:149], v[186:189], v[120:123]
	v_mfma_f32_16x16x32_bf16 v[108:111], v[138:141], v[194:197], v[108:111]
	v_mfma_f32_16x16x32_bf16 v[104:107], v[146:149], v[194:197], v[104:107]
	v_mfma_f32_16x16x32_bf16 v[92:95], v[138:141], v[202:205], v[92:95]
	v_mfma_f32_16x16x32_bf16 v[88:91], v[146:149], v[202:205], v[88:91]
	v_mfma_f32_16x16x32_bf16 v[76:79], v[138:141], v[210:213], v[76:79]
	v_mfma_f32_16x16x32_bf16 v[72:75], v[146:149], v[210:213], v[72:75]
	v_mfma_f32_16x16x32_bf16 v[124:127], v[142:145], v[190:193], v[124:127]
	s_add_i32 s42, 0, 0x14000
	v_mfma_f32_16x16x32_bf16 v[120:123], v[150:153], v[190:193], v[120:123]
	v_add_u32_e32 v154, s42, v135
	v_mfma_f32_16x16x32_bf16 v[108:111], v[142:145], v[198:201], v[108:111]
	s_add_i32 s39, s39, s27
	v_mfma_f32_16x16x32_bf16 v[104:107], v[150:153], v[198:201], v[104:107]
	v_mfma_f32_16x16x32_bf16 v[92:95], v[142:145], v[206:209], v[92:95]
	v_mfma_f32_16x16x32_bf16 v[88:91], v[150:153], v[206:209], v[88:91]
	v_mfma_f32_16x16x32_bf16 v[76:79], v[142:145], v[214:217], v[76:79]
	v_mfma_f32_16x16x32_bf16 v[72:75], v[150:153], v[214:217], v[72:75]
	s_setprio 0
	s_barrier
	ds_read_b128 v[226:229], v154
	ds_read_b128 v[230:233], v154 offset:1024
	ds_read_b128 v[234:237], v154 offset:2048
	ds_read_b128 v[238:241], v154 offset:3072
	v_lshl_add_u64 v[154:155], s[20:21], 0, v[158:159]
	s_mov_b32 m0, s39
	v_lshl_add_u64 v[218:219], s[20:21], 0, v[128:129]
	global_load_lds_dwordx4 v[154:155], off
	s_add_i32 m0, s39, 0x2000
	s_nop 0
	global_load_lds_dwordx4 v[218:219], off
	s_waitcnt lgkmcnt(0)
	s_setprio 1
	s_barrier
	v_mfma_f32_16x16x32_bf16 v[116:119], v[226:229], v[186:189], v[116:119]
	v_mfma_f32_16x16x32_bf16 v[112:115], v[234:237], v[186:189], v[112:115]
	v_mfma_f32_16x16x32_bf16 v[100:103], v[226:229], v[194:197], v[100:103]
	v_mfma_f32_16x16x32_bf16 v[96:99], v[234:237], v[194:197], v[96:99]
	v_mfma_f32_16x16x32_bf16 v[84:87], v[226:229], v[202:205], v[84:87]
	v_mfma_f32_16x16x32_bf16 v[80:83], v[234:237], v[202:205], v[80:83]
	v_mfma_f32_16x16x32_bf16 v[68:71], v[226:229], v[210:213], v[68:71]
	v_mfma_f32_16x16x32_bf16 v[64:67], v[234:237], v[210:213], v[64:67]
	v_mfma_f32_16x16x32_bf16 v[116:119], v[230:233], v[190:193], v[116:119]
	s_mov_b32 m0, s28
	v_mfma_f32_16x16x32_bf16 v[112:115], v[238:241], v[190:193], v[112:115]
	v_lshl_add_u64 v[220:221], s[22:23], 0, v[158:159]
	v_mfma_f32_16x16x32_bf16 v[100:103], v[230:233], v[198:201], v[100:103]
	v_mfma_f32_16x16x32_bf16 v[96:99], v[238:241], v[198:201], v[96:99]
	v_mfma_f32_16x16x32_bf16 v[84:87], v[230:233], v[206:209], v[84:87]
	v_mfma_f32_16x16x32_bf16 v[80:83], v[238:241], v[206:209], v[80:83]
	v_mfma_f32_16x16x32_bf16 v[68:71], v[230:233], v[214:217], v[68:71]
	v_mfma_f32_16x16x32_bf16 v[64:67], v[238:241], v[214:217], v[64:67]
	s_setprio 0
	s_barrier
	ds_read_b128 v[186:189], v137 offset:16384
	ds_read_b128 v[190:193], v137 offset:17408
	ds_read_b128 v[194:197], v137 offset:18432
	ds_read_b128 v[198:201], v137 offset:19456
	ds_read_b128 v[202:205], v137 offset:20480
	ds_read_b128 v[206:209], v137 offset:21504
	ds_read_b128 v[210:213], v137 offset:22528
	ds_read_b128 v[214:217], v137 offset:23552
	global_load_lds_dwordx4 v[220:221], off
	v_lshl_add_u64 v[242:243], s[22:23], 0, v[128:129]
	s_mov_b32 m0, s29
	s_nop 0
	global_load_lds_dwordx4 v[242:243], off
	s_waitcnt lgkmcnt(0)
	s_setprio 1
	s_barrier
	v_mfma_f32_16x16x32_bf16 v[60:63], v[138:141], v[186:189], v[60:63]
	v_mfma_f32_16x16x32_bf16 v[56:59], v[146:149], v[186:189], v[56:59]
	v_mfma_f32_16x16x32_bf16 v[44:47], v[138:141], v[194:197], v[44:47]
	v_mfma_f32_16x16x32_bf16 v[40:43], v[146:149], v[194:197], v[40:43]
	v_mfma_f32_16x16x32_bf16 v[28:31], v[138:141], v[202:205], v[28:31]
	v_mfma_f32_16x16x32_bf16 v[24:27], v[146:149], v[202:205], v[24:27]
	v_mfma_f32_16x16x32_bf16 v[12:15], v[138:141], v[210:213], v[12:15]
	v_mfma_f32_16x16x32_bf16 v[8:11], v[146:149], v[210:213], v[8:11]
	v_mfma_f32_16x16x32_bf16 v[60:63], v[142:145], v[190:193], v[60:63]
	s_add_u32 s40, s20, 0x80000
	v_mfma_f32_16x16x32_bf16 v[56:59], v[150:153], v[190:193], v[56:59]
	s_addc_u32 s41, s21, 0
	v_mfma_f32_16x16x32_bf16 v[44:47], v[142:145], v[198:201], v[44:47]
	s_add_i32 s39, s42, s27
	v_mfma_f32_16x16x32_bf16 v[40:43], v[150:153], v[198:201], v[40:43]
	v_lshl_add_u64 v[138:139], s[40:41], 0, v[158:159]
	v_mfma_f32_16x16x32_bf16 v[28:31], v[142:145], v[206:209], v[28:31]
	s_mov_b32 m0, s39
	v_mfma_f32_16x16x32_bf16 v[24:27], v[150:153], v[206:209], v[24:27]
	v_mfma_f32_16x16x32_bf16 v[12:15], v[142:145], v[214:217], v[12:15]
	v_mfma_f32_16x16x32_bf16 v[8:11], v[150:153], v[214:217], v[8:11]
	s_setprio 0
	s_barrier
; #define PG8_STAGE(bufoff, gbase) do { _Pragma("unroll") for (int _i = 0; _i < 2; ++_i) \
;         __builtin_amdgcn_global_load_lds((const unsigned*)((const char*)(gbase) + voff[_i]), (LAS unsigned*)(lds + (bufoff) + ldsw + _i * 8192), 16, 0, 0); } while (0)
; #define PG8_LDA(dst, b, h) do { _Pragma("unroll") for (int m = 0; m < 4; ++m) _Pragma("unroll") for (int k = 0; k < 2; ++k) dst[m][k] = *(const LAS bf16x8*)(lds + PG8_SA(b, h) + aoff + m * 2048 + k * 1024); } while (0)
; #define PG8_LDB(dst, b, h) do { _Pragma("unroll") for (int n = 0; n < 2; ++n) _Pragma("unroll") for (int k = 0; k < 2; ++k) dst[n][k] = *(const LAS bf16x8*)(lds + PG8_SB(b, h) + boff + n * 2048 + k * 1024); } while (0)
; #define PG8_MMA(ai, bj, At, Bt) do { __builtin_amdgcn_s_setprio(1); _Pragma("unroll") for (int m = 0; m < 4; ++m) _Pragma("unroll") for (int n = 0; n < 2; ++n) _Pragma("unroll") for (int k = 0; k < 2; ++k) \
;         acc[ai][bj][m][n] = __builtin_amdgcn_mfma_f32_16x16x32_bf16(Bt[n][k], At[m][k], acc[ai][bj][m][n], 0, 0, 0); __builtin_amdgcn_s_setprio(0); } while (0)
; #define PG8_WAIT_V(n) asm volatile("s_waitcnt vmcnt(" #n ")" ::: "memory")
; #define PG8_WAIT_L(n) asm volatile("s_waitcnt lgkmcnt(" #n ")" ::: "memory")
; #define PG8_BAR __builtin_amdgcn_s_barrier()
; #define PG8_SCHED __builtin_amdgcn_sched_barrier(0)
; template <class Epi>
; DI void gemm_phase(LAS unsigned char* lds, const Gemm g, const StaticOrder& S, const Epi& E) {
;     ...
;             PG8_WAIT_V(6); PG8_BAR; PG8_MMA(1, 1, At, B1); PG8_BAR;
;             PG8_LDB(B0, 1, 0); PG8_SCHED; PG8_LDA(At, 1, 0); PG8_STAGE(PG8_SA(0, 1), a2 + hstep);
;             PG8_WAIT_L(8); PG8_BAR; PG8_WAIT_L(0); PG8_MMA(0, 0, At, B0); PG8_BAR; PG8_SCHED;
;             PG8_LDB(B1, 1, 1); PG8_STAGE(PG8_SB(1, 0), b3);
;             PG8_BAR; PG8_WAIT_L(0); PG8_MMA(0, 1, At, B1); PG8_BAR;
;             PG8_LDA(At, 1, 1); PG8_STAGE(PG8_SA(1, 0), a3);
;             PG8_BAR; PG8_WAIT_L(0); PG8_MMA(1, 0, At, B0); PG8_BAR; PG8_SCHED;
	s_nop 0
	global_load_lds_dwordx4 v[138:139], off
	v_lshl_add_u64 v[138:139], s[40:41], 0, v[128:129]
	s_add_i32 m0, s39, 0x2000
	s_nop 0
	global_load_lds_dwordx4 v[138:139], off
	s_waitcnt vmcnt(6)
	s_setprio 1
	s_barrier
	v_mfma_f32_16x16x32_bf16 v[52:55], v[226:229], v[186:189], v[52:55]
	v_mfma_f32_16x16x32_bf16 v[48:51], v[234:237], v[186:189], v[48:51]
	v_mfma_f32_16x16x32_bf16 v[36:39], v[226:229], v[194:197], v[36:39]
	v_mfma_f32_16x16x32_bf16 v[32:35], v[234:237], v[194:197], v[32:35]
	v_mfma_f32_16x16x32_bf16 v[20:23], v[226:229], v[202:205], v[20:23]
	v_mfma_f32_16x16x32_bf16 v[16:19], v[234:237], v[202:205], v[16:19]
	v_mfma_f32_16x16x32_bf16 v[4:7], v[226:229], v[210:213], v[4:7]
	v_mfma_f32_16x16x32_bf16 v[0:3], v[234:237], v[210:213], v[0:3]
	v_mfma_f32_16x16x32_bf16 v[52:55], v[230:233], v[190:193], v[52:55]
	s_add_i32 s39, 0, 0x18000
	v_mfma_f32_16x16x32_bf16 v[48:51], v[238:241], v[190:193], v[48:51]
	v_add_u32_e32 v150, s39, v135
	v_mfma_f32_16x16x32_bf16 v[36:39], v[230:233], v[198:201], v[36:39]
	v_mfma_f32_16x16x32_bf16 v[32:35], v[238:241], v[198:201], v[32:35]
	v_mfma_f32_16x16x32_bf16 v[20:23], v[230:233], v[206:209], v[20:23]
	v_mfma_f32_16x16x32_bf16 v[16:19], v[238:241], v[206:209], v[16:19]
	v_mfma_f32_16x16x32_bf16 v[4:7], v[230:233], v[214:217], v[4:7]
	v_mfma_f32_16x16x32_bf16 v[0:3], v[238:241], v[214:217], v[0:3]
	s_setprio 0
	s_barrier
	ds_read_b128 v[138:141], v150
	ds_read_b128 v[142:145], v150 offset:1024
	ds_read_b128 v[146:149], v150 offset:2048
	ds_read_b128 v[150:153], v150 offset:3072
	s_add_u32 s22, s22, 0x80000
	s_addc_u32 s23, s23, 0
	s_mov_b32 m0, s30
	v_lshl_add_u64 v[226:227], s[22:23], 0, v[158:159]
	ds_read_b128 v[186:189], v137 offset:32768
	ds_read_b128 v[190:193], v137 offset:33792
	ds_read_b128 v[194:197], v137 offset:34816
	ds_read_b128 v[198:201], v137 offset:35840
	ds_read_b128 v[202:205], v137 offset:36864
	ds_read_b128 v[206:209], v137 offset:37888
	ds_read_b128 v[210:213], v137 offset:38912
	ds_read_b128 v[214:217], v137 offset:39936
	global_load_lds_dwordx4 v[226:227], off
	v_lshl_add_u64 v[226:227], s[22:23], 0, v[128:129]
	s_mov_b32 m0, s31
	s_nop 0
	global_load_lds_dwordx4 v[226:227], off
	s_waitcnt lgkmcnt(8)
	s_setprio 1
	s_barrier
	s_waitcnt lgkmcnt(0)
	v_mfma_f32_16x16x32_bf16 v[124:127], v[138:141], v[186:189], v[124:127]
	v_mfma_f32_16x16x32_bf16 v[120:123], v[146:149], v[186:189], v[120:123]
	v_mfma_f32_16x16x32_bf16 v[108:111], v[138:141], v[194:197], v[108:111]
	v_mfma_f32_16x16x32_bf16 v[104:107], v[146:149], v[194:197], v[104:107]
	v_mfma_f32_16x16x32_bf16 v[92:95], v[138:141], v[202:205], v[92:95]
	v_mfma_f32_16x16x32_bf16 v[88:91], v[146:149], v[202:205], v[88:91]
	v_mfma_f32_16x16x32_bf16 v[76:79], v[138:141], v[210:213], v[76:79]
	v_mfma_f32_16x16x32_bf16 v[72:75], v[146:149], v[210:213], v[72:75]
	v_mfma_f32_16x16x32_bf16 v[124:127], v[142:145], v[190:193], v[124:127]
	s_add_i32 s22, 0, 0x1c000
	v_mfma_f32_16x16x32_bf16 v[120:123], v[150:153], v[190:193], v[120:123]
	s_add_i32 s23, s39, s27
	v_mfma_f32_16x16x32_bf16 v[108:111], v[142:145], v[198:201], v[108:111]
	v_add_u32_e32 v225, s22, v135
	v_mfma_f32_16x16x32_bf16 v[104:107], v[150:153], v[198:201], v[104:107]
	v_lshl_add_u64 v[154:155], v[154:155], 0, s[94:95]
	v_mfma_f32_16x16x32_bf16 v[92:95], v[142:145], v[206:209], v[92:95]
	s_mov_b32 m0, s23
	v_mfma_f32_16x16x32_bf16 v[88:91], v[150:153], v[206:209], v[88:91]
	v_mfma_f32_16x16x32_bf16 v[76:79], v[142:145], v[214:217], v[76:79]
	v_mfma_f32_16x16x32_bf16 v[72:75], v[150:153], v[214:217], v[72:75]
	s_setprio 0
	s_barrier
	ds_read_b128 v[226:229], v225
	ds_read_b128 v[230:233], v225 offset:1024
	ds_read_b128 v[234:237], v225 offset:2048
	ds_read_b128 v[238:241], v225 offset:3072
	global_load_lds_dwordx4 v[154:155], off
	v_lshl_add_u64 v[154:155], v[218:219], 0, s[94:95]
	s_add_i32 m0, s23, 0x2000
	s_nop 0
	global_load_lds_dwordx4 v[154:155], off
	s_waitcnt lgkmcnt(0)
	s_setprio 1
	s_barrier
	v_mfma_f32_16x16x32_bf16 v[116:119], v[226:229], v[186:189], v[116:119]
	v_mfma_f32_16x16x32_bf16 v[112:115], v[234:237], v[186:189], v[112:115]
	v_mfma_f32_16x16x32_bf16 v[100:103], v[226:229], v[194:197], v[100:103]
	v_mfma_f32_16x16x32_bf16 v[96:99], v[234:237], v[194:197], v[96:99]
	v_mfma_f32_16x16x32_bf16 v[84:87], v[226:229], v[202:205], v[84:87]
	v_mfma_f32_16x16x32_bf16 v[80:83], v[234:237], v[202:205], v[80:83]
	v_mfma_f32_16x16x32_bf16 v[68:71], v[226:229], v[210:213], v[68:71]
	v_mfma_f32_16x16x32_bf16 v[64:67], v[234:237], v[210:213], v[64:67]
	v_mfma_f32_16x16x32_bf16 v[116:119], v[230:233], v[190:193], v[116:119]
	s_mov_b32 m0, s34
	v_mfma_f32_16x16x32_bf16 v[112:115], v[238:241], v[190:193], v[112:115]
	v_lshl_add_u64 v[154:155], v[220:221], 0, s[94:95]
	v_mfma_f32_16x16x32_bf16 v[100:103], v[230:233], v[198:201], v[100:103]
	v_mfma_f32_16x16x32_bf16 v[96:99], v[238:241], v[198:201], v[96:99]
	v_mfma_f32_16x16x32_bf16 v[84:87], v[230:233], v[206:209], v[84:87]
	v_mfma_f32_16x16x32_bf16 v[80:83], v[238:241], v[206:209], v[80:83]
	v_mfma_f32_16x16x32_bf16 v[68:71], v[230:233], v[214:217], v[68:71]
	v_mfma_f32_16x16x32_bf16 v[64:67], v[238:241], v[214:217], v[64:67]
	s_setprio 0
	s_barrier
	ds_read_b128 v[186:189], v137 offset:49152
	ds_read_b128 v[190:193], v137 offset:50176
	ds_read_b128 v[194:197], v137 offset:51200
	ds_read_b128 v[198:201], v137 offset:52224
	ds_read_b128 v[202:205], v137 offset:53248
	ds_read_b128 v[206:209], v137 offset:54272
	ds_read_b128 v[210:213], v137 offset:55296
	ds_read_b128 v[214:217], v137 offset:56320
	global_load_lds_dwordx4 v[154:155], off
	v_lshl_add_u64 v[154:155], v[242:243], 0, s[94:95]
	s_mov_b32 m0, s35
	s_nop 0
	global_load_lds_dwordx4 v[154:155], off
	s_waitcnt lgkmcnt(0)
	s_setprio 1
	s_barrier
; #define PG8_STAGE(bufoff, gbase) do { _Pragma("unroll") for (int _i = 0; _i < 2; ++_i) \
;         __builtin_amdgcn_global_load_lds((const unsigned*)((const char*)(gbase) + voff[_i]), (LAS unsigned*)(lds + (bufoff) + ldsw + _i * 8192), 16, 0, 0); } while (0)
; #define PG8_MMA(ai, bj, At, Bt) do { __builtin_amdgcn_s_setprio(1); _Pragma("unroll") for (int m = 0; m < 4; ++m) _Pragma("unroll") for (int n = 0; n < 2; ++n) _Pragma("unroll") for (int k = 0; k < 2; ++k) \
;         acc[ai][bj][m][n] = __builtin_amdgcn_mfma_f32_16x16x32_bf16(Bt[n][k], At[m][k], acc[ai][bj][m][n], 0, 0, 0); __builtin_amdgcn_s_setprio(0); } while (0)
; #define PG8_WAIT_V(n) asm volatile("s_waitcnt vmcnt(" #n ")" ::: "memory")
; #define PG8_WAIT_L(n) asm volatile("s_waitcnt lgkmcnt(" #n ")" ::: "memory")
; #define PG8_BAR __builtin_amdgcn_s_barrier()
; #define PG8_SCHED __builtin_amdgcn_sched_barrier(0)
; template <class Epi>
; DI void gemm_phase(LAS unsigned char* lds, const Gemm g, const StaticOrder& S, const Epi& E) {
;     ...
;             PG8_BAR; PG8_WAIT_L(0); PG8_MMA(1, 0, At, B0); PG8_BAR; PG8_SCHED;
;             PG8_STAGE(PG8_SB(1, 1), b3 + hstep);
;             PG8_WAIT_V(6); PG8_BAR; PG8_MMA(1, 1, At, B1); PG8_BAR;
;     DI void operator()(const f32x4 (&acc)[2][2][4][2], const Unit& u, int wr, int wc, int fr, int fq) const {
;         const int row0 = u.pm * BM + wr * 64 + fr, col0 = u.pn * HALF + wc * 32 + 8 * fq;
; #pragma unroll
;         for (int ai = 0; ai < 2; ++ai)
; #pragma unroll
;             for (int m = 0; m < 4; ++m) { float hv[8];
; #pragma unroll
;                 for (int n = 0; n < 2; ++n)
; #pragma unroll
;                     for (int e = 0; e < 4; ++e) { const float gt = acc[ai][0][m][n][e], up = acc[ai][1][m][n][e];
;                         hv[n * 4 + e] = gt * __builtin_amdgcn_rcpf(1.f + __builtin_amdgcn_exp2f(-1.4426950408889634f * gt)) * up; }
;                 *(u32x4*)(H + (size_t)(row0 + ai * HALF + m * 16) * DFF + col0) = (u32x4){pk(hv[0], hv[1]), pk(hv[2], hv[3]), pk(hv[4], hv[5]), pk(hv[6], hv[7])}; }
	v_mfma_f32_16x16x32_bf16 v[60:63], v[138:141], v[186:189], v[60:63]
	v_mfma_f32_16x16x32_bf16 v[56:59], v[146:149], v[186:189], v[56:59]
	v_mfma_f32_16x16x32_bf16 v[44:47], v[138:141], v[194:197], v[44:47]
	v_mfma_f32_16x16x32_bf16 v[40:43], v[146:149], v[194:197], v[40:43]
	v_mfma_f32_16x16x32_bf16 v[28:31], v[138:141], v[202:205], v[28:31]
	v_mfma_f32_16x16x32_bf16 v[24:27], v[146:149], v[202:205], v[24:27]
	v_mfma_f32_16x16x32_bf16 v[12:15], v[138:141], v[210:213], v[12:15]
	v_mfma_f32_16x16x32_bf16 v[8:11], v[146:149], v[210:213], v[8:11]
	v_mfma_f32_16x16x32_bf16 v[60:63], v[142:145], v[190:193], v[60:63]
	s_add_u32 s20, s20, 0x80080
	v_mfma_f32_16x16x32_bf16 v[56:59], v[150:153], v[190:193], v[56:59]
	s_addc_u32 s21, s21, 0
	v_mfma_f32_16x16x32_bf16 v[44:47], v[142:145], v[198:201], v[44:47]
	s_add_i32 s22, s22, s27
	v_mfma_f32_16x16x32_bf16 v[40:43], v[150:153], v[198:201], v[40:43]
	v_lshl_add_u64 v[138:139], s[20:21], 0, v[158:159]
	v_mfma_f32_16x16x32_bf16 v[28:31], v[142:145], v[206:209], v[28:31]
	s_mov_b32 m0, s22
	v_mfma_f32_16x16x32_bf16 v[24:27], v[150:153], v[206:209], v[24:27]
	v_mfma_f32_16x16x32_bf16 v[12:15], v[142:145], v[214:217], v[12:15]
	v_mfma_f32_16x16x32_bf16 v[8:11], v[150:153], v[214:217], v[8:11]
	s_setprio 0
	s_barrier
	s_nop 0
	global_load_lds_dwordx4 v[138:139], off
	v_lshl_add_u64 v[138:139], s[20:21], 0, v[128:129]
	s_add_i32 m0, s22, 0x2000
	s_nop 0
	global_load_lds_dwordx4 v[138:139], off
	s_waitcnt vmcnt(6)
	s_setprio 1
	s_barrier
	v_mfma_f32_16x16x32_bf16 v[52:55], v[226:229], v[186:189], v[52:55]
	v_mfma_f32_16x16x32_bf16 v[48:51], v[234:237], v[186:189], v[48:51]
	v_mfma_f32_16x16x32_bf16 v[36:39], v[226:229], v[194:197], v[36:39]
	v_mfma_f32_16x16x32_bf16 v[32:35], v[234:237], v[194:197], v[32:35]
	v_mfma_f32_16x16x32_bf16 v[20:23], v[226:229], v[202:205], v[20:23]
	v_mfma_f32_16x16x32_bf16 v[16:19], v[234:237], v[202:205], v[16:19]
	v_mfma_f32_16x16x32_bf16 v[4:7], v[226:229], v[210:213], v[4:7]
	v_mfma_f32_16x16x32_bf16 v[0:3], v[234:237], v[210:213], v[0:3]
	v_mfma_f32_16x16x32_bf16 v[52:55], v[230:233], v[190:193], v[52:55]
	s_add_i32 s38, s38, 2
	v_mfma_f32_16x16x32_bf16 v[48:51], v[238:241], v[190:193], v[48:51]
	s_add_u32 s18, s18, 0x100
	v_mfma_f32_16x16x32_bf16 v[36:39], v[230:233], v[198:201], v[36:39]
	s_addc_u32 s19, s19, 0
	v_mfma_f32_16x16x32_bf16 v[32:35], v[238:241], v[198:201], v[32:35]
	s_add_u32 s33, s33, 0x100
	v_mfma_f32_16x16x32_bf16 v[20:23], v[230:233], v[206:209], v[20:23]
	s_addc_u32 s37, s37, 0
	v_mfma_f32_16x16x32_bf16 v[16:19], v[238:241], v[206:209], v[16:19]
	s_cmp_gt_u32 s38, 29
	v_mfma_f32_16x16x32_bf16 v[4:7], v[230:233], v[214:217], v[4:7]
	v_mfma_f32_16x16x32_bf16 v[0:3], v[238:241], v[214:217], v[0:3]
	s_setprio 0
	s_barrier
	s_cbranch_scc0 .LBB0_37
	v_mul_f32_e32 v139, 0xbfb8aa3b, v124
	v_exp_f32_e32 v139, v139
	v_lshl_or_b32 v140, s2, 7, v136
	v_lshl_add_u32 v138, s3, 8, v134
	v_ashrrev_i32_e32 v141, 31, v140
	v_add_f32_e32 v139, 1.0, v139
	v_rcp_f32_e32 v142, v139
	v_mul_f32_e32 v139, 0xbfb8aa3b, v125
	v_exp_f32_e32 v139, v139
	s_movk_i32 s4, 0x2c00
	s_and_b64 vcc, exec, s[6:7]
	s_mov_b64 s[20:21], s[16:17]
	v_add_f32_e32 v139, 1.0, v139
	v_rcp_f32_e32 v143, v139
	v_mul_f32_e32 v139, 0xbfb8aa3b, v126
	v_exp_f32_e32 v139, v139
	s_mov_b64 s[18:19], s[14:15]
	v_pk_mul_f32 v[124:125], v[124:125], v[142:143]
	v_add_f32_e32 v139, 1.0, v139
	v_rcp_f32_e32 v144, v139
	v_mul_f32_e32 v139, 0xbfb8aa3b, v127
	v_exp_f32_e32 v139, v139
	v_pk_mul_f32 v[116:117], v[124:125], v[116:117]
	v_add_f32_e32 v139, 1.0, v139
	v_rcp_f32_e32 v145, v139
	v_mul_f32_e32 v139, 0xbfb8aa3b, v120
	v_exp_f32_e32 v139, v139
	v_cvt_pk_bf16_f32 v116, v116, v117
	v_pk_mul_f32 v[124:125], v[126:127], v[144:145]
	v_add_f32_e32 v139, 1.0, v139
	v_rcp_f32_e32 v146, v139
	v_mul_f32_e32 v139, 0xbfb8aa3b, v121
	v_exp_f32_e32 v139, v139
	v_pk_mul_f32 v[118:119], v[124:125], v[118:119]
	v_add_f32_e32 v139, 1.0, v139
	v_rcp_f32_e32 v147, v139
	v_mul_f32_e32 v139, 0xbfb8aa3b, v122
	v_exp_f32_e32 v139, v139
	v_cvt_pk_bf16_f32 v117, v118, v119
	v_pk_mul_f32 v[118:119], v[120:121], v[146:147]
	v_add_f32_e32 v139, 1.0, v139
	v_rcp_f32_e32 v148, v139
	v_mul_f32_e32 v139, 0xbfb8aa3b, v123
	v_exp_f32_e32 v139, v139
	v_pk_mul_f32 v[112:113], v[118:119], v[112:113]
	v_add_f32_e32 v139, 1.0, v139
	v_rcp_f32_e32 v149, v139
	v_cvt_pk_bf16_f32 v118, v112, v113
	v_pk_mul_f32 v[112:113], v[122:123], v[148:149]
	s_nop 0
	v_pk_mul_f32 v[112:113], v[112:113], v[114:115]
	v_lshlrev_b64 v[114:115], 1, v[140:141]
	v_cvt_pk_bf16_f32 v119, v112, v113
	v_mov_b64_e32 v[112:113], s[54:55]
	v_mad_i64_i32 v[120:121], s[2:3], v138, s4, v[112:113]
	v_lshl_add_u64 v[120:121], v[120:121], 0, v[114:115]
	global_store_dwordx4 v[120:121], v[116:119], off
	v_mul_f32_e32 v120, 0xbfb8aa3b, v104
	v_mul_f32_e32 v121, 0xbfb8aa3b, v105
	v_mul_f32_e32 v116, 0xbfb8aa3b, v108
	v_mul_f32_e32 v117, 0xbfb8aa3b, v109
	v_exp_f32_e32 v116, v116
	v_exp_f32_e32 v117, v117
	v_mul_f32_e32 v118, 0xbfb8aa3b, v110
	v_mul_f32_e32 v119, 0xbfb8aa3b, v111
	v_exp_f32_e32 v118, v118
	v_exp_f32_e32 v119, v119
	v_exp_f32_e32 v120, v120
	v_exp_f32_e32 v121, v121
	v_add_f32_e32 v116, 1.0, v116
	v_add_f32_e32 v117, 1.0, v117
	v_mul_f32_e32 v122, 0xbfb8aa3b, v106
	v_mul_f32_e32 v123, 0xbfb8aa3b, v107
	v_rcp_f32_e32 v116, v116
	v_rcp_f32_e32 v117, v117
	v_add_f32_e32 v118, 1.0, v118
	v_add_f32_e32 v119, 1.0, v119
	v_exp_f32_e32 v122, v122
	v_exp_f32_e32 v123, v123
	v_rcp_f32_e32 v118, v118
	v_rcp_f32_e32 v119, v119
	v_add_f32_e32 v120, 1.0, v120
	v_add_f32_e32 v121, 1.0, v121
	v_rcp_f32_e32 v120, v120
	v_rcp_f32_e32 v121, v121
	v_add_f32_e32 v122, 1.0, v122
;     DI void operator()(const f32x4 (&acc)[2][2][4][2], const Unit& u, int wr, int wc, int fr, int fq) const {
;         const int row0 = u.pm * BM + wr * 64 + fr, col0 = u.pn * HALF + wc * 32 + 8 * fq;
; #pragma unroll
;         for (int ai = 0; ai < 2; ++ai)
; #pragma unroll
;             for (int m = 0; m < 4; ++m) { float hv[8];
; #pragma unroll
;                 for (int n = 0; n < 2; ++n)
; #pragma unroll
;                     for (int e = 0; e < 4; ++e) { const float gt = acc[ai][0][m][n][e], up = acc[ai][1][m][n][e];
;                         hv[n * 4 + e] = gt * __builtin_amdgcn_rcpf(1.f + __builtin_amdgcn_exp2f(-1.4426950408889634f * gt)) * up; }
;                 *(u32x4*)(H + (size_t)(row0 + ai * HALF + m * 16) * DFF + col0) = (u32x4){pk(hv[0], hv[1]), pk(hv[2], hv[3]), pk(hv[4], hv[5]), pk(hv[6], hv[7])}; }
	v_add_f32_e32 v123, 1.0, v123
	v_pk_mul_f32 v[108:109], v[108:109], v[116:117]
	v_rcp_f32_e32 v122, v122
	v_rcp_f32_e32 v123, v123
	v_pk_mul_f32 v[100:101], v[108:109], v[100:101]
	v_pk_mul_f32 v[108:109], v[110:111], v[118:119]
	v_cvt_pk_bf16_f32 v100, v100, v101
	v_pk_mul_f32 v[102:103], v[108:109], v[102:103]
	s_nop 0
	v_cvt_pk_bf16_f32 v101, v102, v103
	v_pk_mul_f32 v[102:103], v[104:105], v[120:121]
	s_nop 0
	v_pk_mul_f32 v[96:97], v[102:103], v[96:97]
	s_nop 0
	v_cvt_pk_bf16_f32 v102, v96, v97
	v_pk_mul_f32 v[96:97], v[106:107], v[122:123]
	s_nop 0
	v_pk_mul_f32 v[96:97], v[96:97], v[98:99]
	v_mul_f32_e32 v98, 0xbfb8aa3b, v94
	v_cvt_pk_bf16_f32 v103, v96, v97
	v_or_b32_e32 v96, 16, v138
	v_mad_i64_i32 v[96:97], s[2:3], v96, s4, v[112:113]
	v_lshl_add_u64 v[96:97], v[96:97], 0, v[114:115]
	global_store_dwordx4 v[96:97], v[100:103], off
	v_mul_f32_e32 v96, 0xbfb8aa3b, v92
	v_mul_f32_e32 v97, 0xbfb8aa3b, v93
	v_exp_f32_e32 v96, v96
	v_exp_f32_e32 v97, v97
	v_mul_f32_e32 v99, 0xbfb8aa3b, v95
	v_exp_f32_e32 v98, v98
	v_exp_f32_e32 v99, v99
	v_mul_f32_e32 v100, 0xbfb8aa3b, v88
	v_mul_f32_e32 v101, 0xbfb8aa3b, v89
	v_exp_f32_e32 v100, v100
	v_exp_f32_e32 v101, v101
	v_add_f32_e32 v96, 1.0, v96
	v_add_f32_e32 v97, 1.0, v97
	v_mul_f32_e32 v102, 0xbfb8aa3b, v90
	v_mul_f32_e32 v103, 0xbfb8aa3b, v91
	v_rcp_f32_e32 v96, v96
	v_rcp_f32_e32 v97, v97
	v_add_f32_e32 v98, 1.0, v98
	v_add_f32_e32 v99, 1.0, v99
	v_exp_f32_e32 v102, v102
	v_exp_f32_e32 v103, v103
	v_rcp_f32_e32 v98, v98
	v_rcp_f32_e32 v99, v99
	v_add_f32_e32 v100, 1.0, v100
	v_add_f32_e32 v101, 1.0, v101
	v_rcp_f32_e32 v100, v100
	v_rcp_f32_e32 v101, v101
	v_add_f32_e32 v102, 1.0, v102
	v_add_f32_e32 v103, 1.0, v103
	v_pk_mul_f32 v[92:93], v[92:93], v[96:97]
	v_rcp_f32_e32 v102, v102
	v_rcp_f32_e32 v103, v103
	v_pk_mul_f32 v[84:85], v[92:93], v[84:85]
	v_pk_mul_f32 v[92:93], v[94:95], v[98:99]
	v_cvt_pk_bf16_f32 v84, v84, v85
	v_pk_mul_f32 v[86:87], v[92:93], v[86:87]
	s_nop 0
	v_cvt_pk_bf16_f32 v85, v86, v87
	v_pk_mul_f32 v[86:87], v[88:89], v[100:101]
	s_nop 0
	v_pk_mul_f32 v[80:81], v[86:87], v[80:81]
	s_nop 0
	v_cvt_pk_bf16_f32 v86, v80, v81
	v_pk_mul_f32 v[80:81], v[90:91], v[102:103]
	s_nop 0
	v_pk_mul_f32 v[80:81], v[80:81], v[82:83]
	v_mul_f32_e32 v82, 0xbfb8aa3b, v78
	v_cvt_pk_bf16_f32 v87, v80, v81
	v_or_b32_e32 v80, 32, v138
	v_mad_i64_i32 v[80:81], s[2:3], v80, s4, v[112:113]
	v_lshl_add_u64 v[80:81], v[80:81], 0, v[114:115]
	global_store_dwordx4 v[80:81], v[84:87], off
	v_mul_f32_e32 v80, 0xbfb8aa3b, v76
	v_mul_f32_e32 v81, 0xbfb8aa3b, v77
	v_exp_f32_e32 v80, v80
	v_exp_f32_e32 v81, v81
	v_mul_f32_e32 v83, 0xbfb8aa3b, v79
	v_exp_f32_e32 v82, v82
	v_exp_f32_e32 v83, v83
	v_mul_f32_e32 v84, 0xbfb8aa3b, v72
	v_mul_f32_e32 v85, 0xbfb8aa3b, v73
	v_exp_f32_e32 v84, v84
	v_exp_f32_e32 v85, v85
	v_add_f32_e32 v80, 1.0, v80
	v_add_f32_e32 v81, 1.0, v81
	v_mul_f32_e32 v86, 0xbfb8aa3b, v74
	v_mul_f32_e32 v87, 0xbfb8aa3b, v75
	v_rcp_f32_e32 v80, v80
	v_rcp_f32_e32 v81, v81
	v_add_f32_e32 v82, 1.0, v82
	v_add_f32_e32 v83, 1.0, v83
	v_exp_f32_e32 v86, v86
	v_exp_f32_e32 v87, v87
	v_rcp_f32_e32 v82, v82
	v_rcp_f32_e32 v83, v83
	v_add_f32_e32 v84, 1.0, v84
	v_add_f32_e32 v85, 1.0, v85
	v_rcp_f32_e32 v84, v84
	v_rcp_f32_e32 v85, v85
	v_add_f32_e32 v86, 1.0, v86
	v_add_f32_e32 v87, 1.0, v87
	v_pk_mul_f32 v[76:77], v[76:77], v[80:81]
	v_rcp_f32_e32 v86, v86
	v_rcp_f32_e32 v87, v87
	v_pk_mul_f32 v[68:69], v[76:77], v[68:69]
	v_pk_mul_f32 v[76:77], v[78:79], v[82:83]
	v_cvt_pk_bf16_f32 v68, v68, v69
	v_pk_mul_f32 v[70:71], v[76:77], v[70:71]
	s_nop 0
	v_cvt_pk_bf16_f32 v69, v70, v71
	v_pk_mul_f32 v[70:71], v[72:73], v[84:85]
	v_add_u32_e32 v72, 0x80, v138
	v_pk_mul_f32 v[64:65], v[70:71], v[64:65]
	s_nop 0
	v_cvt_pk_bf16_f32 v70, v64, v65
	v_pk_mul_f32 v[64:65], v[74:75], v[86:87]
	s_nop 0
	v_pk_mul_f32 v[64:65], v[64:65], v[66:67]
	v_mul_f32_e32 v66, 0xbfb8aa3b, v62
	v_cvt_pk_bf16_f32 v71, v64, v65
	v_or_b32_e32 v64, 48, v138
	v_mad_i64_i32 v[64:65], s[2:3], v64, s4, v[112:113]
	v_lshl_add_u64 v[64:65], v[64:65], 0, v[114:115]
	global_store_dwordx4 v[64:65], v[68:71], off
	v_mul_f32_e32 v64, 0xbfb8aa3b, v60
	v_mul_f32_e32 v65, 0xbfb8aa3b, v61
	v_exp_f32_e32 v64, v64
	v_exp_f32_e32 v65, v65
	v_mul_f32_e32 v67, 0xbfb8aa3b, v63
	v_exp_f32_e32 v66, v66
	v_exp_f32_e32 v67, v67
	v_mul_f32_e32 v68, 0xbfb8aa3b, v56
	v_mul_f32_e32 v69, 0xbfb8aa3b, v57
	v_exp_f32_e32 v68, v68
	v_exp_f32_e32 v69, v69
	v_add_f32_e32 v64, 1.0, v64
	v_add_f32_e32 v65, 1.0, v65
	v_mul_f32_e32 v70, 0xbfb8aa3b, v58
	v_mul_f32_e32 v71, 0xbfb8aa3b, v59
	v_rcp_f32_e32 v64, v64
	v_rcp_f32_e32 v65, v65
	v_add_f32_e32 v66, 1.0, v66
	v_add_f32_e32 v67, 1.0, v67
	v_exp_f32_e32 v70, v70
	v_exp_f32_e32 v71, v71
	v_rcp_f32_e32 v66, v66
	v_rcp_f32_e32 v67, v67
	v_add_f32_e32 v68, 1.0, v68
	v_add_f32_e32 v69, 1.0, v69
	v_rcp_f32_e32 v68, v68
	v_rcp_f32_e32 v69, v69
	v_add_f32_e32 v70, 1.0, v70
	v_add_f32_e32 v71, 1.0, v71
	v_pk_mul_f32 v[60:61], v[60:61], v[64:65]
	v_rcp_f32_e32 v70, v70
	v_rcp_f32_e32 v71, v71
	v_pk_mul_f32 v[52:53], v[60:61], v[52:53]
	v_pk_mul_f32 v[60:61], v[62:63], v[66:67]
	v_cvt_pk_bf16_f32 v52, v52, v53
	v_pk_mul_f32 v[54:55], v[60:61], v[54:55]
	s_nop 0
	v_cvt_pk_bf16_f32 v53, v54, v55
	v_pk_mul_f32 v[54:55], v[56:57], v[68:69]
; #define PG8_WAIT_V(n) asm volatile("s_waitcnt vmcnt(" #n ")" ::: "memory")
; #define PG8_BAR __builtin_amdgcn_s_barrier()
; template <class Epi>
; DI void gemm_phase(LAS unsigned char* lds, const Gemm g, const StaticOrder& S, const Epi& E) {
;     ...
;         E(acc, cur, wr, wc, fr, fq);
;         if (!has_next) break;
; #pragma unroll
;         for (int a = 0; a < 2; ++a)
; #pragma unroll
;             for (int b = 0; b < 2; ++b)
; #pragma unroll
;                 for (int m = 0; m < 4; ++m)
; #pragma unroll
;                     for (int n = 0; n < 2; ++n) acc[a][b][m][n] = (f32x4){0.f, 0.f, 0.f, 0.f};
;         cur = nxt; cA = nA; cB = nB; ++ui;
;     }
;     PG8_WAIT_V(0);
;     if (wr == 0) PG8_BAR;
;     PG8_BAR;
;     DI void operator()(const f32x4 (&acc)[2][2][4][2], const Unit& u, int wr, int wc, int fr, int fq) const {
;         const int row0 = u.pm * BM + wr * 64 + fr, col0 = u.pn * HALF + wc * 32 + 8 * fq;
; #pragma unroll
;         for (int ai = 0; ai < 2; ++ai)
; #pragma unroll
;             for (int m = 0; m < 4; ++m) { float hv[8];
; #pragma unroll
;                 for (int n = 0; n < 2; ++n)
; #pragma unroll
;                     for (int e = 0; e < 4; ++e) { const float gt = acc[ai][0][m][n][e], up = acc[ai][1][m][n][e];
;                         hv[n * 4 + e] = gt * __builtin_amdgcn_rcpf(1.f + __builtin_amdgcn_exp2f(-1.4426950408889634f * gt)) * up; }
;                 *(u32x4*)(H + (size_t)(row0 + ai * HALF + m * 16) * DFF + col0) = (u32x4){pk(hv[0], hv[1]), pk(hv[2], hv[3]), pk(hv[4], hv[5]), pk(hv[6], hv[7])}; }
	s_nop 0
	v_pk_mul_f32 v[48:49], v[54:55], v[48:49]
	s_nop 0
	v_cvt_pk_bf16_f32 v54, v48, v49
	v_pk_mul_f32 v[48:49], v[58:59], v[70:71]
	s_nop 0
	v_pk_mul_f32 v[48:49], v[48:49], v[50:51]
	v_mul_f32_e32 v50, 0xbfb8aa3b, v46
	v_cvt_pk_bf16_f32 v55, v48, v49
	v_mad_i64_i32 v[48:49], s[2:3], v72, s4, v[112:113]
	v_lshl_add_u64 v[48:49], v[48:49], 0, v[114:115]
	global_store_dwordx4 v[48:49], v[52:55], off
	v_mul_f32_e32 v48, 0xbfb8aa3b, v44
	v_mul_f32_e32 v49, 0xbfb8aa3b, v45
	v_exp_f32_e32 v48, v48
	v_exp_f32_e32 v49, v49
	v_mul_f32_e32 v51, 0xbfb8aa3b, v47
	v_exp_f32_e32 v50, v50
	v_exp_f32_e32 v51, v51
	v_mul_f32_e32 v52, 0xbfb8aa3b, v40
	v_mul_f32_e32 v53, 0xbfb8aa3b, v41
	v_exp_f32_e32 v52, v52
	v_exp_f32_e32 v53, v53
	v_add_f32_e32 v48, 1.0, v48
	v_add_f32_e32 v49, 1.0, v49
	v_mul_f32_e32 v54, 0xbfb8aa3b, v42
	v_mul_f32_e32 v55, 0xbfb8aa3b, v43
	v_rcp_f32_e32 v48, v48
	v_rcp_f32_e32 v49, v49
	v_add_f32_e32 v50, 1.0, v50
	v_add_f32_e32 v51, 1.0, v51
	v_exp_f32_e32 v54, v54
	v_exp_f32_e32 v55, v55
	v_rcp_f32_e32 v50, v50
	v_rcp_f32_e32 v51, v51
	v_add_f32_e32 v52, 1.0, v52
	v_add_f32_e32 v53, 1.0, v53
	v_rcp_f32_e32 v52, v52
	v_rcp_f32_e32 v53, v53
	v_add_f32_e32 v54, 1.0, v54
	v_add_f32_e32 v55, 1.0, v55
	v_pk_mul_f32 v[44:45], v[44:45], v[48:49]
	v_rcp_f32_e32 v54, v54
	v_rcp_f32_e32 v55, v55
	v_pk_mul_f32 v[36:37], v[44:45], v[36:37]
	v_pk_mul_f32 v[44:45], v[46:47], v[50:51]
	v_cvt_pk_bf16_f32 v36, v36, v37
	v_pk_mul_f32 v[38:39], v[44:45], v[38:39]
	s_nop 0
	v_cvt_pk_bf16_f32 v37, v38, v39
	v_pk_mul_f32 v[38:39], v[40:41], v[52:53]
	s_nop 0
	v_pk_mul_f32 v[32:33], v[38:39], v[32:33]
	s_nop 0
	v_cvt_pk_bf16_f32 v38, v32, v33
	v_pk_mul_f32 v[32:33], v[42:43], v[54:55]
	s_nop 0
	v_pk_mul_f32 v[32:33], v[32:33], v[34:35]
	v_mul_f32_e32 v34, 0xbfb8aa3b, v30
	v_cvt_pk_bf16_f32 v39, v32, v33
	v_add_u32_e32 v32, 0x90, v138
	v_mad_i64_i32 v[32:33], s[2:3], v32, s4, v[112:113]
	v_lshl_add_u64 v[32:33], v[32:33], 0, v[114:115]
	global_store_dwordx4 v[32:33], v[36:39], off
	v_mul_f32_e32 v32, 0xbfb8aa3b, v28
	v_mul_f32_e32 v33, 0xbfb8aa3b, v29
	v_exp_f32_e32 v32, v32
	v_exp_f32_e32 v33, v33
	v_mul_f32_e32 v35, 0xbfb8aa3b, v31
	v_exp_f32_e32 v34, v34
	v_exp_f32_e32 v35, v35
	v_mul_f32_e32 v36, 0xbfb8aa3b, v24
	v_mul_f32_e32 v37, 0xbfb8aa3b, v25
	v_exp_f32_e32 v36, v36
	v_exp_f32_e32 v37, v37
	v_add_f32_e32 v32, 1.0, v32
	v_add_f32_e32 v33, 1.0, v33
	v_mul_f32_e32 v38, 0xbfb8aa3b, v26
	v_mul_f32_e32 v39, 0xbfb8aa3b, v27
	v_rcp_f32_e32 v32, v32
	v_rcp_f32_e32 v33, v33
	v_add_f32_e32 v34, 1.0, v34
	v_add_f32_e32 v35, 1.0, v35
	v_exp_f32_e32 v38, v38
	v_exp_f32_e32 v39, v39
	v_rcp_f32_e32 v34, v34
	v_rcp_f32_e32 v35, v35
	v_add_f32_e32 v36, 1.0, v36
	v_add_f32_e32 v37, 1.0, v37
	v_rcp_f32_e32 v36, v36
	v_rcp_f32_e32 v37, v37
	v_add_f32_e32 v38, 1.0, v38
	v_add_f32_e32 v39, 1.0, v39
	v_pk_mul_f32 v[28:29], v[28:29], v[32:33]
	v_rcp_f32_e32 v38, v38
	v_rcp_f32_e32 v39, v39
	v_pk_mul_f32 v[20:21], v[28:29], v[20:21]
	v_pk_mul_f32 v[28:29], v[30:31], v[34:35]
	v_cvt_pk_bf16_f32 v20, v20, v21
	v_pk_mul_f32 v[22:23], v[28:29], v[22:23]
	s_nop 0
	v_cvt_pk_bf16_f32 v21, v22, v23
	v_pk_mul_f32 v[22:23], v[24:25], v[36:37]
	s_nop 0
	v_pk_mul_f32 v[16:17], v[22:23], v[16:17]
	s_nop 0
	v_cvt_pk_bf16_f32 v22, v16, v17
	v_pk_mul_f32 v[16:17], v[26:27], v[38:39]
	s_nop 0
	v_pk_mul_f32 v[16:17], v[16:17], v[18:19]
	v_mul_f32_e32 v18, 0xbfb8aa3b, v14
	v_cvt_pk_bf16_f32 v23, v16, v17
	v_add_u32_e32 v16, 0xa0, v138
	v_mad_i64_i32 v[16:17], s[2:3], v16, s4, v[112:113]
	v_lshl_add_u64 v[16:17], v[16:17], 0, v[114:115]
	global_store_dwordx4 v[16:17], v[20:23], off
	v_mul_f32_e32 v16, 0xbfb8aa3b, v12
	v_mul_f32_e32 v17, 0xbfb8aa3b, v13
	v_exp_f32_e32 v16, v16
	v_exp_f32_e32 v17, v17
	v_mul_f32_e32 v19, 0xbfb8aa3b, v15
	v_exp_f32_e32 v18, v18
	v_exp_f32_e32 v19, v19
	v_mul_f32_e32 v20, 0xbfb8aa3b, v8
	v_mul_f32_e32 v21, 0xbfb8aa3b, v9
	v_exp_f32_e32 v20, v20
	v_exp_f32_e32 v21, v21
	v_add_f32_e32 v16, 1.0, v16
	v_add_f32_e32 v17, 1.0, v17
	v_mul_f32_e32 v22, 0xbfb8aa3b, v10
	v_mul_f32_e32 v23, 0xbfb8aa3b, v11
	v_rcp_f32_e32 v16, v16
	v_rcp_f32_e32 v17, v17
	v_add_f32_e32 v18, 1.0, v18
	v_add_f32_e32 v19, 1.0, v19
	v_exp_f32_e32 v22, v22
	v_exp_f32_e32 v23, v23
	v_rcp_f32_e32 v18, v18
	v_rcp_f32_e32 v19, v19
	v_add_f32_e32 v20, 1.0, v20
	v_add_f32_e32 v21, 1.0, v21
	v_rcp_f32_e32 v20, v20
	v_rcp_f32_e32 v21, v21
	v_add_f32_e32 v22, 1.0, v22
	v_add_f32_e32 v23, 1.0, v23
	v_pk_mul_f32 v[12:13], v[12:13], v[16:17]
	v_rcp_f32_e32 v22, v22
	v_rcp_f32_e32 v23, v23
	v_pk_mul_f32 v[4:5], v[12:13], v[4:5]
	v_pk_mul_f32 v[12:13], v[14:15], v[18:19]
	v_cvt_pk_bf16_f32 v4, v4, v5
	v_pk_mul_f32 v[6:7], v[12:13], v[6:7]
	s_nop 0
	v_cvt_pk_bf16_f32 v5, v6, v7
	v_pk_mul_f32 v[6:7], v[8:9], v[20:21]
	s_nop 0
	v_pk_mul_f32 v[0:1], v[6:7], v[0:1]
	s_nop 0
	v_cvt_pk_bf16_f32 v6, v0, v1
	v_pk_mul_f32 v[0:1], v[10:11], v[22:23]
	s_nop 0
	v_pk_mul_f32 v[0:1], v[0:1], v[2:3]
	s_nop 0
	v_cvt_pk_bf16_f32 v7, v0, v1
	v_add_u32_e32 v0, 0xb0, v138
	v_mad_i64_i32 v[0:1], s[2:3], v0, s4, v[112:113]
	v_lshl_add_u64 v[0:1], v[0:1], 0, v[114:115]
	s_mov_b32 s2, s8
	s_mov_b32 s3, s10
	global_store_dwordx4 v[0:1], v[4:7], off
	s_cbranch_vccz .LBB0_34
	s_waitcnt vmcnt(0)
	s_cmpk_gt_u32 s24, 0xff
	s_cbranch_scc1 .LBB0_41
	s_barrier

; #define PG8_STAGE(bufoff, gbase) do { _Pragma("unroll") for (int _i = 0; _i < 2; ++_i) \
;         __builtin_amdgcn_global_load_lds((const unsigned*)((const char*)(gbase) + voff[_i]), (LAS unsigned*)(lds + (bufoff) + ldsw + _i * 8192), 16, 0, 0); } while (0)
; #define PG8_LDA(dst, b, h) do { _Pragma("unroll") for (int m = 0; m < 4; ++m) _Pragma("unroll") for (int k = 0; k < 2; ++k) dst[m][k] = *(const LAS bf16x8*)(lds + PG8_SA(b, h) + aoff + m * 2048 + k * 1024); } while (0)
; #define PG8_LDB(dst, b, h) do { _Pragma("unroll") for (int n = 0; n < 2; ++n) _Pragma("unroll") for (int k = 0; k < 2; ++k) dst[n][k] = *(const LAS bf16x8*)(lds + PG8_SB(b, h) + boff + n * 2048 + k * 1024); } while (0)
; #define PG8_MMA(ai, bj, At, Bt) do { __builtin_amdgcn_s_setprio(1); _Pragma("unroll") for (int m = 0; m < 4; ++m) _Pragma("unroll") for (int n = 0; n < 2; ++n) _Pragma("unroll") for (int k = 0; k < 2; ++k) \
;         acc[ai][bj][m][n] = __builtin_amdgcn_mfma_f32_16x16x32_bf16(Bt[n][k], At[m][k], acc[ai][bj][m][n], 0, 0, 0); __builtin_amdgcn_s_setprio(0); } while (0)
; #define PG8_WAIT_L(n) asm volatile("s_waitcnt lgkmcnt(" #n ")" ::: "memory")
; #define PG8_BAR __builtin_amdgcn_s_barrier()
; #define PG8_SCHED __builtin_amdgcn_sched_barrier(0)
; template <class Epi>
; DI void gemm_phase(LAS unsigned char* lds, const Gemm g, const StaticOrder& S, const Epi& E) {
;     ...
;             PG8_LDB(B0, 0, 0); PG8_SCHED; PG8_LDA(At, 0, 0); PG8_STAGE(PG8_SA(1, 1), a1 + hstep);
;             PG8_WAIT_L(8); PG8_BAR; PG8_WAIT_L(0); PG8_MMA(0, 0, At, B0); PG8_BAR; PG8_SCHED;
;             PG8_LDB(B1, 0, 1); PG8_STAGE(PG8_SB(0, 0), b2);
;             PG8_BAR; PG8_WAIT_L(0); PG8_MMA(0, 1, At, B1); PG8_BAR;
;             PG8_LDA(At, 0, 1); PG8_STAGE(PG8_SA(0, 0), a2);
;             PG8_BAR; PG8_WAIT_L(0); PG8_MMA(1, 0, At, B0); PG8_BAR; PG8_SCHED;
;             PG8_STAGE(PG8_SB(0, 1), b2 + hstep);
.LBB0_77:
	s_add_u32 s22, s20, 0x100
	s_addc_u32 s23, s21, 0
	s_add_i32 s43, 0, 0x10000
	v_add_u32_e32 v140, s43, v226
	ds_read_b128 v[128:131], v140
	ds_read_b128 v[132:135], v140 offset:1024
	ds_read_b128 v[136:139], v140 offset:2048
	ds_read_b128 v[140:143], v140 offset:3072
	s_cmp_eq_u32 s33, 32
	s_cselect_b32 s27, s9, s23
	s_cselect_b32 s26, s8, s22
	s_cselect_b32 s25, s11, s5
	s_cselect_b32 s24, s10, s4
	v_lshl_add_u64 v[214:215], s[20:21], 0, v[190:191]
	s_add_i32 m0, s34, 0xc000
	ds_read_b128 v[144:147], v228
	ds_read_b128 v[148:151], v228 offset:1024
	ds_read_b128 v[152:155], v228 offset:2048
	ds_read_b128 v[194:197], v228 offset:3072
	ds_read_b128 v[198:201], v228 offset:4096
	ds_read_b128 v[202:205], v228 offset:5120
	ds_read_b128 v[206:209], v228 offset:6144
	ds_read_b128 v[210:213], v228 offset:7168
	global_load_lds_dwordx4 v[214:215], off
	v_lshl_add_u64 v[214:215], s[20:21], 0, v[192:193]
	s_add_i32 m0, s34, 0xe000
	s_nop 0
	global_load_lds_dwordx4 v[214:215], off
	s_waitcnt lgkmcnt(8)
	s_setprio 1
	s_barrier
	s_waitcnt lgkmcnt(0)
	v_mfma_f32_16x16x32_bf16 v[124:127], v[128:131], v[144:147], v[124:127]
	v_mfma_f32_16x16x32_bf16 v[120:123], v[136:139], v[144:147], v[120:123]
	v_mfma_f32_16x16x32_bf16 v[116:119], v[128:131], v[152:155], v[116:119]
	v_mfma_f32_16x16x32_bf16 v[112:115], v[136:139], v[152:155], v[112:115]
	v_mfma_f32_16x16x32_bf16 v[108:111], v[128:131], v[198:201], v[108:111]
	v_mfma_f32_16x16x32_bf16 v[104:107], v[136:139], v[198:201], v[104:107]
	v_mfma_f32_16x16x32_bf16 v[100:103], v[128:131], v[206:209], v[100:103]
	v_mfma_f32_16x16x32_bf16 v[96:99], v[136:139], v[206:209], v[96:99]
	v_mfma_f32_16x16x32_bf16 v[124:127], v[132:135], v[148:151], v[124:127]
	s_add_i32 s44, 0, 0x14000
	v_mfma_f32_16x16x32_bf16 v[120:123], v[140:143], v[148:151], v[120:123]
	s_add_i32 s20, s43, s31
	v_mfma_f32_16x16x32_bf16 v[116:119], v[132:135], v[194:197], v[116:119]
	v_add_u32_e32 v158, s44, v226
	v_mfma_f32_16x16x32_bf16 v[112:115], v[140:143], v[194:197], v[112:115]
	v_lshl_add_u64 v[218:219], s[24:25], 0, v[188:189]
	v_mfma_f32_16x16x32_bf16 v[108:111], v[132:135], v[202:205], v[108:111]
	s_mov_b32 m0, s20
	v_mfma_f32_16x16x32_bf16 v[104:107], v[140:143], v[202:205], v[104:107]
	v_mfma_f32_16x16x32_bf16 v[100:103], v[132:135], v[210:213], v[100:103]
	v_mfma_f32_16x16x32_bf16 v[96:99], v[140:143], v[210:213], v[96:99]
	s_setprio 0
	s_barrier
	ds_read_b128 v[214:217], v158
	ds_read_b128 v[230:233], v158 offset:1024
	ds_read_b128 v[234:237], v158 offset:2048
	ds_read_b128 v[238:241], v158 offset:3072
	global_load_lds_dwordx4 v[218:219], off
	v_lshl_add_u64 v[220:221], s[24:25], 0, v[186:187]
	s_add_i32 m0, s20, 0x2000
	s_nop 0
	global_load_lds_dwordx4 v[220:221], off
	s_waitcnt lgkmcnt(0)
	s_setprio 1
	s_barrier
	v_mfma_f32_16x16x32_bf16 v[60:63], v[214:217], v[144:147], v[60:63]
	v_mfma_f32_16x16x32_bf16 v[56:59], v[234:237], v[144:147], v[56:59]
	v_mfma_f32_16x16x32_bf16 v[52:55], v[214:217], v[152:155], v[52:55]
	v_mfma_f32_16x16x32_bf16 v[48:51], v[234:237], v[152:155], v[48:51]
	v_mfma_f32_16x16x32_bf16 v[44:47], v[214:217], v[198:201], v[44:47]
	v_mfma_f32_16x16x32_bf16 v[40:43], v[234:237], v[198:201], v[40:43]
	v_mfma_f32_16x16x32_bf16 v[36:39], v[214:217], v[206:209], v[36:39]
	v_mfma_f32_16x16x32_bf16 v[32:35], v[234:237], v[206:209], v[32:35]
	v_mfma_f32_16x16x32_bf16 v[60:63], v[230:233], v[148:151], v[60:63]
	s_mov_b32 m0, s34
	v_mfma_f32_16x16x32_bf16 v[56:59], v[238:241], v[148:151], v[56:59]
	v_lshl_add_u64 v[242:243], s[26:27], 0, v[188:189]
	v_mfma_f32_16x16x32_bf16 v[52:55], v[230:233], v[194:197], v[52:55]
	v_mfma_f32_16x16x32_bf16 v[48:51], v[238:241], v[194:197], v[48:51]
	v_mfma_f32_16x16x32_bf16 v[44:47], v[230:233], v[202:205], v[44:47]
	v_mfma_f32_16x16x32_bf16 v[40:43], v[238:241], v[202:205], v[40:43]
	v_mfma_f32_16x16x32_bf16 v[36:39], v[230:233], v[210:213], v[36:39]
	v_mfma_f32_16x16x32_bf16 v[32:35], v[238:241], v[210:213], v[32:35]
	s_setprio 0
	s_barrier
	ds_read_b128 v[144:147], v228 offset:16384
	ds_read_b128 v[148:151], v228 offset:17408
	ds_read_b128 v[152:155], v228 offset:18432
	ds_read_b128 v[194:197], v228 offset:19456
	ds_read_b128 v[198:201], v228 offset:20480
	ds_read_b128 v[202:205], v228 offset:21504
	ds_read_b128 v[206:209], v228 offset:22528
	ds_read_b128 v[210:213], v228 offset:23552
	global_load_lds_dwordx4 v[242:243], off
	v_lshl_add_u64 v[244:245], s[26:27], 0, v[186:187]
	s_mov_b32 m0, s35
	s_nop 0
	global_load_lds_dwordx4 v[244:245], off
	s_waitcnt lgkmcnt(0)
	s_setprio 1
	s_barrier
	v_mfma_f32_16x16x32_bf16 v[92:95], v[128:131], v[144:147], v[92:95]
	v_mfma_f32_16x16x32_bf16 v[88:91], v[136:139], v[144:147], v[88:91]
	v_mfma_f32_16x16x32_bf16 v[84:87], v[128:131], v[152:155], v[84:87]
	v_mfma_f32_16x16x32_bf16 v[80:83], v[136:139], v[152:155], v[80:83]
	v_mfma_f32_16x16x32_bf16 v[76:79], v[128:131], v[198:201], v[76:79]
	v_mfma_f32_16x16x32_bf16 v[72:75], v[136:139], v[198:201], v[72:75]
	v_mfma_f32_16x16x32_bf16 v[68:71], v[128:131], v[206:209], v[68:71]
	v_mfma_f32_16x16x32_bf16 v[64:67], v[136:139], v[206:209], v[64:67]
	v_mfma_f32_16x16x32_bf16 v[92:95], v[132:135], v[148:151], v[92:95]
	s_add_u32 s20, s24, 0x90000
	v_mfma_f32_16x16x32_bf16 v[88:91], v[140:143], v[148:151], v[88:91]
	s_addc_u32 s21, s25, 0
	v_mfma_f32_16x16x32_bf16 v[84:87], v[132:135], v[194:197], v[84:87]
	s_add_i32 s43, s44, s31
	v_mfma_f32_16x16x32_bf16 v[80:83], v[140:143], v[194:197], v[80:83]
	v_lshl_add_u64 v[128:129], s[20:21], 0, v[188:189]
	v_mfma_f32_16x16x32_bf16 v[76:79], v[132:135], v[202:205], v[76:79]
	s_mov_b32 m0, s43
	v_mfma_f32_16x16x32_bf16 v[72:75], v[140:143], v[202:205], v[72:75]
	v_mfma_f32_16x16x32_bf16 v[68:71], v[132:135], v[210:213], v[68:71]
	v_mfma_f32_16x16x32_bf16 v[64:67], v[140:143], v[210:213], v[64:67]
	s_setprio 0
	s_barrier
; #define PG8_STAGE(bufoff, gbase) do { _Pragma("unroll") for (int _i = 0; _i < 2; ++_i) \
;         __builtin_amdgcn_global_load_lds((const unsigned*)((const char*)(gbase) + voff[_i]), (LAS unsigned*)(lds + (bufoff) + ldsw + _i * 8192), 16, 0, 0); } while (0)
; #define PG8_LDA(dst, b, h) do { _Pragma("unroll") for (int m = 0; m < 4; ++m) _Pragma("unroll") for (int k = 0; k < 2; ++k) dst[m][k] = *(const LAS bf16x8*)(lds + PG8_SA(b, h) + aoff + m * 2048 + k * 1024); } while (0)
; #define PG8_LDB(dst, b, h) do { _Pragma("unroll") for (int n = 0; n < 2; ++n) _Pragma("unroll") for (int k = 0; k < 2; ++k) dst[n][k] = *(const LAS bf16x8*)(lds + PG8_SB(b, h) + boff + n * 2048 + k * 1024); } while (0)
; #define PG8_MMA(ai, bj, At, Bt) do { __builtin_amdgcn_s_setprio(1); _Pragma("unroll") for (int m = 0; m < 4; ++m) _Pragma("unroll") for (int n = 0; n < 2; ++n) _Pragma("unroll") for (int k = 0; k < 2; ++k) \
;         acc[ai][bj][m][n] = __builtin_amdgcn_mfma_f32_16x16x32_bf16(Bt[n][k], At[m][k], acc[ai][bj][m][n], 0, 0, 0); __builtin_amdgcn_s_setprio(0); } while (0)
; #define PG8_WAIT_V(n) asm volatile("s_waitcnt vmcnt(" #n ")" ::: "memory")
; #define PG8_WAIT_L(n) asm volatile("s_waitcnt lgkmcnt(" #n ")" ::: "memory")
; #define PG8_BAR __builtin_amdgcn_s_barrier()
; #define PG8_SCHED __builtin_amdgcn_sched_barrier(0)
; template <class Epi>
; DI void gemm_phase(LAS unsigned char* lds, const Gemm g, const StaticOrder& S, const Epi& E) {
;     ...
;             PG8_WAIT_V(6); PG8_BAR; PG8_MMA(1, 1, At, B1); PG8_BAR;
;             PG8_LDB(B0, 1, 0); PG8_SCHED; PG8_LDA(At, 1, 0); PG8_STAGE(PG8_SA(0, 1), a2 + hstep);
;             PG8_WAIT_L(8); PG8_BAR; PG8_WAIT_L(0); PG8_MMA(0, 0, At, B0); PG8_BAR; PG8_SCHED;
;             PG8_LDB(B1, 1, 1); PG8_STAGE(PG8_SB(1, 0), b3);
;             PG8_BAR; PG8_WAIT_L(0); PG8_MMA(0, 1, At, B1); PG8_BAR;
;             PG8_LDA(At, 1, 1); PG8_STAGE(PG8_SA(1, 0), a3);
;             PG8_BAR; PG8_WAIT_L(0); PG8_MMA(1, 0, At, B0); PG8_BAR; PG8_SCHED;
	s_nop 0
	global_load_lds_dwordx4 v[128:129], off
	v_lshl_add_u64 v[128:129], s[20:21], 0, v[186:187]
	s_add_i32 m0, s43, 0x2000
	s_nop 0
	global_load_lds_dwordx4 v[128:129], off
	s_waitcnt vmcnt(6)
	s_setprio 1
	s_barrier
	v_mfma_f32_16x16x32_bf16 v[28:31], v[214:217], v[144:147], v[28:31]
	v_mfma_f32_16x16x32_bf16 v[24:27], v[234:237], v[144:147], v[24:27]
	v_mfma_f32_16x16x32_bf16 v[20:23], v[214:217], v[152:155], v[20:23]
	v_mfma_f32_16x16x32_bf16 v[16:19], v[234:237], v[152:155], v[16:19]
	v_mfma_f32_16x16x32_bf16 v[12:15], v[214:217], v[198:201], v[12:15]
	v_mfma_f32_16x16x32_bf16 v[8:11], v[234:237], v[198:201], v[8:11]
	v_mfma_f32_16x16x32_bf16 v[4:7], v[214:217], v[206:209], v[4:7]
	v_mfma_f32_16x16x32_bf16 v[0:3], v[234:237], v[206:209], v[0:3]
	v_mfma_f32_16x16x32_bf16 v[28:31], v[230:233], v[148:151], v[28:31]
	s_add_i32 s43, 0, 0x18000
	v_mfma_f32_16x16x32_bf16 v[24:27], v[238:241], v[148:151], v[24:27]
	v_add_u32_e32 v140, s43, v226
	v_mfma_f32_16x16x32_bf16 v[20:23], v[230:233], v[194:197], v[20:23]
	v_mfma_f32_16x16x32_bf16 v[16:19], v[238:241], v[194:197], v[16:19]
	v_mfma_f32_16x16x32_bf16 v[12:15], v[230:233], v[202:205], v[12:15]
	v_mfma_f32_16x16x32_bf16 v[8:11], v[238:241], v[202:205], v[8:11]
	v_mfma_f32_16x16x32_bf16 v[4:7], v[230:233], v[210:213], v[4:7]
	v_mfma_f32_16x16x32_bf16 v[0:3], v[238:241], v[210:213], v[0:3]
	s_setprio 0
	s_barrier
	ds_read_b128 v[128:131], v140
	ds_read_b128 v[132:135], v140 offset:1024
	ds_read_b128 v[136:139], v140 offset:2048
	ds_read_b128 v[140:143], v140 offset:3072
	s_add_u32 s20, s26, 0x90000
	s_addc_u32 s21, s27, 0
	s_mov_b32 m0, s36
	v_lshl_add_u64 v[214:215], s[20:21], 0, v[188:189]
	ds_read_b128 v[144:147], v228 offset:32768
	ds_read_b128 v[148:151], v228 offset:33792
	ds_read_b128 v[152:155], v228 offset:34816
	ds_read_b128 v[194:197], v228 offset:35840
	ds_read_b128 v[198:201], v228 offset:36864
	ds_read_b128 v[202:205], v228 offset:37888
	ds_read_b128 v[206:209], v228 offset:38912
	ds_read_b128 v[210:213], v228 offset:39936
	global_load_lds_dwordx4 v[214:215], off
	v_lshl_add_u64 v[214:215], s[20:21], 0, v[186:187]
	s_mov_b32 m0, s37
	s_nop 0
	global_load_lds_dwordx4 v[214:215], off
	s_waitcnt lgkmcnt(8)
	s_setprio 1
	s_barrier
	s_waitcnt lgkmcnt(0)
	v_mfma_f32_16x16x32_bf16 v[124:127], v[128:131], v[144:147], v[124:127]
	v_mfma_f32_16x16x32_bf16 v[120:123], v[136:139], v[144:147], v[120:123]
	v_mfma_f32_16x16x32_bf16 v[116:119], v[128:131], v[152:155], v[116:119]
	v_mfma_f32_16x16x32_bf16 v[112:115], v[136:139], v[152:155], v[112:115]
	v_mfma_f32_16x16x32_bf16 v[108:111], v[128:131], v[198:201], v[108:111]
	v_mfma_f32_16x16x32_bf16 v[104:107], v[136:139], v[198:201], v[104:107]
	v_mfma_f32_16x16x32_bf16 v[100:103], v[128:131], v[206:209], v[100:103]
	v_mfma_f32_16x16x32_bf16 v[96:99], v[136:139], v[206:209], v[96:99]
	v_mfma_f32_16x16x32_bf16 v[124:127], v[132:135], v[148:151], v[124:127]
	s_add_i32 s26, 0, 0x1c000
	v_mfma_f32_16x16x32_bf16 v[120:123], v[140:143], v[148:151], v[120:123]
	s_add_i32 s20, s43, s31
	v_mfma_f32_16x16x32_bf16 v[116:119], v[132:135], v[194:197], v[116:119]
	v_add_u32_e32 v158, s26, v226
	v_mfma_f32_16x16x32_bf16 v[112:115], v[140:143], v[194:197], v[112:115]
	v_lshl_add_u64 v[218:219], v[218:219], 0, s[94:95]
	v_mfma_f32_16x16x32_bf16 v[108:111], v[132:135], v[202:205], v[108:111]
	s_mov_b32 m0, s20
	v_mfma_f32_16x16x32_bf16 v[104:107], v[140:143], v[202:205], v[104:107]
	v_mfma_f32_16x16x32_bf16 v[100:103], v[132:135], v[210:213], v[100:103]
	v_mfma_f32_16x16x32_bf16 v[96:99], v[140:143], v[210:213], v[96:99]
	s_setprio 0
	s_barrier
	ds_read_b128 v[214:217], v158
	ds_read_b128 v[230:233], v158 offset:1024
	ds_read_b128 v[234:237], v158 offset:2048
	ds_read_b128 v[238:241], v158 offset:3072
	global_load_lds_dwordx4 v[218:219], off
	v_lshl_add_u64 v[218:219], v[220:221], 0, s[94:95]
	s_add_i32 m0, s20, 0x2000
	s_nop 0
	global_load_lds_dwordx4 v[218:219], off
	s_waitcnt lgkmcnt(0)
	s_setprio 1
	s_barrier
	v_mfma_f32_16x16x32_bf16 v[60:63], v[214:217], v[144:147], v[60:63]
	v_mfma_f32_16x16x32_bf16 v[56:59], v[234:237], v[144:147], v[56:59]
	v_mfma_f32_16x16x32_bf16 v[52:55], v[214:217], v[152:155], v[52:55]
	v_mfma_f32_16x16x32_bf16 v[48:51], v[234:237], v[152:155], v[48:51]
	v_mfma_f32_16x16x32_bf16 v[44:47], v[214:217], v[198:201], v[44:47]
	v_mfma_f32_16x16x32_bf16 v[40:43], v[234:237], v[198:201], v[40:43]
	v_mfma_f32_16x16x32_bf16 v[36:39], v[214:217], v[206:209], v[36:39]
	v_mfma_f32_16x16x32_bf16 v[32:35], v[234:237], v[206:209], v[32:35]
	v_mfma_f32_16x16x32_bf16 v[60:63], v[230:233], v[148:151], v[60:63]
	s_mov_b32 m0, s38
	v_mfma_f32_16x16x32_bf16 v[56:59], v[238:241], v[148:151], v[56:59]
	v_lshl_add_u64 v[218:219], v[242:243], 0, s[94:95]
	v_mfma_f32_16x16x32_bf16 v[52:55], v[230:233], v[194:197], v[52:55]
	v_mfma_f32_16x16x32_bf16 v[48:51], v[238:241], v[194:197], v[48:51]
	v_mfma_f32_16x16x32_bf16 v[44:47], v[230:233], v[202:205], v[44:47]
	v_mfma_f32_16x16x32_bf16 v[40:43], v[238:241], v[202:205], v[40:43]
	v_mfma_f32_16x16x32_bf16 v[36:39], v[230:233], v[210:213], v[36:39]
	v_mfma_f32_16x16x32_bf16 v[32:35], v[238:241], v[210:213], v[32:35]
	s_setprio 0
	s_barrier
	ds_read_b128 v[144:147], v228 offset:49152
	ds_read_b128 v[148:151], v228 offset:50176
	ds_read_b128 v[152:155], v228 offset:51200
	ds_read_b128 v[194:197], v228 offset:52224
	ds_read_b128 v[198:201], v228 offset:53248
	ds_read_b128 v[202:205], v228 offset:54272
	ds_read_b128 v[206:209], v228 offset:55296
	ds_read_b128 v[210:213], v228 offset:56320
	global_load_lds_dwordx4 v[218:219], off
	v_lshl_add_u64 v[218:219], v[244:245], 0, s[94:95]
	s_mov_b32 m0, s39
	s_nop 0
	global_load_lds_dwordx4 v[218:219], off
	s_waitcnt lgkmcnt(0)
	s_setprio 1
	s_barrier
; #define PG8_WAIT_V(n) asm volatile("s_waitcnt vmcnt(" #n ")" ::: "memory")
; #define PG8_WAIT_L(n) asm volatile("s_waitcnt lgkmcnt(" #n ")" ::: "memory")
; #define PG8_BAR __builtin_amdgcn_s_barrier()
; template <class Epi>
; DI void gemm_phase(LAS unsigned char* lds, const Gemm g, const StaticOrder& S, const Epi& E) {
;     ...
;             PG8_BAR; PG8_WAIT_L(0); PG8_MMA(1, 0, At, B0); PG8_BAR; PG8_SCHED;
;             PG8_STAGE(PG8_SB(1, 1), b3 + hstep);
;             PG8_WAIT_V(6); PG8_BAR; PG8_MMA(1, 1, At, B1); PG8_BAR;
;     template <bool LN, int BJ, int LO, int HI> DI void batch(const f32x4 (&acc)[2][2][4][2], unsigned row0, unsigned col0, const f32x4 (&gv)[2], const f32x4 (&bv)[2]) const {
;         f32x4 r[HI - LO]; float mean[(HI - LO) / 2], rstd[(HI - LO) / 2];
; #pragma unroll
;         for (int i = LO; i < HI; ++i) { const int ai = i >> 3, m = (i >> 1) & 3, n = i & 1; const unsigned row = row0 + ai * HALF + m * 16;
;             if (n == 0) { mean[(i - LO) >> 1] = 0.f; rstd[(i - LO) >> 1] = 1.f;
;                 if (LN) { const float2 st = *(const float2*)(stats + row * 2u); mean[(i - LO) >> 1] = st.x; rstd[(i - LO) >> 1] = st.y; } }
;             r[i - LO] = *(const f32x4*)(src + (row * (unsigned)DM + col0 + BJ * HALF + n * 16)); }
; #pragma unroll
;         for (int i = LO; i < HI; ++i) { const int ai = i >> 3, m = (i >> 1) & 3, n = i & 1; const unsigned row = row0 + ai * HALF + m * 16;
;             *(f32x4*)(Y + (row * (unsigned)DM + col0 + BJ * HALF + n * 16)) = acc[ai][BJ][m][n] + ((r[i - LO] - mean[(i - LO) >> 1]) * rstd[(i - LO) >> 1]) * gv[n] + bv[n]; }
;         __builtin_amdgcn_sched_barrier(0);
;     }
;     template <bool LN, int BJ> DI void load_gb(unsigned col0, f32x4 (&gv)[2], f32x4 (&bv)[2]) const {
; #pragma unroll
;         for (int n = 0; n < 2; ++n) {
;             if (LN) { gv[n] = *(const f32x4*)(gam + col0 + BJ * HALF + n * 16) * ALPHA; bv[n] = *(const f32x4*)(bet + col0 + BJ * HALF + n * 16) * ALPHA; }
;             else { gv[n] = (f32x4){ALPHA, ALPHA, ALPHA, ALPHA}; bv[n] = (f32x4){0.f, 0.f, 0.f, 0.f}; }
;         }
;     }
;     template <bool LN> DI void run(const f32x4 (&acc)[2][2][4][2], const Unit& u, int wr, int wc, int fr, int fq) const {
;         const unsigned row0 = u.pm * BM + wr * 64 + fr, col0 = u.pn * BM + wc * 32 + 4 * fq;
;         f32x4 gv[2], bv[2];
;         load_gb<LN, 0>(col0, gv, bv);
	v_mfma_f32_16x16x32_bf16 v[92:95], v[128:131], v[144:147], v[92:95]
	v_mfma_f32_16x16x32_bf16 v[88:91], v[136:139], v[144:147], v[88:91]
	v_mfma_f32_16x16x32_bf16 v[84:87], v[128:131], v[152:155], v[84:87]
	v_mfma_f32_16x16x32_bf16 v[80:83], v[136:139], v[152:155], v[80:83]
	v_mfma_f32_16x16x32_bf16 v[76:79], v[128:131], v[198:201], v[76:79]
	v_mfma_f32_16x16x32_bf16 v[72:75], v[136:139], v[198:201], v[72:75]
	v_mfma_f32_16x16x32_bf16 v[68:71], v[128:131], v[206:209], v[68:71]
	v_mfma_f32_16x16x32_bf16 v[64:67], v[136:139], v[206:209], v[64:67]
	v_mfma_f32_16x16x32_bf16 v[92:95], v[132:135], v[148:151], v[92:95]
	s_add_u32 s20, s24, 0x90080
	v_mfma_f32_16x16x32_bf16 v[88:91], v[140:143], v[148:151], v[88:91]
	s_addc_u32 s21, s25, 0
	v_mfma_f32_16x16x32_bf16 v[84:87], v[132:135], v[194:197], v[84:87]
	s_add_i32 s24, s26, s31
	v_mfma_f32_16x16x32_bf16 v[80:83], v[140:143], v[194:197], v[80:83]
	v_lshl_add_u64 v[128:129], s[20:21], 0, v[188:189]
	v_mfma_f32_16x16x32_bf16 v[76:79], v[132:135], v[202:205], v[76:79]
	s_mov_b32 m0, s24
	v_mfma_f32_16x16x32_bf16 v[72:75], v[140:143], v[202:205], v[72:75]
	v_mfma_f32_16x16x32_bf16 v[68:71], v[132:135], v[210:213], v[68:71]
	v_mfma_f32_16x16x32_bf16 v[64:67], v[140:143], v[210:213], v[64:67]
	s_setprio 0
	s_barrier
	s_nop 0
	global_load_lds_dwordx4 v[128:129], off
	v_lshl_add_u64 v[128:129], s[20:21], 0, v[186:187]
	s_add_i32 m0, s24, 0x2000
	s_nop 0
	global_load_lds_dwordx4 v[128:129], off
	s_waitcnt vmcnt(6)
	s_setprio 1
	s_barrier
	v_mfma_f32_16x16x32_bf16 v[28:31], v[214:217], v[144:147], v[28:31]
	v_mfma_f32_16x16x32_bf16 v[24:27], v[234:237], v[144:147], v[24:27]
	v_mfma_f32_16x16x32_bf16 v[20:23], v[214:217], v[152:155], v[20:23]
	v_mfma_f32_16x16x32_bf16 v[16:19], v[234:237], v[152:155], v[16:19]
	v_mfma_f32_16x16x32_bf16 v[12:15], v[214:217], v[198:201], v[12:15]
	v_mfma_f32_16x16x32_bf16 v[8:11], v[234:237], v[198:201], v[8:11]
	v_mfma_f32_16x16x32_bf16 v[4:7], v[214:217], v[206:209], v[4:7]
	v_mfma_f32_16x16x32_bf16 v[0:3], v[234:237], v[206:209], v[0:3]
	v_mfma_f32_16x16x32_bf16 v[28:31], v[230:233], v[148:151], v[28:31]
	s_add_i32 s33, s33, 2
	v_mfma_f32_16x16x32_bf16 v[24:27], v[238:241], v[148:151], v[24:27]
	s_add_u32 s4, s4, 0x100
	v_mfma_f32_16x16x32_bf16 v[20:23], v[230:233], v[194:197], v[20:23]
	s_addc_u32 s5, s5, 0
	v_mfma_f32_16x16x32_bf16 v[16:19], v[238:241], v[194:197], v[16:19]
	s_cmp_gt_u32 s33, 33
	v_mfma_f32_16x16x32_bf16 v[12:15], v[230:233], v[202:205], v[12:15]
	s_mov_b64 s[20:21], s[22:23]
	v_mfma_f32_16x16x32_bf16 v[8:11], v[238:241], v[202:205], v[8:11]
	v_mfma_f32_16x16x32_bf16 v[4:7], v[230:233], v[210:213], v[4:7]
	v_mfma_f32_16x16x32_bf16 v[0:3], v[238:241], v[210:213], v[0:3]
	s_setprio 0
	s_barrier
	s_cbranch_scc0 .LBB0_77
	v_lshl_add_u32 v206, s3, 8, v225
	v_lshl_or_b32 v158, s2, 8, v227
	v_lshlrev_b32_e32 v232, 11, v206
	s_andn2_b64 vcc, exec, s[14:15]
	v_or_b32_e32 v231, 16, v158
	v_add_u32_e32 v194, v232, v158
	v_or_b32_e32 v230, 0x80, v158
	v_or_b32_e32 v229, 0x90, v158
	s_cbranch_vccnz .LBB0_80
	v_lshlrev_b64 v[132:133], 2, v[158:159]
	v_lshl_add_u64 v[140:141], s[16:17], 0, v[132:133]
	global_load_dwordx4 v[128:131], v[140:141], off
	v_lshl_add_u64 v[142:143], s[18:19], 0, v[132:133]
	v_readlane_b32 s2, v253, 8
	v_mov_b32_e32 v195, v159
	v_lshlrev_b32_e32 v136, 1, v206
	v_mov_b32_e32 v137, v159
	v_readlane_b32 s3, v253, 9
	v_lshlrev_b64 v[212:213], 2, v[194:195]
	v_add_u32_e32 v146, v232, v231
	v_lshl_add_u64 v[144:145], v[136:137], 2, s[2:3]
	v_lshl_add_u64 v[136:137], s[88:89], 0, v[212:213]
	v_mov_b32_e32 v147, v159
	v_lshl_add_u64 v[146:147], v[146:147], 2, s[88:89]
	v_or_b32_e32 v195, 16, v206
	v_mov_b32_e32 v201, v159
	v_mov_b32_e32 v209, v159
	v_lshl_add_u64 v[212:213], s[90:91], 0, v[212:213]
	s_waitcnt vmcnt(0)
	v_pk_mul_f32 v[152:153], v[130:131], s[78:79] op_sel_hi:[1,0]
	v_pk_mul_f32 v[154:155], v[128:129], s[78:79] op_sel_hi:[1,0]
	global_load_dwordx4 v[132:135], v[142:143], off
	global_load_dwordx4 v[128:131], v[140:141], off offset:64
	global_load_dwordx2 v[204:205], v[144:145], off
	global_load_dwordx4 v[196:199], v[146:147], off
	v_lshlrev_b32_e32 v146, 1, v195
	global_load_dwordx4 v[136:139], v[136:137], off
	v_lshlrev_b32_e32 v195, 11, v195
	v_mov_b32_e32 v147, v159
	v_add_u32_e32 v200, v195, v158
	v_lshl_add_u64 v[146:147], v[146:147], 2, s[2:3]
	v_lshl_add_u64 v[200:201], v[200:201], 2, s[88:89]
	global_load_dwordx2 v[214:215], v[146:147], off
	v_add_u32_e32 v208, v195, v231
	global_load_dwordx4 v[200:203], v[200:201], off
	v_lshl_add_u64 v[208:209], v[208:209], 2, s[88:89]
	global_load_dwordx4 v[208:211], v[208:209], off
	s_waitcnt vmcnt(0)
	v_pk_mul_f32 v[148:149], v[130:131], s[78:79] op_sel_hi:[1,0]
	v_pk_mul_f32 v[150:151], v[128:129], s[78:79] op_sel_hi:[1,0]
	global_load_dwordx4 v[128:131], v[142:143], off offset:64
	v_sub_f32_e32 v137, v137, v204
	v_sub_f32_e32 v136, v136, v204
	v_sub_f32_e32 v139, v139, v204
	v_sub_f32_e32 v138, v138, v204
	v_pk_mul_f32 v[138:139], v[204:205], v[138:139] op_sel:[1,0]
	v_pk_mul_f32 v[136:137], v[204:205], v[136:137] op_sel:[1,0]
	v_pk_fma_f32 v[138:139], v[152:153], v[138:139], v[126:127]
	v_pk_fma_f32 v[136:137], v[154:155], v[136:137], v[124:125]
	v_pk_fma_f32 v[138:139], v[134:135], s[78:79], v[138:139] op_sel_hi:[1,0,1]
	v_pk_fma_f32 v[136:137], v[132:133], s[78:79], v[136:137] op_sel_hi:[1,0,1]
	global_store_dwordx4 v[212:213], v[136:139], off
	s_nop 1
	v_sub_f32_e32 v137, v197, v204
	v_sub_f32_e32 v136, v196, v204
	v_sub_f32_e32 v139, v199, v204
	v_sub_f32_e32 v138, v198, v204
	v_pk_mul_f32 v[138:139], v[204:205], v[138:139] op_sel:[1,0]
	v_pk_mul_f32 v[136:137], v[204:205], v[136:137] op_sel:[1,0]
	v_pk_fma_f32 v[138:139], v[148:149], v[138:139], v[122:123]
	v_pk_fma_f32 v[136:137], v[150:151], v[136:137], v[120:121]
	v_or_b32_e32 v196, 16, v194
	v_mov_b32_e32 v197, v159
	v_lshl_add_u64 v[196:197], v[196:197], 2, s[90:91]
	s_waitcnt vmcnt(0)
;     template <bool LN, int BJ, int LO, int HI> DI void batch(const f32x4 (&acc)[2][2][4][2], unsigned row0, unsigned col0, const f32x4 (&gv)[2], const f32x4 (&bv)[2]) const {
;         f32x4 r[HI - LO]; float mean[(HI - LO) / 2], rstd[(HI - LO) / 2];
; #pragma unroll
;         for (int i = LO; i < HI; ++i) { const int ai = i >> 3, m = (i >> 1) & 3, n = i & 1; const unsigned row = row0 + ai * HALF + m * 16;
;             if (n == 0) { mean[(i - LO) >> 1] = 0.f; rstd[(i - LO) >> 1] = 1.f;
;                 if (LN) { const float2 st = *(const float2*)(stats + row * 2u); mean[(i - LO) >> 1] = st.x; rstd[(i - LO) >> 1] = st.y; } }
;             r[i - LO] = *(const f32x4*)(src + (row * (unsigned)DM + col0 + BJ * HALF + n * 16)); }
; #pragma unroll
;         for (int i = LO; i < HI; ++i) { const int ai = i >> 3, m = (i >> 1) & 3, n = i & 1; const unsigned row = row0 + ai * HALF + m * 16;
;             *(f32x4*)(Y + (row * (unsigned)DM + col0 + BJ * HALF + n * 16)) = acc[ai][BJ][m][n] + ((r[i - LO] - mean[(i - LO) >> 1]) * rstd[(i - LO) >> 1]) * gv[n] + bv[n]; }
;         __builtin_amdgcn_sched_barrier(0);
;     }
;     template <bool LN, int BJ> DI void load_gb(unsigned col0, f32x4 (&gv)[2], f32x4 (&bv)[2]) const {
; #pragma unroll
;         for (int n = 0; n < 2; ++n) {
;             if (LN) { gv[n] = *(const f32x4*)(gam + col0 + BJ * HALF + n * 16) * ALPHA; bv[n] = *(const f32x4*)(bet + col0 + BJ * HALF + n * 16) * ALPHA; }
;             else { gv[n] = (f32x4){ALPHA, ALPHA, ALPHA, ALPHA}; bv[n] = (f32x4){0.f, 0.f, 0.f, 0.f}; }
;         }
;     }
;     template <bool LN> DI void run(const f32x4 (&acc)[2][2][4][2], const Unit& u, int wr, int wc, int fr, int fq) const {
;         const unsigned row0 = u.pm * BM + wr * 64 + fr, col0 = u.pn * BM + wc * 32 + 4 * fq;
;         f32x4 gv[2], bv[2];
;         load_gb<LN, 0>(col0, gv, bv);
;         batch<LN, 0, 0, 4>(acc, row0, col0, gv, bv);
;         batch<LN, 0, 4, 8>(acc, row0, col0, gv, bv);
;         batch<LN, 0, 8, 12>(acc, row0, col0, gv, bv);
;         batch<LN, 0, 12, 16>(acc, row0, col0, gv, bv);
;         load_gb<LN, 1>(col0, gv, bv);
;         batch<LN, 1, 0, 8>(acc, row0, col0, gv, bv);
;         batch<LN, 1, 8, 16>(acc, row0, col0, gv, bv);
	v_pk_fma_f32 v[138:139], v[130:131], s[78:79], v[138:139] op_sel_hi:[1,0,1]
	v_pk_fma_f32 v[136:137], v[128:129], s[78:79], v[136:137] op_sel_hi:[1,0,1]
	global_store_dwordx4 v[196:197], v[136:139], off
	v_add_u32_e32 v196, 0x8000, v194
	v_mov_b32_e32 v197, v159
	v_sub_f32_e32 v137, v201, v214
	v_sub_f32_e32 v136, v200, v214
	v_sub_f32_e32 v139, v203, v214
	v_sub_f32_e32 v138, v202, v214
	v_pk_mul_f32 v[138:139], v[214:215], v[138:139] op_sel:[1,0]
	v_pk_mul_f32 v[136:137], v[214:215], v[136:137] op_sel:[1,0]
	v_pk_fma_f32 v[138:139], v[152:153], v[138:139], v[118:119]
	v_pk_fma_f32 v[136:137], v[154:155], v[136:137], v[116:117]
	v_pk_fma_f32 v[138:139], v[134:135], s[78:79], v[138:139] op_sel_hi:[1,0,1]
	v_pk_fma_f32 v[136:137], v[132:133], s[78:79], v[136:137] op_sel_hi:[1,0,1]
	v_lshl_add_u64 v[196:197], v[196:197], 2, s[90:91]
	global_store_dwordx4 v[196:197], v[136:139], off
	v_add_u32_e32 v196, 0x8010, v194
	v_mov_b32_e32 v197, v159
	v_sub_f32_e32 v137, v209, v214
	v_sub_f32_e32 v136, v208, v214
	v_sub_f32_e32 v139, v211, v214
	v_sub_f32_e32 v138, v210, v214
	v_pk_mul_f32 v[138:139], v[214:215], v[138:139] op_sel:[1,0]
	v_pk_mul_f32 v[136:137], v[214:215], v[136:137] op_sel:[1,0]
	v_pk_fma_f32 v[138:139], v[148:149], v[138:139], v[114:115]
	v_pk_fma_f32 v[136:137], v[150:151], v[136:137], v[112:113]
	v_pk_fma_f32 v[138:139], v[130:131], s[78:79], v[138:139] op_sel_hi:[1,0,1]
	v_pk_fma_f32 v[136:137], v[128:129], s[78:79], v[136:137] op_sel_hi:[1,0,1]
	v_lshl_add_u64 v[196:197], v[196:197], 2, s[90:91]
	global_store_dwordx4 v[196:197], v[136:139], off
	s_nop 1
	v_or_b32_e32 v138, 32, v206
	v_lshlrev_b32_e32 v136, 1, v138
	v_mov_b32_e32 v137, v159
	v_lshlrev_b32_e32 v236, 11, v138
	v_lshl_add_u64 v[200:201], v[136:137], 2, s[2:3]
	v_add_u32_e32 v136, v236, v158
	v_lshl_add_u64 v[136:137], v[136:137], 2, s[88:89]
	global_load_dwordx2 v[204:205], v[200:201], off
	v_add_u32_e32 v196, v236, v231
	global_load_dwordx4 v[136:139], v[136:137], off
	v_mov_b32_e32 v197, v159
	v_lshl_add_u64 v[196:197], v[196:197], 2, s[88:89]
	global_load_dwordx4 v[196:199], v[196:197], off
	v_or_b32_e32 v207, 48, v206
	v_lshlrev_b32_e32 v235, 11, v207
	v_lshlrev_b32_e32 v202, 1, v207
	v_mov_b32_e32 v203, v159
	v_add_u32_e32 v208, v235, v158
	v_mov_b32_e32 v209, v159
	v_lshl_add_u64 v[202:203], v[202:203], 2, s[2:3]
	v_lshl_add_u64 v[208:209], v[208:209], 2, s[88:89]
	global_load_dwordx2 v[216:217], v[202:203], off
	v_add_u32_e32 v212, v235, v231
	global_load_dwordx4 v[208:211], v[208:209], off
	v_mov_b32_e32 v213, v159
	v_lshl_add_u64 v[212:213], v[212:213], 2, s[88:89]
	global_load_dwordx4 v[212:215], v[212:213], off
	v_add_u32_e32 v218, 0x10000, v194
	v_mov_b32_e32 v219, v159
	v_lshl_add_u64 v[218:219], v[218:219], 2, s[90:91]
	s_waitcnt vmcnt(0)
	v_sub_f32_e32 v137, v137, v204
	v_sub_f32_e32 v136, v136, v204
	v_sub_f32_e32 v139, v139, v204
	v_sub_f32_e32 v138, v138, v204
	v_pk_mul_f32 v[138:139], v[204:205], v[138:139] op_sel:[1,0]
	v_pk_mul_f32 v[136:137], v[204:205], v[136:137] op_sel:[1,0]
	v_pk_fma_f32 v[138:139], v[152:153], v[138:139], v[110:111]
	v_pk_fma_f32 v[136:137], v[154:155], v[136:137], v[108:109]
	v_pk_fma_f32 v[138:139], v[134:135], s[78:79], v[138:139] op_sel_hi:[1,0,1]
	v_pk_fma_f32 v[136:137], v[132:133], s[78:79], v[136:137] op_sel_hi:[1,0,1]
	global_store_dwordx4 v[218:219], v[136:139], off
	s_nop 1
	v_sub_f32_e32 v137, v197, v204
	v_sub_f32_e32 v136, v196, v204
	v_sub_f32_e32 v139, v199, v204
	v_sub_f32_e32 v138, v198, v204
	v_pk_mul_f32 v[138:139], v[204:205], v[138:139] op_sel:[1,0]
	v_pk_mul_f32 v[136:137], v[204:205], v[136:137] op_sel:[1,0]
	v_pk_fma_f32 v[138:139], v[148:149], v[138:139], v[106:107]
	v_pk_fma_f32 v[136:137], v[150:151], v[136:137], v[104:105]
	v_add_u32_e32 v196, 0x10010, v194
	v_mov_b32_e32 v197, v159
	v_pk_fma_f32 v[138:139], v[130:131], s[78:79], v[138:139] op_sel_hi:[1,0,1]
	v_pk_fma_f32 v[136:137], v[128:129], s[78:79], v[136:137] op_sel_hi:[1,0,1]
	v_lshl_add_u64 v[196:197], v[196:197], 2, s[90:91]
	global_store_dwordx4 v[196:197], v[136:139], off
	v_add_u32_e32 v196, 0x18000, v194
	v_mov_b32_e32 v197, v159
	v_sub_f32_e32 v137, v209, v216
	v_sub_f32_e32 v136, v208, v216
	v_sub_f32_e32 v139, v211, v216
	v_sub_f32_e32 v138, v210, v216
	v_pk_mul_f32 v[138:139], v[216:217], v[138:139] op_sel:[1,0]
	v_pk_mul_f32 v[136:137], v[216:217], v[136:137] op_sel:[1,0]
	v_pk_fma_f32 v[138:139], v[152:153], v[138:139], v[102:103]
	v_pk_fma_f32 v[136:137], v[154:155], v[136:137], v[100:101]
	v_pk_fma_f32 v[138:139], v[134:135], s[78:79], v[138:139] op_sel_hi:[1,0,1]
	v_pk_fma_f32 v[136:137], v[132:133], s[78:79], v[136:137] op_sel_hi:[1,0,1]
	v_lshl_add_u64 v[196:197], v[196:197], 2, s[90:91]
	global_store_dwordx4 v[196:197], v[136:139], off
	v_add_u32_e32 v196, 0x18010, v194
	v_mov_b32_e32 v197, v159
	v_sub_f32_e32 v137, v213, v216
	v_sub_f32_e32 v136, v212, v216
	v_sub_f32_e32 v139, v215, v216
	v_sub_f32_e32 v138, v214, v216
	v_pk_mul_f32 v[138:139], v[216:217], v[138:139] op_sel:[1,0]
	v_pk_mul_f32 v[136:137], v[216:217], v[136:137] op_sel:[1,0]
	v_pk_fma_f32 v[138:139], v[148:149], v[138:139], v[98:99]
	v_pk_fma_f32 v[136:137], v[150:151], v[136:137], v[96:97]
	v_pk_fma_f32 v[138:139], v[130:131], s[78:79], v[138:139] op_sel_hi:[1,0,1]
	v_pk_fma_f32 v[136:137], v[128:129], s[78:79], v[136:137] op_sel_hi:[1,0,1]
	v_lshl_add_u64 v[196:197], v[196:197], 2, s[90:91]
	global_store_dwordx4 v[196:197], v[136:139], off
	s_nop 1
	v_add_u32_e32 v138, 0x80, v206
	v_lshlrev_b32_e32 v136, 1, v138
	v_mov_b32_e32 v137, v159
	v_lshlrev_b32_e32 v233, 11, v138
	v_lshl_add_u64 v[196:197], v[136:137], 2, s[2:3]
	v_add_u32_e32 v136, v233, v158
	v_lshl_add_u64 v[136:137], v[136:137], 2, s[88:89]
	global_load_dwordx2 v[204:205], v[196:197], off
	v_add_u32_e32 v198, v233, v231
	global_load_dwordx4 v[136:139], v[136:137], off
	v_mov_b32_e32 v199, v159
	v_add_u32_e32 v207, 0x90, v206
	v_lshl_add_u64 v[198:199], v[198:199], 2, s[88:89]
	v_lshlrev_b32_e32 v234, 11, v207
	global_load_dwordx4 v[208:211], v[198:199], off
	v_add_u32_e32 v212, v234, v158
	v_mov_b32_e32 v213, v159
	v_lshl_add_u64 v[212:213], v[212:213], 2, s[88:89]
	global_load_dwordx4 v[212:215], v[212:213], off
	v_lshlrev_b32_e32 v198, 1, v207
	v_mov_b32_e32 v199, v159
	v_lshl_add_u64 v[198:199], v[198:199], 2, s[2:3]
	global_load_dwordx2 v[220:221], v[198:199], off
	v_add_u32_e32 v216, v234, v231
	v_mov_b32_e32 v217, v159
	v_lshl_add_u64 v[216:217], v[216:217], 2, s[88:89]
	global_load_dwordx4 v[216:219], v[216:217], off
	v_add_u32_e32 v238, 0x40000, v194
	v_mov_b32_e32 v239, v159
	v_lshl_add_u64 v[238:239], v[238:239], 2, s[90:91]
	s_waitcnt vmcnt(0)
;     template <bool LN, int BJ, int LO, int HI> DI void batch(const f32x4 (&acc)[2][2][4][2], unsigned row0, unsigned col0, const f32x4 (&gv)[2], const f32x4 (&bv)[2]) const {
;         f32x4 r[HI - LO]; float mean[(HI - LO) / 2], rstd[(HI - LO) / 2];
; #pragma unroll
;         for (int i = LO; i < HI; ++i) { const int ai = i >> 3, m = (i >> 1) & 3, n = i & 1; const unsigned row = row0 + ai * HALF + m * 16;
;             if (n == 0) { mean[(i - LO) >> 1] = 0.f; rstd[(i - LO) >> 1] = 1.f;
;                 if (LN) { const float2 st = *(const float2*)(stats + row * 2u); mean[(i - LO) >> 1] = st.x; rstd[(i - LO) >> 1] = st.y; } }
;             r[i - LO] = *(const f32x4*)(src + (row * (unsigned)DM + col0 + BJ * HALF + n * 16)); }
; #pragma unroll
;         for (int i = LO; i < HI; ++i) { const int ai = i >> 3, m = (i >> 1) & 3, n = i & 1; const unsigned row = row0 + ai * HALF + m * 16;
;             *(f32x4*)(Y + (row * (unsigned)DM + col0 + BJ * HALF + n * 16)) = acc[ai][BJ][m][n] + ((r[i - LO] - mean[(i - LO) >> 1]) * rstd[(i - LO) >> 1]) * gv[n] + bv[n]; }
;         __builtin_amdgcn_sched_barrier(0);
;     }
;     template <bool LN, int BJ> DI void load_gb(unsigned col0, f32x4 (&gv)[2], f32x4 (&bv)[2]) const {
; #pragma unroll
;         for (int n = 0; n < 2; ++n) {
;             if (LN) { gv[n] = *(const f32x4*)(gam + col0 + BJ * HALF + n * 16) * ALPHA; bv[n] = *(const f32x4*)(bet + col0 + BJ * HALF + n * 16) * ALPHA; }
;             else { gv[n] = (f32x4){ALPHA, ALPHA, ALPHA, ALPHA}; bv[n] = (f32x4){0.f, 0.f, 0.f, 0.f}; }
;         }
;     }
;     template <bool LN> DI void run(const f32x4 (&acc)[2][2][4][2], const Unit& u, int wr, int wc, int fr, int fq) const {
;         const unsigned row0 = u.pm * BM + wr * 64 + fr, col0 = u.pn * BM + wc * 32 + 4 * fq;
;         f32x4 gv[2], bv[2];
;         load_gb<LN, 0>(col0, gv, bv);
;         batch<LN, 0, 0, 4>(acc, row0, col0, gv, bv);
;         batch<LN, 0, 4, 8>(acc, row0, col0, gv, bv);
;         batch<LN, 0, 8, 12>(acc, row0, col0, gv, bv);
;         batch<LN, 0, 12, 16>(acc, row0, col0, gv, bv);
;         load_gb<LN, 1>(col0, gv, bv);
;         batch<LN, 1, 0, 8>(acc, row0, col0, gv, bv);
;         batch<LN, 1, 8, 16>(acc, row0, col0, gv, bv);
	v_sub_f32_e32 v137, v137, v204
	v_sub_f32_e32 v136, v136, v204
	v_sub_f32_e32 v139, v139, v204
	v_sub_f32_e32 v138, v138, v204
	v_pk_mul_f32 v[138:139], v[204:205], v[138:139] op_sel:[1,0]
	v_pk_mul_f32 v[136:137], v[204:205], v[136:137] op_sel:[1,0]
	v_pk_fma_f32 v[138:139], v[152:153], v[138:139], v[94:95]
	v_pk_fma_f32 v[136:137], v[154:155], v[136:137], v[92:93]
	v_pk_fma_f32 v[138:139], v[134:135], s[78:79], v[138:139] op_sel_hi:[1,0,1]
	v_pk_fma_f32 v[136:137], v[132:133], s[78:79], v[136:137] op_sel_hi:[1,0,1]
	global_store_dwordx4 v[238:239], v[136:139], off
	s_nop 1
	v_sub_f32_e32 v137, v209, v204
	v_sub_f32_e32 v136, v208, v204
	v_sub_f32_e32 v139, v211, v204
	v_sub_f32_e32 v138, v210, v204
	v_pk_mul_f32 v[138:139], v[204:205], v[138:139] op_sel:[1,0]
	v_pk_mul_f32 v[136:137], v[204:205], v[136:137] op_sel:[1,0]
	v_pk_fma_f32 v[138:139], v[148:149], v[138:139], v[90:91]
	v_pk_fma_f32 v[136:137], v[150:151], v[136:137], v[88:89]
	v_add_u32_e32 v204, 0x40010, v194
	v_mov_b32_e32 v205, v159
	v_pk_fma_f32 v[138:139], v[130:131], s[78:79], v[138:139] op_sel_hi:[1,0,1]
	v_pk_fma_f32 v[136:137], v[128:129], s[78:79], v[136:137] op_sel_hi:[1,0,1]
	v_lshl_add_u64 v[204:205], v[204:205], 2, s[90:91]
	global_store_dwordx4 v[204:205], v[136:139], off
	v_add_u32_e32 v204, 0x48000, v194
	v_mov_b32_e32 v205, v159
	v_sub_f32_e32 v137, v213, v220
	v_sub_f32_e32 v136, v212, v220
	v_sub_f32_e32 v139, v215, v220
	v_sub_f32_e32 v138, v214, v220
	v_pk_mul_f32 v[138:139], v[220:221], v[138:139] op_sel:[1,0]
	v_pk_mul_f32 v[136:137], v[220:221], v[136:137] op_sel:[1,0]
	v_pk_fma_f32 v[138:139], v[152:153], v[138:139], v[86:87]
	v_pk_fma_f32 v[136:137], v[154:155], v[136:137], v[84:85]
	v_pk_fma_f32 v[138:139], v[134:135], s[78:79], v[138:139] op_sel_hi:[1,0,1]
	v_pk_fma_f32 v[136:137], v[132:133], s[78:79], v[136:137] op_sel_hi:[1,0,1]
	v_lshl_add_u64 v[204:205], v[204:205], 2, s[90:91]
	global_store_dwordx4 v[204:205], v[136:139], off
	v_add_u32_e32 v204, 0x48010, v194
	v_mov_b32_e32 v205, v159
	v_sub_f32_e32 v137, v217, v220
	v_sub_f32_e32 v136, v216, v220
	v_sub_f32_e32 v139, v219, v220
	v_sub_f32_e32 v138, v218, v220
	v_pk_mul_f32 v[138:139], v[220:221], v[138:139] op_sel:[1,0]
	v_pk_mul_f32 v[136:137], v[220:221], v[136:137] op_sel:[1,0]
	v_pk_fma_f32 v[138:139], v[148:149], v[138:139], v[82:83]
	v_pk_fma_f32 v[136:137], v[150:151], v[136:137], v[80:81]
	v_pk_fma_f32 v[138:139], v[130:131], s[78:79], v[138:139] op_sel_hi:[1,0,1]
	v_pk_fma_f32 v[136:137], v[128:129], s[78:79], v[136:137] op_sel_hi:[1,0,1]
	v_lshl_add_u64 v[204:205], v[204:205], 2, s[90:91]
	global_store_dwordx4 v[204:205], v[136:139], off
	s_nop 1
	v_add_u32_e32 v138, 0xa0, v206
	v_lshlrev_b32_e32 v136, 1, v138
	v_mov_b32_e32 v137, v159
	v_lshlrev_b32_e32 v237, 11, v138
	v_lshl_add_u64 v[204:205], v[136:137], 2, s[2:3]
	v_add_u32_e32 v136, v237, v158
	v_lshl_add_u64 v[136:137], v[136:137], 2, s[88:89]
	global_load_dwordx2 v[220:221], v[204:205], off
	v_add_u32_e32 v208, v237, v231
	global_load_dwordx4 v[136:139], v[136:137], off
	v_mov_b32_e32 v209, v159
	v_lshl_add_u64 v[208:209], v[208:209], 2, s[88:89]
	global_load_dwordx4 v[212:215], v[208:209], off
	v_add_u32_e32 v208, 0xb0, v206
	v_lshlrev_b32_e32 v206, 1, v208
	v_mov_b32_e32 v207, v159
	v_lshlrev_b32_e32 v238, 11, v208
	v_lshl_add_u64 v[210:211], v[206:207], 2, s[2:3]
	v_add_u32_e32 v206, v238, v158
	v_lshl_add_u64 v[206:207], v[206:207], 2, s[88:89]
	global_load_dwordx2 v[240:241], v[210:211], off
	v_add_u32_e32 v216, v238, v231
	global_load_dwordx4 v[206:209], v[206:207], off
	v_mov_b32_e32 v217, v159
	v_lshl_add_u64 v[216:217], v[216:217], 2, s[88:89]
	global_load_dwordx4 v[216:219], v[216:217], off
	v_add_u32_e32 v242, 0x50000, v194
	v_mov_b32_e32 v243, v159
	v_lshl_add_u64 v[242:243], v[242:243], 2, s[90:91]
	s_waitcnt vmcnt(0)
	v_sub_f32_e32 v137, v137, v220
	v_sub_f32_e32 v136, v136, v220
	v_sub_f32_e32 v139, v139, v220
	v_sub_f32_e32 v138, v138, v220
	v_pk_mul_f32 v[138:139], v[220:221], v[138:139] op_sel:[1,0]
	v_pk_mul_f32 v[136:137], v[220:221], v[136:137] op_sel:[1,0]
	v_pk_fma_f32 v[138:139], v[152:153], v[138:139], v[78:79]
	v_pk_fma_f32 v[136:137], v[154:155], v[136:137], v[76:77]
	v_pk_fma_f32 v[138:139], v[134:135], s[78:79], v[138:139] op_sel_hi:[1,0,1]
	v_pk_fma_f32 v[136:137], v[132:133], s[78:79], v[136:137] op_sel_hi:[1,0,1]
	global_store_dwordx4 v[242:243], v[136:139], off
	s_nop 1
	v_sub_f32_e32 v137, v213, v220
	v_sub_f32_e32 v136, v212, v220
	v_sub_f32_e32 v139, v215, v220
	v_sub_f32_e32 v138, v214, v220
	v_pk_mul_f32 v[138:139], v[220:221], v[138:139] op_sel:[1,0]
	v_pk_mul_f32 v[136:137], v[220:221], v[136:137] op_sel:[1,0]
	v_pk_fma_f32 v[138:139], v[148:149], v[138:139], v[74:75]
	v_pk_fma_f32 v[136:137], v[150:151], v[136:137], v[72:73]
	v_add_u32_e32 v212, 0x50010, v194
	v_mov_b32_e32 v213, v159
	v_pk_fma_f32 v[138:139], v[130:131], s[78:79], v[138:139] op_sel_hi:[1,0,1]
	v_pk_fma_f32 v[136:137], v[128:129], s[78:79], v[136:137] op_sel_hi:[1,0,1]
	v_lshl_add_u64 v[212:213], v[212:213], 2, s[90:91]
	global_store_dwordx4 v[212:213], v[136:139], off
	s_nop 1
	v_sub_f32_e32 v137, v207, v240
	v_sub_f32_e32 v136, v206, v240
	v_sub_f32_e32 v139, v209, v240
	v_sub_f32_e32 v138, v208, v240
	v_pk_mul_f32 v[136:137], v[240:241], v[136:137] op_sel:[1,0]
	v_pk_mul_f32 v[138:139], v[240:241], v[138:139] op_sel:[1,0]
	v_pk_fma_f32 v[136:137], v[154:155], v[136:137], v[68:69]
	v_pk_fma_f32 v[138:139], v[152:153], v[138:139], v[70:71]
	v_pk_fma_f32 v[132:133], v[132:133], s[78:79], v[136:137] op_sel_hi:[1,0,1]
	v_add_u32_e32 v136, 0x58000, v194
	v_mov_b32_e32 v137, v159
	v_pk_fma_f32 v[134:135], v[134:135], s[78:79], v[138:139] op_sel_hi:[1,0,1]
	v_lshl_add_u64 v[136:137], v[136:137], 2, s[90:91]
	global_store_dwordx4 v[136:137], v[132:135], off
	s_nop 1
	v_sub_f32_e32 v133, v217, v240
	v_sub_f32_e32 v132, v216, v240
	v_sub_f32_e32 v135, v219, v240
	v_sub_f32_e32 v134, v218, v240
	v_pk_mul_f32 v[132:133], v[240:241], v[132:133] op_sel:[1,0]
	v_pk_mul_f32 v[134:135], v[240:241], v[134:135] op_sel:[1,0]
	v_pk_fma_f32 v[132:133], v[150:151], v[132:133], v[64:65]
	v_pk_fma_f32 v[134:135], v[148:149], v[134:135], v[66:67]
	v_pk_fma_f32 v[128:129], v[128:129], s[78:79], v[132:133] op_sel_hi:[1,0,1]
	v_add_u32_e32 v132, 0x58010, v194
	v_mov_b32_e32 v133, v159
	v_pk_fma_f32 v[130:131], v[130:131], s[78:79], v[134:135] op_sel_hi:[1,0,1]
	v_lshl_add_u64 v[132:133], v[132:133], 2, s[90:91]
	global_store_dwordx4 v[132:133], v[128:131], off
	global_load_dwordx4 v[128:131], v[140:141], off offset:512
	v_add_u32_e32 v136, v232, v230
	v_mov_b32_e32 v137, v159
	v_lshl_add_u64 v[136:137], v[136:137], 2, s[88:89]
	s_waitcnt vmcnt(0)
;     template <bool LN, int BJ, int LO, int HI> DI void batch(const f32x4 (&acc)[2][2][4][2], unsigned row0, unsigned col0, const f32x4 (&gv)[2], const f32x4 (&bv)[2]) const {
;         f32x4 r[HI - LO]; float mean[(HI - LO) / 2], rstd[(HI - LO) / 2];
; #pragma unroll
;         for (int i = LO; i < HI; ++i) { const int ai = i >> 3, m = (i >> 1) & 3, n = i & 1; const unsigned row = row0 + ai * HALF + m * 16;
;             if (n == 0) { mean[(i - LO) >> 1] = 0.f; rstd[(i - LO) >> 1] = 1.f;
;                 if (LN) { const float2 st = *(const float2*)(stats + row * 2u); mean[(i - LO) >> 1] = st.x; rstd[(i - LO) >> 1] = st.y; } }
;             r[i - LO] = *(const f32x4*)(src + (row * (unsigned)DM + col0 + BJ * HALF + n * 16)); }
; #pragma unroll
;         for (int i = LO; i < HI; ++i) { const int ai = i >> 3, m = (i >> 1) & 3, n = i & 1; const unsigned row = row0 + ai * HALF + m * 16;
;             *(f32x4*)(Y + (row * (unsigned)DM + col0 + BJ * HALF + n * 16)) = acc[ai][BJ][m][n] + ((r[i - LO] - mean[(i - LO) >> 1]) * rstd[(i - LO) >> 1]) * gv[n] + bv[n]; }
;         __builtin_amdgcn_sched_barrier(0);
;     }
;     template <bool LN, int BJ> DI void load_gb(unsigned col0, f32x4 (&gv)[2], f32x4 (&bv)[2]) const {
; #pragma unroll
;         for (int n = 0; n < 2; ++n) {
;             if (LN) { gv[n] = *(const f32x4*)(gam + col0 + BJ * HALF + n * 16) * ALPHA; bv[n] = *(const f32x4*)(bet + col0 + BJ * HALF + n * 16) * ALPHA; }
;             else { gv[n] = (f32x4){ALPHA, ALPHA, ALPHA, ALPHA}; bv[n] = (f32x4){0.f, 0.f, 0.f, 0.f}; }
;         }
;     }
;     template <bool LN> DI void run(const f32x4 (&acc)[2][2][4][2], const Unit& u, int wr, int wc, int fr, int fq) const {
;         const unsigned row0 = u.pm * BM + wr * 64 + fr, col0 = u.pn * BM + wc * 32 + 4 * fq;
;         f32x4 gv[2], bv[2];
;         load_gb<LN, 0>(col0, gv, bv);
;         batch<LN, 0, 0, 4>(acc, row0, col0, gv, bv);
;         batch<LN, 0, 4, 8>(acc, row0, col0, gv, bv);
;         batch<LN, 0, 8, 12>(acc, row0, col0, gv, bv);
;         batch<LN, 0, 12, 16>(acc, row0, col0, gv, bv);
;         load_gb<LN, 1>(col0, gv, bv);
;         batch<LN, 1, 0, 8>(acc, row0, col0, gv, bv);
;         batch<LN, 1, 8, 16>(acc, row0, col0, gv, bv);
	v_pk_mul_f32 v[212:213], v[130:131], s[78:79] op_sel_hi:[1,0]
	v_pk_mul_f32 v[214:215], v[128:129], s[78:79] op_sel_hi:[1,0]
	global_load_dwordx4 v[132:135], v[142:143], off offset:512
	global_load_dwordx4 v[128:131], v[140:141], off offset:576
	s_waitcnt vmcnt(0)
	v_pk_mul_f32 v[206:207], v[130:131], s[78:79] op_sel_hi:[1,0]
	v_pk_mul_f32 v[208:209], v[128:129], s[78:79] op_sel_hi:[1,0]
	global_load_dwordx4 v[128:131], v[142:143], off offset:576
	global_load_dwordx2 v[220:221], v[144:145], off
	global_load_dwordx4 v[240:243], v[136:137], off
	v_add_u32_e32 v136, v232, v229
	v_mov_b32_e32 v137, v159
	v_lshl_add_u64 v[136:137], v[136:137], 2, s[88:89]
	global_load_dwordx4 v[244:247], v[136:137], off
	global_load_dwordx2 v[218:219], v[146:147], off
	v_add_u32_e32 v136, v195, v230
	v_mov_b32_e32 v137, v159
	v_lshl_add_u64 v[136:137], v[136:137], 2, s[88:89]
	global_load_dwordx4 v[248:251], v[136:137], off
	v_add_u32_e32 v136, v195, v229
	v_mov_b32_e32 v137, v159
	v_lshl_add_u64 v[136:137], v[136:137], 2, s[88:89]
	global_load_dwordx4 v[152:155], v[136:137], off
	global_load_dwordx2 v[216:217], v[200:201], off
	v_add_u32_e32 v136, v236, v230
	v_mov_b32_e32 v137, v159
	v_lshl_add_u64 v[136:137], v[136:137], 2, s[88:89]
	global_load_dwordx4 v[148:151], v[136:137], off
	v_add_u32_e32 v136, v236, v229
	v_mov_b32_e32 v137, v159
	v_lshl_add_u64 v[136:137], v[136:137], 2, s[88:89]
	global_load_dwordx4 v[144:147], v[136:137], off
	global_load_dwordx2 v[200:201], v[202:203], off
	v_add_u32_e32 v136, v235, v230
	v_mov_b32_e32 v137, v159
	v_lshl_add_u64 v[136:137], v[136:137], 2, s[88:89]
	global_load_dwordx4 v[140:143], v[136:137], off
	v_add_u32_e32 v136, v235, v229
	v_mov_b32_e32 v137, v159
	v_lshl_add_u64 v[136:137], v[136:137], 2, s[88:89]
	global_load_dwordx4 v[136:139], v[136:137], off
	v_add_u32_e32 v202, 0x80, v194
	v_mov_b32_e32 v203, v159
	v_lshl_add_u64 v[202:203], v[202:203], 2, s[90:91]
	s_waitcnt vmcnt(0)
	v_sub_f32_e32 v241, v241, v220
	v_sub_f32_e32 v240, v240, v220
	v_sub_f32_e32 v243, v243, v220
	v_sub_f32_e32 v242, v242, v220
	v_pk_mul_f32 v[242:243], v[220:221], v[242:243] op_sel:[1,0]
	v_pk_mul_f32 v[240:241], v[220:221], v[240:241] op_sel:[1,0]
	v_pk_fma_f32 v[242:243], v[212:213], v[242:243], v[62:63]
	v_pk_fma_f32 v[240:241], v[214:215], v[240:241], v[60:61]
	v_pk_fma_f32 v[242:243], v[134:135], s[78:79], v[242:243] op_sel_hi:[1,0,1]
	v_pk_fma_f32 v[240:241], v[132:133], s[78:79], v[240:241] op_sel_hi:[1,0,1]
	global_store_dwordx4 v[202:203], v[240:243], off
	v_sub_f32_e32 v203, v245, v220
	v_sub_f32_e32 v202, v244, v220
	v_sub_f32_e32 v241, v247, v220
	v_sub_f32_e32 v240, v246, v220
	v_pk_mul_f32 v[202:203], v[220:221], v[202:203] op_sel:[1,0]
	v_pk_mul_f32 v[240:241], v[220:221], v[240:241] op_sel:[1,0]
	v_pk_fma_f32 v[202:203], v[208:209], v[202:203], v[56:57]
	v_pk_fma_f32 v[220:221], v[206:207], v[240:241], v[58:59]
	v_pk_fma_f32 v[240:241], v[128:129], s[78:79], v[202:203] op_sel_hi:[1,0,1]
	v_add_u32_e32 v202, 0x90, v194
	v_mov_b32_e32 v203, v159
	v_pk_fma_f32 v[242:243], v[130:131], s[78:79], v[220:221] op_sel_hi:[1,0,1]
	v_lshl_add_u64 v[202:203], v[202:203], 2, s[90:91]
	global_store_dwordx4 v[202:203], v[240:243], off
	v_sub_f32_e32 v203, v249, v218
	v_sub_f32_e32 v202, v248, v218
	v_sub_f32_e32 v221, v251, v218
	v_sub_f32_e32 v220, v250, v218
	v_pk_mul_f32 v[202:203], v[218:219], v[202:203] op_sel:[1,0]
	v_pk_mul_f32 v[220:221], v[218:219], v[220:221] op_sel:[1,0]
	v_pk_fma_f32 v[202:203], v[214:215], v[202:203], v[52:53]
	v_pk_fma_f32 v[220:221], v[212:213], v[220:221], v[54:55]
	v_pk_fma_f32 v[240:241], v[132:133], s[78:79], v[202:203] op_sel_hi:[1,0,1]
	v_add_u32_e32 v202, 0x8080, v194
	v_mov_b32_e32 v203, v159
	v_sub_f32_e32 v153, v153, v218
	v_sub_f32_e32 v152, v152, v218
	v_sub_f32_e32 v155, v155, v218
	v_sub_f32_e32 v154, v154, v218
	v_pk_fma_f32 v[242:243], v[134:135], s[78:79], v[220:221] op_sel_hi:[1,0,1]
	v_lshl_add_u64 v[202:203], v[202:203], 2, s[90:91]
	v_pk_mul_f32 v[154:155], v[218:219], v[154:155] op_sel:[1,0]
	v_pk_mul_f32 v[152:153], v[218:219], v[152:153] op_sel:[1,0]
	global_store_dwordx4 v[202:203], v[240:243], off
	v_pk_fma_f32 v[152:153], v[208:209], v[152:153], v[48:49]
	v_pk_fma_f32 v[154:155], v[206:207], v[154:155], v[50:51]
	v_add_u32_e32 v202, 0x8090, v194
	v_mov_b32_e32 v203, v159
	v_sub_f32_e32 v149, v149, v216
	v_sub_f32_e32 v148, v148, v216
	v_sub_f32_e32 v151, v151, v216
	v_sub_f32_e32 v150, v150, v216
	v_pk_fma_f32 v[154:155], v[130:131], s[78:79], v[154:155] op_sel_hi:[1,0,1]
	v_pk_fma_f32 v[152:153], v[128:129], s[78:79], v[152:153] op_sel_hi:[1,0,1]
	v_lshl_add_u64 v[202:203], v[202:203], 2, s[90:91]
	v_pk_mul_f32 v[150:151], v[216:217], v[150:151] op_sel:[1,0]
	v_pk_mul_f32 v[148:149], v[216:217], v[148:149] op_sel:[1,0]
	global_store_dwordx4 v[202:203], v[152:155], off
	v_pk_fma_f32 v[148:149], v[214:215], v[148:149], v[44:45]
	v_pk_fma_f32 v[150:151], v[212:213], v[150:151], v[46:47]
	v_add_u32_e32 v152, 0x10080, v194
	v_mov_b32_e32 v153, v159
	v_sub_f32_e32 v145, v145, v216
	v_sub_f32_e32 v144, v144, v216
	v_sub_f32_e32 v147, v147, v216
	v_sub_f32_e32 v146, v146, v216
	v_pk_fma_f32 v[150:151], v[134:135], s[78:79], v[150:151] op_sel_hi:[1,0,1]
	v_pk_fma_f32 v[148:149], v[132:133], s[78:79], v[148:149] op_sel_hi:[1,0,1]
	v_lshl_add_u64 v[152:153], v[152:153], 2, s[90:91]
	v_pk_mul_f32 v[146:147], v[216:217], v[146:147] op_sel:[1,0]
	v_pk_mul_f32 v[144:145], v[216:217], v[144:145] op_sel:[1,0]
	global_store_dwordx4 v[152:153], v[148:151], off
	v_pk_fma_f32 v[144:145], v[208:209], v[144:145], v[40:41]
	v_pk_fma_f32 v[146:147], v[206:207], v[146:147], v[42:43]
;     template <bool LN, int BJ, int LO, int HI> DI void batch(const f32x4 (&acc)[2][2][4][2], unsigned row0, unsigned col0, const f32x4 (&gv)[2], const f32x4 (&bv)[2]) const {
;         f32x4 r[HI - LO]; float mean[(HI - LO) / 2], rstd[(HI - LO) / 2];
; #pragma unroll
;         for (int i = LO; i < HI; ++i) { const int ai = i >> 3, m = (i >> 1) & 3, n = i & 1; const unsigned row = row0 + ai * HALF + m * 16;
;             if (n == 0) { mean[(i - LO) >> 1] = 0.f; rstd[(i - LO) >> 1] = 1.f;
;                 if (LN) { const float2 st = *(const float2*)(stats + row * 2u); mean[(i - LO) >> 1] = st.x; rstd[(i - LO) >> 1] = st.y; } }
;             r[i - LO] = *(const f32x4*)(src + (row * (unsigned)DM + col0 + BJ * HALF + n * 16)); }
; #pragma unroll
;         for (int i = LO; i < HI; ++i) { const int ai = i >> 3, m = (i >> 1) & 3, n = i & 1; const unsigned row = row0 + ai * HALF + m * 16;
;             *(f32x4*)(Y + (row * (unsigned)DM + col0 + BJ * HALF + n * 16)) = acc[ai][BJ][m][n] + ((r[i - LO] - mean[(i - LO) >> 1]) * rstd[(i - LO) >> 1]) * gv[n] + bv[n]; }
;         __builtin_amdgcn_sched_barrier(0);
;     }
;     template <bool LN, int BJ> DI void load_gb(unsigned col0, f32x4 (&gv)[2], f32x4 (&bv)[2]) const {
; #pragma unroll
;         for (int n = 0; n < 2; ++n) {
;             if (LN) { gv[n] = *(const f32x4*)(gam + col0 + BJ * HALF + n * 16) * ALPHA; bv[n] = *(const f32x4*)(bet + col0 + BJ * HALF + n * 16) * ALPHA; }
;             else { gv[n] = (f32x4){ALPHA, ALPHA, ALPHA, ALPHA}; bv[n] = (f32x4){0.f, 0.f, 0.f, 0.f}; }
;         }
;     }
;     template <bool LN> DI void run(const f32x4 (&acc)[2][2][4][2], const Unit& u, int wr, int wc, int fr, int fq) const {
;         const unsigned row0 = u.pm * BM + wr * 64 + fr, col0 = u.pn * BM + wc * 32 + 4 * fq;
;         f32x4 gv[2], bv[2];
;         load_gb<LN, 0>(col0, gv, bv);
;         batch<LN, 0, 0, 4>(acc, row0, col0, gv, bv);
;         batch<LN, 0, 4, 8>(acc, row0, col0, gv, bv);
;         batch<LN, 0, 8, 12>(acc, row0, col0, gv, bv);
;         batch<LN, 0, 12, 16>(acc, row0, col0, gv, bv);
;         load_gb<LN, 1>(col0, gv, bv);
;         batch<LN, 1, 0, 8>(acc, row0, col0, gv, bv);
;         batch<LN, 1, 8, 16>(acc, row0, col0, gv, bv);
	v_add_u32_e32 v148, 0x10090, v194
	v_mov_b32_e32 v149, v159
	v_sub_f32_e32 v141, v141, v200
	v_sub_f32_e32 v140, v140, v200
	v_sub_f32_e32 v143, v143, v200
	v_sub_f32_e32 v142, v142, v200
	v_pk_fma_f32 v[146:147], v[130:131], s[78:79], v[146:147] op_sel_hi:[1,0,1]
	v_pk_fma_f32 v[144:145], v[128:129], s[78:79], v[144:145] op_sel_hi:[1,0,1]
	v_lshl_add_u64 v[148:149], v[148:149], 2, s[90:91]
	v_pk_mul_f32 v[142:143], v[200:201], v[142:143] op_sel:[1,0]
	v_pk_mul_f32 v[140:141], v[200:201], v[140:141] op_sel:[1,0]
	global_store_dwordx4 v[148:149], v[144:147], off
	v_pk_fma_f32 v[140:141], v[214:215], v[140:141], v[36:37]
	v_pk_fma_f32 v[142:143], v[212:213], v[142:143], v[38:39]
	v_add_u32_e32 v144, 0x18080, v194
	v_mov_b32_e32 v145, v159
	v_sub_f32_e32 v137, v137, v200
	v_sub_f32_e32 v136, v136, v200
	v_sub_f32_e32 v139, v139, v200
	v_sub_f32_e32 v138, v138, v200
	v_pk_fma_f32 v[142:143], v[134:135], s[78:79], v[142:143] op_sel_hi:[1,0,1]
	v_pk_fma_f32 v[140:141], v[132:133], s[78:79], v[140:141] op_sel_hi:[1,0,1]
	v_lshl_add_u64 v[144:145], v[144:145], 2, s[90:91]
	v_pk_mul_f32 v[138:139], v[200:201], v[138:139] op_sel:[1,0]
	v_pk_mul_f32 v[136:137], v[200:201], v[136:137] op_sel:[1,0]
	global_store_dwordx4 v[144:145], v[140:143], off
	v_pk_fma_f32 v[136:137], v[208:209], v[136:137], v[32:33]
	v_pk_fma_f32 v[138:139], v[206:207], v[138:139], v[34:35]
	v_add_u32_e32 v140, 0x18090, v194
	v_mov_b32_e32 v141, v159
	v_pk_fma_f32 v[138:139], v[130:131], s[78:79], v[138:139] op_sel_hi:[1,0,1]
	v_pk_fma_f32 v[136:137], v[128:129], s[78:79], v[136:137] op_sel_hi:[1,0,1]
	v_lshl_add_u64 v[140:141], v[140:141], 2, s[90:91]
	global_store_dwordx4 v[140:141], v[136:139], off
	s_nop 1
	v_add_u32_e32 v136, v233, v230
	v_mov_b32_e32 v137, v159
	v_lshl_add_u64 v[136:137], v[136:137], 2, s[88:89]
	global_load_dwordx2 v[220:221], v[196:197], off
	global_load_dwordx4 v[216:219], v[136:137], off
	v_add_u32_e32 v136, v233, v229
	v_mov_b32_e32 v137, v159
	v_lshl_add_u64 v[136:137], v[136:137], 2, s[88:89]
	global_load_dwordx4 v[240:243], v[136:137], off
	global_load_dwordx2 v[200:201], v[198:199], off
	v_add_u32_e32 v136, v234, v230
	v_mov_b32_e32 v137, v159
	v_lshl_add_u64 v[136:137], v[136:137], 2, s[88:89]
	global_load_dwordx4 v[244:247], v[136:137], off
	v_add_u32_e32 v136, v234, v229
	v_mov_b32_e32 v137, v159
	v_lshl_add_u64 v[136:137], v[136:137], 2, s[88:89]
	global_load_dwordx4 v[152:155], v[136:137], off
	global_load_dwordx2 v[198:199], v[204:205], off
	v_add_u32_e32 v136, v237, v230
	v_mov_b32_e32 v137, v159
	v_lshl_add_u64 v[136:137], v[136:137], 2, s[88:89]
	global_load_dwordx4 v[148:151], v[136:137], off
	v_add_u32_e32 v136, v237, v229
	v_mov_b32_e32 v137, v159
	v_lshl_add_u64 v[136:137], v[136:137], 2, s[88:89]
	global_load_dwordx4 v[144:147], v[136:137], off
	global_load_dwordx2 v[196:197], v[210:211], off
	v_add_u32_e32 v136, v238, v230
	v_mov_b32_e32 v137, v159
	v_lshl_add_u64 v[136:137], v[136:137], 2, s[88:89]
	global_load_dwordx4 v[140:143], v[136:137], off
	v_add_u32_e32 v136, v238, v229
	v_mov_b32_e32 v137, v159
	v_lshl_add_u64 v[136:137], v[136:137], 2, s[88:89]
	global_load_dwordx4 v[136:139], v[136:137], off
	v_add_u32_e32 v210, 0x40080, v194
	v_mov_b32_e32 v211, v159
	v_lshl_add_u64 v[210:211], v[210:211], 2, s[90:91]
	s_waitcnt vmcnt(0)
;     template <bool LN, int BJ, int LO, int HI> DI void batch(const f32x4 (&acc)[2][2][4][2], unsigned row0, unsigned col0, const f32x4 (&gv)[2], const f32x4 (&bv)[2]) const {
;         f32x4 r[HI - LO]; float mean[(HI - LO) / 2], rstd[(HI - LO) / 2];
; #pragma unroll
;         for (int i = LO; i < HI; ++i) { const int ai = i >> 3, m = (i >> 1) & 3, n = i & 1; const unsigned row = row0 + ai * HALF + m * 16;
;             if (n == 0) { mean[(i - LO) >> 1] = 0.f; rstd[(i - LO) >> 1] = 1.f;
;                 if (LN) { const float2 st = *(const float2*)(stats + row * 2u); mean[(i - LO) >> 1] = st.x; rstd[(i - LO) >> 1] = st.y; } }
;             r[i - LO] = *(const f32x4*)(src + (row * (unsigned)DM + col0 + BJ * HALF + n * 16)); }
; #pragma unroll
;         for (int i = LO; i < HI; ++i) { const int ai = i >> 3, m = (i >> 1) & 3, n = i & 1; const unsigned row = row0 + ai * HALF + m * 16;
;             *(f32x4*)(Y + (row * (unsigned)DM + col0 + BJ * HALF + n * 16)) = acc[ai][BJ][m][n] + ((r[i - LO] - mean[(i - LO) >> 1]) * rstd[(i - LO) >> 1]) * gv[n] + bv[n]; }
;         __builtin_amdgcn_sched_barrier(0);
;     }
;     template <bool LN, int BJ> DI void load_gb(unsigned col0, f32x4 (&gv)[2], f32x4 (&bv)[2]) const {
; #pragma unroll
;         for (int n = 0; n < 2; ++n) {
;             if (LN) { gv[n] = *(const f32x4*)(gam + col0 + BJ * HALF + n * 16) * ALPHA; bv[n] = *(const f32x4*)(bet + col0 + BJ * HALF + n * 16) * ALPHA; }
;             else { gv[n] = (f32x4){ALPHA, ALPHA, ALPHA, ALPHA}; bv[n] = (f32x4){0.f, 0.f, 0.f, 0.f}; }
;         }
;     }
;     template <bool LN> DI void run(const f32x4 (&acc)[2][2][4][2], const Unit& u, int wr, int wc, int fr, int fq) const {
;         const unsigned row0 = u.pm * BM + wr * 64 + fr, col0 = u.pn * BM + wc * 32 + 4 * fq;
;         f32x4 gv[2], bv[2];
;         load_gb<LN, 0>(col0, gv, bv);
;         batch<LN, 0, 0, 4>(acc, row0, col0, gv, bv);
;         batch<LN, 0, 4, 8>(acc, row0, col0, gv, bv);
;         batch<LN, 0, 8, 12>(acc, row0, col0, gv, bv);
;         batch<LN, 0, 12, 16>(acc, row0, col0, gv, bv);
;         load_gb<LN, 1>(col0, gv, bv);
;         batch<LN, 1, 0, 8>(acc, row0, col0, gv, bv);
;         batch<LN, 1, 8, 16>(acc, row0, col0, gv, bv);
	v_sub_f32_e32 v203, v217, v220
	v_sub_f32_e32 v202, v216, v220
	v_sub_f32_e32 v205, v219, v220
	v_sub_f32_e32 v204, v218, v220
	v_pk_mul_f32 v[204:205], v[220:221], v[204:205] op_sel:[1,0]
	v_pk_mul_f32 v[202:203], v[220:221], v[202:203] op_sel:[1,0]
	v_pk_fma_f32 v[204:205], v[212:213], v[204:205], v[30:31]
	v_pk_fma_f32 v[202:203], v[214:215], v[202:203], v[28:29]
	v_pk_fma_f32 v[204:205], v[134:135], s[78:79], v[204:205] op_sel_hi:[1,0,1]
	v_pk_fma_f32 v[202:203], v[132:133], s[78:79], v[202:203] op_sel_hi:[1,0,1]
	global_store_dwordx4 v[210:211], v[202:205], off
	v_add_u32_e32 v210, 0x40090, v194
	v_mov_b32_e32 v211, v159
	v_sub_f32_e32 v203, v241, v220
	v_sub_f32_e32 v202, v240, v220
	v_sub_f32_e32 v205, v243, v220
	v_sub_f32_e32 v204, v242, v220
	v_pk_mul_f32 v[204:205], v[220:221], v[204:205] op_sel:[1,0]
	v_pk_mul_f32 v[202:203], v[220:221], v[202:203] op_sel:[1,0]
	v_pk_fma_f32 v[204:205], v[206:207], v[204:205], v[26:27]
	v_pk_fma_f32 v[202:203], v[208:209], v[202:203], v[24:25]
	v_pk_fma_f32 v[204:205], v[130:131], s[78:79], v[204:205] op_sel_hi:[1,0,1]
	v_pk_fma_f32 v[202:203], v[128:129], s[78:79], v[202:203] op_sel_hi:[1,0,1]
	v_lshl_add_u64 v[210:211], v[210:211], 2, s[90:91]
	global_store_dwordx4 v[210:211], v[202:205], off
	v_sub_f32_e32 v149, v149, v198
	v_sub_f32_e32 v148, v148, v198
	v_sub_f32_e32 v203, v245, v200
	v_sub_f32_e32 v202, v244, v200
	v_sub_f32_e32 v141, v141, v196
	v_sub_f32_e32 v140, v140, v196
	v_sub_f32_e32 v205, v247, v200
	v_sub_f32_e32 v204, v246, v200
	v_pk_mul_f32 v[202:203], v[200:201], v[202:203] op_sel:[1,0]
	v_sub_f32_e32 v151, v151, v198
	v_sub_f32_e32 v150, v150, v198
	v_pk_mul_f32 v[148:149], v[198:199], v[148:149] op_sel:[1,0]
	v_sub_f32_e32 v143, v143, v196
	v_sub_f32_e32 v142, v142, v196
	v_pk_mul_f32 v[140:141], v[196:197], v[140:141] op_sel:[1,0]
	v_pk_mul_f32 v[204:205], v[200:201], v[204:205] op_sel:[1,0]
	v_pk_fma_f32 v[202:203], v[214:215], v[202:203], v[20:21]
	v_sub_f32_e32 v153, v153, v200
	v_sub_f32_e32 v152, v152, v200
	v_sub_f32_e32 v155, v155, v200
	v_sub_f32_e32 v154, v154, v200
	v_pk_mul_f32 v[150:151], v[198:199], v[150:151] op_sel:[1,0]
	v_pk_fma_f32 v[148:149], v[214:215], v[148:149], v[12:13]
	v_pk_mul_f32 v[142:143], v[196:197], v[142:143] op_sel:[1,0]
	v_pk_fma_f32 v[140:141], v[214:215], v[140:141], v[4:5]
	v_pk_fma_f32 v[204:205], v[212:213], v[204:205], v[22:23]
	v_pk_fma_f32 v[202:203], v[132:133], s[78:79], v[202:203] op_sel_hi:[1,0,1]
	v_pk_mul_f32 v[154:155], v[200:201], v[154:155] op_sel:[1,0]
	v_pk_mul_f32 v[152:153], v[200:201], v[152:153] op_sel:[1,0]
	v_pk_fma_f32 v[150:151], v[212:213], v[150:151], v[14:15]
	v_pk_fma_f32 v[148:149], v[132:133], s[78:79], v[148:149] op_sel_hi:[1,0,1]
	v_pk_fma_f32 v[142:143], v[212:213], v[142:143], v[6:7]
	v_pk_fma_f32 v[132:133], v[132:133], s[78:79], v[140:141] op_sel_hi:[1,0,1]
	v_add_u32_e32 v140, 0x58080, v194
	v_mov_b32_e32 v141, v159
	v_pk_fma_f32 v[204:205], v[134:135], s[78:79], v[204:205] op_sel_hi:[1,0,1]
	v_pk_fma_f32 v[152:153], v[208:209], v[152:153], v[16:17]
	v_pk_fma_f32 v[154:155], v[206:207], v[154:155], v[18:19]
	v_add_u32_e32 v200, 0x48090, v194
	v_mov_b32_e32 v201, v159
	v_pk_fma_f32 v[150:151], v[134:135], s[78:79], v[150:151] op_sel_hi:[1,0,1]
	v_pk_fma_f32 v[134:135], v[134:135], s[78:79], v[142:143] op_sel_hi:[1,0,1]
	v_lshl_add_u64 v[140:141], v[140:141], 2, s[90:91]
	v_pk_fma_f32 v[154:155], v[130:131], s[78:79], v[154:155] op_sel_hi:[1,0,1]
	v_pk_fma_f32 v[152:153], v[128:129], s[78:79], v[152:153] op_sel_hi:[1,0,1]
	v_lshl_add_u64 v[200:201], v[200:201], 2, s[90:91]
	v_sub_f32_e32 v145, v145, v198
	v_sub_f32_e32 v144, v144, v198
	global_store_dwordx4 v[140:141], v[132:135], off
	global_store_dwordx4 v[200:201], v[152:155], off
	v_sub_f32_e32 v147, v147, v198
	v_sub_f32_e32 v133, v137, v196
	v_sub_f32_e32 v132, v136, v196
	v_add_u32_e32 v152, 0x50080, v194
	v_mov_b32_e32 v153, v159
	v_sub_f32_e32 v146, v146, v198
	v_pk_mul_f32 v[144:145], v[198:199], v[144:145] op_sel:[1,0]
	v_sub_f32_e32 v135, v139, v196
	v_sub_f32_e32 v134, v138, v196
	v_pk_mul_f32 v[132:133], v[196:197], v[132:133] op_sel:[1,0]
	v_lshl_add_u64 v[152:153], v[152:153], 2, s[90:91]
	v_pk_mul_f32 v[146:147], v[198:199], v[146:147] op_sel:[1,0]
	v_pk_fma_f32 v[144:145], v[208:209], v[144:145], v[8:9]
	v_pk_mul_f32 v[134:135], v[196:197], v[134:135] op_sel:[1,0]
	v_pk_fma_f32 v[132:133], v[208:209], v[132:133], v[0:1]
	v_add_u32_e32 v210, 0x48080, v194
	v_mov_b32_e32 v211, v159
	global_store_dwordx4 v[152:153], v[148:151], off
	v_pk_fma_f32 v[146:147], v[206:207], v[146:147], v[10:11]
	v_pk_fma_f32 v[144:145], v[128:129], s[78:79], v[144:145] op_sel_hi:[1,0,1]
	v_add_u32_e32 v148, 0x50090, v194
	v_mov_b32_e32 v149, v159
	v_pk_fma_f32 v[134:135], v[206:207], v[134:135], v[2:3]
	v_pk_fma_f32 v[128:129], v[128:129], s[78:79], v[132:133] op_sel_hi:[1,0,1]
	v_add_u32_e32 v132, 0x58090, v194
	v_mov_b32_e32 v133, v159
	v_lshl_add_u64 v[210:211], v[210:211], 2, s[90:91]
	v_pk_fma_f32 v[146:147], v[130:131], s[78:79], v[146:147] op_sel_hi:[1,0,1]
	v_lshl_add_u64 v[148:149], v[148:149], 2, s[90:91]
	v_pk_fma_f32 v[130:131], v[130:131], s[78:79], v[134:135] op_sel_hi:[1,0,1]
	v_lshl_add_u64 v[132:133], v[132:133], 2, s[90:91]
	global_store_dwordx4 v[210:211], v[202:205], off
	global_store_dwordx4 v[148:149], v[144:147], off
	global_store_dwordx4 v[132:133], v[128:131], off
	s_mov_b64 s[20:21], 0
	s_branch .LBB0_81

; #define PG8_STAGE(bufoff, gbase) do { _Pragma("unroll") for (int _i = 0; _i < 2; ++_i) \
;         __builtin_amdgcn_global_load_lds((const unsigned*)((const char*)(gbase) + voff[_i]), (LAS unsigned*)(lds + (bufoff) + ldsw + _i * 8192), 16, 0, 0); } while (0)
; #define PG8_LDA(dst, b, h) do { _Pragma("unroll") for (int m = 0; m < 4; ++m) _Pragma("unroll") for (int k = 0; k < 2; ++k) dst[m][k] = *(const LAS bf16x8*)(lds + PG8_SA(b, h) + aoff + m * 2048 + k * 1024); } while (0)
; #define PG8_LDB(dst, b, h) do { _Pragma("unroll") for (int n = 0; n < 2; ++n) _Pragma("unroll") for (int k = 0; k < 2; ++k) dst[n][k] = *(const LAS bf16x8*)(lds + PG8_SB(b, h) + boff + n * 2048 + k * 1024); } while (0)
; #define PG8_MMA(ai, bj, At, Bt) do { __builtin_amdgcn_s_setprio(1); _Pragma("unroll") for (int m = 0; m < 4; ++m) _Pragma("unroll") for (int n = 0; n < 2; ++n) _Pragma("unroll") for (int k = 0; k < 2; ++k) \
;         acc[ai][bj][m][n] = __builtin_amdgcn_mfma_f32_16x16x32_bf16(Bt[n][k], At[m][k], acc[ai][bj][m][n], 0, 0, 0); __builtin_amdgcn_s_setprio(0); } while (0)
; #define PG8_WAIT_L(n) asm volatile("s_waitcnt lgkmcnt(" #n ")" ::: "memory")
; #define PG8_BAR __builtin_amdgcn_s_barrier()
; #define PG8_SCHED __builtin_amdgcn_sched_barrier(0)
; template <class Epi>
; DI void gemm_phase(LAS unsigned char* lds, const Gemm g, const StaticOrder& S, const Epi& E) {
;     ...
;             PG8_LDB(B0, 0, 0); PG8_SCHED; PG8_LDA(At, 0, 0); PG8_STAGE(PG8_SA(1, 1), a1 + hstep);
;             PG8_WAIT_L(8); PG8_BAR; PG8_WAIT_L(0); PG8_MMA(0, 0, At, B0); PG8_BAR; PG8_SCHED;
;             PG8_LDB(B1, 0, 1); PG8_STAGE(PG8_SB(0, 0), b2);
;             PG8_BAR; PG8_WAIT_L(0); PG8_MMA(0, 1, At, B1); PG8_BAR;
;             PG8_LDA(At, 0, 1); PG8_STAGE(PG8_SA(0, 0), a2);
;             PG8_BAR; PG8_WAIT_L(0); PG8_MMA(1, 0, At, B0); PG8_BAR; PG8_SCHED;
;             PG8_STAGE(PG8_SB(0, 1), b2 + hstep);
.LBB0_134:
	s_add_u32 s18, s16, 0x100
	s_addc_u32 s19, s17, 0
	s_add_i32 s39, 0, 0x10000
	v_add_u32_e32 v148, s39, v199
	ds_read_b128 v[96:99], v148
	ds_read_b128 v[100:103], v148 offset:1024
	ds_read_b128 v[136:139], v148 offset:2048
	ds_read_b128 v[148:151], v148 offset:3072
	s_cmpk_eq_i32 s33, 0x54
	s_cselect_b32 s23, s9, s19
	s_cselect_b32 s22, s8, s18
	s_cselect_b32 s21, s11, s5
	s_cselect_b32 s20, s10, s4
	v_lshl_add_u64 v[218:219], s[16:17], 0, v[144:145]
	s_add_i32 m0, s28, 0xc000
	ds_read_b128 v[152:155], v201
	ds_read_b128 v[186:189], v201 offset:1024
	ds_read_b128 v[190:193], v201 offset:2048
	ds_read_b128 v[194:197], v201 offset:3072
	ds_read_b128 v[202:205], v201 offset:4096
	ds_read_b128 v[206:209], v201 offset:5120
	ds_read_b128 v[210:213], v201 offset:6144
	ds_read_b128 v[214:217], v201 offset:7168
	global_load_lds_dwordx4 v[218:219], off
	v_lshl_add_u64 v[218:219], s[16:17], 0, v[146:147]
	s_add_i32 m0, s28, 0xe000
	s_nop 0
	global_load_lds_dwordx4 v[218:219], off
	s_waitcnt lgkmcnt(8)
	s_setprio 1
	s_barrier
	s_waitcnt lgkmcnt(0)
	v_mfma_f32_16x16x32_bf16 v[132:135], v[96:99], v[152:155], v[132:135]
	v_mfma_f32_16x16x32_bf16 v[128:131], v[136:139], v[152:155], v[128:131]
	v_mfma_f32_16x16x32_bf16 v[124:127], v[96:99], v[190:193], v[124:127]
	v_mfma_f32_16x16x32_bf16 v[120:123], v[136:139], v[190:193], v[120:123]
	v_mfma_f32_16x16x32_bf16 v[116:119], v[96:99], v[202:205], v[116:119]
	v_mfma_f32_16x16x32_bf16 v[112:115], v[136:139], v[202:205], v[112:115]
	v_mfma_f32_16x16x32_bf16 v[108:111], v[96:99], v[210:213], v[108:111]
	v_mfma_f32_16x16x32_bf16 v[104:107], v[136:139], v[210:213], v[104:107]
	v_mfma_f32_16x16x32_bf16 v[132:135], v[100:103], v[186:189], v[132:135]
	s_add_i32 s40, 0, 0x14000
	v_mfma_f32_16x16x32_bf16 v[128:131], v[148:151], v[186:189], v[128:131]
	s_add_i32 s16, s39, s27
	v_mfma_f32_16x16x32_bf16 v[124:127], v[100:103], v[194:197], v[124:127]
	v_add_u32_e32 v158, s40, v199
	v_mfma_f32_16x16x32_bf16 v[120:123], v[148:151], v[194:197], v[120:123]
	v_lshl_add_u64 v[218:219], s[20:21], 0, v[142:143]
	v_mfma_f32_16x16x32_bf16 v[116:119], v[100:103], v[206:209], v[116:119]
	s_mov_b32 m0, s16
	v_mfma_f32_16x16x32_bf16 v[112:115], v[148:151], v[206:209], v[112:115]
	v_mfma_f32_16x16x32_bf16 v[108:111], v[100:103], v[214:217], v[108:111]
	v_mfma_f32_16x16x32_bf16 v[104:107], v[148:151], v[214:217], v[104:107]
	s_setprio 0
	s_barrier
	ds_read_b128 v[226:229], v158
	ds_read_b128 v[230:233], v158 offset:1024
	ds_read_b128 v[234:237], v158 offset:2048
	ds_read_b128 v[238:241], v158 offset:3072
	global_load_lds_dwordx4 v[218:219], off
	v_lshl_add_u64 v[220:221], s[20:21], 0, v[140:141]
	s_add_i32 m0, s16, 0x2000
	s_nop 0
	global_load_lds_dwordx4 v[220:221], off
	s_waitcnt lgkmcnt(0)
	s_setprio 1
	s_barrier
	v_mfma_f32_16x16x32_bf16 v[60:63], v[226:229], v[152:155], v[60:63]
	v_mfma_f32_16x16x32_bf16 v[56:59], v[234:237], v[152:155], v[56:59]
	v_mfma_f32_16x16x32_bf16 v[52:55], v[226:229], v[190:193], v[52:55]
	v_mfma_f32_16x16x32_bf16 v[48:51], v[234:237], v[190:193], v[48:51]
	v_mfma_f32_16x16x32_bf16 v[44:47], v[226:229], v[202:205], v[44:47]
	v_mfma_f32_16x16x32_bf16 v[40:43], v[234:237], v[202:205], v[40:43]
	v_mfma_f32_16x16x32_bf16 v[36:39], v[226:229], v[210:213], v[36:39]
	v_mfma_f32_16x16x32_bf16 v[32:35], v[234:237], v[210:213], v[32:35]
	v_mfma_f32_16x16x32_bf16 v[60:63], v[230:233], v[186:189], v[60:63]
	s_mov_b32 m0, s28
	v_mfma_f32_16x16x32_bf16 v[56:59], v[238:241], v[186:189], v[56:59]
	v_lshl_add_u64 v[242:243], s[22:23], 0, v[142:143]
	v_mfma_f32_16x16x32_bf16 v[52:55], v[230:233], v[194:197], v[52:55]
	v_mfma_f32_16x16x32_bf16 v[48:51], v[238:241], v[194:197], v[48:51]
	v_mfma_f32_16x16x32_bf16 v[44:47], v[230:233], v[206:209], v[44:47]
	v_mfma_f32_16x16x32_bf16 v[40:43], v[238:241], v[206:209], v[40:43]
	v_mfma_f32_16x16x32_bf16 v[36:39], v[230:233], v[214:217], v[36:39]
	v_mfma_f32_16x16x32_bf16 v[32:35], v[238:241], v[214:217], v[32:35]
	s_setprio 0
	s_barrier
	ds_read_b128 v[152:155], v201 offset:16384
	ds_read_b128 v[186:189], v201 offset:17408
	ds_read_b128 v[190:193], v201 offset:18432
	ds_read_b128 v[194:197], v201 offset:19456
	ds_read_b128 v[202:205], v201 offset:20480
	ds_read_b128 v[206:209], v201 offset:21504
	ds_read_b128 v[210:213], v201 offset:22528
	ds_read_b128 v[214:217], v201 offset:23552
	global_load_lds_dwordx4 v[242:243], off
	v_lshl_add_u64 v[244:245], s[22:23], 0, v[140:141]
	s_mov_b32 m0, s29
	s_nop 0
	global_load_lds_dwordx4 v[244:245], off
	s_waitcnt lgkmcnt(0)
	s_setprio 1
	s_barrier
	v_mfma_f32_16x16x32_bf16 v[92:95], v[96:99], v[152:155], v[92:95]
	v_mfma_f32_16x16x32_bf16 v[88:91], v[136:139], v[152:155], v[88:91]
	v_mfma_f32_16x16x32_bf16 v[84:87], v[96:99], v[190:193], v[84:87]
	v_mfma_f32_16x16x32_bf16 v[80:83], v[136:139], v[190:193], v[80:83]
	v_mfma_f32_16x16x32_bf16 v[76:79], v[96:99], v[202:205], v[76:79]
	v_mfma_f32_16x16x32_bf16 v[72:75], v[136:139], v[202:205], v[72:75]
	v_mfma_f32_16x16x32_bf16 v[68:71], v[96:99], v[210:213], v[68:71]
	v_mfma_f32_16x16x32_bf16 v[64:67], v[136:139], v[210:213], v[64:67]
	v_mfma_f32_16x16x32_bf16 v[92:95], v[100:103], v[186:189], v[92:95]
	s_add_u32 s16, s20, 0x160000
	v_mfma_f32_16x16x32_bf16 v[88:91], v[148:151], v[186:189], v[88:91]
	s_addc_u32 s17, s21, 0
	v_mfma_f32_16x16x32_bf16 v[84:87], v[100:103], v[194:197], v[84:87]
	s_add_i32 s39, s40, s27
	v_mfma_f32_16x16x32_bf16 v[80:83], v[148:151], v[194:197], v[80:83]
	v_lshl_add_u64 v[96:97], s[16:17], 0, v[142:143]
	v_mfma_f32_16x16x32_bf16 v[76:79], v[100:103], v[206:209], v[76:79]
	s_mov_b32 m0, s39
	v_mfma_f32_16x16x32_bf16 v[72:75], v[148:151], v[206:209], v[72:75]
	v_mfma_f32_16x16x32_bf16 v[68:71], v[100:103], v[214:217], v[68:71]
	v_mfma_f32_16x16x32_bf16 v[64:67], v[148:151], v[214:217], v[64:67]
	s_setprio 0
	s_barrier
; #define PG8_STAGE(bufoff, gbase) do { _Pragma("unroll") for (int _i = 0; _i < 2; ++_i) \
;         __builtin_amdgcn_global_load_lds((const unsigned*)((const char*)(gbase) + voff[_i]), (LAS unsigned*)(lds + (bufoff) + ldsw + _i * 8192), 16, 0, 0); } while (0)
; #define PG8_LDA(dst, b, h) do { _Pragma("unroll") for (int m = 0; m < 4; ++m) _Pragma("unroll") for (int k = 0; k < 2; ++k) dst[m][k] = *(const LAS bf16x8*)(lds + PG8_SA(b, h) + aoff + m * 2048 + k * 1024); } while (0)
; #define PG8_LDB(dst, b, h) do { _Pragma("unroll") for (int n = 0; n < 2; ++n) _Pragma("unroll") for (int k = 0; k < 2; ++k) dst[n][k] = *(const LAS bf16x8*)(lds + PG8_SB(b, h) + boff + n * 2048 + k * 1024); } while (0)
; #define PG8_MMA(ai, bj, At, Bt) do { __builtin_amdgcn_s_setprio(1); _Pragma("unroll") for (int m = 0; m < 4; ++m) _Pragma("unroll") for (int n = 0; n < 2; ++n) _Pragma("unroll") for (int k = 0; k < 2; ++k) \
;         acc[ai][bj][m][n] = __builtin_amdgcn_mfma_f32_16x16x32_bf16(Bt[n][k], At[m][k], acc[ai][bj][m][n], 0, 0, 0); __builtin_amdgcn_s_setprio(0); } while (0)
; #define PG8_WAIT_V(n) asm volatile("s_waitcnt vmcnt(" #n ")" ::: "memory")
; #define PG8_WAIT_L(n) asm volatile("s_waitcnt lgkmcnt(" #n ")" ::: "memory")
; #define PG8_BAR __builtin_amdgcn_s_barrier()
; #define PG8_SCHED __builtin_amdgcn_sched_barrier(0)
; template <class Epi>
; DI void gemm_phase(LAS unsigned char* lds, const Gemm g, const StaticOrder& S, const Epi& E) {
;     ...
;             PG8_STAGE(PG8_SB(0, 1), b2 + hstep);
;             PG8_WAIT_V(6); PG8_BAR; PG8_MMA(1, 1, At, B1); PG8_BAR;
;             PG8_LDB(B0, 1, 0); PG8_SCHED; PG8_LDA(At, 1, 0); PG8_STAGE(PG8_SA(0, 1), a2 + hstep);
;             PG8_WAIT_L(8); PG8_BAR; PG8_WAIT_L(0); PG8_MMA(0, 0, At, B0); PG8_BAR; PG8_SCHED;
;             PG8_LDB(B1, 1, 1); PG8_STAGE(PG8_SB(1, 0), b3);
;             PG8_BAR; PG8_WAIT_L(0); PG8_MMA(0, 1, At, B1); PG8_BAR;
;             PG8_LDA(At, 1, 1); PG8_STAGE(PG8_SA(1, 0), a3);
;             PG8_BAR; PG8_WAIT_L(0); PG8_MMA(1, 0, At, B0); PG8_BAR; PG8_SCHED;
	s_nop 0
	global_load_lds_dwordx4 v[96:97], off
	v_lshl_add_u64 v[96:97], s[16:17], 0, v[140:141]
	s_add_i32 m0, s39, 0x2000
	s_nop 0
	global_load_lds_dwordx4 v[96:97], off
	s_waitcnt vmcnt(6)
	s_setprio 1
	s_barrier
	v_mfma_f32_16x16x32_bf16 v[28:31], v[226:229], v[152:155], v[28:31]
	v_mfma_f32_16x16x32_bf16 v[24:27], v[234:237], v[152:155], v[24:27]
	v_mfma_f32_16x16x32_bf16 v[20:23], v[226:229], v[190:193], v[20:23]
	v_mfma_f32_16x16x32_bf16 v[16:19], v[234:237], v[190:193], v[16:19]
	v_mfma_f32_16x16x32_bf16 v[12:15], v[226:229], v[202:205], v[12:15]
	v_mfma_f32_16x16x32_bf16 v[8:11], v[234:237], v[202:205], v[8:11]
	v_mfma_f32_16x16x32_bf16 v[4:7], v[226:229], v[210:213], v[4:7]
	v_mfma_f32_16x16x32_bf16 v[0:3], v[234:237], v[210:213], v[0:3]
	v_mfma_f32_16x16x32_bf16 v[28:31], v[230:233], v[186:189], v[28:31]
	s_add_i32 s39, 0, 0x18000
	v_mfma_f32_16x16x32_bf16 v[24:27], v[238:241], v[186:189], v[24:27]
	v_add_u32_e32 v148, s39, v199
	v_mfma_f32_16x16x32_bf16 v[20:23], v[230:233], v[194:197], v[20:23]
	v_mfma_f32_16x16x32_bf16 v[16:19], v[238:241], v[194:197], v[16:19]
	v_mfma_f32_16x16x32_bf16 v[12:15], v[230:233], v[206:209], v[12:15]
	v_mfma_f32_16x16x32_bf16 v[8:11], v[238:241], v[206:209], v[8:11]
	v_mfma_f32_16x16x32_bf16 v[4:7], v[230:233], v[214:217], v[4:7]
	v_mfma_f32_16x16x32_bf16 v[0:3], v[238:241], v[214:217], v[0:3]
	s_setprio 0
	s_barrier
	ds_read_b128 v[96:99], v148
	ds_read_b128 v[100:103], v148 offset:1024
	ds_read_b128 v[136:139], v148 offset:2048
	ds_read_b128 v[148:151], v148 offset:3072
	s_add_u32 s16, s22, 0x160000
	s_addc_u32 s17, s23, 0
	s_mov_b32 m0, s30
	v_lshl_add_u64 v[226:227], s[16:17], 0, v[142:143]
	ds_read_b128 v[152:155], v201 offset:32768
	ds_read_b128 v[186:189], v201 offset:33792
	ds_read_b128 v[190:193], v201 offset:34816
	ds_read_b128 v[194:197], v201 offset:35840
	ds_read_b128 v[202:205], v201 offset:36864
	ds_read_b128 v[206:209], v201 offset:37888
	ds_read_b128 v[210:213], v201 offset:38912
	ds_read_b128 v[214:217], v201 offset:39936
	global_load_lds_dwordx4 v[226:227], off
	v_lshl_add_u64 v[226:227], s[16:17], 0, v[140:141]
	s_mov_b32 m0, s31
	s_nop 0
	global_load_lds_dwordx4 v[226:227], off
	s_waitcnt lgkmcnt(8)
	s_setprio 1
	s_barrier
	s_waitcnt lgkmcnt(0)
	v_mfma_f32_16x16x32_bf16 v[132:135], v[96:99], v[152:155], v[132:135]
	v_mfma_f32_16x16x32_bf16 v[128:131], v[136:139], v[152:155], v[128:131]
	v_mfma_f32_16x16x32_bf16 v[124:127], v[96:99], v[190:193], v[124:127]
	v_mfma_f32_16x16x32_bf16 v[120:123], v[136:139], v[190:193], v[120:123]
	v_mfma_f32_16x16x32_bf16 v[116:119], v[96:99], v[202:205], v[116:119]
	v_mfma_f32_16x16x32_bf16 v[112:115], v[136:139], v[202:205], v[112:115]
	v_mfma_f32_16x16x32_bf16 v[108:111], v[96:99], v[210:213], v[108:111]
	v_mfma_f32_16x16x32_bf16 v[104:107], v[136:139], v[210:213], v[104:107]
	v_mfma_f32_16x16x32_bf16 v[132:135], v[100:103], v[186:189], v[132:135]
	s_add_i32 s22, 0, 0x1c000
	v_mfma_f32_16x16x32_bf16 v[128:131], v[148:151], v[186:189], v[128:131]
	s_add_i32 s16, s39, s27
	v_mfma_f32_16x16x32_bf16 v[124:127], v[100:103], v[194:197], v[124:127]
	v_add_u32_e32 v158, s22, v199
	v_mfma_f32_16x16x32_bf16 v[120:123], v[148:151], v[194:197], v[120:123]
	v_lshl_add_u64 v[218:219], v[218:219], 0, s[94:95]
	v_mfma_f32_16x16x32_bf16 v[116:119], v[100:103], v[206:209], v[116:119]
	s_mov_b32 m0, s16
	v_mfma_f32_16x16x32_bf16 v[112:115], v[148:151], v[206:209], v[112:115]
	v_mfma_f32_16x16x32_bf16 v[108:111], v[100:103], v[214:217], v[108:111]
	v_mfma_f32_16x16x32_bf16 v[104:107], v[148:151], v[214:217], v[104:107]
	s_setprio 0
	s_barrier
	ds_read_b128 v[226:229], v158
	ds_read_b128 v[230:233], v158 offset:1024
	ds_read_b128 v[234:237], v158 offset:2048
	ds_read_b128 v[238:241], v158 offset:3072
	global_load_lds_dwordx4 v[218:219], off
	v_lshl_add_u64 v[218:219], v[220:221], 0, s[94:95]
	s_add_i32 m0, s16, 0x2000
	s_nop 0
	global_load_lds_dwordx4 v[218:219], off
	s_waitcnt lgkmcnt(0)
	s_setprio 1
	s_barrier
	v_mfma_f32_16x16x32_bf16 v[60:63], v[226:229], v[152:155], v[60:63]
	v_mfma_f32_16x16x32_bf16 v[56:59], v[234:237], v[152:155], v[56:59]
	v_mfma_f32_16x16x32_bf16 v[52:55], v[226:229], v[190:193], v[52:55]
	v_mfma_f32_16x16x32_bf16 v[48:51], v[234:237], v[190:193], v[48:51]
	v_mfma_f32_16x16x32_bf16 v[44:47], v[226:229], v[202:205], v[44:47]
	v_mfma_f32_16x16x32_bf16 v[40:43], v[234:237], v[202:205], v[40:43]
	v_mfma_f32_16x16x32_bf16 v[36:39], v[226:229], v[210:213], v[36:39]
	v_mfma_f32_16x16x32_bf16 v[32:35], v[234:237], v[210:213], v[32:35]
	v_mfma_f32_16x16x32_bf16 v[60:63], v[230:233], v[186:189], v[60:63]
	s_mov_b32 m0, s34
	v_mfma_f32_16x16x32_bf16 v[56:59], v[238:241], v[186:189], v[56:59]
	v_lshl_add_u64 v[218:219], v[242:243], 0, s[94:95]
	v_mfma_f32_16x16x32_bf16 v[52:55], v[230:233], v[194:197], v[52:55]
	v_mfma_f32_16x16x32_bf16 v[48:51], v[238:241], v[194:197], v[48:51]
	v_mfma_f32_16x16x32_bf16 v[44:47], v[230:233], v[206:209], v[44:47]
	v_mfma_f32_16x16x32_bf16 v[40:43], v[238:241], v[206:209], v[40:43]
	v_mfma_f32_16x16x32_bf16 v[36:39], v[230:233], v[214:217], v[36:39]
	v_mfma_f32_16x16x32_bf16 v[32:35], v[238:241], v[214:217], v[32:35]
	s_setprio 0
	s_barrier
	ds_read_b128 v[152:155], v201 offset:49152
	ds_read_b128 v[186:189], v201 offset:50176
	ds_read_b128 v[190:193], v201 offset:51200
	ds_read_b128 v[194:197], v201 offset:52224
	ds_read_b128 v[202:205], v201 offset:53248
	ds_read_b128 v[206:209], v201 offset:54272
	ds_read_b128 v[210:213], v201 offset:55296
	ds_read_b128 v[214:217], v201 offset:56320
	global_load_lds_dwordx4 v[218:219], off
	v_lshl_add_u64 v[218:219], v[244:245], 0, s[94:95]
	s_mov_b32 m0, s35
	s_nop 0
	global_load_lds_dwordx4 v[218:219], off
	s_waitcnt lgkmcnt(0)
	s_setprio 1
	s_barrier
; template <class Epi>
; DI void gemm_phase(LAS unsigned char* lds, const Gemm g, const StaticOrder& S, const Epi& E) {
;     ...
;             PG8_BAR; PG8_WAIT_L(0); PG8_MMA(1, 0, At, B0); PG8_BAR; PG8_SCHED;
;             PG8_STAGE(PG8_SB(1, 1), b3 + hstep);
;             PG8_WAIT_V(6); PG8_BAR; PG8_MMA(1, 1, At, B1); PG8_BAR;
;         }
;     template <bool LN, int BJ, int LO, int HI> DI void batch(const f32x4 (&acc)[2][2][4][2], unsigned row0, unsigned col0, const f32x4 (&gv)[2], const f32x4 (&bv)[2]) const {
;         f32x4 r[HI - LO]; float mean[(HI - LO) / 2], rstd[(HI - LO) / 2];
; #pragma unroll
;         for (int i = LO; i < HI; ++i) { const int ai = i >> 3, m = (i >> 1) & 3, n = i & 1; const unsigned row = row0 + ai * HALF + m * 16;
;             if (n == 0) { mean[(i - LO) >> 1] = 0.f; rstd[(i - LO) >> 1] = 1.f;
;                 if (LN) { const float2 st = *(const float2*)(stats + row * 2u); mean[(i - LO) >> 1] = st.x; rstd[(i - LO) >> 1] = st.y; } }
;             r[i - LO] = *(const f32x4*)(src + (row * (unsigned)DM + col0 + BJ * HALF + n * 16)); }
; #pragma unroll
;         for (int i = LO; i < HI; ++i) { const int ai = i >> 3, m = (i >> 1) & 3, n = i & 1; const unsigned row = row0 + ai * HALF + m * 16;
;             *(f32x4*)(Y + (row * (unsigned)DM + col0 + BJ * HALF + n * 16)) = acc[ai][BJ][m][n] + ((r[i - LO] - mean[(i - LO) >> 1]) * rstd[(i - LO) >> 1]) * gv[n] + bv[n]; }
;         __builtin_amdgcn_sched_barrier(0);
;     }
;     template <bool LN, int BJ> DI void load_gb(unsigned col0, f32x4 (&gv)[2], f32x4 (&bv)[2]) const {
; #pragma unroll
;         for (int n = 0; n < 2; ++n) {
;             if (LN) { gv[n] = *(const f32x4*)(gam + col0 + BJ * HALF + n * 16) * ALPHA; bv[n] = *(const f32x4*)(bet + col0 + BJ * HALF + n * 16) * ALPHA; }
;             else { gv[n] = (f32x4){ALPHA, ALPHA, ALPHA, ALPHA}; bv[n] = (f32x4){0.f, 0.f, 0.f, 0.f}; }
;         }
;     }
;     template <bool LN> DI void run(const f32x4 (&acc)[2][2][4][2], const Unit& u, int wr, int wc, int fr, int fq) const {
;         const unsigned row0 = u.pm * BM + wr * 64 + fr, col0 = u.pn * BM + wc * 32 + 4 * fq;
;         f32x4 gv[2], bv[2];
;         load_gb<LN, 0>(col0, gv, bv);
;         batch<LN, 0, 0, 4>(acc, row0, col0, gv, bv);
;         batch<LN, 0, 4, 8>(acc, row0, col0, gv, bv);
;         batch<LN, 0, 8, 12>(acc, row0, col0, gv, bv);
	v_mfma_f32_16x16x32_bf16 v[92:95], v[96:99], v[152:155], v[92:95]
	v_mfma_f32_16x16x32_bf16 v[88:91], v[136:139], v[152:155], v[88:91]
	v_mfma_f32_16x16x32_bf16 v[84:87], v[96:99], v[190:193], v[84:87]
	v_mfma_f32_16x16x32_bf16 v[80:83], v[136:139], v[190:193], v[80:83]
	v_mfma_f32_16x16x32_bf16 v[76:79], v[96:99], v[202:205], v[76:79]
	v_mfma_f32_16x16x32_bf16 v[72:75], v[136:139], v[202:205], v[72:75]
	v_mfma_f32_16x16x32_bf16 v[68:71], v[96:99], v[210:213], v[68:71]
	v_mfma_f32_16x16x32_bf16 v[64:67], v[136:139], v[210:213], v[64:67]
	v_mfma_f32_16x16x32_bf16 v[92:95], v[100:103], v[186:189], v[92:95]
	s_add_u32 s16, s20, 0x160080
	v_mfma_f32_16x16x32_bf16 v[88:91], v[148:151], v[186:189], v[88:91]
	s_addc_u32 s17, s21, 0
	v_mfma_f32_16x16x32_bf16 v[84:87], v[100:103], v[194:197], v[84:87]
	s_add_i32 s20, s22, s27
	v_mfma_f32_16x16x32_bf16 v[80:83], v[148:151], v[194:197], v[80:83]
	v_lshl_add_u64 v[96:97], s[16:17], 0, v[142:143]
	v_mfma_f32_16x16x32_bf16 v[76:79], v[100:103], v[206:209], v[76:79]
	s_mov_b32 m0, s20
	v_mfma_f32_16x16x32_bf16 v[72:75], v[148:151], v[206:209], v[72:75]
	v_mfma_f32_16x16x32_bf16 v[68:71], v[100:103], v[214:217], v[68:71]
	v_mfma_f32_16x16x32_bf16 v[64:67], v[148:151], v[214:217], v[64:67]
	s_setprio 0
	s_barrier
	s_nop 0
	global_load_lds_dwordx4 v[96:97], off
	v_lshl_add_u64 v[96:97], s[16:17], 0, v[140:141]
	s_add_i32 m0, s20, 0x2000
	s_nop 0
	global_load_lds_dwordx4 v[96:97], off
	s_waitcnt vmcnt(6)
	s_setprio 1
	s_barrier
	v_mfma_f32_16x16x32_bf16 v[28:31], v[226:229], v[152:155], v[28:31]
	v_mfma_f32_16x16x32_bf16 v[24:27], v[234:237], v[152:155], v[24:27]
	v_mfma_f32_16x16x32_bf16 v[20:23], v[226:229], v[190:193], v[20:23]
	v_mfma_f32_16x16x32_bf16 v[16:19], v[234:237], v[190:193], v[16:19]
	v_mfma_f32_16x16x32_bf16 v[12:15], v[226:229], v[202:205], v[12:15]
	v_mfma_f32_16x16x32_bf16 v[8:11], v[234:237], v[202:205], v[8:11]
	v_mfma_f32_16x16x32_bf16 v[4:7], v[226:229], v[210:213], v[4:7]
	v_mfma_f32_16x16x32_bf16 v[0:3], v[234:237], v[210:213], v[0:3]
	v_mfma_f32_16x16x32_bf16 v[28:31], v[230:233], v[186:189], v[28:31]
	s_add_i32 s33, s33, 2
	v_mfma_f32_16x16x32_bf16 v[24:27], v[238:241], v[186:189], v[24:27]
	s_add_u32 s4, s4, 0x100
	v_mfma_f32_16x16x32_bf16 v[20:23], v[230:233], v[194:197], v[20:23]
	s_addc_u32 s5, s5, 0
	v_mfma_f32_16x16x32_bf16 v[16:19], v[238:241], v[194:197], v[16:19]
	s_cmpk_gt_u32 s33, 0x55
	v_mfma_f32_16x16x32_bf16 v[12:15], v[230:233], v[206:209], v[12:15]
	s_mov_b64 s[16:17], s[18:19]
	v_mfma_f32_16x16x32_bf16 v[8:11], v[238:241], v[206:209], v[8:11]
	v_mfma_f32_16x16x32_bf16 v[4:7], v[230:233], v[214:217], v[4:7]
	v_mfma_f32_16x16x32_bf16 v[0:3], v[238:241], v[214:217], v[0:3]
	s_setprio 0
	s_barrier
	s_cbranch_scc0 .LBB0_134
	v_lshl_or_b32 v158, s2, 8, v200
	v_lshlrev_b64 v[100:101], 2, v[158:159]
	v_lshl_add_u64 v[150:151], s[12:13], 0, v[100:101]
	global_load_dwordx4 v[96:99], v[150:151], off
	v_lshl_add_u64 v[152:153], s[14:15], 0, v[100:101]
	v_lshl_add_u32 v203, s3, 8, v198
	v_lshlrev_b32_e32 v202, 11, v203
	v_add_u32_e32 v148, v202, v158
	v_mov_b32_e32 v149, v159
	v_lshlrev_b32_e32 v136, 1, v203
	v_mov_b32_e32 v137, v159
	v_lshlrev_b64 v[220:221], 2, v[148:149]
	v_lshl_add_u64 v[154:155], v[136:137], 2, s[96:97]
	v_lshl_add_u64 v[136:137], s[90:91], 0, v[220:221]
	v_or_b32_e32 v204, 16, v158
	v_or_b32_e32 v138, 16, v203
	v_lshlrev_b32_e32 v149, 11, v138
	s_waitcnt vmcnt(0)
	v_pk_mul_f32 v[192:193], v[98:99], s[78:79] op_sel_hi:[1,0]
	v_pk_mul_f32 v[194:195], v[96:97], s[78:79] op_sel_hi:[1,0]
	global_load_dwordx4 v[100:103], v[152:153], off
	global_load_dwordx4 v[96:99], v[150:151], off offset:64
	global_load_dwordx2 v[218:219], v[154:155], off
	global_load_dwordx4 v[206:209], v[136:137], off
	v_add_u32_e32 v136, v202, v204
	v_mov_b32_e32 v137, v159
	v_lshl_add_u64 v[136:137], v[136:137], 2, s[90:91]
	global_load_dwordx4 v[210:213], v[136:137], off
	v_lshlrev_b32_e32 v136, 1, v138
	v_mov_b32_e32 v137, v159
	v_lshl_add_u64 v[186:187], v[136:137], 2, s[96:97]
	v_add_u32_e32 v136, v149, v158
	v_lshl_add_u64 v[136:137], v[136:137], 2, s[90:91]
	global_load_dwordx2 v[196:197], v[186:187], off
	global_load_dwordx4 v[214:217], v[136:137], off
	v_add_u32_e32 v136, v149, v204
	v_mov_b32_e32 v137, v159
	v_lshl_add_u64 v[136:137], v[136:137], 2, s[90:91]
	global_load_dwordx4 v[136:139], v[136:137], off
	s_waitcnt vmcnt(0)
	v_pk_mul_f32 v[188:189], v[98:99], s[78:79] op_sel_hi:[1,0]
	v_pk_mul_f32 v[190:191], v[96:97], s[78:79] op_sel_hi:[1,0]
	global_load_dwordx4 v[96:99], v[152:153], off offset:64
	v_sub_f32_e32 v207, v207, v218
	v_sub_f32_e32 v206, v206, v218
	v_sub_f32_e32 v209, v209, v218
	v_sub_f32_e32 v208, v208, v218
	v_pk_mul_f32 v[208:209], v[218:219], v[208:209] op_sel:[1,0]
	v_pk_mul_f32 v[206:207], v[218:219], v[206:207] op_sel:[1,0]
	v_pk_fma_f32 v[134:135], v[192:193], v[208:209], v[134:135]
	v_pk_fma_f32 v[132:133], v[194:195], v[206:207], v[132:133]
	v_pk_fma_f32 v[134:135], v[102:103], s[78:79], v[134:135] op_sel_hi:[1,0,1]
	v_pk_fma_f32 v[132:133], v[100:101], s[78:79], v[132:133] op_sel_hi:[1,0,1]
	v_lshl_add_u64 v[206:207], s[88:89], 0, v[220:221]
	global_store_dwordx4 v[206:207], v[132:135], off
	s_nop 1
	v_sub_f32_e32 v133, v211, v218
	v_sub_f32_e32 v132, v210, v218
	v_sub_f32_e32 v135, v213, v218
	v_sub_f32_e32 v134, v212, v218
	v_pk_mul_f32 v[134:135], v[218:219], v[134:135] op_sel:[1,0]
	v_pk_mul_f32 v[132:133], v[218:219], v[132:133] op_sel:[1,0]
	v_pk_fma_f32 v[130:131], v[188:189], v[134:135], v[130:131]
	v_pk_fma_f32 v[128:129], v[190:191], v[132:133], v[128:129]
	v_or_b32_e32 v132, 16, v148
	v_mov_b32_e32 v133, v159
	v_lshl_add_u64 v[132:133], v[132:133], 2, s[88:89]
	s_waitcnt vmcnt(0)
;     template <bool LN, int BJ, int LO, int HI> DI void batch(const f32x4 (&acc)[2][2][4][2], unsigned row0, unsigned col0, const f32x4 (&gv)[2], const f32x4 (&bv)[2]) const {
;         f32x4 r[HI - LO]; float mean[(HI - LO) / 2], rstd[(HI - LO) / 2];
; #pragma unroll
;         for (int i = LO; i < HI; ++i) { const int ai = i >> 3, m = (i >> 1) & 3, n = i & 1; const unsigned row = row0 + ai * HALF + m * 16;
;             if (n == 0) { mean[(i - LO) >> 1] = 0.f; rstd[(i - LO) >> 1] = 1.f;
;                 if (LN) { const float2 st = *(const float2*)(stats + row * 2u); mean[(i - LO) >> 1] = st.x; rstd[(i - LO) >> 1] = st.y; } }
;             r[i - LO] = *(const f32x4*)(src + (row * (unsigned)DM + col0 + BJ * HALF + n * 16)); }
; #pragma unroll
;         for (int i = LO; i < HI; ++i) { const int ai = i >> 3, m = (i >> 1) & 3, n = i & 1; const unsigned row = row0 + ai * HALF + m * 16;
;             *(f32x4*)(Y + (row * (unsigned)DM + col0 + BJ * HALF + n * 16)) = acc[ai][BJ][m][n] + ((r[i - LO] - mean[(i - LO) >> 1]) * rstd[(i - LO) >> 1]) * gv[n] + bv[n]; }
;         __builtin_amdgcn_sched_barrier(0);
;     }
;     template <bool LN, int BJ> DI void load_gb(unsigned col0, f32x4 (&gv)[2], f32x4 (&bv)[2]) const {
; #pragma unroll
;         for (int n = 0; n < 2; ++n) {
;             if (LN) { gv[n] = *(const f32x4*)(gam + col0 + BJ * HALF + n * 16) * ALPHA; bv[n] = *(const f32x4*)(bet + col0 + BJ * HALF + n * 16) * ALPHA; }
;             else { gv[n] = (f32x4){ALPHA, ALPHA, ALPHA, ALPHA}; bv[n] = (f32x4){0.f, 0.f, 0.f, 0.f}; }
;         }
;     }
;     template <bool LN> DI void run(const f32x4 (&acc)[2][2][4][2], const Unit& u, int wr, int wc, int fr, int fq) const {
;         const unsigned row0 = u.pm * BM + wr * 64 + fr, col0 = u.pn * BM + wc * 32 + 4 * fq;
;         f32x4 gv[2], bv[2];
;         load_gb<LN, 0>(col0, gv, bv);
;         batch<LN, 0, 0, 4>(acc, row0, col0, gv, bv);
;         batch<LN, 0, 4, 8>(acc, row0, col0, gv, bv);
;         batch<LN, 0, 8, 12>(acc, row0, col0, gv, bv);
;         batch<LN, 0, 12, 16>(acc, row0, col0, gv, bv);
;         load_gb<LN, 1>(col0, gv, bv);
;         batch<LN, 1, 0, 8>(acc, row0, col0, gv, bv);
;         batch<LN, 1, 8, 16>(acc, row0, col0, gv, bv);
	v_pk_fma_f32 v[130:131], v[98:99], s[78:79], v[130:131] op_sel_hi:[1,0,1]
	v_pk_fma_f32 v[128:129], v[96:97], s[78:79], v[128:129] op_sel_hi:[1,0,1]
	global_store_dwordx4 v[132:133], v[128:131], off
	s_nop 1
	v_sub_f32_e32 v129, v215, v196
	v_sub_f32_e32 v128, v214, v196
	v_sub_f32_e32 v131, v217, v196
	v_sub_f32_e32 v130, v216, v196
	v_pk_mul_f32 v[130:131], v[196:197], v[130:131] op_sel:[1,0]
	v_pk_mul_f32 v[128:129], v[196:197], v[128:129] op_sel:[1,0]
	v_pk_fma_f32 v[126:127], v[192:193], v[130:131], v[126:127]
	v_pk_fma_f32 v[124:125], v[194:195], v[128:129], v[124:125]
	v_add_u32_e32 v128, 0x8000, v148
	v_mov_b32_e32 v129, v159
	v_pk_fma_f32 v[126:127], v[102:103], s[78:79], v[126:127] op_sel_hi:[1,0,1]
	v_pk_fma_f32 v[124:125], v[100:101], s[78:79], v[124:125] op_sel_hi:[1,0,1]
	v_lshl_add_u64 v[128:129], v[128:129], 2, s[88:89]
	global_store_dwordx4 v[128:129], v[124:127], off
	s_nop 1
	v_sub_f32_e32 v125, v137, v196
	v_sub_f32_e32 v124, v136, v196
	v_sub_f32_e32 v127, v139, v196
	v_sub_f32_e32 v126, v138, v196
	v_pk_mul_f32 v[126:127], v[196:197], v[126:127] op_sel:[1,0]
	v_pk_mul_f32 v[124:125], v[196:197], v[124:125] op_sel:[1,0]
	v_pk_fma_f32 v[122:123], v[188:189], v[126:127], v[122:123]
	v_pk_fma_f32 v[120:121], v[190:191], v[124:125], v[120:121]
	v_add_u32_e32 v124, 0x8010, v148
	v_mov_b32_e32 v125, v159
	v_pk_fma_f32 v[122:123], v[98:99], s[78:79], v[122:123] op_sel_hi:[1,0,1]
	v_pk_fma_f32 v[120:121], v[96:97], s[78:79], v[120:121] op_sel_hi:[1,0,1]
	v_lshl_add_u64 v[124:125], v[124:125], 2, s[88:89]
	global_store_dwordx4 v[124:125], v[120:123], off
	s_nop 1
	v_or_b32_e32 v122, 32, v203
	v_lshlrev_b32_e32 v124, 11, v122
	v_lshlrev_b32_e32 v120, 1, v122
	v_mov_b32_e32 v121, v159
	v_add_u32_e32 v122, v124, v158
	v_mov_b32_e32 v123, v159
	v_lshl_add_u64 v[120:121], v[120:121], 2, s[96:97]
	v_lshl_add_u64 v[122:123], v[122:123], 2, s[90:91]
	global_load_dwordx2 v[138:139], v[120:121], off
	global_load_dwordx4 v[126:129], v[122:123], off
	v_add_u32_e32 v122, v124, v204
	v_mov_b32_e32 v123, v159
	v_lshl_add_u64 v[122:123], v[122:123], 2, s[90:91]
	global_load_dwordx4 v[130:133], v[122:123], off
	v_or_b32_e32 v125, 48, v203
	v_lshlrev_b32_e32 v122, 1, v125
	v_lshlrev_b32_e32 v125, 11, v125
	v_mov_b32_e32 v123, v159
	v_add_u32_e32 v134, v125, v158
	v_mov_b32_e32 v135, v159
	v_lshl_add_u64 v[122:123], v[122:123], 2, s[96:97]
	v_lshl_add_u64 v[134:135], v[134:135], 2, s[90:91]
	global_load_dwordx2 v[196:197], v[122:123], off
	v_add_u32_e32 v206, v125, v204
	global_load_dwordx4 v[134:137], v[134:135], off
	v_mov_b32_e32 v207, v159
	v_lshl_add_u64 v[206:207], v[206:207], 2, s[90:91]
	global_load_dwordx4 v[206:209], v[206:207], off
	s_waitcnt vmcnt(0)
	v_sub_f32_e32 v127, v127, v138
	v_sub_f32_e32 v126, v126, v138
	v_sub_f32_e32 v129, v129, v138
	v_sub_f32_e32 v128, v128, v138
	v_pk_mul_f32 v[128:129], v[138:139], v[128:129] op_sel:[1,0]
	v_pk_mul_f32 v[126:127], v[138:139], v[126:127] op_sel:[1,0]
	v_pk_fma_f32 v[118:119], v[192:193], v[128:129], v[118:119]
	v_pk_fma_f32 v[116:117], v[194:195], v[126:127], v[116:117]
	v_add_u32_e32 v126, 0x10000, v148
	v_mov_b32_e32 v127, v159
	v_pk_fma_f32 v[118:119], v[102:103], s[78:79], v[118:119] op_sel_hi:[1,0,1]
	v_pk_fma_f32 v[116:117], v[100:101], s[78:79], v[116:117] op_sel_hi:[1,0,1]
	v_lshl_add_u64 v[126:127], v[126:127], 2, s[88:89]
	global_store_dwordx4 v[126:127], v[116:119], off
	s_nop 1
	v_sub_f32_e32 v117, v131, v138
	v_sub_f32_e32 v116, v130, v138
	v_sub_f32_e32 v119, v133, v138
	v_sub_f32_e32 v118, v132, v138
	v_pk_mul_f32 v[118:119], v[138:139], v[118:119] op_sel:[1,0]
	v_pk_mul_f32 v[116:117], v[138:139], v[116:117] op_sel:[1,0]
	v_pk_fma_f32 v[114:115], v[188:189], v[118:119], v[114:115]
	v_pk_fma_f32 v[112:113], v[190:191], v[116:117], v[112:113]
	v_add_u32_e32 v116, 0x10010, v148
	v_mov_b32_e32 v117, v159
	v_pk_fma_f32 v[114:115], v[98:99], s[78:79], v[114:115] op_sel_hi:[1,0,1]
	v_pk_fma_f32 v[112:113], v[96:97], s[78:79], v[112:113] op_sel_hi:[1,0,1]
	v_lshl_add_u64 v[116:117], v[116:117], 2, s[88:89]
	global_store_dwordx4 v[116:117], v[112:115], off
	s_nop 1
	v_sub_f32_e32 v113, v135, v196
	v_sub_f32_e32 v112, v134, v196
	v_sub_f32_e32 v115, v137, v196
	v_sub_f32_e32 v114, v136, v196
	v_pk_mul_f32 v[114:115], v[196:197], v[114:115] op_sel:[1,0]
	v_pk_mul_f32 v[112:113], v[196:197], v[112:113] op_sel:[1,0]
	v_pk_fma_f32 v[110:111], v[192:193], v[114:115], v[110:111]
	v_pk_fma_f32 v[108:109], v[194:195], v[112:113], v[108:109]
	v_add_u32_e32 v112, 0x18000, v148
	v_mov_b32_e32 v113, v159
	v_pk_fma_f32 v[110:111], v[102:103], s[78:79], v[110:111] op_sel_hi:[1,0,1]
	v_pk_fma_f32 v[108:109], v[100:101], s[78:79], v[108:109] op_sel_hi:[1,0,1]
	v_lshl_add_u64 v[112:113], v[112:113], 2, s[88:89]
	global_store_dwordx4 v[112:113], v[108:111], off
	s_nop 1
	v_sub_f32_e32 v109, v207, v196
	v_sub_f32_e32 v108, v206, v196
	v_sub_f32_e32 v111, v209, v196
	v_sub_f32_e32 v110, v208, v196
	v_pk_mul_f32 v[110:111], v[196:197], v[110:111] op_sel:[1,0]
	v_pk_mul_f32 v[108:109], v[196:197], v[108:109] op_sel:[1,0]
	v_pk_fma_f32 v[106:107], v[188:189], v[110:111], v[106:107]
	v_pk_fma_f32 v[104:105], v[190:191], v[108:109], v[104:105]
	v_add_u32_e32 v108, 0x18010, v148
	v_mov_b32_e32 v109, v159
	v_pk_fma_f32 v[106:107], v[98:99], s[78:79], v[106:107] op_sel_hi:[1,0,1]
	v_pk_fma_f32 v[104:105], v[96:97], s[78:79], v[104:105] op_sel_hi:[1,0,1]
	v_lshl_add_u64 v[108:109], v[108:109], 2, s[88:89]
	global_store_dwordx4 v[108:109], v[104:107], off
	s_nop 1
	v_add_u32_e32 v106, 0x80, v203
	v_lshlrev_b32_e32 v114, 11, v106
	v_lshlrev_b32_e32 v104, 1, v106
	v_mov_b32_e32 v105, v159
	v_add_u32_e32 v106, v114, v158
	v_mov_b32_e32 v107, v159
	v_lshl_add_u64 v[104:105], v[104:105], 2, s[96:97]
	v_lshl_add_u64 v[106:107], v[106:107], 2, s[90:91]
	global_load_dwordx2 v[112:113], v[104:105], off
	global_load_dwordx4 v[108:111], v[106:107], off
	v_add_u32_e32 v106, v114, v204
	v_mov_b32_e32 v107, v159
	v_lshl_add_u64 v[106:107], v[106:107], 2, s[90:91]
	global_load_dwordx4 v[116:119], v[106:107], off
	v_add_u32_e32 v115, 0x90, v203
	v_lshlrev_b32_e32 v106, 1, v115
	v_lshlrev_b32_e32 v115, 11, v115
	v_mov_b32_e32 v107, v159
	v_add_u32_e32 v126, v115, v158
	v_mov_b32_e32 v127, v159
	v_lshl_add_u64 v[106:107], v[106:107], 2, s[96:97]
	v_lshl_add_u64 v[126:127], v[126:127], 2, s[90:91]
	global_load_dwordx2 v[134:135], v[106:107], off
	v_add_u32_e32 v130, v115, v204
	global_load_dwordx4 v[126:129], v[126:127], off
	v_mov_b32_e32 v131, v159
	v_lshl_add_u64 v[130:131], v[130:131], 2, s[90:91]
	global_load_dwordx4 v[130:133], v[130:131], off
	s_waitcnt vmcnt(0)
;     template <bool LN, int BJ, int LO, int HI> DI void batch(const f32x4 (&acc)[2][2][4][2], unsigned row0, unsigned col0, const f32x4 (&gv)[2], const f32x4 (&bv)[2]) const {
;         f32x4 r[HI - LO]; float mean[(HI - LO) / 2], rstd[(HI - LO) / 2];
; #pragma unroll
;         for (int i = LO; i < HI; ++i) { const int ai = i >> 3, m = (i >> 1) & 3, n = i & 1; const unsigned row = row0 + ai * HALF + m * 16;
;             if (n == 0) { mean[(i - LO) >> 1] = 0.f; rstd[(i - LO) >> 1] = 1.f;
;                 if (LN) { const float2 st = *(const float2*)(stats + row * 2u); mean[(i - LO) >> 1] = st.x; rstd[(i - LO) >> 1] = st.y; } }
;             r[i - LO] = *(const f32x4*)(src + (row * (unsigned)DM + col0 + BJ * HALF + n * 16)); }
; #pragma unroll
;         for (int i = LO; i < HI; ++i) { const int ai = i >> 3, m = (i >> 1) & 3, n = i & 1; const unsigned row = row0 + ai * HALF + m * 16;
;             *(f32x4*)(Y + (row * (unsigned)DM + col0 + BJ * HALF + n * 16)) = acc[ai][BJ][m][n] + ((r[i - LO] - mean[(i - LO) >> 1]) * rstd[(i - LO) >> 1]) * gv[n] + bv[n]; }
;         __builtin_amdgcn_sched_barrier(0);
;     }
;     template <bool LN, int BJ> DI void load_gb(unsigned col0, f32x4 (&gv)[2], f32x4 (&bv)[2]) const {
; #pragma unroll
;         for (int n = 0; n < 2; ++n) {
;             if (LN) { gv[n] = *(const f32x4*)(gam + col0 + BJ * HALF + n * 16) * ALPHA; bv[n] = *(const f32x4*)(bet + col0 + BJ * HALF + n * 16) * ALPHA; }
;             else { gv[n] = (f32x4){ALPHA, ALPHA, ALPHA, ALPHA}; bv[n] = (f32x4){0.f, 0.f, 0.f, 0.f}; }
;         }
;     }
;     template <bool LN> DI void run(const f32x4 (&acc)[2][2][4][2], const Unit& u, int wr, int wc, int fr, int fq) const {
;         const unsigned row0 = u.pm * BM + wr * 64 + fr, col0 = u.pn * BM + wc * 32 + 4 * fq;
;         f32x4 gv[2], bv[2];
;         load_gb<LN, 0>(col0, gv, bv);
;         batch<LN, 0, 0, 4>(acc, row0, col0, gv, bv);
;         batch<LN, 0, 4, 8>(acc, row0, col0, gv, bv);
;         batch<LN, 0, 8, 12>(acc, row0, col0, gv, bv);
;         batch<LN, 0, 12, 16>(acc, row0, col0, gv, bv);
;         load_gb<LN, 1>(col0, gv, bv);
;         batch<LN, 1, 0, 8>(acc, row0, col0, gv, bv);
;         batch<LN, 1, 8, 16>(acc, row0, col0, gv, bv);
	v_sub_f32_e32 v109, v109, v112
	v_sub_f32_e32 v108, v108, v112
	v_sub_f32_e32 v111, v111, v112
	v_sub_f32_e32 v110, v110, v112
	v_pk_mul_f32 v[110:111], v[112:113], v[110:111] op_sel:[1,0]
	v_pk_mul_f32 v[108:109], v[112:113], v[108:109] op_sel:[1,0]
	v_pk_fma_f32 v[94:95], v[192:193], v[110:111], v[94:95]
	v_pk_fma_f32 v[92:93], v[194:195], v[108:109], v[92:93]
	v_add_u32_e32 v108, 0x40000, v148
	v_mov_b32_e32 v109, v159
	v_pk_fma_f32 v[94:95], v[102:103], s[78:79], v[94:95] op_sel_hi:[1,0,1]
	v_pk_fma_f32 v[92:93], v[100:101], s[78:79], v[92:93] op_sel_hi:[1,0,1]
	v_lshl_add_u64 v[108:109], v[108:109], 2, s[88:89]
	global_store_dwordx4 v[108:109], v[92:95], off
	s_nop 1
	v_sub_f32_e32 v93, v117, v112
	v_sub_f32_e32 v92, v116, v112
	v_sub_f32_e32 v95, v119, v112
	v_sub_f32_e32 v94, v118, v112
	v_pk_mul_f32 v[94:95], v[112:113], v[94:95] op_sel:[1,0]
	v_pk_mul_f32 v[92:93], v[112:113], v[92:93] op_sel:[1,0]
	v_pk_fma_f32 v[90:91], v[188:189], v[94:95], v[90:91]
	v_pk_fma_f32 v[88:89], v[190:191], v[92:93], v[88:89]
	v_add_u32_e32 v92, 0x40010, v148
	v_mov_b32_e32 v93, v159
	v_pk_fma_f32 v[90:91], v[98:99], s[78:79], v[90:91] op_sel_hi:[1,0,1]
	v_pk_fma_f32 v[88:89], v[96:97], s[78:79], v[88:89] op_sel_hi:[1,0,1]
	v_lshl_add_u64 v[92:93], v[92:93], 2, s[88:89]
	global_store_dwordx4 v[92:93], v[88:91], off
	s_nop 1
	v_sub_f32_e32 v89, v127, v134
	v_sub_f32_e32 v88, v126, v134
	v_sub_f32_e32 v91, v129, v134
	v_sub_f32_e32 v90, v128, v134
	v_pk_mul_f32 v[90:91], v[134:135], v[90:91] op_sel:[1,0]
	v_pk_mul_f32 v[88:89], v[134:135], v[88:89] op_sel:[1,0]
	v_pk_fma_f32 v[86:87], v[192:193], v[90:91], v[86:87]
	v_pk_fma_f32 v[84:85], v[194:195], v[88:89], v[84:85]
	v_add_u32_e32 v88, 0x48000, v148
	v_mov_b32_e32 v89, v159
	v_pk_fma_f32 v[86:87], v[102:103], s[78:79], v[86:87] op_sel_hi:[1,0,1]
	v_pk_fma_f32 v[84:85], v[100:101], s[78:79], v[84:85] op_sel_hi:[1,0,1]
	v_lshl_add_u64 v[88:89], v[88:89], 2, s[88:89]
	global_store_dwordx4 v[88:89], v[84:87], off
	s_nop 1
	v_sub_f32_e32 v85, v131, v134
	v_sub_f32_e32 v84, v130, v134
	v_sub_f32_e32 v87, v133, v134
	v_sub_f32_e32 v86, v132, v134
	v_pk_mul_f32 v[86:87], v[134:135], v[86:87] op_sel:[1,0]
	v_pk_mul_f32 v[84:85], v[134:135], v[84:85] op_sel:[1,0]
	v_pk_fma_f32 v[82:83], v[188:189], v[86:87], v[82:83]
	v_pk_fma_f32 v[80:81], v[190:191], v[84:85], v[80:81]
	v_add_u32_e32 v84, 0x48010, v148
	v_mov_b32_e32 v85, v159
	v_pk_fma_f32 v[82:83], v[98:99], s[78:79], v[82:83] op_sel_hi:[1,0,1]
	v_pk_fma_f32 v[80:81], v[96:97], s[78:79], v[80:81] op_sel_hi:[1,0,1]
	v_lshl_add_u64 v[84:85], v[84:85], 2, s[88:89]
	global_store_dwordx4 v[84:85], v[80:83], off
	s_nop 1
	v_add_u32_e32 v82, 0xa0, v203
	v_lshlrev_b32_e32 v80, 1, v82
	v_mov_b32_e32 v81, v159
	v_lshlrev_b32_e32 v116, 11, v82
	v_lshl_add_u64 v[108:109], v[80:81], 2, s[96:97]
	v_add_u32_e32 v80, v116, v158
	v_lshl_add_u64 v[80:81], v[80:81], 2, s[90:91]
	global_load_dwordx2 v[112:113], v[108:109], off
	v_add_u32_e32 v84, v116, v204
	global_load_dwordx4 v[80:83], v[80:81], off
	v_mov_b32_e32 v85, v159
	v_lshl_add_u64 v[84:85], v[84:85], 2, s[90:91]
	global_load_dwordx4 v[84:87], v[84:85], off
	v_add_u32_e32 v90, 0xb0, v203
	v_lshlrev_b32_e32 v88, 1, v90
	v_mov_b32_e32 v89, v159
	v_lshlrev_b32_e32 v117, 11, v90
	v_lshl_add_u64 v[110:111], v[88:89], 2, s[96:97]
	v_add_u32_e32 v88, v117, v158
	v_lshl_add_u64 v[88:89], v[88:89], 2, s[90:91]
	global_load_dwordx2 v[118:119], v[110:111], off
	v_add_u32_e32 v92, v117, v204
	global_load_dwordx4 v[88:91], v[88:89], off
	v_mov_b32_e32 v93, v159
	v_lshl_add_u64 v[92:93], v[92:93], 2, s[90:91]
	global_load_dwordx4 v[92:95], v[92:93], off
	s_waitcnt vmcnt(0)
	v_sub_f32_e32 v81, v81, v112
	v_sub_f32_e32 v80, v80, v112
	v_sub_f32_e32 v83, v83, v112
	v_sub_f32_e32 v82, v82, v112
	v_pk_mul_f32 v[82:83], v[112:113], v[82:83] op_sel:[1,0]
	v_pk_mul_f32 v[80:81], v[112:113], v[80:81] op_sel:[1,0]
	v_pk_fma_f32 v[78:79], v[192:193], v[82:83], v[78:79]
	v_pk_fma_f32 v[76:77], v[194:195], v[80:81], v[76:77]
	v_add_u32_e32 v80, 0x50000, v148
	v_mov_b32_e32 v81, v159
	v_pk_fma_f32 v[78:79], v[102:103], s[78:79], v[78:79] op_sel_hi:[1,0,1]
	v_pk_fma_f32 v[76:77], v[100:101], s[78:79], v[76:77] op_sel_hi:[1,0,1]
	v_lshl_add_u64 v[80:81], v[80:81], 2, s[88:89]
	global_store_dwordx4 v[80:81], v[76:79], off
	s_nop 1
	v_sub_f32_e32 v77, v85, v112
	v_sub_f32_e32 v76, v84, v112
	v_sub_f32_e32 v79, v87, v112
	v_sub_f32_e32 v78, v86, v112
	v_pk_mul_f32 v[78:79], v[112:113], v[78:79] op_sel:[1,0]
	v_pk_mul_f32 v[76:77], v[112:113], v[76:77] op_sel:[1,0]
	v_pk_fma_f32 v[74:75], v[188:189], v[78:79], v[74:75]
	v_pk_fma_f32 v[72:73], v[190:191], v[76:77], v[72:73]
	v_add_u32_e32 v76, 0x50010, v148
	v_mov_b32_e32 v77, v159
	v_pk_fma_f32 v[74:75], v[98:99], s[78:79], v[74:75] op_sel_hi:[1,0,1]
	v_pk_fma_f32 v[72:73], v[96:97], s[78:79], v[72:73] op_sel_hi:[1,0,1]
	v_lshl_add_u64 v[76:77], v[76:77], 2, s[88:89]
	global_store_dwordx4 v[76:77], v[72:75], off
	s_nop 1
	v_sub_f32_e32 v73, v89, v118
	v_sub_f32_e32 v72, v88, v118
	v_sub_f32_e32 v75, v91, v118
	v_sub_f32_e32 v74, v90, v118
	v_pk_mul_f32 v[74:75], v[118:119], v[74:75] op_sel:[1,0]
	v_pk_mul_f32 v[72:73], v[118:119], v[72:73] op_sel:[1,0]
	v_pk_fma_f32 v[70:71], v[192:193], v[74:75], v[70:71]
	v_pk_fma_f32 v[68:69], v[194:195], v[72:73], v[68:69]
	v_add_u32_e32 v72, 0x58000, v148
	v_mov_b32_e32 v73, v159
	v_pk_fma_f32 v[70:71], v[102:103], s[78:79], v[70:71] op_sel_hi:[1,0,1]
	v_pk_fma_f32 v[68:69], v[100:101], s[78:79], v[68:69] op_sel_hi:[1,0,1]
	v_lshl_add_u64 v[72:73], v[72:73], 2, s[88:89]
	global_store_dwordx4 v[72:73], v[68:71], off
	s_nop 1
	v_sub_f32_e32 v69, v93, v118
	v_sub_f32_e32 v68, v92, v118
	v_sub_f32_e32 v71, v95, v118
	v_sub_f32_e32 v70, v94, v118
	v_pk_mul_f32 v[70:71], v[118:119], v[70:71] op_sel:[1,0]
	v_pk_mul_f32 v[68:69], v[118:119], v[68:69] op_sel:[1,0]
	v_pk_fma_f32 v[66:67], v[188:189], v[70:71], v[66:67]
	v_pk_fma_f32 v[64:65], v[190:191], v[68:69], v[64:65]
	v_add_u32_e32 v68, 0x58010, v148
	v_mov_b32_e32 v69, v159
	v_pk_fma_f32 v[66:67], v[98:99], s[78:79], v[66:67] op_sel_hi:[1,0,1]
	v_pk_fma_f32 v[64:65], v[96:97], s[78:79], v[64:65] op_sel_hi:[1,0,1]
	v_lshl_add_u64 v[68:69], v[68:69], 2, s[88:89]
	global_store_dwordx4 v[68:69], v[64:67], off
	global_load_dwordx4 v[64:67], v[150:151], off offset:512
	v_or_b32_e32 v119, 0x80, v158
	v_add_u32_e32 v72, v202, v119
	v_mov_b32_e32 v73, v159
	v_lshl_add_u64 v[72:73], v[72:73], 2, s[90:91]
	v_or_b32_e32 v118, 0x90, v158
	v_add_u32_e32 v158, v202, v118
	s_waitcnt vmcnt(0)
;     template <bool LN, int BJ, int LO, int HI> DI void batch(const f32x4 (&acc)[2][2][4][2], unsigned row0, unsigned col0, const f32x4 (&gv)[2], const f32x4 (&bv)[2]) const {
;         f32x4 r[HI - LO]; float mean[(HI - LO) / 2], rstd[(HI - LO) / 2];
; #pragma unroll
;         for (int i = LO; i < HI; ++i) { const int ai = i >> 3, m = (i >> 1) & 3, n = i & 1; const unsigned row = row0 + ai * HALF + m * 16;
;             if (n == 0) { mean[(i - LO) >> 1] = 0.f; rstd[(i - LO) >> 1] = 1.f;
;                 if (LN) { const float2 st = *(const float2*)(stats + row * 2u); mean[(i - LO) >> 1] = st.x; rstd[(i - LO) >> 1] = st.y; } }
;             r[i - LO] = *(const f32x4*)(src + (row * (unsigned)DM + col0 + BJ * HALF + n * 16)); }
; #pragma unroll
;         for (int i = LO; i < HI; ++i) { const int ai = i >> 3, m = (i >> 1) & 3, n = i & 1; const unsigned row = row0 + ai * HALF + m * 16;
;             *(f32x4*)(Y + (row * (unsigned)DM + col0 + BJ * HALF + n * 16)) = acc[ai][BJ][m][n] + ((r[i - LO] - mean[(i - LO) >> 1]) * rstd[(i - LO) >> 1]) * gv[n] + bv[n]; }
;         __builtin_amdgcn_sched_barrier(0);
;     }
;     template <bool LN, int BJ> DI void load_gb(unsigned col0, f32x4 (&gv)[2], f32x4 (&bv)[2]) const {
; #pragma unroll
;         for (int n = 0; n < 2; ++n) {
;             if (LN) { gv[n] = *(const f32x4*)(gam + col0 + BJ * HALF + n * 16) * ALPHA; bv[n] = *(const f32x4*)(bet + col0 + BJ * HALF + n * 16) * ALPHA; }
;             else { gv[n] = (f32x4){ALPHA, ALPHA, ALPHA, ALPHA}; bv[n] = (f32x4){0.f, 0.f, 0.f, 0.f}; }
;         }
;     }
;     template <bool LN> DI void run(const f32x4 (&acc)[2][2][4][2], const Unit& u, int wr, int wc, int fr, int fq) const {
;         const unsigned row0 = u.pm * BM + wr * 64 + fr, col0 = u.pn * BM + wc * 32 + 4 * fq;
;         f32x4 gv[2], bv[2];
;         load_gb<LN, 0>(col0, gv, bv);
;         batch<LN, 0, 0, 4>(acc, row0, col0, gv, bv);
;         batch<LN, 0, 4, 8>(acc, row0, col0, gv, bv);
;         batch<LN, 0, 8, 12>(acc, row0, col0, gv, bv);
;         batch<LN, 0, 12, 16>(acc, row0, col0, gv, bv);
;         load_gb<LN, 1>(col0, gv, bv);
;         batch<LN, 1, 0, 8>(acc, row0, col0, gv, bv);
;         batch<LN, 1, 8, 16>(acc, row0, col0, gv, bv);
	v_pk_mul_f32 v[96:97], v[66:67], s[78:79] op_sel_hi:[1,0]
	v_pk_mul_f32 v[98:99], v[64:65], s[78:79] op_sel_hi:[1,0]
	global_load_dwordx4 v[68:71], v[152:153], off offset:512
	global_load_dwordx4 v[64:67], v[150:151], off offset:576
	global_load_dwordx2 v[138:139], v[154:155], off
	global_load_dwordx4 v[126:129], v[72:73], off
	v_lshl_add_u64 v[72:73], v[158:159], 2, s[90:91]
	v_add_u32_e32 v158, v149, v119
	s_waitcnt vmcnt(0)
	v_pk_mul_f32 v[92:93], v[66:67], s[78:79] op_sel_hi:[1,0]
	v_pk_mul_f32 v[94:95], v[64:65], s[78:79] op_sel_hi:[1,0]
	global_load_dwordx4 v[64:67], v[152:153], off offset:576
	global_load_dwordx4 v[130:133], v[72:73], off
	global_load_dwordx2 v[112:113], v[186:187], off
	v_lshl_add_u64 v[72:73], v[158:159], 2, s[90:91]
	global_load_dwordx4 v[134:137], v[72:73], off
	v_add_u32_e32 v158, v149, v118
	v_lshl_add_u64 v[72:73], v[158:159], 2, s[90:91]
	global_load_dwordx4 v[88:91], v[72:73], off
	global_load_dwordx2 v[102:103], v[120:121], off
	v_add_u32_e32 v158, v124, v119
	v_lshl_add_u64 v[72:73], v[158:159], 2, s[90:91]
	global_load_dwordx4 v[84:87], v[72:73], off
	v_add_u32_e32 v158, v124, v118
	v_lshl_add_u64 v[72:73], v[158:159], 2, s[90:91]
	global_load_dwordx4 v[80:83], v[72:73], off
	global_load_dwordx2 v[100:101], v[122:123], off
	v_add_u32_e32 v158, v125, v119
	v_lshl_add_u64 v[72:73], v[158:159], 2, s[90:91]
	global_load_dwordx4 v[76:79], v[72:73], off
	v_add_u32_e32 v158, v125, v118
	v_lshl_add_u64 v[72:73], v[158:159], 2, s[90:91]
	global_load_dwordx4 v[72:75], v[72:73], off
	v_sub_f32_e32 v121, v127, v138
	v_sub_f32_e32 v120, v126, v138
	v_sub_f32_e32 v123, v129, v138
	v_sub_f32_e32 v122, v128, v138
	v_pk_mul_f32 v[122:123], v[138:139], v[122:123] op_sel:[1,0]
	v_pk_mul_f32 v[120:121], v[138:139], v[120:121] op_sel:[1,0]
	v_or_b32_e32 v158, 0x80, v148
	v_pk_fma_f32 v[60:61], v[98:99], v[120:121], v[60:61]
	v_pk_fma_f32 v[62:63], v[96:97], v[122:123], v[62:63]
	v_pk_fma_f32 v[60:61], v[68:69], s[78:79], v[60:61] op_sel_hi:[1,0,1]
	v_pk_fma_f32 v[62:63], v[70:71], s[78:79], v[62:63] op_sel_hi:[1,0,1]
	v_lshl_add_u64 v[120:121], v[158:159], 2, s[88:89]
	global_store_dwordx4 v[120:121], v[60:63], off
	v_or_b32_e32 v158, 0x90, v148
	s_waitcnt vmcnt(0)
	v_sub_f32_e32 v61, v131, v138
	v_sub_f32_e32 v60, v130, v138
	v_sub_f32_e32 v63, v133, v138
	v_sub_f32_e32 v62, v132, v138
	v_pk_mul_f32 v[62:63], v[138:139], v[62:63] op_sel:[1,0]
	v_pk_mul_f32 v[60:61], v[138:139], v[60:61] op_sel:[1,0]
	v_pk_fma_f32 v[58:59], v[92:93], v[62:63], v[58:59]
	v_pk_fma_f32 v[56:57], v[94:95], v[60:61], v[56:57]
	v_pk_fma_f32 v[58:59], v[66:67], s[78:79], v[58:59] op_sel_hi:[1,0,1]
	v_pk_fma_f32 v[56:57], v[64:65], s[78:79], v[56:57] op_sel_hi:[1,0,1]
	v_lshl_add_u64 v[60:61], v[158:159], 2, s[88:89]
	global_store_dwordx4 v[60:61], v[56:59], off
	v_add_u32_e32 v158, 0x8080, v148
	s_nop 0
	v_sub_f32_e32 v57, v135, v112
	v_sub_f32_e32 v56, v134, v112
	v_sub_f32_e32 v59, v137, v112
	v_sub_f32_e32 v58, v136, v112
	v_pk_mul_f32 v[58:59], v[112:113], v[58:59] op_sel:[1,0]
	v_pk_mul_f32 v[56:57], v[112:113], v[56:57] op_sel:[1,0]
	v_pk_fma_f32 v[54:55], v[96:97], v[58:59], v[54:55]
	v_pk_fma_f32 v[52:53], v[98:99], v[56:57], v[52:53]
	v_pk_fma_f32 v[54:55], v[70:71], s[78:79], v[54:55] op_sel_hi:[1,0,1]
	v_pk_fma_f32 v[52:53], v[68:69], s[78:79], v[52:53] op_sel_hi:[1,0,1]
	v_lshl_add_u64 v[56:57], v[158:159], 2, s[88:89]
	global_store_dwordx4 v[56:57], v[52:55], off
	v_add_u32_e32 v158, 0x8090, v148
	s_nop 0
	v_sub_f32_e32 v53, v89, v112
	v_sub_f32_e32 v52, v88, v112
	v_sub_f32_e32 v55, v91, v112
	v_sub_f32_e32 v54, v90, v112
	v_pk_mul_f32 v[54:55], v[112:113], v[54:55] op_sel:[1,0]
	v_pk_mul_f32 v[52:53], v[112:113], v[52:53] op_sel:[1,0]
	v_pk_fma_f32 v[50:51], v[92:93], v[54:55], v[50:51]
	v_pk_fma_f32 v[48:49], v[94:95], v[52:53], v[48:49]
	v_pk_fma_f32 v[50:51], v[66:67], s[78:79], v[50:51] op_sel_hi:[1,0,1]
	v_pk_fma_f32 v[48:49], v[64:65], s[78:79], v[48:49] op_sel_hi:[1,0,1]
	v_lshl_add_u64 v[52:53], v[158:159], 2, s[88:89]
	global_store_dwordx4 v[52:53], v[48:51], off
	v_add_u32_e32 v158, 0x10080, v148
	s_nop 0
	v_sub_f32_e32 v49, v85, v102
	v_sub_f32_e32 v48, v84, v102
	v_sub_f32_e32 v51, v87, v102
	v_sub_f32_e32 v50, v86, v102
	v_pk_mul_f32 v[50:51], v[102:103], v[50:51] op_sel:[1,0]
	v_pk_mul_f32 v[48:49], v[102:103], v[48:49] op_sel:[1,0]
	v_pk_fma_f32 v[46:47], v[96:97], v[50:51], v[46:47]
	v_pk_fma_f32 v[44:45], v[98:99], v[48:49], v[44:45]
	v_pk_fma_f32 v[46:47], v[70:71], s[78:79], v[46:47] op_sel_hi:[1,0,1]
	v_pk_fma_f32 v[44:45], v[68:69], s[78:79], v[44:45] op_sel_hi:[1,0,1]
	v_lshl_add_u64 v[48:49], v[158:159], 2, s[88:89]
	global_store_dwordx4 v[48:49], v[44:47], off
	v_add_u32_e32 v158, 0x10090, v148
	s_nop 0
	v_sub_f32_e32 v45, v81, v102
	v_sub_f32_e32 v44, v80, v102
	v_sub_f32_e32 v47, v83, v102
	v_sub_f32_e32 v46, v82, v102
	v_pk_mul_f32 v[46:47], v[102:103], v[46:47] op_sel:[1,0]
	v_pk_mul_f32 v[44:45], v[102:103], v[44:45] op_sel:[1,0]
	v_pk_fma_f32 v[42:43], v[92:93], v[46:47], v[42:43]
	v_pk_fma_f32 v[40:41], v[94:95], v[44:45], v[40:41]
	v_pk_fma_f32 v[42:43], v[66:67], s[78:79], v[42:43] op_sel_hi:[1,0,1]
	v_pk_fma_f32 v[40:41], v[64:65], s[78:79], v[40:41] op_sel_hi:[1,0,1]
	v_lshl_add_u64 v[44:45], v[158:159], 2, s[88:89]
	global_store_dwordx4 v[44:45], v[40:43], off
	v_add_u32_e32 v158, 0x18080, v148
	s_nop 0
	v_sub_f32_e32 v41, v77, v100
	v_sub_f32_e32 v40, v76, v100
	v_sub_f32_e32 v43, v79, v100
	v_sub_f32_e32 v42, v78, v100
	v_pk_mul_f32 v[42:43], v[100:101], v[42:43] op_sel:[1,0]
	v_pk_mul_f32 v[40:41], v[100:101], v[40:41] op_sel:[1,0]
	v_pk_fma_f32 v[38:39], v[96:97], v[42:43], v[38:39]
;     template <bool LN, int BJ, int LO, int HI> DI void batch(const f32x4 (&acc)[2][2][4][2], unsigned row0, unsigned col0, const f32x4 (&gv)[2], const f32x4 (&bv)[2]) const {
;         f32x4 r[HI - LO]; float mean[(HI - LO) / 2], rstd[(HI - LO) / 2];
; #pragma unroll
;         for (int i = LO; i < HI; ++i) { const int ai = i >> 3, m = (i >> 1) & 3, n = i & 1; const unsigned row = row0 + ai * HALF + m * 16;
;             if (n == 0) { mean[(i - LO) >> 1] = 0.f; rstd[(i - LO) >> 1] = 1.f;
;                 if (LN) { const float2 st = *(const float2*)(stats + row * 2u); mean[(i - LO) >> 1] = st.x; rstd[(i - LO) >> 1] = st.y; } }
;             r[i - LO] = *(const f32x4*)(src + (row * (unsigned)DM + col0 + BJ * HALF + n * 16)); }
; #pragma unroll
;         for (int i = LO; i < HI; ++i) { const int ai = i >> 3, m = (i >> 1) & 3, n = i & 1; const unsigned row = row0 + ai * HALF + m * 16;
;             *(f32x4*)(Y + (row * (unsigned)DM + col0 + BJ * HALF + n * 16)) = acc[ai][BJ][m][n] + ((r[i - LO] - mean[(i - LO) >> 1]) * rstd[(i - LO) >> 1]) * gv[n] + bv[n]; }
;         __builtin_amdgcn_sched_barrier(0);
;     }
;     template <bool LN, int BJ> DI void load_gb(unsigned col0, f32x4 (&gv)[2], f32x4 (&bv)[2]) const {
; #pragma unroll
;         for (int n = 0; n < 2; ++n) {
;             if (LN) { gv[n] = *(const f32x4*)(gam + col0 + BJ * HALF + n * 16) * ALPHA; bv[n] = *(const f32x4*)(bet + col0 + BJ * HALF + n * 16) * ALPHA; }
;             else { gv[n] = (f32x4){ALPHA, ALPHA, ALPHA, ALPHA}; bv[n] = (f32x4){0.f, 0.f, 0.f, 0.f}; }
;         }
;     }
;     template <bool LN> DI void run(const f32x4 (&acc)[2][2][4][2], const Unit& u, int wr, int wc, int fr, int fq) const {
;         const unsigned row0 = u.pm * BM + wr * 64 + fr, col0 = u.pn * BM + wc * 32 + 4 * fq;
;         f32x4 gv[2], bv[2];
;         load_gb<LN, 0>(col0, gv, bv);
;         batch<LN, 0, 0, 4>(acc, row0, col0, gv, bv);
;         batch<LN, 0, 4, 8>(acc, row0, col0, gv, bv);
;         batch<LN, 0, 8, 12>(acc, row0, col0, gv, bv);
;         batch<LN, 0, 12, 16>(acc, row0, col0, gv, bv);
;         load_gb<LN, 1>(col0, gv, bv);
;         batch<LN, 1, 0, 8>(acc, row0, col0, gv, bv);
;         batch<LN, 1, 8, 16>(acc, row0, col0, gv, bv);
	v_pk_fma_f32 v[36:37], v[98:99], v[40:41], v[36:37]
	v_pk_fma_f32 v[38:39], v[70:71], s[78:79], v[38:39] op_sel_hi:[1,0,1]
	v_pk_fma_f32 v[36:37], v[68:69], s[78:79], v[36:37] op_sel_hi:[1,0,1]
	v_lshl_add_u64 v[40:41], v[158:159], 2, s[88:89]
	global_store_dwordx4 v[40:41], v[36:39], off
	v_add_u32_e32 v158, 0x18090, v148
	s_nop 0
	v_sub_f32_e32 v37, v73, v100
	v_sub_f32_e32 v36, v72, v100
	v_sub_f32_e32 v39, v75, v100
	v_sub_f32_e32 v38, v74, v100
	v_pk_mul_f32 v[38:39], v[100:101], v[38:39] op_sel:[1,0]
	v_pk_mul_f32 v[36:37], v[100:101], v[36:37] op_sel:[1,0]
	v_pk_fma_f32 v[34:35], v[92:93], v[38:39], v[34:35]
	v_pk_fma_f32 v[32:33], v[94:95], v[36:37], v[32:33]
	v_pk_fma_f32 v[34:35], v[66:67], s[78:79], v[34:35] op_sel_hi:[1,0,1]
	v_pk_fma_f32 v[32:33], v[64:65], s[78:79], v[32:33] op_sel_hi:[1,0,1]
	v_lshl_add_u64 v[36:37], v[158:159], 2, s[88:89]
	global_store_dwordx4 v[36:37], v[32:35], off
	v_add_u32_e32 v158, v114, v119
	s_nop 0
	v_lshl_add_u64 v[32:33], v[158:159], 2, s[90:91]
	global_load_dwordx2 v[62:63], v[104:105], off
	global_load_dwordx4 v[54:57], v[32:33], off
	v_add_u32_e32 v158, v114, v118
	v_lshl_add_u64 v[32:33], v[158:159], 2, s[90:91]
	global_load_dwordx4 v[58:61], v[32:33], off
	global_load_dwordx2 v[52:53], v[106:107], off
	v_add_u32_e32 v158, v115, v119
	v_lshl_add_u64 v[32:33], v[158:159], 2, s[90:91]
	global_load_dwordx4 v[72:75], v[32:33], off
	v_add_u32_e32 v158, v115, v118
	v_lshl_add_u64 v[32:33], v[158:159], 2, s[90:91]
	global_load_dwordx4 v[76:79], v[32:33], off
	global_load_dwordx2 v[50:51], v[108:109], off
	v_add_u32_e32 v158, v116, v119
	v_lshl_add_u64 v[32:33], v[158:159], 2, s[90:91]
	global_load_dwordx4 v[44:47], v[32:33], off
	v_add_u32_e32 v158, v116, v118
	v_lshl_add_u64 v[32:33], v[158:159], 2, s[90:91]
	global_load_dwordx4 v[40:43], v[32:33], off
	global_load_dwordx2 v[48:49], v[110:111], off
	v_add_u32_e32 v158, v117, v119
	v_lshl_add_u64 v[32:33], v[158:159], 2, s[90:91]
	global_load_dwordx4 v[36:39], v[32:33], off
	v_add_u32_e32 v158, v117, v118
	v_lshl_add_u64 v[32:33], v[158:159], 2, s[90:91]
	global_load_dwordx4 v[32:35], v[32:33], off
	v_add_u32_e32 v158, 0x40080, v148
	s_waitcnt vmcnt(0)
; template <class Epi>
; DI void gemm_phase(LAS unsigned char* lds, const Gemm g, const StaticOrder& S, const Epi& E) {
;     ...
;         E(acc, cur, wr, wc, fr, fq);
;     template <bool LN, int BJ, int LO, int HI> DI void batch(const f32x4 (&acc)[2][2][4][2], unsigned row0, unsigned col0, const f32x4 (&gv)[2], const f32x4 (&bv)[2]) const {
;         f32x4 r[HI - LO]; float mean[(HI - LO) / 2], rstd[(HI - LO) / 2];
; #pragma unroll
;         for (int i = LO; i < HI; ++i) { const int ai = i >> 3, m = (i >> 1) & 3, n = i & 1; const unsigned row = row0 + ai * HALF + m * 16;
;             if (n == 0) { mean[(i - LO) >> 1] = 0.f; rstd[(i - LO) >> 1] = 1.f;
;                 if (LN) { const float2 st = *(const float2*)(stats + row * 2u); mean[(i - LO) >> 1] = st.x; rstd[(i - LO) >> 1] = st.y; } }
;             r[i - LO] = *(const f32x4*)(src + (row * (unsigned)DM + col0 + BJ * HALF + n * 16)); }
; #pragma unroll
;         for (int i = LO; i < HI; ++i) { const int ai = i >> 3, m = (i >> 1) & 3, n = i & 1; const unsigned row = row0 + ai * HALF + m * 16;
;             *(f32x4*)(Y + (row * (unsigned)DM + col0 + BJ * HALF + n * 16)) = acc[ai][BJ][m][n] + ((r[i - LO] - mean[(i - LO) >> 1]) * rstd[(i - LO) >> 1]) * gv[n] + bv[n]; }
;         __builtin_amdgcn_sched_barrier(0);
;     }
;     template <bool LN, int BJ> DI void load_gb(unsigned col0, f32x4 (&gv)[2], f32x4 (&bv)[2]) const {
; #pragma unroll
;         for (int n = 0; n < 2; ++n) {
;             if (LN) { gv[n] = *(const f32x4*)(gam + col0 + BJ * HALF + n * 16) * ALPHA; bv[n] = *(const f32x4*)(bet + col0 + BJ * HALF + n * 16) * ALPHA; }
;             else { gv[n] = (f32x4){ALPHA, ALPHA, ALPHA, ALPHA}; bv[n] = (f32x4){0.f, 0.f, 0.f, 0.f}; }
;         }
;     }
;     template <bool LN> DI void run(const f32x4 (&acc)[2][2][4][2], const Unit& u, int wr, int wc, int fr, int fq) const {
;         const unsigned row0 = u.pm * BM + wr * 64 + fr, col0 = u.pn * BM + wc * 32 + 4 * fq;
;         f32x4 gv[2], bv[2];
;         load_gb<LN, 0>(col0, gv, bv);
;         batch<LN, 0, 0, 4>(acc, row0, col0, gv, bv);
;         batch<LN, 0, 4, 8>(acc, row0, col0, gv, bv);
;         batch<LN, 0, 8, 12>(acc, row0, col0, gv, bv);
;         batch<LN, 0, 12, 16>(acc, row0, col0, gv, bv);
;         load_gb<LN, 1>(col0, gv, bv);
;         batch<LN, 1, 0, 8>(acc, row0, col0, gv, bv);
;         batch<LN, 1, 8, 16>(acc, row0, col0, gv, bv);
	v_sub_f32_e32 v55, v55, v62
	v_sub_f32_e32 v54, v54, v62
	v_sub_f32_e32 v57, v57, v62
	v_sub_f32_e32 v56, v56, v62
	v_pk_mul_f32 v[56:57], v[62:63], v[56:57] op_sel:[1,0]
	v_pk_mul_f32 v[54:55], v[62:63], v[54:55] op_sel:[1,0]
	v_pk_fma_f32 v[30:31], v[96:97], v[56:57], v[30:31]
	v_pk_fma_f32 v[28:29], v[98:99], v[54:55], v[28:29]
	v_pk_fma_f32 v[30:31], v[70:71], s[78:79], v[30:31] op_sel_hi:[1,0,1]
	v_pk_fma_f32 v[28:29], v[68:69], s[78:79], v[28:29] op_sel_hi:[1,0,1]
	v_lshl_add_u64 v[54:55], v[158:159], 2, s[88:89]
	global_store_dwordx4 v[54:55], v[28:31], off
	v_add_u32_e32 v158, 0x40090, v148
	s_nop 0
	v_sub_f32_e32 v29, v59, v62
	v_sub_f32_e32 v28, v58, v62
	v_sub_f32_e32 v31, v61, v62
	v_sub_f32_e32 v30, v60, v62
	v_pk_mul_f32 v[30:31], v[62:63], v[30:31] op_sel:[1,0]
	v_pk_mul_f32 v[28:29], v[62:63], v[28:29] op_sel:[1,0]
	v_pk_fma_f32 v[26:27], v[92:93], v[30:31], v[26:27]
	v_pk_fma_f32 v[24:25], v[94:95], v[28:29], v[24:25]
	v_pk_fma_f32 v[26:27], v[66:67], s[78:79], v[26:27] op_sel_hi:[1,0,1]
	v_pk_fma_f32 v[24:25], v[64:65], s[78:79], v[24:25] op_sel_hi:[1,0,1]
	v_lshl_add_u64 v[28:29], v[158:159], 2, s[88:89]
	global_store_dwordx4 v[28:29], v[24:27], off
	v_add_u32_e32 v158, 0x48080, v148
	s_nop 0
	v_sub_f32_e32 v25, v73, v52
	v_sub_f32_e32 v24, v72, v52
	v_sub_f32_e32 v27, v75, v52
	v_sub_f32_e32 v26, v74, v52
	v_pk_mul_f32 v[26:27], v[52:53], v[26:27] op_sel:[1,0]
	v_pk_mul_f32 v[24:25], v[52:53], v[24:25] op_sel:[1,0]
	v_pk_fma_f32 v[22:23], v[96:97], v[26:27], v[22:23]
	v_pk_fma_f32 v[20:21], v[98:99], v[24:25], v[20:21]
	v_pk_fma_f32 v[22:23], v[70:71], s[78:79], v[22:23] op_sel_hi:[1,0,1]
	v_pk_fma_f32 v[20:21], v[68:69], s[78:79], v[20:21] op_sel_hi:[1,0,1]
	v_lshl_add_u64 v[24:25], v[158:159], 2, s[88:89]
	global_store_dwordx4 v[24:25], v[20:23], off
	v_add_u32_e32 v158, 0x48090, v148
	s_nop 0
	v_sub_f32_e32 v21, v77, v52
	v_sub_f32_e32 v20, v76, v52
	v_sub_f32_e32 v23, v79, v52
	v_sub_f32_e32 v22, v78, v52
	v_pk_mul_f32 v[22:23], v[52:53], v[22:23] op_sel:[1,0]
	v_pk_mul_f32 v[20:21], v[52:53], v[20:21] op_sel:[1,0]
	v_pk_fma_f32 v[18:19], v[92:93], v[22:23], v[18:19]
	v_pk_fma_f32 v[16:17], v[94:95], v[20:21], v[16:17]
	v_pk_fma_f32 v[18:19], v[66:67], s[78:79], v[18:19] op_sel_hi:[1,0,1]
	v_pk_fma_f32 v[16:17], v[64:65], s[78:79], v[16:17] op_sel_hi:[1,0,1]
	v_lshl_add_u64 v[20:21], v[158:159], 2, s[88:89]
	global_store_dwordx4 v[20:21], v[16:19], off
	v_add_u32_e32 v158, 0x50080, v148
	s_nop 0
	v_sub_f32_e32 v17, v45, v50
	v_sub_f32_e32 v16, v44, v50
	v_sub_f32_e32 v19, v47, v50
	v_sub_f32_e32 v18, v46, v50
	v_pk_mul_f32 v[18:19], v[50:51], v[18:19] op_sel:[1,0]
	v_pk_mul_f32 v[16:17], v[50:51], v[16:17] op_sel:[1,0]
	v_pk_fma_f32 v[14:15], v[96:97], v[18:19], v[14:15]
	v_pk_fma_f32 v[12:13], v[98:99], v[16:17], v[12:13]
	v_pk_fma_f32 v[14:15], v[70:71], s[78:79], v[14:15] op_sel_hi:[1,0,1]
	v_pk_fma_f32 v[12:13], v[68:69], s[78:79], v[12:13] op_sel_hi:[1,0,1]
	v_lshl_add_u64 v[16:17], v[158:159], 2, s[88:89]
	global_store_dwordx4 v[16:17], v[12:15], off
	v_add_u32_e32 v158, 0x50090, v148
	s_nop 0
	v_sub_f32_e32 v13, v41, v50
	v_sub_f32_e32 v12, v40, v50
	v_sub_f32_e32 v15, v43, v50
	v_sub_f32_e32 v14, v42, v50
	v_pk_mul_f32 v[14:15], v[50:51], v[14:15] op_sel:[1,0]
	v_pk_mul_f32 v[12:13], v[50:51], v[12:13] op_sel:[1,0]
	v_pk_fma_f32 v[10:11], v[92:93], v[14:15], v[10:11]
	v_pk_fma_f32 v[8:9], v[94:95], v[12:13], v[8:9]
	v_pk_fma_f32 v[10:11], v[66:67], s[78:79], v[10:11] op_sel_hi:[1,0,1]
	v_pk_fma_f32 v[8:9], v[64:65], s[78:79], v[8:9] op_sel_hi:[1,0,1]
	v_lshl_add_u64 v[12:13], v[158:159], 2, s[88:89]
	global_store_dwordx4 v[12:13], v[8:11], off
	v_add_u32_e32 v158, 0x58080, v148
	s_nop 0
	v_sub_f32_e32 v9, v37, v48
	v_sub_f32_e32 v8, v36, v48
	v_sub_f32_e32 v11, v39, v48
	v_sub_f32_e32 v10, v38, v48
	v_pk_mul_f32 v[10:11], v[48:49], v[10:11] op_sel:[1,0]
	v_pk_mul_f32 v[8:9], v[48:49], v[8:9] op_sel:[1,0]
	v_pk_fma_f32 v[6:7], v[96:97], v[10:11], v[6:7]
	v_pk_fma_f32 v[4:5], v[98:99], v[8:9], v[4:5]
	v_pk_fma_f32 v[6:7], v[70:71], s[78:79], v[6:7] op_sel_hi:[1,0,1]
	v_pk_fma_f32 v[4:5], v[68:69], s[78:79], v[4:5] op_sel_hi:[1,0,1]
	v_lshl_add_u64 v[8:9], v[158:159], 2, s[88:89]
	global_store_dwordx4 v[8:9], v[4:7], off
	v_add_u32_e32 v158, 0x58090, v148
	s_nop 0
	v_sub_f32_e32 v5, v33, v48
	v_sub_f32_e32 v4, v32, v48
	v_sub_f32_e32 v7, v35, v48
	v_sub_f32_e32 v6, v34, v48
	v_pk_mul_f32 v[6:7], v[48:49], v[6:7] op_sel:[1,0]
	v_pk_mul_f32 v[4:5], v[48:49], v[4:5] op_sel:[1,0]
	v_pk_fma_f32 v[2:3], v[92:93], v[6:7], v[2:3]
	v_pk_fma_f32 v[0:1], v[94:95], v[4:5], v[0:1]
	v_pk_fma_f32 v[2:3], v[66:67], s[78:79], v[2:3] op_sel_hi:[1,0,1]
	v_pk_fma_f32 v[0:1], v[64:65], s[78:79], v[0:1] op_sel_hi:[1,0,1]
	v_lshl_add_u64 v[4:5], v[158:159], 2, s[88:89]
	global_store_dwordx4 v[4:5], v[0:3], off
	s_and_b64 vcc, exec, s[6:7]
	s_mov_b32 s2, s37
	s_mov_b32 s3, s38
	s_mov_b64 s[18:19], s[10:11]
	s_mov_b64 s[16:17], s[8:9]
	v_readlane_b32 s33, v255, 39
	s_cbranch_vccz .LBB0_123
	s_waitcnt vmcnt(0)
	s_cmpk_gt_u32 s24, 0xff
	s_cbranch_scc1 .LBB0_138
	s_barrier

; #define PG8_STAGE(bufoff, gbase) do { _Pragma("unroll") for (int _i = 0; _i < 2; ++_i) \
;         __builtin_amdgcn_global_load_lds((const unsigned*)((const char*)(gbase) + voff[_i]), (LAS unsigned*)(lds + (bufoff) + ldsw + _i * 8192), 16, 0, 0); } while (0)
; #define PG8_LDA(dst, b, h) do { _Pragma("unroll") for (int m = 0; m < 4; ++m) _Pragma("unroll") for (int k = 0; k < 2; ++k) dst[m][k] = *(const LAS bf16x8*)(lds + PG8_SA(b, h) + aoff + m * 2048 + k * 1024); } while (0)
; #define PG8_LDB(dst, b, h) do { _Pragma("unroll") for (int n = 0; n < 2; ++n) _Pragma("unroll") for (int k = 0; k < 2; ++k) dst[n][k] = *(const LAS bf16x8*)(lds + PG8_SB(b, h) + boff + n * 2048 + k * 1024); } while (0)
; #define PG8_MMA(ai, bj, At, Bt) do { __builtin_amdgcn_s_setprio(1); _Pragma("unroll") for (int m = 0; m < 4; ++m) _Pragma("unroll") for (int n = 0; n < 2; ++n) _Pragma("unroll") for (int k = 0; k < 2; ++k) \
;         acc[ai][bj][m][n] = __builtin_amdgcn_mfma_f32_16x16x32_bf16(Bt[n][k], At[m][k], acc[ai][bj][m][n], 0, 0, 0); __builtin_amdgcn_s_setprio(0); } while (0)
; #define PG8_WAIT_L(n) asm volatile("s_waitcnt lgkmcnt(" #n ")" ::: "memory")
; #define PG8_BAR __builtin_amdgcn_s_barrier()
; #define PG8_SCHED __builtin_amdgcn_sched_barrier(0)
; template <class Epi>
; DI void gemm_phase(LAS unsigned char* lds, const Gemm g, const StaticOrder& S, const Epi& E) {
;     ...
;         for (int t = 0; t < nt; t += 2) {
;             const bool last = (t == nt - 2);
;             const char* a1 = cA + (size_t)(t + 1) * kstep;
;             const char* a2 = last ? nA : cA + (size_t)(t + 2) * kstep; const char* b2 = last ? nB : cB + (size_t)(t + 2) * kstep;
;             const char* a3 = a2 + kstep; const char* b3 = b2 + kstep;
;             PG8_LDB(B0, 0, 0); PG8_SCHED; PG8_LDA(At, 0, 0); PG8_STAGE(PG8_SA(1, 1), a1 + hstep);
;             PG8_WAIT_L(8); PG8_BAR; PG8_WAIT_L(0); PG8_MMA(0, 0, At, B0); PG8_BAR; PG8_SCHED;
;             PG8_LDB(B1, 0, 1); PG8_STAGE(PG8_SB(0, 0), b2);
;             PG8_BAR; PG8_WAIT_L(0); PG8_MMA(0, 1, At, B1); PG8_BAR;
;             PG8_LDA(At, 0, 1); PG8_STAGE(PG8_SA(0, 0), a2);
;             PG8_BAR; PG8_WAIT_L(0); PG8_MMA(1, 0, At, B0); PG8_BAR; PG8_SCHED;
.LBB0_202:
	s_add_u32 s18, s8, 0xfff80080
	s_addc_u32 s19, s9, -1
	s_add_i32 s37, 0, 0x10000
	v_add_u32_e32 v140, s37, v187
	s_waitcnt lgkmcnt(0)
	ds_read_b128 v[128:131], v140
	ds_read_b128 v[132:135], v140 offset:1024
	ds_read_b128 v[136:139], v140 offset:2048
	ds_read_b128 v[190:193], v140 offset:3072
	s_cmp_eq_u32 s36, 28
	s_cselect_b32 s21, s4, s19
	s_cselect_b32 s20, s5, s18
	s_cselect_b32 s19, s11, s35
	s_cselect_b32 s18, s13, s33
	v_lshl_add_u64 v[140:141], s[8:9], 0, v[150:151]
	s_add_i32 m0, s26, 0xc000
	ds_read_b128 v[194:197], v189
	ds_read_b128 v[198:201], v189 offset:1024
	ds_read_b128 v[202:205], v189 offset:2048
	ds_read_b128 v[206:209], v189 offset:3072
	ds_read_b128 v[210:213], v189 offset:4096
	ds_read_b128 v[214:217], v189 offset:5120
	ds_read_b128 v[226:229], v189 offset:6144
	ds_read_b128 v[230:233], v189 offset:7168
	global_load_lds_dwordx4 v[140:141], off
	v_lshl_add_u64 v[140:141], s[8:9], 0, v[152:153]
	s_add_i32 m0, s26, 0xe000
	s_nop 0
	global_load_lds_dwordx4 v[140:141], off
	s_waitcnt lgkmcnt(8)
	s_setprio 1
	s_barrier
	s_waitcnt lgkmcnt(0)
	v_mfma_f32_16x16x32_bf16 v[124:127], v[128:131], v[194:197], v[124:127]
	v_mfma_f32_16x16x32_bf16 v[120:123], v[136:139], v[194:197], v[120:123]
	v_mfma_f32_16x16x32_bf16 v[108:111], v[128:131], v[202:205], v[108:111]
	v_mfma_f32_16x16x32_bf16 v[104:107], v[136:139], v[202:205], v[104:107]
	v_mfma_f32_16x16x32_bf16 v[92:95], v[128:131], v[210:213], v[92:95]
	v_mfma_f32_16x16x32_bf16 v[88:91], v[136:139], v[210:213], v[88:91]
	v_mfma_f32_16x16x32_bf16 v[76:79], v[128:131], v[226:229], v[76:79]
	v_mfma_f32_16x16x32_bf16 v[72:75], v[136:139], v[226:229], v[72:75]
	v_mfma_f32_16x16x32_bf16 v[124:127], v[132:135], v[198:201], v[124:127]
	s_add_i32 s40, 0, 0x14000
	v_mfma_f32_16x16x32_bf16 v[120:123], v[190:193], v[198:201], v[120:123]
	v_add_u32_e32 v140, s40, v187
	v_mfma_f32_16x16x32_bf16 v[108:111], v[132:135], v[206:209], v[108:111]
	s_add_i32 s37, s37, s25
	v_mfma_f32_16x16x32_bf16 v[104:107], v[190:193], v[206:209], v[104:107]
	v_mfma_f32_16x16x32_bf16 v[92:95], v[132:135], v[214:217], v[92:95]
	v_mfma_f32_16x16x32_bf16 v[88:91], v[190:193], v[214:217], v[88:91]
	v_mfma_f32_16x16x32_bf16 v[76:79], v[132:135], v[230:233], v[76:79]
	v_mfma_f32_16x16x32_bf16 v[72:75], v[190:193], v[230:233], v[72:75]
	s_setprio 0
	s_barrier
	ds_read_b128 v[234:237], v140
	ds_read_b128 v[238:241], v140 offset:1024
	ds_read_b128 v[242:245], v140 offset:2048
	ds_read_b128 v[246:249], v140 offset:3072
	v_lshl_add_u64 v[140:141], s[18:19], 0, v[144:145]
	s_mov_b32 m0, s37
	v_lshl_add_u64 v[154:155], s[18:19], 0, v[142:143]
	global_load_lds_dwordx4 v[140:141], off
	s_add_i32 m0, s37, 0x2000
	s_nop 0
	global_load_lds_dwordx4 v[154:155], off
	s_waitcnt lgkmcnt(0)
	s_setprio 1
	s_barrier
	v_mfma_f32_16x16x32_bf16 v[116:119], v[234:237], v[194:197], v[116:119]
	v_mfma_f32_16x16x32_bf16 v[112:115], v[242:245], v[194:197], v[112:115]
	v_mfma_f32_16x16x32_bf16 v[100:103], v[234:237], v[202:205], v[100:103]
	v_mfma_f32_16x16x32_bf16 v[96:99], v[242:245], v[202:205], v[96:99]
	v_mfma_f32_16x16x32_bf16 v[84:87], v[234:237], v[210:213], v[84:87]
	v_mfma_f32_16x16x32_bf16 v[80:83], v[242:245], v[210:213], v[80:83]
	v_mfma_f32_16x16x32_bf16 v[68:71], v[234:237], v[226:229], v[68:71]
	v_mfma_f32_16x16x32_bf16 v[64:67], v[242:245], v[226:229], v[64:67]
	v_mfma_f32_16x16x32_bf16 v[116:119], v[238:241], v[198:201], v[116:119]
	s_mov_b32 m0, s26
	v_mfma_f32_16x16x32_bf16 v[112:115], v[246:249], v[198:201], v[112:115]
	v_lshl_add_u64 v[218:219], s[20:21], 0, v[144:145]
	v_mfma_f32_16x16x32_bf16 v[100:103], v[238:241], v[206:209], v[100:103]
	v_mfma_f32_16x16x32_bf16 v[96:99], v[246:249], v[206:209], v[96:99]
	v_mfma_f32_16x16x32_bf16 v[84:87], v[238:241], v[214:217], v[84:87]
	v_mfma_f32_16x16x32_bf16 v[80:83], v[246:249], v[214:217], v[80:83]
	v_mfma_f32_16x16x32_bf16 v[68:71], v[238:241], v[230:233], v[68:71]
	v_mfma_f32_16x16x32_bf16 v[64:67], v[246:249], v[230:233], v[64:67]
	s_setprio 0
	s_barrier
	ds_read_b128 v[194:197], v189 offset:16384
	ds_read_b128 v[198:201], v189 offset:17408
	ds_read_b128 v[202:205], v189 offset:18432
	ds_read_b128 v[206:209], v189 offset:19456
	ds_read_b128 v[210:213], v189 offset:20480
	ds_read_b128 v[214:217], v189 offset:21504
	ds_read_b128 v[226:229], v189 offset:22528
	ds_read_b128 v[230:233], v189 offset:23552
	global_load_lds_dwordx4 v[218:219], off
	v_lshl_add_u64 v[250:251], s[20:21], 0, v[142:143]
	s_mov_b32 m0, s27
	s_nop 0
	global_load_lds_dwordx4 v[250:251], off
	s_waitcnt lgkmcnt(0)
	s_setprio 1
	s_barrier
	v_mfma_f32_16x16x32_bf16 v[60:63], v[128:131], v[194:197], v[60:63]
	v_mfma_f32_16x16x32_bf16 v[56:59], v[136:139], v[194:197], v[56:59]
	v_mfma_f32_16x16x32_bf16 v[44:47], v[128:131], v[202:205], v[44:47]
	v_mfma_f32_16x16x32_bf16 v[40:43], v[136:139], v[202:205], v[40:43]
	v_mfma_f32_16x16x32_bf16 v[28:31], v[128:131], v[210:213], v[28:31]
	v_mfma_f32_16x16x32_bf16 v[24:27], v[136:139], v[210:213], v[24:27]
	v_mfma_f32_16x16x32_bf16 v[12:15], v[128:131], v[226:229], v[12:15]
	v_mfma_f32_16x16x32_bf16 v[8:11], v[136:139], v[226:229], v[8:11]
	v_mfma_f32_16x16x32_bf16 v[60:63], v[132:135], v[198:201], v[60:63]
	s_add_u32 s38, s18, 0x80000
	v_mfma_f32_16x16x32_bf16 v[56:59], v[190:193], v[198:201], v[56:59]
	s_addc_u32 s39, s19, 0
	v_mfma_f32_16x16x32_bf16 v[44:47], v[132:135], v[206:209], v[44:47]
	s_add_i32 s37, s40, s25
	v_mfma_f32_16x16x32_bf16 v[40:43], v[190:193], v[206:209], v[40:43]
	v_lshl_add_u64 v[128:129], s[38:39], 0, v[144:145]
	v_mfma_f32_16x16x32_bf16 v[28:31], v[132:135], v[214:217], v[28:31]
	s_mov_b32 m0, s37
	v_mfma_f32_16x16x32_bf16 v[24:27], v[190:193], v[214:217], v[24:27]
	v_mfma_f32_16x16x32_bf16 v[12:15], v[132:135], v[230:233], v[12:15]
	v_mfma_f32_16x16x32_bf16 v[8:11], v[190:193], v[230:233], v[8:11]
	s_setprio 0
	s_barrier
; #define PG8_STAGE(bufoff, gbase) do { _Pragma("unroll") for (int _i = 0; _i < 2; ++_i) \
;         __builtin_amdgcn_global_load_lds((const unsigned*)((const char*)(gbase) + voff[_i]), (LAS unsigned*)(lds + (bufoff) + ldsw + _i * 8192), 16, 0, 0); } while (0)
; #define PG8_LDA(dst, b, h) do { _Pragma("unroll") for (int m = 0; m < 4; ++m) _Pragma("unroll") for (int k = 0; k < 2; ++k) dst[m][k] = *(const LAS bf16x8*)(lds + PG8_SA(b, h) + aoff + m * 2048 + k * 1024); } while (0)
; #define PG8_LDB(dst, b, h) do { _Pragma("unroll") for (int n = 0; n < 2; ++n) _Pragma("unroll") for (int k = 0; k < 2; ++k) dst[n][k] = *(const LAS bf16x8*)(lds + PG8_SB(b, h) + boff + n * 2048 + k * 1024); } while (0)
; #define PG8_MMA(ai, bj, At, Bt) do { __builtin_amdgcn_s_setprio(1); _Pragma("unroll") for (int m = 0; m < 4; ++m) _Pragma("unroll") for (int n = 0; n < 2; ++n) _Pragma("unroll") for (int k = 0; k < 2; ++k) \
;         acc[ai][bj][m][n] = __builtin_amdgcn_mfma_f32_16x16x32_bf16(Bt[n][k], At[m][k], acc[ai][bj][m][n], 0, 0, 0); __builtin_amdgcn_s_setprio(0); } while (0)
; #define PG8_WAIT_V(n) asm volatile("s_waitcnt vmcnt(" #n ")" ::: "memory")
; #define PG8_WAIT_L(n) asm volatile("s_waitcnt lgkmcnt(" #n ")" ::: "memory")
; #define PG8_BAR __builtin_amdgcn_s_barrier()
; #define PG8_SCHED __builtin_amdgcn_sched_barrier(0)
; template <class Epi>
; DI void gemm_phase(LAS unsigned char* lds, const Gemm g, const StaticOrder& S, const Epi& E) {
;     ...
;             PG8_STAGE(PG8_SB(0, 1), b2 + hstep);
;             PG8_WAIT_V(6); PG8_BAR; PG8_MMA(1, 1, At, B1); PG8_BAR;
;             PG8_LDB(B0, 1, 0); PG8_SCHED; PG8_LDA(At, 1, 0); PG8_STAGE(PG8_SA(0, 1), a2 + hstep);
;             PG8_WAIT_L(8); PG8_BAR; PG8_WAIT_L(0); PG8_MMA(0, 0, At, B0); PG8_BAR; PG8_SCHED;
;             PG8_LDB(B1, 1, 1); PG8_STAGE(PG8_SB(1, 0), b3);
;             PG8_BAR; PG8_WAIT_L(0); PG8_MMA(0, 1, At, B1); PG8_BAR;
;             PG8_LDA(At, 1, 1); PG8_STAGE(PG8_SA(1, 0), a3);
	s_nop 0
	global_load_lds_dwordx4 v[128:129], off
	v_lshl_add_u64 v[128:129], s[38:39], 0, v[142:143]
	s_add_i32 m0, s37, 0x2000
	s_nop 0
	global_load_lds_dwordx4 v[128:129], off
	s_waitcnt vmcnt(6)
	s_setprio 1
	s_barrier
	v_mfma_f32_16x16x32_bf16 v[52:55], v[234:237], v[194:197], v[52:55]
	v_mfma_f32_16x16x32_bf16 v[48:51], v[242:245], v[194:197], v[48:51]
	v_mfma_f32_16x16x32_bf16 v[36:39], v[234:237], v[202:205], v[36:39]
	v_mfma_f32_16x16x32_bf16 v[32:35], v[242:245], v[202:205], v[32:35]
	v_mfma_f32_16x16x32_bf16 v[20:23], v[234:237], v[210:213], v[20:23]
	v_mfma_f32_16x16x32_bf16 v[16:19], v[242:245], v[210:213], v[16:19]
	v_mfma_f32_16x16x32_bf16 v[4:7], v[234:237], v[226:229], v[4:7]
	v_mfma_f32_16x16x32_bf16 v[0:3], v[242:245], v[226:229], v[0:3]
	v_mfma_f32_16x16x32_bf16 v[52:55], v[238:241], v[198:201], v[52:55]
	s_add_i32 s37, 0, 0x18000
	v_mfma_f32_16x16x32_bf16 v[48:51], v[246:249], v[198:201], v[48:51]
	v_add_u32_e32 v158, s37, v187
	v_mfma_f32_16x16x32_bf16 v[36:39], v[238:241], v[206:209], v[36:39]
	v_mfma_f32_16x16x32_bf16 v[32:35], v[246:249], v[206:209], v[32:35]
	v_mfma_f32_16x16x32_bf16 v[20:23], v[238:241], v[214:217], v[20:23]
	v_mfma_f32_16x16x32_bf16 v[16:19], v[246:249], v[214:217], v[16:19]
	v_mfma_f32_16x16x32_bf16 v[4:7], v[238:241], v[230:233], v[4:7]
	v_mfma_f32_16x16x32_bf16 v[0:3], v[246:249], v[230:233], v[0:3]
	s_setprio 0
	s_barrier
	ds_read_b128 v[128:131], v158
	ds_read_b128 v[132:135], v158 offset:1024
	ds_read_b128 v[136:139], v158 offset:2048
	ds_read_b128 v[190:193], v158 offset:3072
	s_add_u32 s20, s20, 0x80000
	s_addc_u32 s21, s21, 0
	s_mov_b32 m0, s28
	v_lshl_add_u64 v[234:235], s[20:21], 0, v[144:145]
	ds_read_b128 v[194:197], v189 offset:32768
	ds_read_b128 v[198:201], v189 offset:33792
	ds_read_b128 v[202:205], v189 offset:34816
	ds_read_b128 v[206:209], v189 offset:35840
	ds_read_b128 v[210:213], v189 offset:36864
	ds_read_b128 v[214:217], v189 offset:37888
	ds_read_b128 v[226:229], v189 offset:38912
	ds_read_b128 v[230:233], v189 offset:39936
	global_load_lds_dwordx4 v[234:235], off
	v_lshl_add_u64 v[234:235], s[20:21], 0, v[142:143]
	s_mov_b32 m0, s29
	s_nop 0
	global_load_lds_dwordx4 v[234:235], off
	s_waitcnt lgkmcnt(8)
	s_setprio 1
	s_barrier
	s_waitcnt lgkmcnt(0)
	v_mfma_f32_16x16x32_bf16 v[124:127], v[128:131], v[194:197], v[124:127]
	v_mfma_f32_16x16x32_bf16 v[120:123], v[136:139], v[194:197], v[120:123]
	v_mfma_f32_16x16x32_bf16 v[108:111], v[128:131], v[202:205], v[108:111]
	v_mfma_f32_16x16x32_bf16 v[104:107], v[136:139], v[202:205], v[104:107]
	v_mfma_f32_16x16x32_bf16 v[92:95], v[128:131], v[210:213], v[92:95]
	v_mfma_f32_16x16x32_bf16 v[88:91], v[136:139], v[210:213], v[88:91]
	v_mfma_f32_16x16x32_bf16 v[76:79], v[128:131], v[226:229], v[76:79]
	v_mfma_f32_16x16x32_bf16 v[72:75], v[136:139], v[226:229], v[72:75]
	v_mfma_f32_16x16x32_bf16 v[124:127], v[132:135], v[198:201], v[124:127]
	s_add_i32 s20, 0, 0x1c000
	v_mfma_f32_16x16x32_bf16 v[120:123], v[190:193], v[198:201], v[120:123]
	s_add_i32 s21, s37, s25
	v_mfma_f32_16x16x32_bf16 v[108:111], v[132:135], v[206:209], v[108:111]
	v_add_u32_e32 v158, s20, v187
	v_mfma_f32_16x16x32_bf16 v[104:107], v[190:193], v[206:209], v[104:107]
	v_lshl_add_u64 v[140:141], v[140:141], 0, s[94:95]
	v_mfma_f32_16x16x32_bf16 v[92:95], v[132:135], v[214:217], v[92:95]
	s_mov_b32 m0, s21
	v_mfma_f32_16x16x32_bf16 v[88:91], v[190:193], v[214:217], v[88:91]
	v_mfma_f32_16x16x32_bf16 v[76:79], v[132:135], v[230:233], v[76:79]
	v_mfma_f32_16x16x32_bf16 v[72:75], v[190:193], v[230:233], v[72:75]
	s_setprio 0
	s_barrier
	ds_read_b128 v[234:237], v158
	ds_read_b128 v[238:241], v158 offset:1024
	ds_read_b128 v[242:245], v158 offset:2048
	ds_read_b128 v[246:249], v158 offset:3072
	global_load_lds_dwordx4 v[140:141], off
	v_lshl_add_u64 v[140:141], v[154:155], 0, s[94:95]
	s_add_i32 m0, s21, 0x2000
	s_nop 0
	global_load_lds_dwordx4 v[140:141], off
	s_waitcnt lgkmcnt(0)
	s_setprio 1
	s_barrier
	v_mfma_f32_16x16x32_bf16 v[116:119], v[234:237], v[194:197], v[116:119]
	v_mfma_f32_16x16x32_bf16 v[112:115], v[242:245], v[194:197], v[112:115]
	v_mfma_f32_16x16x32_bf16 v[100:103], v[234:237], v[202:205], v[100:103]
	v_mfma_f32_16x16x32_bf16 v[96:99], v[242:245], v[202:205], v[96:99]
	v_mfma_f32_16x16x32_bf16 v[84:87], v[234:237], v[210:213], v[84:87]
	v_mfma_f32_16x16x32_bf16 v[80:83], v[242:245], v[210:213], v[80:83]
	v_mfma_f32_16x16x32_bf16 v[68:71], v[234:237], v[226:229], v[68:71]
	v_mfma_f32_16x16x32_bf16 v[64:67], v[242:245], v[226:229], v[64:67]
	v_mfma_f32_16x16x32_bf16 v[116:119], v[238:241], v[198:201], v[116:119]
	s_mov_b32 m0, s30
	v_mfma_f32_16x16x32_bf16 v[112:115], v[246:249], v[198:201], v[112:115]
	v_lshl_add_u64 v[140:141], v[218:219], 0, s[94:95]
	v_mfma_f32_16x16x32_bf16 v[100:103], v[238:241], v[206:209], v[100:103]
	v_mfma_f32_16x16x32_bf16 v[96:99], v[246:249], v[206:209], v[96:99]
	v_mfma_f32_16x16x32_bf16 v[84:87], v[238:241], v[214:217], v[84:87]
	v_mfma_f32_16x16x32_bf16 v[80:83], v[246:249], v[214:217], v[80:83]
	v_mfma_f32_16x16x32_bf16 v[68:71], v[238:241], v[230:233], v[68:71]
	v_mfma_f32_16x16x32_bf16 v[64:67], v[246:249], v[230:233], v[64:67]
	s_setprio 0
	s_barrier
; #define PG8_STAGE(bufoff, gbase) do { _Pragma("unroll") for (int _i = 0; _i < 2; ++_i) \
;         __builtin_amdgcn_global_load_lds((const unsigned*)((const char*)(gbase) + voff[_i]), (LAS unsigned*)(lds + (bufoff) + ldsw + _i * 8192), 16, 0, 0); } while (0)
; #define PG8_MMA(ai, bj, At, Bt) do { __builtin_amdgcn_s_setprio(1); _Pragma("unroll") for (int m = 0; m < 4; ++m) _Pragma("unroll") for (int n = 0; n < 2; ++n) _Pragma("unroll") for (int k = 0; k < 2; ++k) \
;         acc[ai][bj][m][n] = __builtin_amdgcn_mfma_f32_16x16x32_bf16(Bt[n][k], At[m][k], acc[ai][bj][m][n], 0, 0, 0); __builtin_amdgcn_s_setprio(0); } while (0)
; #define PG8_WAIT_V(n) asm volatile("s_waitcnt vmcnt(" #n ")" ::: "memory")
; #define PG8_WAIT_L(n) asm volatile("s_waitcnt lgkmcnt(" #n ")" ::: "memory")
; #define PG8_BAR __builtin_amdgcn_s_barrier()
; #define PG8_SCHED __builtin_amdgcn_sched_barrier(0)
; template <class Epi>
; DI void gemm_phase(LAS unsigned char* lds, const Gemm g, const StaticOrder& S, const Epi& E) {
;     ...
;             PG8_BAR; PG8_WAIT_L(0); PG8_MMA(1, 0, At, B0); PG8_BAR; PG8_SCHED;
;             PG8_STAGE(PG8_SB(1, 1), b3 + hstep);
;             PG8_WAIT_V(6); PG8_BAR; PG8_MMA(1, 1, At, B1); PG8_BAR;
;         }
;     DI void operator()(const f32x4 (&acc)[2][2][4][2], const Unit& u, int wr, int wc, int fr, int fq) const {
;         const int row0 = u.pm * BM + wr * 64 + fr, col0 = u.pn * BM + wc * 16 + 4 * fq;
;         const bool rot = u.pn < 18;
; #pragma unroll
;         for (int ai = 0; ai < 2; ++ai)
; #pragma unroll
;             for (int m = 0; m < 4; ++m) { const int row = row0 + ai * HALF + m * 16; u16* rowp = O + (size_t)row * NQKV_DIL + col0;
;                 f32x4 c4 = (f32x4){1.f, 1.f, 1.f, 1.f}, s4 = (f32x4){0.f, 0.f, 0.f, 0.f};
;                 if (rot) { const int pos = row & (SEQ - 1); c4 = *(const f32x4*)(cs + pos * 64 + wc * 16 + 4 * fq); s4 = *(const f32x4*)(sn + pos * 64 + wc * 16 + 4 * fq); }
	ds_read_b128 v[194:197], v189 offset:49152
	ds_read_b128 v[198:201], v189 offset:50176
	ds_read_b128 v[202:205], v189 offset:51200
	ds_read_b128 v[206:209], v189 offset:52224
	ds_read_b128 v[210:213], v189 offset:53248
	ds_read_b128 v[214:217], v189 offset:54272
	ds_read_b128 v[226:229], v189 offset:55296
	ds_read_b128 v[230:233], v189 offset:56320
	global_load_lds_dwordx4 v[140:141], off
	v_lshl_add_u64 v[140:141], v[250:251], 0, s[94:95]
	s_mov_b32 m0, s31
	s_nop 0
	global_load_lds_dwordx4 v[140:141], off
	s_waitcnt lgkmcnt(0)
	s_setprio 1
	s_barrier
	v_mfma_f32_16x16x32_bf16 v[60:63], v[128:131], v[194:197], v[60:63]
	v_mfma_f32_16x16x32_bf16 v[56:59], v[136:139], v[194:197], v[56:59]
	v_mfma_f32_16x16x32_bf16 v[44:47], v[128:131], v[202:205], v[44:47]
	v_mfma_f32_16x16x32_bf16 v[40:43], v[136:139], v[202:205], v[40:43]
	v_mfma_f32_16x16x32_bf16 v[28:31], v[128:131], v[210:213], v[28:31]
	v_mfma_f32_16x16x32_bf16 v[24:27], v[136:139], v[210:213], v[24:27]
	v_mfma_f32_16x16x32_bf16 v[12:15], v[128:131], v[226:229], v[12:15]
	v_mfma_f32_16x16x32_bf16 v[8:11], v[136:139], v[226:229], v[8:11]
	v_mfma_f32_16x16x32_bf16 v[60:63], v[132:135], v[198:201], v[60:63]
	s_add_u32 s18, s18, 0x80080
	v_mfma_f32_16x16x32_bf16 v[56:59], v[190:193], v[198:201], v[56:59]
	s_addc_u32 s19, s19, 0
	v_mfma_f32_16x16x32_bf16 v[44:47], v[132:135], v[206:209], v[44:47]
	s_add_i32 s20, s20, s25
	v_mfma_f32_16x16x32_bf16 v[40:43], v[190:193], v[206:209], v[40:43]
	v_lshl_add_u64 v[128:129], s[18:19], 0, v[144:145]
	v_mfma_f32_16x16x32_bf16 v[28:31], v[132:135], v[214:217], v[28:31]
	s_mov_b32 m0, s20
	v_mfma_f32_16x16x32_bf16 v[24:27], v[190:193], v[214:217], v[24:27]
	v_mfma_f32_16x16x32_bf16 v[12:15], v[132:135], v[230:233], v[12:15]
	v_mfma_f32_16x16x32_bf16 v[8:11], v[190:193], v[230:233], v[8:11]
	s_setprio 0
	s_barrier
	s_nop 0
	global_load_lds_dwordx4 v[128:129], off
	v_lshl_add_u64 v[128:129], s[18:19], 0, v[142:143]
	s_add_i32 m0, s20, 0x2000
	s_nop 0
	global_load_lds_dwordx4 v[128:129], off
	s_waitcnt vmcnt(6)
	s_setprio 1
	s_barrier
	v_mfma_f32_16x16x32_bf16 v[52:55], v[234:237], v[194:197], v[52:55]
	v_mfma_f32_16x16x32_bf16 v[48:51], v[242:245], v[194:197], v[48:51]
	v_mfma_f32_16x16x32_bf16 v[36:39], v[234:237], v[202:205], v[36:39]
	v_mfma_f32_16x16x32_bf16 v[32:35], v[242:245], v[202:205], v[32:35]
	v_mfma_f32_16x16x32_bf16 v[20:23], v[234:237], v[210:213], v[20:23]
	v_mfma_f32_16x16x32_bf16 v[16:19], v[242:245], v[210:213], v[16:19]
	v_mfma_f32_16x16x32_bf16 v[4:7], v[234:237], v[226:229], v[4:7]
	v_mfma_f32_16x16x32_bf16 v[0:3], v[242:245], v[226:229], v[0:3]
	v_mfma_f32_16x16x32_bf16 v[52:55], v[238:241], v[198:201], v[52:55]
	s_add_i32 s36, s36, 2
	v_mfma_f32_16x16x32_bf16 v[48:51], v[246:249], v[198:201], v[48:51]
	s_add_u32 s8, s8, 0x100
	v_mfma_f32_16x16x32_bf16 v[36:39], v[238:241], v[206:209], v[36:39]
	s_addc_u32 s9, s9, 0
	v_mfma_f32_16x16x32_bf16 v[32:35], v[246:249], v[206:209], v[32:35]
	s_add_u32 s33, s33, 0x100
	v_mfma_f32_16x16x32_bf16 v[20:23], v[238:241], v[214:217], v[20:23]
	s_addc_u32 s35, s35, 0
	v_mfma_f32_16x16x32_bf16 v[16:19], v[246:249], v[214:217], v[16:19]
	s_cmp_gt_u32 s36, 29
	v_mfma_f32_16x16x32_bf16 v[4:7], v[238:241], v[230:233], v[4:7]
	v_mfma_f32_16x16x32_bf16 v[0:3], v[246:249], v[230:233], v[0:3]
	s_setprio 0
	s_barrier
	s_cbranch_scc0 .LBB0_202
	s_cmp_lt_i32 s2, 18
	v_lshl_add_u32 v190, s3, 8, v186
	v_mov_b32_e32 v128, 1.0
	v_mov_b32_e32 v132, 0
	s_cselect_b64 s[18:19], -1, 0
	s_cmp_gt_i32 s2, 17
	v_mov_b32_e32 v134, 0
	v_mov_b32_e32 v135, 0
	v_mov_b32_e32 v136, 0
	v_mov_b32_e32 v137, 0
	v_mov_b32_e32 v138, 1.0
	v_mov_b32_e32 v139, 1.0
	v_mov_b32_e32 v140, 1.0
	v_mov_b32_e32 v141, 1.0
	s_cbranch_scc1 .LBB0_205
	v_lshlrev_b32_e32 v129, 8, v190
	v_and_b32_e32 v158, 0xfcf00, v129
	v_lshl_add_u64 v[130:131], v[146:147], 0, v[158:159]
	v_lshl_add_u64 v[134:135], v[148:149], 0, v[158:159]
	global_load_dwordx4 v[138:141], v[130:131], off
	s_nop 0
	global_load_dwordx4 v[134:137], v[134:135], off

; #define PG8_STAGE(bufoff, gbase) do { _Pragma("unroll") for (int _i = 0; _i < 2; ++_i) \
;         __builtin_amdgcn_global_load_lds((const unsigned*)((const char*)(gbase) + voff[_i]), (LAS unsigned*)(lds + (bufoff) + ldsw + _i * 8192), 16, 0, 0); } while (0)
; #define PG8_LDA(dst, b, h) do { _Pragma("unroll") for (int m = 0; m < 4; ++m) _Pragma("unroll") for (int k = 0; k < 2; ++k) dst[m][k] = *(const LAS bf16x8*)(lds + PG8_SA(b, h) + aoff + m * 2048 + k * 1024); } while (0)
; #define PG8_LDB(dst, b, h) do { _Pragma("unroll") for (int n = 0; n < 2; ++n) _Pragma("unroll") for (int k = 0; k < 2; ++k) dst[n][k] = *(const LAS bf16x8*)(lds + PG8_SB(b, h) + boff + n * 2048 + k * 1024); } while (0)
; #define PG8_MMA(ai, bj, At, Bt) do { __builtin_amdgcn_s_setprio(1); _Pragma("unroll") for (int m = 0; m < 4; ++m) _Pragma("unroll") for (int n = 0; n < 2; ++n) _Pragma("unroll") for (int k = 0; k < 2; ++k) \
;         acc[ai][bj][m][n] = __builtin_amdgcn_mfma_f32_16x16x32_bf16(Bt[n][k], At[m][k], acc[ai][bj][m][n], 0, 0, 0); __builtin_amdgcn_s_setprio(0); } while (0)
; #define PG8_WAIT_L(n) asm volatile("s_waitcnt lgkmcnt(" #n ")" ::: "memory")
; #define PG8_BAR __builtin_amdgcn_s_barrier()
; #define PG8_SCHED __builtin_amdgcn_sched_barrier(0)
; template <class Epi>
; DI void gemm_phase(LAS unsigned char* lds, const Gemm g, const StaticOrder& S, const Epi& E) {
;     ...
;         for (int t = 0; t < nt; t += 2) {
;             const bool last = (t == nt - 2);
;             const char* a1 = cA + (size_t)(t + 1) * kstep;
;             const char* a2 = last ? nA : cA + (size_t)(t + 2) * kstep; const char* b2 = last ? nB : cB + (size_t)(t + 2) * kstep;
;             const char* a3 = a2 + kstep; const char* b3 = b2 + kstep;
;             PG8_LDB(B0, 0, 0); PG8_SCHED; PG8_LDA(At, 0, 0); PG8_STAGE(PG8_SA(1, 1), a1 + hstep);
;             PG8_WAIT_L(8); PG8_BAR; PG8_WAIT_L(0); PG8_MMA(0, 0, At, B0); PG8_BAR; PG8_SCHED;
;             PG8_LDB(B1, 0, 1); PG8_STAGE(PG8_SB(0, 0), b2);
;             PG8_BAR; PG8_WAIT_L(0); PG8_MMA(0, 1, At, B1); PG8_BAR;
;             PG8_LDA(At, 0, 1); PG8_STAGE(PG8_SA(0, 0), a2);
;             PG8_BAR; PG8_WAIT_L(0); PG8_MMA(1, 0, At, B0); PG8_BAR; PG8_SCHED;
.LBB0_231:
	s_add_u32 s18, s16, 0xfff80080
	s_addc_u32 s19, s17, -1
	s_add_i32 s37, 0, 0x10000
	v_add_u32_e32 v150, s37, v135
	ds_read_b128 v[138:141], v150
	ds_read_b128 v[142:145], v150 offset:1024
	ds_read_b128 v[146:149], v150 offset:2048
	ds_read_b128 v[150:153], v150 offset:3072
	s_cmp_eq_u32 s36, 28
	s_cselect_b32 s21, s4, s19
	s_cselect_b32 s20, s5, s18
	s_cselect_b32 s19, s9, s35
	s_cselect_b32 s18, s11, s34
	v_lshl_add_u64 v[154:155], s[16:17], 0, v[130:131]
	s_add_i32 m0, s24, 0xc000
	ds_read_b128 v[186:189], v137
	ds_read_b128 v[190:193], v137 offset:1024
	ds_read_b128 v[194:197], v137 offset:2048
	ds_read_b128 v[198:201], v137 offset:3072
	ds_read_b128 v[202:205], v137 offset:4096
	ds_read_b128 v[206:209], v137 offset:5120
	ds_read_b128 v[210:213], v137 offset:6144
	ds_read_b128 v[214:217], v137 offset:7168
	global_load_lds_dwordx4 v[154:155], off
	v_lshl_add_u64 v[154:155], s[16:17], 0, v[132:133]
	s_add_i32 m0, s24, 0xe000
	s_nop 0
	global_load_lds_dwordx4 v[154:155], off
	s_waitcnt lgkmcnt(8)
	s_setprio 1
	s_barrier
	s_waitcnt lgkmcnt(0)
	v_mfma_f32_16x16x32_bf16 v[124:127], v[138:141], v[186:189], v[124:127]
	v_mfma_f32_16x16x32_bf16 v[120:123], v[146:149], v[186:189], v[120:123]
	v_mfma_f32_16x16x32_bf16 v[116:119], v[138:141], v[194:197], v[116:119]
	v_mfma_f32_16x16x32_bf16 v[112:115], v[146:149], v[194:197], v[112:115]
	v_mfma_f32_16x16x32_bf16 v[100:103], v[138:141], v[202:205], v[100:103]
	v_mfma_f32_16x16x32_bf16 v[96:99], v[146:149], v[202:205], v[96:99]
	v_mfma_f32_16x16x32_bf16 v[84:87], v[138:141], v[210:213], v[84:87]
	v_mfma_f32_16x16x32_bf16 v[80:83], v[146:149], v[210:213], v[80:83]
	v_mfma_f32_16x16x32_bf16 v[124:127], v[142:145], v[190:193], v[124:127]
	s_add_i32 s40, 0, 0x14000
	v_mfma_f32_16x16x32_bf16 v[120:123], v[150:153], v[190:193], v[120:123]
	v_add_u32_e32 v154, s40, v135
	v_mfma_f32_16x16x32_bf16 v[116:119], v[142:145], v[198:201], v[116:119]
	s_add_i32 s37, s37, s23
	v_mfma_f32_16x16x32_bf16 v[112:115], v[150:153], v[198:201], v[112:115]
	v_mfma_f32_16x16x32_bf16 v[100:103], v[142:145], v[206:209], v[100:103]
	v_mfma_f32_16x16x32_bf16 v[96:99], v[150:153], v[206:209], v[96:99]
	v_mfma_f32_16x16x32_bf16 v[84:87], v[142:145], v[214:217], v[84:87]
	v_mfma_f32_16x16x32_bf16 v[80:83], v[150:153], v[214:217], v[80:83]
	s_setprio 0
	s_barrier
	ds_read_b128 v[226:229], v154
	ds_read_b128 v[230:233], v154 offset:1024
	ds_read_b128 v[234:237], v154 offset:2048
	ds_read_b128 v[238:241], v154 offset:3072
	v_lshl_add_u64 v[154:155], s[18:19], 0, v[158:159]
	s_mov_b32 m0, s37
	v_lshl_add_u64 v[218:219], s[18:19], 0, v[128:129]
	global_load_lds_dwordx4 v[154:155], off
	s_add_i32 m0, s37, 0x2000
	s_nop 0
	global_load_lds_dwordx4 v[218:219], off
	s_waitcnt lgkmcnt(0)
	s_setprio 1
	s_barrier
	v_mfma_f32_16x16x32_bf16 v[108:111], v[226:229], v[186:189], v[108:111]
	v_mfma_f32_16x16x32_bf16 v[104:107], v[234:237], v[186:189], v[104:107]
	v_mfma_f32_16x16x32_bf16 v[92:95], v[226:229], v[194:197], v[92:95]
	v_mfma_f32_16x16x32_bf16 v[88:91], v[234:237], v[194:197], v[88:91]
	v_mfma_f32_16x16x32_bf16 v[76:79], v[226:229], v[202:205], v[76:79]
	v_mfma_f32_16x16x32_bf16 v[72:75], v[234:237], v[202:205], v[72:75]
	v_mfma_f32_16x16x32_bf16 v[68:71], v[226:229], v[210:213], v[68:71]
	v_mfma_f32_16x16x32_bf16 v[64:67], v[234:237], v[210:213], v[64:67]
	v_mfma_f32_16x16x32_bf16 v[108:111], v[230:233], v[190:193], v[108:111]
	s_mov_b32 m0, s24
	v_mfma_f32_16x16x32_bf16 v[104:107], v[238:241], v[190:193], v[104:107]
	v_lshl_add_u64 v[242:243], s[20:21], 0, v[158:159]
	v_mfma_f32_16x16x32_bf16 v[92:95], v[230:233], v[198:201], v[92:95]
	v_mfma_f32_16x16x32_bf16 v[88:91], v[238:241], v[198:201], v[88:91]
	v_mfma_f32_16x16x32_bf16 v[76:79], v[230:233], v[206:209], v[76:79]
	v_mfma_f32_16x16x32_bf16 v[72:75], v[238:241], v[206:209], v[72:75]
	v_mfma_f32_16x16x32_bf16 v[68:71], v[230:233], v[214:217], v[68:71]
	v_mfma_f32_16x16x32_bf16 v[64:67], v[238:241], v[214:217], v[64:67]
	s_setprio 0
	s_barrier
	ds_read_b128 v[186:189], v137 offset:16384
	ds_read_b128 v[190:193], v137 offset:17408
	ds_read_b128 v[194:197], v137 offset:18432
	ds_read_b128 v[198:201], v137 offset:19456
	ds_read_b128 v[202:205], v137 offset:20480
	ds_read_b128 v[206:209], v137 offset:21504
	ds_read_b128 v[210:213], v137 offset:22528
	ds_read_b128 v[214:217], v137 offset:23552
	global_load_lds_dwordx4 v[242:243], off
	v_lshl_add_u64 v[244:245], s[20:21], 0, v[128:129]
	s_mov_b32 m0, s25
	s_nop 0
	global_load_lds_dwordx4 v[244:245], off
	s_waitcnt lgkmcnt(0)
	s_setprio 1
	s_barrier
	v_mfma_f32_16x16x32_bf16 v[60:63], v[138:141], v[186:189], v[60:63]
	v_mfma_f32_16x16x32_bf16 v[56:59], v[146:149], v[186:189], v[56:59]
	v_mfma_f32_16x16x32_bf16 v[52:55], v[138:141], v[194:197], v[52:55]
	v_mfma_f32_16x16x32_bf16 v[48:51], v[146:149], v[194:197], v[48:51]
	v_mfma_f32_16x16x32_bf16 v[36:39], v[138:141], v[202:205], v[36:39]
	v_mfma_f32_16x16x32_bf16 v[32:35], v[146:149], v[202:205], v[32:35]
	v_mfma_f32_16x16x32_bf16 v[20:23], v[138:141], v[210:213], v[20:23]
	v_mfma_f32_16x16x32_bf16 v[16:19], v[146:149], v[210:213], v[16:19]
	v_mfma_f32_16x16x32_bf16 v[60:63], v[142:145], v[190:193], v[60:63]
	s_add_u32 s38, s18, 0x80000
	v_mfma_f32_16x16x32_bf16 v[56:59], v[150:153], v[190:193], v[56:59]
	s_addc_u32 s39, s19, 0
	v_mfma_f32_16x16x32_bf16 v[52:55], v[142:145], v[198:201], v[52:55]
	s_add_i32 s37, s40, s23
	v_mfma_f32_16x16x32_bf16 v[48:51], v[150:153], v[198:201], v[48:51]
	v_lshl_add_u64 v[138:139], s[38:39], 0, v[158:159]
	v_mfma_f32_16x16x32_bf16 v[36:39], v[142:145], v[206:209], v[36:39]
	s_mov_b32 m0, s37
	v_mfma_f32_16x16x32_bf16 v[32:35], v[150:153], v[206:209], v[32:35]
	v_mfma_f32_16x16x32_bf16 v[20:23], v[142:145], v[214:217], v[20:23]
	v_mfma_f32_16x16x32_bf16 v[16:19], v[150:153], v[214:217], v[16:19]
	s_setprio 0
	s_barrier
; #define PG8_STAGE(bufoff, gbase) do { _Pragma("unroll") for (int _i = 0; _i < 2; ++_i) \
;         __builtin_amdgcn_global_load_lds((const unsigned*)((const char*)(gbase) + voff[_i]), (LAS unsigned*)(lds + (bufoff) + ldsw + _i * 8192), 16, 0, 0); } while (0)
; #define PG8_LDA(dst, b, h) do { _Pragma("unroll") for (int m = 0; m < 4; ++m) _Pragma("unroll") for (int k = 0; k < 2; ++k) dst[m][k] = *(const LAS bf16x8*)(lds + PG8_SA(b, h) + aoff + m * 2048 + k * 1024); } while (0)
; #define PG8_LDB(dst, b, h) do { _Pragma("unroll") for (int n = 0; n < 2; ++n) _Pragma("unroll") for (int k = 0; k < 2; ++k) dst[n][k] = *(const LAS bf16x8*)(lds + PG8_SB(b, h) + boff + n * 2048 + k * 1024); } while (0)
; #define PG8_MMA(ai, bj, At, Bt) do { __builtin_amdgcn_s_setprio(1); _Pragma("unroll") for (int m = 0; m < 4; ++m) _Pragma("unroll") for (int n = 0; n < 2; ++n) _Pragma("unroll") for (int k = 0; k < 2; ++k) \
;         acc[ai][bj][m][n] = __builtin_amdgcn_mfma_f32_16x16x32_bf16(Bt[n][k], At[m][k], acc[ai][bj][m][n], 0, 0, 0); __builtin_amdgcn_s_setprio(0); } while (0)
; #define PG8_WAIT_V(n) asm volatile("s_waitcnt vmcnt(" #n ")" ::: "memory")
; #define PG8_WAIT_L(n) asm volatile("s_waitcnt lgkmcnt(" #n ")" ::: "memory")
; #define PG8_BAR __builtin_amdgcn_s_barrier()
; #define PG8_SCHED __builtin_amdgcn_sched_barrier(0)
; template <class Epi>
; DI void gemm_phase(LAS unsigned char* lds, const Gemm g, const StaticOrder& S, const Epi& E) {
;     ...
;             PG8_STAGE(PG8_SB(0, 1), b2 + hstep);
;             PG8_WAIT_V(6); PG8_BAR; PG8_MMA(1, 1, At, B1); PG8_BAR;
;             PG8_LDB(B0, 1, 0); PG8_SCHED; PG8_LDA(At, 1, 0); PG8_STAGE(PG8_SA(0, 1), a2 + hstep);
;             PG8_WAIT_L(8); PG8_BAR; PG8_WAIT_L(0); PG8_MMA(0, 0, At, B0); PG8_BAR; PG8_SCHED;
;             PG8_LDB(B1, 1, 1); PG8_STAGE(PG8_SB(1, 0), b3);
;             PG8_BAR; PG8_WAIT_L(0); PG8_MMA(0, 1, At, B1); PG8_BAR;
;             PG8_LDA(At, 1, 1); PG8_STAGE(PG8_SA(1, 0), a3);
	s_nop 0
	global_load_lds_dwordx4 v[138:139], off
	v_lshl_add_u64 v[138:139], s[38:39], 0, v[128:129]
	s_add_i32 m0, s37, 0x2000
	s_nop 0
	global_load_lds_dwordx4 v[138:139], off
	s_waitcnt vmcnt(6)
	s_setprio 1
	s_barrier
	v_mfma_f32_16x16x32_bf16 v[44:47], v[226:229], v[186:189], v[44:47]
	v_mfma_f32_16x16x32_bf16 v[40:43], v[234:237], v[186:189], v[40:43]
	v_mfma_f32_16x16x32_bf16 v[28:31], v[226:229], v[194:197], v[28:31]
	v_mfma_f32_16x16x32_bf16 v[24:27], v[234:237], v[194:197], v[24:27]
	v_mfma_f32_16x16x32_bf16 v[12:15], v[226:229], v[202:205], v[12:15]
	v_mfma_f32_16x16x32_bf16 v[8:11], v[234:237], v[202:205], v[8:11]
	v_mfma_f32_16x16x32_bf16 v[4:7], v[226:229], v[210:213], v[4:7]
	v_mfma_f32_16x16x32_bf16 v[0:3], v[234:237], v[210:213], v[0:3]
	v_mfma_f32_16x16x32_bf16 v[44:47], v[230:233], v[190:193], v[44:47]
	s_add_i32 s37, 0, 0x18000
	v_mfma_f32_16x16x32_bf16 v[40:43], v[238:241], v[190:193], v[40:43]
	v_add_u32_e32 v150, s37, v135
	v_mfma_f32_16x16x32_bf16 v[28:31], v[230:233], v[198:201], v[28:31]
	v_mfma_f32_16x16x32_bf16 v[24:27], v[238:241], v[198:201], v[24:27]
	v_mfma_f32_16x16x32_bf16 v[12:15], v[230:233], v[206:209], v[12:15]
	v_mfma_f32_16x16x32_bf16 v[8:11], v[238:241], v[206:209], v[8:11]
	v_mfma_f32_16x16x32_bf16 v[4:7], v[230:233], v[214:217], v[4:7]
	v_mfma_f32_16x16x32_bf16 v[0:3], v[238:241], v[214:217], v[0:3]
	s_setprio 0
	s_barrier
	ds_read_b128 v[138:141], v150
	ds_read_b128 v[142:145], v150 offset:1024
	ds_read_b128 v[146:149], v150 offset:2048
	ds_read_b128 v[150:153], v150 offset:3072
	s_add_u32 s20, s20, 0x80000
	s_addc_u32 s21, s21, 0
	s_mov_b32 m0, s26
	v_lshl_add_u64 v[226:227], s[20:21], 0, v[158:159]
	ds_read_b128 v[186:189], v137 offset:32768
	ds_read_b128 v[190:193], v137 offset:33792
	ds_read_b128 v[194:197], v137 offset:34816
	ds_read_b128 v[198:201], v137 offset:35840
	ds_read_b128 v[202:205], v137 offset:36864
	ds_read_b128 v[206:209], v137 offset:37888
	ds_read_b128 v[210:213], v137 offset:38912
	ds_read_b128 v[214:217], v137 offset:39936
	global_load_lds_dwordx4 v[226:227], off
	v_lshl_add_u64 v[226:227], s[20:21], 0, v[128:129]
	s_mov_b32 m0, s27
	s_nop 0
	global_load_lds_dwordx4 v[226:227], off
	s_waitcnt lgkmcnt(8)
	s_setprio 1
	s_barrier
	s_waitcnt lgkmcnt(0)
	v_mfma_f32_16x16x32_bf16 v[124:127], v[138:141], v[186:189], v[124:127]
	v_mfma_f32_16x16x32_bf16 v[120:123], v[146:149], v[186:189], v[120:123]
	v_mfma_f32_16x16x32_bf16 v[116:119], v[138:141], v[194:197], v[116:119]
	v_mfma_f32_16x16x32_bf16 v[112:115], v[146:149], v[194:197], v[112:115]
	v_mfma_f32_16x16x32_bf16 v[100:103], v[138:141], v[202:205], v[100:103]
	v_mfma_f32_16x16x32_bf16 v[96:99], v[146:149], v[202:205], v[96:99]
	v_mfma_f32_16x16x32_bf16 v[84:87], v[138:141], v[210:213], v[84:87]
	v_mfma_f32_16x16x32_bf16 v[80:83], v[146:149], v[210:213], v[80:83]
	v_mfma_f32_16x16x32_bf16 v[124:127], v[142:145], v[190:193], v[124:127]
	s_add_i32 s20, 0, 0x1c000
	v_mfma_f32_16x16x32_bf16 v[120:123], v[150:153], v[190:193], v[120:123]
	s_add_i32 s21, s37, s23
	v_mfma_f32_16x16x32_bf16 v[116:119], v[142:145], v[198:201], v[116:119]
	v_add_u32_e32 v220, s20, v135
	v_mfma_f32_16x16x32_bf16 v[112:115], v[150:153], v[198:201], v[112:115]
	v_lshl_add_u64 v[154:155], v[154:155], 0, s[94:95]
	v_mfma_f32_16x16x32_bf16 v[100:103], v[142:145], v[206:209], v[100:103]
	s_mov_b32 m0, s21
	v_mfma_f32_16x16x32_bf16 v[96:99], v[150:153], v[206:209], v[96:99]
	v_mfma_f32_16x16x32_bf16 v[84:87], v[142:145], v[214:217], v[84:87]
	v_mfma_f32_16x16x32_bf16 v[80:83], v[150:153], v[214:217], v[80:83]
	s_setprio 0
	s_barrier
	ds_read_b128 v[226:229], v220
	ds_read_b128 v[230:233], v220 offset:1024
	ds_read_b128 v[234:237], v220 offset:2048
	ds_read_b128 v[238:241], v220 offset:3072
	global_load_lds_dwordx4 v[154:155], off
	v_lshl_add_u64 v[154:155], v[218:219], 0, s[94:95]
	s_add_i32 m0, s21, 0x2000
	s_nop 0
	global_load_lds_dwordx4 v[154:155], off
	s_waitcnt lgkmcnt(0)
	s_setprio 1
	s_barrier
	v_mfma_f32_16x16x32_bf16 v[108:111], v[226:229], v[186:189], v[108:111]
	v_mfma_f32_16x16x32_bf16 v[104:107], v[234:237], v[186:189], v[104:107]
	v_mfma_f32_16x16x32_bf16 v[92:95], v[226:229], v[194:197], v[92:95]
	v_mfma_f32_16x16x32_bf16 v[88:91], v[234:237], v[194:197], v[88:91]
	v_mfma_f32_16x16x32_bf16 v[76:79], v[226:229], v[202:205], v[76:79]
	v_mfma_f32_16x16x32_bf16 v[72:75], v[234:237], v[202:205], v[72:75]
	v_mfma_f32_16x16x32_bf16 v[68:71], v[226:229], v[210:213], v[68:71]
	v_mfma_f32_16x16x32_bf16 v[64:67], v[234:237], v[210:213], v[64:67]
	v_mfma_f32_16x16x32_bf16 v[108:111], v[230:233], v[190:193], v[108:111]
	s_mov_b32 m0, s28
	v_mfma_f32_16x16x32_bf16 v[104:107], v[238:241], v[190:193], v[104:107]
	v_lshl_add_u64 v[154:155], v[242:243], 0, s[94:95]
	v_mfma_f32_16x16x32_bf16 v[92:95], v[230:233], v[198:201], v[92:95]
	v_mfma_f32_16x16x32_bf16 v[88:91], v[238:241], v[198:201], v[88:91]
	v_mfma_f32_16x16x32_bf16 v[76:79], v[230:233], v[206:209], v[76:79]
	v_mfma_f32_16x16x32_bf16 v[72:75], v[238:241], v[206:209], v[72:75]
	v_mfma_f32_16x16x32_bf16 v[68:71], v[230:233], v[214:217], v[68:71]
	v_mfma_f32_16x16x32_bf16 v[64:67], v[238:241], v[214:217], v[64:67]
	s_setprio 0
	s_barrier
	ds_read_b128 v[186:189], v137 offset:49152
	ds_read_b128 v[190:193], v137 offset:50176
	ds_read_b128 v[194:197], v137 offset:51200
	ds_read_b128 v[198:201], v137 offset:52224
	ds_read_b128 v[202:205], v137 offset:53248
	ds_read_b128 v[206:209], v137 offset:54272
	ds_read_b128 v[210:213], v137 offset:55296
	ds_read_b128 v[214:217], v137 offset:56320
	global_load_lds_dwordx4 v[154:155], off
	v_lshl_add_u64 v[154:155], v[244:245], 0, s[94:95]
	s_mov_b32 m0, s29
	s_nop 0
	global_load_lds_dwordx4 v[154:155], off
	s_waitcnt lgkmcnt(0)
	s_setprio 1
	s_barrier
; #define PG8_STAGE(bufoff, gbase) do { _Pragma("unroll") for (int _i = 0; _i < 2; ++_i) \
;         __builtin_amdgcn_global_load_lds((const unsigned*)((const char*)(gbase) + voff[_i]), (LAS unsigned*)(lds + (bufoff) + ldsw + _i * 8192), 16, 0, 0); } while (0)
; #define PG8_MMA(ai, bj, At, Bt) do { __builtin_amdgcn_s_setprio(1); _Pragma("unroll") for (int m = 0; m < 4; ++m) _Pragma("unroll") for (int n = 0; n < 2; ++n) _Pragma("unroll") for (int k = 0; k < 2; ++k) \
;         acc[ai][bj][m][n] = __builtin_amdgcn_mfma_f32_16x16x32_bf16(Bt[n][k], At[m][k], acc[ai][bj][m][n], 0, 0, 0); __builtin_amdgcn_s_setprio(0); } while (0)
; #define PG8_WAIT_V(n) asm volatile("s_waitcnt vmcnt(" #n ")" ::: "memory")
; #define PG8_WAIT_L(n) asm volatile("s_waitcnt lgkmcnt(" #n ")" ::: "memory")
; #define PG8_BAR __builtin_amdgcn_s_barrier()
; #define PG8_SCHED __builtin_amdgcn_sched_barrier(0)
; template <class Epi>
; DI void gemm_phase(LAS unsigned char* lds, const Gemm g, const StaticOrder& S, const Epi& E) {
;     ...
;             PG8_BAR; PG8_WAIT_L(0); PG8_MMA(1, 0, At, B0); PG8_BAR; PG8_SCHED;
;             PG8_STAGE(PG8_SB(1, 1), b3 + hstep);
;             PG8_WAIT_V(6); PG8_BAR; PG8_MMA(1, 1, At, B1); PG8_BAR;
;         }
	v_mfma_f32_16x16x32_bf16 v[60:63], v[138:141], v[186:189], v[60:63]
	v_mfma_f32_16x16x32_bf16 v[56:59], v[146:149], v[186:189], v[56:59]
	v_mfma_f32_16x16x32_bf16 v[52:55], v[138:141], v[194:197], v[52:55]
	v_mfma_f32_16x16x32_bf16 v[48:51], v[146:149], v[194:197], v[48:51]
	v_mfma_f32_16x16x32_bf16 v[36:39], v[138:141], v[202:205], v[36:39]
	v_mfma_f32_16x16x32_bf16 v[32:35], v[146:149], v[202:205], v[32:35]
	v_mfma_f32_16x16x32_bf16 v[20:23], v[138:141], v[210:213], v[20:23]
	v_mfma_f32_16x16x32_bf16 v[16:19], v[146:149], v[210:213], v[16:19]
	v_mfma_f32_16x16x32_bf16 v[60:63], v[142:145], v[190:193], v[60:63]
	s_add_u32 s18, s18, 0x80080
	v_mfma_f32_16x16x32_bf16 v[56:59], v[150:153], v[190:193], v[56:59]
	s_addc_u32 s19, s19, 0
	v_mfma_f32_16x16x32_bf16 v[52:55], v[142:145], v[198:201], v[52:55]
	s_add_i32 s20, s20, s23
	v_mfma_f32_16x16x32_bf16 v[48:51], v[150:153], v[198:201], v[48:51]
	v_lshl_add_u64 v[138:139], s[18:19], 0, v[158:159]
	v_mfma_f32_16x16x32_bf16 v[36:39], v[142:145], v[206:209], v[36:39]
	s_mov_b32 m0, s20
	v_mfma_f32_16x16x32_bf16 v[32:35], v[150:153], v[206:209], v[32:35]
	v_mfma_f32_16x16x32_bf16 v[20:23], v[142:145], v[214:217], v[20:23]
	v_mfma_f32_16x16x32_bf16 v[16:19], v[150:153], v[214:217], v[16:19]
	s_setprio 0
	s_barrier
	s_nop 0
	global_load_lds_dwordx4 v[138:139], off
	v_lshl_add_u64 v[138:139], s[18:19], 0, v[128:129]
	s_add_i32 m0, s20, 0x2000
	s_nop 0
	global_load_lds_dwordx4 v[138:139], off
	s_waitcnt vmcnt(6)
	s_setprio 1
	s_barrier
	v_mfma_f32_16x16x32_bf16 v[44:47], v[226:229], v[186:189], v[44:47]
	v_mfma_f32_16x16x32_bf16 v[40:43], v[234:237], v[186:189], v[40:43]
	v_mfma_f32_16x16x32_bf16 v[28:31], v[226:229], v[194:197], v[28:31]
	v_mfma_f32_16x16x32_bf16 v[24:27], v[234:237], v[194:197], v[24:27]
	v_mfma_f32_16x16x32_bf16 v[12:15], v[226:229], v[202:205], v[12:15]
	v_mfma_f32_16x16x32_bf16 v[8:11], v[234:237], v[202:205], v[8:11]
	v_mfma_f32_16x16x32_bf16 v[4:7], v[226:229], v[210:213], v[4:7]
	v_mfma_f32_16x16x32_bf16 v[0:3], v[234:237], v[210:213], v[0:3]
	v_mfma_f32_16x16x32_bf16 v[44:47], v[230:233], v[190:193], v[44:47]
	s_add_i32 s36, s36, 2
	v_mfma_f32_16x16x32_bf16 v[40:43], v[238:241], v[190:193], v[40:43]
	s_add_u32 s16, s16, 0x100
	v_mfma_f32_16x16x32_bf16 v[28:31], v[230:233], v[198:201], v[28:31]
	s_addc_u32 s17, s17, 0
	v_mfma_f32_16x16x32_bf16 v[24:27], v[238:241], v[198:201], v[24:27]
	s_add_u32 s34, s34, 0x100
	v_mfma_f32_16x16x32_bf16 v[12:15], v[230:233], v[206:209], v[12:15]
	s_addc_u32 s35, s35, 0
	v_mfma_f32_16x16x32_bf16 v[8:11], v[238:241], v[206:209], v[8:11]
	s_cmp_gt_u32 s36, 29
	v_mfma_f32_16x16x32_bf16 v[4:7], v[230:233], v[214:217], v[4:7]
	v_mfma_f32_16x16x32_bf16 v[0:3], v[238:241], v[214:217], v[0:3]
	s_setprio 0
	s_barrier
	s_cbranch_scc0 .LBB0_231
; #define PG8_WAIT_V(n) asm volatile("s_waitcnt vmcnt(" #n ")" ::: "memory")
; #define PG8_BAR __builtin_amdgcn_s_barrier()
; template <class Epi>
; DI void gemm_phase(LAS unsigned char* lds, const Gemm g, const StaticOrder& S, const Epi& E) {
;     ...
;         E(acc, cur, wr, wc, fr, fq);
;         if (!has_next) break;
; #pragma unroll
;         for (int a = 0; a < 2; ++a)
; #pragma unroll
;             for (int b = 0; b < 2; ++b)
; #pragma unroll
;                 for (int m = 0; m < 4; ++m)
; #pragma unroll
;                     for (int n = 0; n < 2; ++n) acc[a][b][m][n] = (f32x4){0.f, 0.f, 0.f, 0.f};
;         cur = nxt; cA = nA; cB = nB; ++ui;
;     }
;     PG8_WAIT_V(0);
;     if (wr == 0) PG8_BAR;
;     DI void operator()(const f32x4 (&acc)[2][2][4][2], const Unit& u, int wr, int wc, int fr, int fq) const {
;         const int row0 = u.pm * BM + wr * 64 + fr, col0 = u.pn * BM + wc * 32 + 8 * fq;
; #pragma unroll
;         for (int ai = 0; ai < 2; ++ai)
; #pragma unroll
;             for (int m = 0; m < 4; ++m) { u16* rowp = O + (size_t)(row0 + ai * HALF + m * 16) * ldc + col0;
; #pragma unroll
;                 for (int bj = 0; bj < 2; ++bj) { const f32x4 v0 = acc[ai][bj][m][0], v1 = acc[ai][bj][m][1];
;                     *(u32x4*)(rowp + bj * HALF) = (u32x4){pk(v0[0], v0[1]), pk(v0[2], v0[3]), pk(v1[0], v1[1]), pk(v1[2], v1[3])}; } }
;     }
	v_lshl_add_u32 v144, s33, 8, v134
	v_lshl_or_b32 v138, s31, 8, v136
	v_ashrrev_i32_e32 v139, 31, v138
	v_mov_b64_e32 v[140:141], s[50:51]
	s_movk_i32 s9, 0x3000
	v_cvt_pk_bf16_f32 v68, v68, v69
	v_cvt_pk_bf16_f32 v69, v70, v71
	v_cvt_pk_bf16_f32 v70, v64, v65
	v_add_u32_e32 v64, 0x80, v144
	v_mad_i64_i32 v[142:143], s[4:5], v144, s9, v[140:141]
	v_lshlrev_b64 v[138:139], 1, v[138:139]
	v_cvt_pk_bf16_f32 v108, v108, v109
	v_cvt_pk_bf16_f32 v109, v110, v111
	v_cvt_pk_bf16_f32 v110, v104, v105
	v_or_b32_e32 v104, 16, v144
	v_mad_i64_i32 v[64:65], s[4:5], v64, s9, v[140:141]
	v_cvt_pk_bf16_f32 v44, v44, v45
	v_cvt_pk_bf16_f32 v45, v46, v47
	v_cvt_pk_bf16_f32 v46, v40, v41
	v_add_u32_e32 v40, 0x90, v144
	v_lshl_add_u64 v[142:143], v[142:143], 0, v[138:139]
	v_cvt_pk_bf16_f32 v111, v106, v107
	v_mad_i64_i32 v[104:105], s[4:5], v104, s9, v[140:141]
	v_cvt_pk_bf16_f32 v92, v92, v93
	v_cvt_pk_bf16_f32 v93, v94, v95
	v_cvt_pk_bf16_f32 v94, v88, v89
	v_or_b32_e32 v88, 32, v144
	v_lshl_add_u64 v[64:65], v[64:65], 0, v[138:139]
	v_cvt_pk_bf16_f32 v47, v42, v43
	v_mad_i64_i32 v[40:41], s[4:5], v40, s9, v[140:141]
	v_cvt_pk_bf16_f32 v28, v28, v29
	v_cvt_pk_bf16_f32 v29, v30, v31
	v_cvt_pk_bf16_f32 v30, v24, v25
	v_add_u32_e32 v24, 0xa0, v144
	global_store_dwordx4 v[142:143], v[108:111], off offset:256
	v_cvt_pk_bf16_f32 v95, v90, v91
	v_mad_i64_i32 v[88:89], s[4:5], v88, s9, v[140:141]
	v_lshl_add_u64 v[108:109], v[104:105], 0, v[138:139]
	v_cvt_pk_bf16_f32 v76, v76, v77
	v_cvt_pk_bf16_f32 v77, v78, v79
	v_cvt_pk_bf16_f32 v78, v72, v73
	v_or_b32_e32 v72, 48, v144
	global_store_dwordx4 v[64:65], v[44:47], off offset:256
	v_cvt_pk_bf16_f32 v31, v26, v27
	v_mad_i64_i32 v[24:25], s[4:5], v24, s9, v[140:141]
	v_lshl_add_u64 v[44:45], v[40:41], 0, v[138:139]
	v_cvt_pk_bf16_f32 v12, v12, v13
	v_cvt_pk_bf16_f32 v13, v14, v15
	v_cvt_pk_bf16_f32 v14, v8, v9
	v_add_u32_e32 v8, 0xb0, v144
	global_store_dwordx4 v[108:109], v[92:95], off offset:256
	v_cvt_pk_bf16_f32 v79, v74, v75
	v_mad_i64_i32 v[72:73], s[4:5], v72, s9, v[140:141]
	v_lshl_add_u64 v[92:93], v[88:89], 0, v[138:139]
	global_store_dwordx4 v[44:45], v[28:31], off offset:256
	v_cvt_pk_bf16_f32 v15, v10, v11
	v_mad_i64_i32 v[8:9], s[4:5], v8, s9, v[140:141]
	v_lshl_add_u64 v[28:29], v[24:25], 0, v[138:139]
	v_cvt_pk_bf16_f32 v124, v124, v125
	v_cvt_pk_bf16_f32 v125, v126, v127
	v_cvt_pk_bf16_f32 v126, v120, v121
	v_cvt_pk_bf16_f32 v127, v122, v123
	v_cvt_pk_bf16_f32 v104, v116, v117
	v_cvt_pk_bf16_f32 v105, v118, v119
	v_cvt_pk_bf16_f32 v106, v112, v113
	v_cvt_pk_bf16_f32 v107, v114, v115
	v_cvt_pk_bf16_f32 v88, v100, v101
	v_cvt_pk_bf16_f32 v89, v102, v103
	v_cvt_pk_bf16_f32 v90, v96, v97
	v_cvt_pk_bf16_f32 v91, v98, v99
	global_store_dwordx4 v[92:93], v[76:79], off offset:256
	v_cvt_pk_bf16_f32 v74, v80, v81
	v_cvt_pk_bf16_f32 v75, v82, v83
	v_lshl_add_u64 v[76:77], v[72:73], 0, v[138:139]
	v_cvt_pk_bf16_f32 v72, v84, v85
	v_cvt_pk_bf16_f32 v73, v86, v87
	v_cvt_pk_bf16_f32 v71, v66, v67
	v_cvt_pk_bf16_f32 v60, v60, v61
	v_cvt_pk_bf16_f32 v61, v62, v63
	v_cvt_pk_bf16_f32 v62, v56, v57
	v_cvt_pk_bf16_f32 v63, v58, v59
	v_cvt_pk_bf16_f32 v40, v52, v53
	v_cvt_pk_bf16_f32 v41, v54, v55
	v_cvt_pk_bf16_f32 v42, v48, v49
	v_cvt_pk_bf16_f32 v43, v50, v51
	v_cvt_pk_bf16_f32 v24, v36, v37
	v_cvt_pk_bf16_f32 v25, v38, v39
	v_cvt_pk_bf16_f32 v26, v32, v33
	v_cvt_pk_bf16_f32 v27, v34, v35
	global_store_dwordx4 v[28:29], v[12:15], off offset:256
	v_cvt_pk_bf16_f32 v10, v16, v17
	v_cvt_pk_bf16_f32 v11, v18, v19
	v_lshl_add_u64 v[12:13], v[8:9], 0, v[138:139]
	v_cvt_pk_bf16_f32 v8, v20, v21
	v_cvt_pk_bf16_f32 v9, v22, v23
	v_cvt_pk_bf16_f32 v4, v4, v5
	v_cvt_pk_bf16_f32 v5, v6, v7
	v_cvt_pk_bf16_f32 v6, v0, v1
	v_cvt_pk_bf16_f32 v7, v2, v3
	s_and_b64 vcc, exec, s[6:7]
	s_mov_b32 s31, s8
	s_mov_b32 s33, s10
	s_mov_b64 s[18:19], s[14:15]
	s_mov_b64 s[16:17], s[12:13]
	global_store_dwordx4 v[142:143], v[124:127], off
	global_store_dwordx4 v[108:109], v[104:107], off
	global_store_dwordx4 v[92:93], v[88:91], off
	global_store_dwordx4 v[76:77], v[72:75], off
	global_store_dwordx4 v[76:77], v[68:71], off offset:256
	global_store_dwordx4 v[64:65], v[60:63], off
	global_store_dwordx4 v[44:45], v[40:43], off
	global_store_dwordx4 v[28:29], v[24:27], off
	global_store_dwordx4 v[12:13], v[8:11], off
	global_store_dwordx4 v[12:13], v[4:7], off offset:256
	s_cbranch_vccz .LBB0_228
	s_waitcnt vmcnt(0)
	s_cmpk_gt_u32 s2, 0xff
	s_cbranch_scc1 .LBB0_235
	s_barrier

; #define PG8_STAGE(bufoff, gbase) do { _Pragma("unroll") for (int _i = 0; _i < 2; ++_i) \
;         __builtin_amdgcn_global_load_lds((const unsigned*)((const char*)(gbase) + voff[_i]), (LAS unsigned*)(lds + (bufoff) + ldsw + _i * 8192), 16, 0, 0); } while (0)
; #define PG8_LDA(dst, b, h) do { _Pragma("unroll") for (int m = 0; m < 4; ++m) _Pragma("unroll") for (int k = 0; k < 2; ++k) dst[m][k] = *(const LAS bf16x8*)(lds + PG8_SA(b, h) + aoff + m * 2048 + k * 1024); } while (0)
; #define PG8_LDB(dst, b, h) do { _Pragma("unroll") for (int n = 0; n < 2; ++n) _Pragma("unroll") for (int k = 0; k < 2; ++k) dst[n][k] = *(const LAS bf16x8*)(lds + PG8_SB(b, h) + boff + n * 2048 + k * 1024); } while (0)
; #define PG8_MMA(ai, bj, At, Bt) do { __builtin_amdgcn_s_setprio(1); _Pragma("unroll") for (int m = 0; m < 4; ++m) _Pragma("unroll") for (int n = 0; n < 2; ++n) _Pragma("unroll") for (int k = 0; k < 2; ++k) \
;         acc[ai][bj][m][n] = __builtin_amdgcn_mfma_f32_16x16x32_bf16(Bt[n][k], At[m][k], acc[ai][bj][m][n], 0, 0, 0); __builtin_amdgcn_s_setprio(0); } while (0)
; #define PG8_WAIT_L(n) asm volatile("s_waitcnt lgkmcnt(" #n ")" ::: "memory")
; #define PG8_BAR __builtin_amdgcn_s_barrier()
; #define PG8_SCHED __builtin_amdgcn_sched_barrier(0)
; template <class Epi>
; DI void gemm_phase(LAS unsigned char* lds, const Gemm g, const StaticOrder& S, const Epi& E) {
;     ...
;         for (int t = 0; t < nt; t += 2) {
;             const bool last = (t == nt - 2);
;             const char* a1 = cA + (size_t)(t + 1) * kstep;
;             const char* a2 = last ? nA : cA + (size_t)(t + 2) * kstep; const char* b2 = last ? nB : cB + (size_t)(t + 2) * kstep;
;             const char* a3 = a2 + kstep; const char* b3 = b2 + kstep;
;             PG8_LDB(B0, 0, 0); PG8_SCHED; PG8_LDA(At, 0, 0); PG8_STAGE(PG8_SA(1, 1), a1 + hstep);
;             PG8_WAIT_L(8); PG8_BAR; PG8_WAIT_L(0); PG8_MMA(0, 0, At, B0); PG8_BAR; PG8_SCHED;
;             PG8_LDB(B1, 0, 1); PG8_STAGE(PG8_SB(0, 0), b2);
;             PG8_BAR; PG8_WAIT_L(0); PG8_MMA(0, 1, At, B1); PG8_BAR;
;             PG8_LDA(At, 0, 1); PG8_STAGE(PG8_SA(0, 0), a2);
;             PG8_BAR; PG8_WAIT_L(0); PG8_MMA(1, 0, At, B0); PG8_BAR; PG8_SCHED;
.LBB0_320:
	s_add_u32 s26, s24, 0x100
	s_addc_u32 s27, s25, 0
	s_add_i32 s47, 0, 0x10000
	v_add_u32_e32 v140, s47, v226
	ds_read_b128 v[128:131], v140
	ds_read_b128 v[132:135], v140 offset:1024
	ds_read_b128 v[136:139], v140 offset:2048
	ds_read_b128 v[140:143], v140 offset:3072
	s_cmp_eq_u32 s46, 28
	s_cselect_b32 s31, s4, s27
	s_cselect_b32 s30, s5, s26
	s_cselect_b32 s29, s9, s45
	s_cselect_b32 s28, s11, s33
	v_lshl_add_u64 v[214:215], s[24:25], 0, v[190:191]
	s_add_i32 m0, s38, 0xc000
	ds_read_b128 v[144:147], v228
	ds_read_b128 v[148:151], v228 offset:1024
	ds_read_b128 v[152:155], v228 offset:2048
	ds_read_b128 v[194:197], v228 offset:3072
	ds_read_b128 v[198:201], v228 offset:4096
	ds_read_b128 v[202:205], v228 offset:5120
	ds_read_b128 v[206:209], v228 offset:6144
	ds_read_b128 v[210:213], v228 offset:7168
	global_load_lds_dwordx4 v[214:215], off
	v_lshl_add_u64 v[214:215], s[24:25], 0, v[192:193]
	s_add_i32 m0, s38, 0xe000
	s_nop 0
	global_load_lds_dwordx4 v[214:215], off
	s_waitcnt lgkmcnt(8)
	s_setprio 1
	s_barrier
	s_waitcnt lgkmcnt(0)
	v_mfma_f32_16x16x32_bf16 v[124:127], v[128:131], v[144:147], v[124:127]
	v_mfma_f32_16x16x32_bf16 v[120:123], v[136:139], v[144:147], v[120:123]
	v_mfma_f32_16x16x32_bf16 v[116:119], v[128:131], v[152:155], v[116:119]
	v_mfma_f32_16x16x32_bf16 v[112:115], v[136:139], v[152:155], v[112:115]
	v_mfma_f32_16x16x32_bf16 v[108:111], v[128:131], v[198:201], v[108:111]
	v_mfma_f32_16x16x32_bf16 v[104:107], v[136:139], v[198:201], v[104:107]
	v_mfma_f32_16x16x32_bf16 v[100:103], v[128:131], v[206:209], v[100:103]
	v_mfma_f32_16x16x32_bf16 v[96:99], v[136:139], v[206:209], v[96:99]
	v_mfma_f32_16x16x32_bf16 v[124:127], v[132:135], v[148:151], v[124:127]
	s_add_i32 s48, 0, 0x14000
	v_mfma_f32_16x16x32_bf16 v[120:123], v[140:143], v[148:151], v[120:123]
	s_add_i32 s24, s47, s37
	v_mfma_f32_16x16x32_bf16 v[116:119], v[132:135], v[194:197], v[116:119]
	v_add_u32_e32 v158, s48, v226
	v_mfma_f32_16x16x32_bf16 v[112:115], v[140:143], v[194:197], v[112:115]
	v_lshl_add_u64 v[218:219], s[28:29], 0, v[188:189]
	v_mfma_f32_16x16x32_bf16 v[108:111], v[132:135], v[202:205], v[108:111]
	s_mov_b32 m0, s24
	v_mfma_f32_16x16x32_bf16 v[104:107], v[140:143], v[202:205], v[104:107]
	v_mfma_f32_16x16x32_bf16 v[100:103], v[132:135], v[210:213], v[100:103]
	v_mfma_f32_16x16x32_bf16 v[96:99], v[140:143], v[210:213], v[96:99]
	s_setprio 0
	s_barrier
	ds_read_b128 v[214:217], v158
	ds_read_b128 v[230:233], v158 offset:1024
	ds_read_b128 v[234:237], v158 offset:2048
	ds_read_b128 v[238:241], v158 offset:3072
	global_load_lds_dwordx4 v[218:219], off
	v_lshl_add_u64 v[220:221], s[28:29], 0, v[186:187]
	s_add_i32 m0, s24, 0x2000
	s_nop 0
	global_load_lds_dwordx4 v[220:221], off
	s_waitcnt lgkmcnt(0)
	s_setprio 1
	s_barrier
	v_mfma_f32_16x16x32_bf16 v[60:63], v[214:217], v[144:147], v[60:63]
	v_mfma_f32_16x16x32_bf16 v[56:59], v[234:237], v[144:147], v[56:59]
	v_mfma_f32_16x16x32_bf16 v[52:55], v[214:217], v[152:155], v[52:55]
	v_mfma_f32_16x16x32_bf16 v[48:51], v[234:237], v[152:155], v[48:51]
	v_mfma_f32_16x16x32_bf16 v[44:47], v[214:217], v[198:201], v[44:47]
	v_mfma_f32_16x16x32_bf16 v[40:43], v[234:237], v[198:201], v[40:43]
	v_mfma_f32_16x16x32_bf16 v[36:39], v[214:217], v[206:209], v[36:39]
	v_mfma_f32_16x16x32_bf16 v[32:35], v[234:237], v[206:209], v[32:35]
	v_mfma_f32_16x16x32_bf16 v[60:63], v[230:233], v[148:151], v[60:63]
	s_mov_b32 m0, s38
	v_mfma_f32_16x16x32_bf16 v[56:59], v[238:241], v[148:151], v[56:59]
	v_lshl_add_u64 v[242:243], s[30:31], 0, v[188:189]
	v_mfma_f32_16x16x32_bf16 v[52:55], v[230:233], v[194:197], v[52:55]
	v_mfma_f32_16x16x32_bf16 v[48:51], v[238:241], v[194:197], v[48:51]
	v_mfma_f32_16x16x32_bf16 v[44:47], v[230:233], v[202:205], v[44:47]
	v_mfma_f32_16x16x32_bf16 v[40:43], v[238:241], v[202:205], v[40:43]
	v_mfma_f32_16x16x32_bf16 v[36:39], v[230:233], v[210:213], v[36:39]
	v_mfma_f32_16x16x32_bf16 v[32:35], v[238:241], v[210:213], v[32:35]
	s_setprio 0
	s_barrier
	ds_read_b128 v[144:147], v228 offset:16384
	ds_read_b128 v[148:151], v228 offset:17408
	ds_read_b128 v[152:155], v228 offset:18432
	ds_read_b128 v[194:197], v228 offset:19456
	ds_read_b128 v[198:201], v228 offset:20480
	ds_read_b128 v[202:205], v228 offset:21504
	ds_read_b128 v[206:209], v228 offset:22528
	ds_read_b128 v[210:213], v228 offset:23552
	global_load_lds_dwordx4 v[242:243], off
	v_lshl_add_u64 v[244:245], s[30:31], 0, v[186:187]
	s_mov_b32 m0, s39
	s_nop 0
	global_load_lds_dwordx4 v[244:245], off
	s_waitcnt lgkmcnt(0)
	s_setprio 1
	s_barrier
	v_mfma_f32_16x16x32_bf16 v[92:95], v[128:131], v[144:147], v[92:95]
	v_mfma_f32_16x16x32_bf16 v[88:91], v[136:139], v[144:147], v[88:91]
	v_mfma_f32_16x16x32_bf16 v[84:87], v[128:131], v[152:155], v[84:87]
	v_mfma_f32_16x16x32_bf16 v[80:83], v[136:139], v[152:155], v[80:83]
	v_mfma_f32_16x16x32_bf16 v[76:79], v[128:131], v[198:201], v[76:79]
	v_mfma_f32_16x16x32_bf16 v[72:75], v[136:139], v[198:201], v[72:75]
	v_mfma_f32_16x16x32_bf16 v[68:71], v[128:131], v[206:209], v[68:71]
	v_mfma_f32_16x16x32_bf16 v[64:67], v[136:139], v[206:209], v[64:67]
	v_mfma_f32_16x16x32_bf16 v[92:95], v[132:135], v[148:151], v[92:95]
	s_add_u32 s24, s28, 0x80000
	v_mfma_f32_16x16x32_bf16 v[88:91], v[140:143], v[148:151], v[88:91]
	s_addc_u32 s25, s29, 0
	v_mfma_f32_16x16x32_bf16 v[84:87], v[132:135], v[194:197], v[84:87]
	s_add_i32 s47, s48, s37
	v_mfma_f32_16x16x32_bf16 v[80:83], v[140:143], v[194:197], v[80:83]
	v_lshl_add_u64 v[128:129], s[24:25], 0, v[188:189]
	v_mfma_f32_16x16x32_bf16 v[76:79], v[132:135], v[202:205], v[76:79]
	s_mov_b32 m0, s47
	v_mfma_f32_16x16x32_bf16 v[72:75], v[140:143], v[202:205], v[72:75]
	v_mfma_f32_16x16x32_bf16 v[68:71], v[132:135], v[210:213], v[68:71]
	v_mfma_f32_16x16x32_bf16 v[64:67], v[140:143], v[210:213], v[64:67]
	s_setprio 0
	s_barrier
; #define PG8_STAGE(bufoff, gbase) do { _Pragma("unroll") for (int _i = 0; _i < 2; ++_i) \
;         __builtin_amdgcn_global_load_lds((const unsigned*)((const char*)(gbase) + voff[_i]), (LAS unsigned*)(lds + (bufoff) + ldsw + _i * 8192), 16, 0, 0); } while (0)
; #define PG8_LDA(dst, b, h) do { _Pragma("unroll") for (int m = 0; m < 4; ++m) _Pragma("unroll") for (int k = 0; k < 2; ++k) dst[m][k] = *(const LAS bf16x8*)(lds + PG8_SA(b, h) + aoff + m * 2048 + k * 1024); } while (0)
; #define PG8_LDB(dst, b, h) do { _Pragma("unroll") for (int n = 0; n < 2; ++n) _Pragma("unroll") for (int k = 0; k < 2; ++k) dst[n][k] = *(const LAS bf16x8*)(lds + PG8_SB(b, h) + boff + n * 2048 + k * 1024); } while (0)
; #define PG8_MMA(ai, bj, At, Bt) do { __builtin_amdgcn_s_setprio(1); _Pragma("unroll") for (int m = 0; m < 4; ++m) _Pragma("unroll") for (int n = 0; n < 2; ++n) _Pragma("unroll") for (int k = 0; k < 2; ++k) \
;         acc[ai][bj][m][n] = __builtin_amdgcn_mfma_f32_16x16x32_bf16(Bt[n][k], At[m][k], acc[ai][bj][m][n], 0, 0, 0); __builtin_amdgcn_s_setprio(0); } while (0)
; #define PG8_WAIT_V(n) asm volatile("s_waitcnt vmcnt(" #n ")" ::: "memory")
; #define PG8_WAIT_L(n) asm volatile("s_waitcnt lgkmcnt(" #n ")" ::: "memory")
; #define PG8_BAR __builtin_amdgcn_s_barrier()
; #define PG8_SCHED __builtin_amdgcn_sched_barrier(0)
; template <class Epi>
; DI void gemm_phase(LAS unsigned char* lds, const Gemm g, const StaticOrder& S, const Epi& E) {
;     ...
;             PG8_STAGE(PG8_SB(0, 1), b2 + hstep);
;             PG8_WAIT_V(6); PG8_BAR; PG8_MMA(1, 1, At, B1); PG8_BAR;
;             PG8_LDB(B0, 1, 0); PG8_SCHED; PG8_LDA(At, 1, 0); PG8_STAGE(PG8_SA(0, 1), a2 + hstep);
;             PG8_WAIT_L(8); PG8_BAR; PG8_WAIT_L(0); PG8_MMA(0, 0, At, B0); PG8_BAR; PG8_SCHED;
;             PG8_LDB(B1, 1, 1); PG8_STAGE(PG8_SB(1, 0), b3);
;             PG8_BAR; PG8_WAIT_L(0); PG8_MMA(0, 1, At, B1); PG8_BAR;
;             PG8_LDA(At, 1, 1); PG8_STAGE(PG8_SA(1, 0), a3);
	s_nop 0
	global_load_lds_dwordx4 v[128:129], off
	v_lshl_add_u64 v[128:129], s[24:25], 0, v[186:187]
	s_add_i32 m0, s47, 0x2000
	s_nop 0
	global_load_lds_dwordx4 v[128:129], off
	s_waitcnt vmcnt(6)
	s_setprio 1
	s_barrier
	v_mfma_f32_16x16x32_bf16 v[28:31], v[214:217], v[144:147], v[28:31]
	v_mfma_f32_16x16x32_bf16 v[24:27], v[234:237], v[144:147], v[24:27]
	v_mfma_f32_16x16x32_bf16 v[20:23], v[214:217], v[152:155], v[20:23]
	v_mfma_f32_16x16x32_bf16 v[16:19], v[234:237], v[152:155], v[16:19]
	v_mfma_f32_16x16x32_bf16 v[12:15], v[214:217], v[198:201], v[12:15]
	v_mfma_f32_16x16x32_bf16 v[8:11], v[234:237], v[198:201], v[8:11]
	v_mfma_f32_16x16x32_bf16 v[4:7], v[214:217], v[206:209], v[4:7]
	v_mfma_f32_16x16x32_bf16 v[0:3], v[234:237], v[206:209], v[0:3]
	v_mfma_f32_16x16x32_bf16 v[28:31], v[230:233], v[148:151], v[28:31]
	s_add_i32 s47, 0, 0x18000
	v_mfma_f32_16x16x32_bf16 v[24:27], v[238:241], v[148:151], v[24:27]
	v_add_u32_e32 v140, s47, v226
	v_mfma_f32_16x16x32_bf16 v[20:23], v[230:233], v[194:197], v[20:23]
	v_mfma_f32_16x16x32_bf16 v[16:19], v[238:241], v[194:197], v[16:19]
	v_mfma_f32_16x16x32_bf16 v[12:15], v[230:233], v[202:205], v[12:15]
	v_mfma_f32_16x16x32_bf16 v[8:11], v[238:241], v[202:205], v[8:11]
	v_mfma_f32_16x16x32_bf16 v[4:7], v[230:233], v[210:213], v[4:7]
	v_mfma_f32_16x16x32_bf16 v[0:3], v[238:241], v[210:213], v[0:3]
	s_setprio 0
	s_barrier
	ds_read_b128 v[128:131], v140
	ds_read_b128 v[132:135], v140 offset:1024
	ds_read_b128 v[136:139], v140 offset:2048
	ds_read_b128 v[140:143], v140 offset:3072
	s_add_u32 s24, s30, 0x80000
	s_addc_u32 s25, s31, 0
	s_mov_b32 m0, s40
	v_lshl_add_u64 v[214:215], s[24:25], 0, v[188:189]
	ds_read_b128 v[144:147], v228 offset:32768
	ds_read_b128 v[148:151], v228 offset:33792
	ds_read_b128 v[152:155], v228 offset:34816
	ds_read_b128 v[194:197], v228 offset:35840
	ds_read_b128 v[198:201], v228 offset:36864
	ds_read_b128 v[202:205], v228 offset:37888
	ds_read_b128 v[206:209], v228 offset:38912
	ds_read_b128 v[210:213], v228 offset:39936
	global_load_lds_dwordx4 v[214:215], off
	v_lshl_add_u64 v[214:215], s[24:25], 0, v[186:187]
	s_mov_b32 m0, s41
	s_nop 0
	global_load_lds_dwordx4 v[214:215], off
	s_waitcnt lgkmcnt(8)
	s_setprio 1
	s_barrier
	s_waitcnt lgkmcnt(0)
	v_mfma_f32_16x16x32_bf16 v[124:127], v[128:131], v[144:147], v[124:127]
	v_mfma_f32_16x16x32_bf16 v[120:123], v[136:139], v[144:147], v[120:123]
	v_mfma_f32_16x16x32_bf16 v[116:119], v[128:131], v[152:155], v[116:119]
	v_mfma_f32_16x16x32_bf16 v[112:115], v[136:139], v[152:155], v[112:115]
	v_mfma_f32_16x16x32_bf16 v[108:111], v[128:131], v[198:201], v[108:111]
	v_mfma_f32_16x16x32_bf16 v[104:107], v[136:139], v[198:201], v[104:107]
	v_mfma_f32_16x16x32_bf16 v[100:103], v[128:131], v[206:209], v[100:103]
	v_mfma_f32_16x16x32_bf16 v[96:99], v[136:139], v[206:209], v[96:99]
	v_mfma_f32_16x16x32_bf16 v[124:127], v[132:135], v[148:151], v[124:127]
	s_add_i32 s30, 0, 0x1c000
	v_mfma_f32_16x16x32_bf16 v[120:123], v[140:143], v[148:151], v[120:123]
	s_add_i32 s24, s47, s37
	v_mfma_f32_16x16x32_bf16 v[116:119], v[132:135], v[194:197], v[116:119]
	v_add_u32_e32 v158, s30, v226
	v_mfma_f32_16x16x32_bf16 v[112:115], v[140:143], v[194:197], v[112:115]
	v_lshl_add_u64 v[218:219], v[218:219], 0, s[94:95]
	v_mfma_f32_16x16x32_bf16 v[108:111], v[132:135], v[202:205], v[108:111]
	s_mov_b32 m0, s24
	v_mfma_f32_16x16x32_bf16 v[104:107], v[140:143], v[202:205], v[104:107]
	v_mfma_f32_16x16x32_bf16 v[100:103], v[132:135], v[210:213], v[100:103]
	v_mfma_f32_16x16x32_bf16 v[96:99], v[140:143], v[210:213], v[96:99]
	s_setprio 0
	s_barrier
	ds_read_b128 v[214:217], v158
	ds_read_b128 v[230:233], v158 offset:1024
	ds_read_b128 v[234:237], v158 offset:2048
	ds_read_b128 v[238:241], v158 offset:3072
	global_load_lds_dwordx4 v[218:219], off
	v_lshl_add_u64 v[218:219], v[220:221], 0, s[94:95]
	s_add_i32 m0, s24, 0x2000
	s_nop 0
	global_load_lds_dwordx4 v[218:219], off
	s_waitcnt lgkmcnt(0)
	s_setprio 1
	s_barrier
	v_mfma_f32_16x16x32_bf16 v[60:63], v[214:217], v[144:147], v[60:63]
	v_mfma_f32_16x16x32_bf16 v[56:59], v[234:237], v[144:147], v[56:59]
	v_mfma_f32_16x16x32_bf16 v[52:55], v[214:217], v[152:155], v[52:55]
	v_mfma_f32_16x16x32_bf16 v[48:51], v[234:237], v[152:155], v[48:51]
	v_mfma_f32_16x16x32_bf16 v[44:47], v[214:217], v[198:201], v[44:47]
	v_mfma_f32_16x16x32_bf16 v[40:43], v[234:237], v[198:201], v[40:43]
	v_mfma_f32_16x16x32_bf16 v[36:39], v[214:217], v[206:209], v[36:39]
	v_mfma_f32_16x16x32_bf16 v[32:35], v[234:237], v[206:209], v[32:35]
	v_mfma_f32_16x16x32_bf16 v[60:63], v[230:233], v[148:151], v[60:63]
	s_mov_b32 m0, s42
	v_mfma_f32_16x16x32_bf16 v[56:59], v[238:241], v[148:151], v[56:59]
	v_lshl_add_u64 v[218:219], v[242:243], 0, s[94:95]
	v_mfma_f32_16x16x32_bf16 v[52:55], v[230:233], v[194:197], v[52:55]
	v_mfma_f32_16x16x32_bf16 v[48:51], v[238:241], v[194:197], v[48:51]
	v_mfma_f32_16x16x32_bf16 v[44:47], v[230:233], v[202:205], v[44:47]
	v_mfma_f32_16x16x32_bf16 v[40:43], v[238:241], v[202:205], v[40:43]
	v_mfma_f32_16x16x32_bf16 v[36:39], v[230:233], v[210:213], v[36:39]
	v_mfma_f32_16x16x32_bf16 v[32:35], v[238:241], v[210:213], v[32:35]
	s_setprio 0
	s_barrier
	ds_read_b128 v[144:147], v228 offset:49152
	ds_read_b128 v[148:151], v228 offset:50176
	ds_read_b128 v[152:155], v228 offset:51200
	ds_read_b128 v[194:197], v228 offset:52224
	ds_read_b128 v[198:201], v228 offset:53248
	ds_read_b128 v[202:205], v228 offset:54272
	ds_read_b128 v[206:209], v228 offset:55296
	ds_read_b128 v[210:213], v228 offset:56320
	global_load_lds_dwordx4 v[218:219], off
	v_lshl_add_u64 v[218:219], v[244:245], 0, s[94:95]
	s_mov_b32 m0, s43
	s_nop 0
	global_load_lds_dwordx4 v[218:219], off
	s_waitcnt lgkmcnt(0)
	s_setprio 1
	s_barrier
; #define PG8_WAIT_V(n) asm volatile("s_waitcnt vmcnt(" #n ")" ::: "memory")
; #define PG8_BAR __builtin_amdgcn_s_barrier()
; template <class Epi>
; DI void gemm_phase(LAS unsigned char* lds, const Gemm g, const StaticOrder& S, const Epi& E) {
;     ...
;             PG8_BAR; PG8_WAIT_L(0); PG8_MMA(1, 0, At, B0); PG8_BAR; PG8_SCHED;
;             PG8_STAGE(PG8_SB(1, 1), b3 + hstep);
;             PG8_WAIT_V(6); PG8_BAR; PG8_MMA(1, 1, At, B1); PG8_BAR;
;         }
;     template <bool LN, int BJ, int LO, int HI> DI void batch(const f32x4 (&acc)[2][2][4][2], unsigned row0, unsigned col0, const f32x4 (&gv)[2], const f32x4 (&bv)[2]) const {
;         f32x4 r[HI - LO]; float mean[(HI - LO) / 2], rstd[(HI - LO) / 2];
; #pragma unroll
;         for (int i = LO; i < HI; ++i) { const int ai = i >> 3, m = (i >> 1) & 3, n = i & 1; const unsigned row = row0 + ai * HALF + m * 16;
;             if (n == 0) { mean[(i - LO) >> 1] = 0.f; rstd[(i - LO) >> 1] = 1.f;
;                 if (LN) { const float2 st = *(const float2*)(stats + row * 2u); mean[(i - LO) >> 1] = st.x; rstd[(i - LO) >> 1] = st.y; } }
;             r[i - LO] = *(const f32x4*)(src + (row * (unsigned)DM + col0 + BJ * HALF + n * 16)); }
; #pragma unroll
;         for (int i = LO; i < HI; ++i) { const int ai = i >> 3, m = (i >> 1) & 3, n = i & 1; const unsigned row = row0 + ai * HALF + m * 16;
;             *(f32x4*)(Y + (row * (unsigned)DM + col0 + BJ * HALF + n * 16)) = acc[ai][BJ][m][n] + ((r[i - LO] - mean[(i - LO) >> 1]) * rstd[(i - LO) >> 1]) * gv[n] + bv[n]; }
;         __builtin_amdgcn_sched_barrier(0);
;     }
;     template <bool LN, int BJ> DI void load_gb(unsigned col0, f32x4 (&gv)[2], f32x4 (&bv)[2]) const {
; #pragma unroll
;         for (int n = 0; n < 2; ++n) {
;             if (LN) { gv[n] = *(const f32x4*)(gam + col0 + BJ * HALF + n * 16) * ALPHA; bv[n] = *(const f32x4*)(bet + col0 + BJ * HALF + n * 16) * ALPHA; }
;             else { gv[n] = (f32x4){ALPHA, ALPHA, ALPHA, ALPHA}; bv[n] = (f32x4){0.f, 0.f, 0.f, 0.f}; }
;         }
;     }
;     template <bool LN> DI void run(const f32x4 (&acc)[2][2][4][2], const Unit& u, int wr, int wc, int fr, int fq) const {
;         const unsigned row0 = u.pm * BM + wr * 64 + fr, col0 = u.pn * BM + wc * 32 + 4 * fq;
;         f32x4 gv[2], bv[2];
;         load_gb<LN, 0>(col0, gv, bv);
;         batch<LN, 0, 0, 4>(acc, row0, col0, gv, bv);
	v_mfma_f32_16x16x32_bf16 v[92:95], v[128:131], v[144:147], v[92:95]
	v_mfma_f32_16x16x32_bf16 v[88:91], v[136:139], v[144:147], v[88:91]
	v_mfma_f32_16x16x32_bf16 v[84:87], v[128:131], v[152:155], v[84:87]
	v_mfma_f32_16x16x32_bf16 v[80:83], v[136:139], v[152:155], v[80:83]
	v_mfma_f32_16x16x32_bf16 v[76:79], v[128:131], v[198:201], v[76:79]
	v_mfma_f32_16x16x32_bf16 v[72:75], v[136:139], v[198:201], v[72:75]
	v_mfma_f32_16x16x32_bf16 v[68:71], v[128:131], v[206:209], v[68:71]
	v_mfma_f32_16x16x32_bf16 v[64:67], v[136:139], v[206:209], v[64:67]
	v_mfma_f32_16x16x32_bf16 v[92:95], v[132:135], v[148:151], v[92:95]
	s_add_u32 s24, s28, 0x80080
	v_mfma_f32_16x16x32_bf16 v[88:91], v[140:143], v[148:151], v[88:91]
	s_addc_u32 s25, s29, 0
	v_mfma_f32_16x16x32_bf16 v[84:87], v[132:135], v[194:197], v[84:87]
	s_add_i32 s28, s30, s37
	v_mfma_f32_16x16x32_bf16 v[80:83], v[140:143], v[194:197], v[80:83]
	v_lshl_add_u64 v[128:129], s[24:25], 0, v[188:189]
	v_mfma_f32_16x16x32_bf16 v[76:79], v[132:135], v[202:205], v[76:79]
	s_mov_b32 m0, s28
	v_mfma_f32_16x16x32_bf16 v[72:75], v[140:143], v[202:205], v[72:75]
	v_mfma_f32_16x16x32_bf16 v[68:71], v[132:135], v[210:213], v[68:71]
	v_mfma_f32_16x16x32_bf16 v[64:67], v[140:143], v[210:213], v[64:67]
	s_setprio 0
	s_barrier
	s_nop 0
	global_load_lds_dwordx4 v[128:129], off
	v_lshl_add_u64 v[128:129], s[24:25], 0, v[186:187]
	s_add_i32 m0, s28, 0x2000
	s_nop 0
	global_load_lds_dwordx4 v[128:129], off
	s_waitcnt vmcnt(6)
	s_setprio 1
	s_barrier
	v_mfma_f32_16x16x32_bf16 v[28:31], v[214:217], v[144:147], v[28:31]
	v_mfma_f32_16x16x32_bf16 v[24:27], v[234:237], v[144:147], v[24:27]
	v_mfma_f32_16x16x32_bf16 v[20:23], v[214:217], v[152:155], v[20:23]
	v_mfma_f32_16x16x32_bf16 v[16:19], v[234:237], v[152:155], v[16:19]
	v_mfma_f32_16x16x32_bf16 v[12:15], v[214:217], v[198:201], v[12:15]
	v_mfma_f32_16x16x32_bf16 v[8:11], v[234:237], v[198:201], v[8:11]
	v_mfma_f32_16x16x32_bf16 v[4:7], v[214:217], v[206:209], v[4:7]
	v_mfma_f32_16x16x32_bf16 v[0:3], v[234:237], v[206:209], v[0:3]
	v_mfma_f32_16x16x32_bf16 v[28:31], v[230:233], v[148:151], v[28:31]
	s_add_i32 s46, s46, 2
	v_mfma_f32_16x16x32_bf16 v[24:27], v[238:241], v[148:151], v[24:27]
	s_add_u32 s33, s33, 0x100
	v_mfma_f32_16x16x32_bf16 v[20:23], v[230:233], v[194:197], v[20:23]
	s_addc_u32 s45, s45, 0
	v_mfma_f32_16x16x32_bf16 v[16:19], v[238:241], v[194:197], v[16:19]
	s_cmp_gt_u32 s46, 29
	v_mfma_f32_16x16x32_bf16 v[12:15], v[230:233], v[202:205], v[12:15]
	s_mov_b64 s[24:25], s[26:27]
	v_mfma_f32_16x16x32_bf16 v[8:11], v[238:241], v[202:205], v[8:11]
	v_mfma_f32_16x16x32_bf16 v[4:7], v[230:233], v[210:213], v[4:7]
	v_mfma_f32_16x16x32_bf16 v[0:3], v[238:241], v[210:213], v[0:3]
	s_setprio 0
	s_barrier
	s_cbranch_scc0 .LBB0_320
	v_lshl_add_u32 v206, s3, 8, v225
	v_lshl_or_b32 v158, s2, 8, v227
	v_lshlrev_b32_e32 v232, 11, v206
	s_andn2_b64 vcc, exec, s[14:15]
	v_or_b32_e32 v231, 16, v158
	v_add_u32_e32 v194, v232, v158
	v_or_b32_e32 v230, 0x80, v158
	v_or_b32_e32 v229, 0x90, v158
	s_cbranch_vccnz .LBB0_323
	v_lshlrev_b64 v[132:133], 2, v[158:159]
	v_lshl_add_u64 v[140:141], s[16:17], 0, v[132:133]
	global_load_dwordx4 v[128:131], v[140:141], off
	v_lshl_add_u64 v[142:143], s[18:19], 0, v[132:133]
	v_readlane_b32 s2, v253, 8
	v_mov_b32_e32 v195, v159
	v_lshlrev_b32_e32 v136, 1, v206
	v_mov_b32_e32 v137, v159
	v_readlane_b32 s3, v253, 9
	v_lshlrev_b64 v[212:213], 2, v[194:195]
	v_add_u32_e32 v146, v232, v231
	v_lshl_add_u64 v[144:145], v[136:137], 2, s[2:3]
	v_lshl_add_u64 v[136:137], s[88:89], 0, v[212:213]
	v_mov_b32_e32 v147, v159
	v_lshl_add_u64 v[146:147], v[146:147], 2, s[88:89]
	v_or_b32_e32 v195, 16, v206
	v_mov_b32_e32 v201, v159
	v_mov_b32_e32 v209, v159
	v_lshl_add_u64 v[212:213], s[90:91], 0, v[212:213]
	s_waitcnt vmcnt(0)
	v_pk_mul_f32 v[152:153], v[130:131], s[78:79] op_sel_hi:[1,0]
	v_pk_mul_f32 v[154:155], v[128:129], s[78:79] op_sel_hi:[1,0]
	global_load_dwordx4 v[132:135], v[142:143], off
	global_load_dwordx4 v[128:131], v[140:141], off offset:64
	global_load_dwordx2 v[204:205], v[144:145], off
	global_load_dwordx4 v[196:199], v[146:147], off
	v_lshlrev_b32_e32 v146, 1, v195
	global_load_dwordx4 v[136:139], v[136:137], off
	v_lshlrev_b32_e32 v195, 11, v195
	v_mov_b32_e32 v147, v159
	v_add_u32_e32 v200, v195, v158
	v_lshl_add_u64 v[146:147], v[146:147], 2, s[2:3]
	v_lshl_add_u64 v[200:201], v[200:201], 2, s[88:89]
	global_load_dwordx2 v[214:215], v[146:147], off
	v_add_u32_e32 v208, v195, v231
	global_load_dwordx4 v[200:203], v[200:201], off
	v_lshl_add_u64 v[208:209], v[208:209], 2, s[88:89]
	global_load_dwordx4 v[208:211], v[208:209], off
	s_waitcnt vmcnt(0)
	v_pk_mul_f32 v[148:149], v[130:131], s[78:79] op_sel_hi:[1,0]
	v_pk_mul_f32 v[150:151], v[128:129], s[78:79] op_sel_hi:[1,0]
	global_load_dwordx4 v[128:131], v[142:143], off offset:64
	v_sub_f32_e32 v137, v137, v204
	v_sub_f32_e32 v136, v136, v204
	v_sub_f32_e32 v139, v139, v204
	v_sub_f32_e32 v138, v138, v204
	v_pk_mul_f32 v[138:139], v[204:205], v[138:139] op_sel:[1,0]
	v_pk_mul_f32 v[136:137], v[204:205], v[136:137] op_sel:[1,0]
	v_pk_fma_f32 v[138:139], v[152:153], v[138:139], v[126:127]
	v_pk_fma_f32 v[136:137], v[154:155], v[136:137], v[124:125]
	v_pk_fma_f32 v[138:139], v[134:135], s[78:79], v[138:139] op_sel_hi:[1,0,1]
	v_pk_fma_f32 v[136:137], v[132:133], s[78:79], v[136:137] op_sel_hi:[1,0,1]
	global_store_dwordx4 v[212:213], v[136:139], off
	s_nop 1
	v_sub_f32_e32 v137, v197, v204
	v_sub_f32_e32 v136, v196, v204
	v_sub_f32_e32 v139, v199, v204
	v_sub_f32_e32 v138, v198, v204
	v_pk_mul_f32 v[138:139], v[204:205], v[138:139] op_sel:[1,0]
	v_pk_mul_f32 v[136:137], v[204:205], v[136:137] op_sel:[1,0]
	v_pk_fma_f32 v[138:139], v[148:149], v[138:139], v[122:123]
	v_pk_fma_f32 v[136:137], v[150:151], v[136:137], v[120:121]
	v_or_b32_e32 v196, 16, v194
	v_mov_b32_e32 v197, v159
	v_lshl_add_u64 v[196:197], v[196:197], 2, s[90:91]
	s_waitcnt vmcnt(0)
;     template <bool LN, int BJ, int LO, int HI> DI void batch(const f32x4 (&acc)[2][2][4][2], unsigned row0, unsigned col0, const f32x4 (&gv)[2], const f32x4 (&bv)[2]) const {
;         f32x4 r[HI - LO]; float mean[(HI - LO) / 2], rstd[(HI - LO) / 2];
; #pragma unroll
;         for (int i = LO; i < HI; ++i) { const int ai = i >> 3, m = (i >> 1) & 3, n = i & 1; const unsigned row = row0 + ai * HALF + m * 16;
;             if (n == 0) { mean[(i - LO) >> 1] = 0.f; rstd[(i - LO) >> 1] = 1.f;
;                 if (LN) { const float2 st = *(const float2*)(stats + row * 2u); mean[(i - LO) >> 1] = st.x; rstd[(i - LO) >> 1] = st.y; } }
;             r[i - LO] = *(const f32x4*)(src + (row * (unsigned)DM + col0 + BJ * HALF + n * 16)); }
; #pragma unroll
;         for (int i = LO; i < HI; ++i) { const int ai = i >> 3, m = (i >> 1) & 3, n = i & 1; const unsigned row = row0 + ai * HALF + m * 16;
;             *(f32x4*)(Y + (row * (unsigned)DM + col0 + BJ * HALF + n * 16)) = acc[ai][BJ][m][n] + ((r[i - LO] - mean[(i - LO) >> 1]) * rstd[(i - LO) >> 1]) * gv[n] + bv[n]; }
;         __builtin_amdgcn_sched_barrier(0);
;     }
;     template <bool LN, int BJ> DI void load_gb(unsigned col0, f32x4 (&gv)[2], f32x4 (&bv)[2]) const {
; #pragma unroll
;         for (int n = 0; n < 2; ++n) {
;             if (LN) { gv[n] = *(const f32x4*)(gam + col0 + BJ * HALF + n * 16) * ALPHA; bv[n] = *(const f32x4*)(bet + col0 + BJ * HALF + n * 16) * ALPHA; }
;             else { gv[n] = (f32x4){ALPHA, ALPHA, ALPHA, ALPHA}; bv[n] = (f32x4){0.f, 0.f, 0.f, 0.f}; }
;         }
;     }
;     template <bool LN> DI void run(const f32x4 (&acc)[2][2][4][2], const Unit& u, int wr, int wc, int fr, int fq) const {
;         const unsigned row0 = u.pm * BM + wr * 64 + fr, col0 = u.pn * BM + wc * 32 + 4 * fq;
;         f32x4 gv[2], bv[2];
;         load_gb<LN, 0>(col0, gv, bv);
;         batch<LN, 0, 0, 4>(acc, row0, col0, gv, bv);
;         batch<LN, 0, 4, 8>(acc, row0, col0, gv, bv);
;         batch<LN, 0, 8, 12>(acc, row0, col0, gv, bv);
;         batch<LN, 0, 12, 16>(acc, row0, col0, gv, bv);
;         load_gb<LN, 1>(col0, gv, bv);
;         batch<LN, 1, 0, 8>(acc, row0, col0, gv, bv);
;         batch<LN, 1, 8, 16>(acc, row0, col0, gv, bv);
	v_pk_fma_f32 v[138:139], v[130:131], s[78:79], v[138:139] op_sel_hi:[1,0,1]
	v_pk_fma_f32 v[136:137], v[128:129], s[78:79], v[136:137] op_sel_hi:[1,0,1]
	global_store_dwordx4 v[196:197], v[136:139], off
	v_add_u32_e32 v196, 0x8000, v194
	v_mov_b32_e32 v197, v159
	v_sub_f32_e32 v137, v201, v214
	v_sub_f32_e32 v136, v200, v214
	v_sub_f32_e32 v139, v203, v214
	v_sub_f32_e32 v138, v202, v214
	v_pk_mul_f32 v[138:139], v[214:215], v[138:139] op_sel:[1,0]
	v_pk_mul_f32 v[136:137], v[214:215], v[136:137] op_sel:[1,0]
	v_pk_fma_f32 v[138:139], v[152:153], v[138:139], v[118:119]
	v_pk_fma_f32 v[136:137], v[154:155], v[136:137], v[116:117]
	v_pk_fma_f32 v[138:139], v[134:135], s[78:79], v[138:139] op_sel_hi:[1,0,1]
	v_pk_fma_f32 v[136:137], v[132:133], s[78:79], v[136:137] op_sel_hi:[1,0,1]
	v_lshl_add_u64 v[196:197], v[196:197], 2, s[90:91]
	global_store_dwordx4 v[196:197], v[136:139], off
	v_add_u32_e32 v196, 0x8010, v194
	v_mov_b32_e32 v197, v159
	v_sub_f32_e32 v137, v209, v214
	v_sub_f32_e32 v136, v208, v214
	v_sub_f32_e32 v139, v211, v214
	v_sub_f32_e32 v138, v210, v214
	v_pk_mul_f32 v[138:139], v[214:215], v[138:139] op_sel:[1,0]
	v_pk_mul_f32 v[136:137], v[214:215], v[136:137] op_sel:[1,0]
	v_pk_fma_f32 v[138:139], v[148:149], v[138:139], v[114:115]
	v_pk_fma_f32 v[136:137], v[150:151], v[136:137], v[112:113]
	v_pk_fma_f32 v[138:139], v[130:131], s[78:79], v[138:139] op_sel_hi:[1,0,1]
	v_pk_fma_f32 v[136:137], v[128:129], s[78:79], v[136:137] op_sel_hi:[1,0,1]
	v_lshl_add_u64 v[196:197], v[196:197], 2, s[90:91]
	global_store_dwordx4 v[196:197], v[136:139], off
	s_nop 1
	v_or_b32_e32 v138, 32, v206
	v_lshlrev_b32_e32 v136, 1, v138
	v_mov_b32_e32 v137, v159
	v_lshlrev_b32_e32 v236, 11, v138
	v_lshl_add_u64 v[200:201], v[136:137], 2, s[2:3]
	v_add_u32_e32 v136, v236, v158
	v_lshl_add_u64 v[136:137], v[136:137], 2, s[88:89]
	global_load_dwordx2 v[204:205], v[200:201], off
	v_add_u32_e32 v196, v236, v231
	global_load_dwordx4 v[136:139], v[136:137], off
	v_mov_b32_e32 v197, v159
	v_lshl_add_u64 v[196:197], v[196:197], 2, s[88:89]
	global_load_dwordx4 v[196:199], v[196:197], off
	v_or_b32_e32 v207, 48, v206
	v_lshlrev_b32_e32 v235, 11, v207
	v_lshlrev_b32_e32 v202, 1, v207
	v_mov_b32_e32 v203, v159
	v_add_u32_e32 v208, v235, v158
	v_mov_b32_e32 v209, v159
	v_lshl_add_u64 v[202:203], v[202:203], 2, s[2:3]
	v_lshl_add_u64 v[208:209], v[208:209], 2, s[88:89]
	global_load_dwordx2 v[216:217], v[202:203], off
	v_add_u32_e32 v212, v235, v231
	global_load_dwordx4 v[208:211], v[208:209], off
	v_mov_b32_e32 v213, v159
	v_lshl_add_u64 v[212:213], v[212:213], 2, s[88:89]
	global_load_dwordx4 v[212:215], v[212:213], off
	v_add_u32_e32 v218, 0x10000, v194
	v_mov_b32_e32 v219, v159
	v_lshl_add_u64 v[218:219], v[218:219], 2, s[90:91]
	s_waitcnt vmcnt(0)
	v_sub_f32_e32 v137, v137, v204
	v_sub_f32_e32 v136, v136, v204
	v_sub_f32_e32 v139, v139, v204
	v_sub_f32_e32 v138, v138, v204
	v_pk_mul_f32 v[138:139], v[204:205], v[138:139] op_sel:[1,0]
	v_pk_mul_f32 v[136:137], v[204:205], v[136:137] op_sel:[1,0]
	v_pk_fma_f32 v[138:139], v[152:153], v[138:139], v[110:111]
	v_pk_fma_f32 v[136:137], v[154:155], v[136:137], v[108:109]
	v_pk_fma_f32 v[138:139], v[134:135], s[78:79], v[138:139] op_sel_hi:[1,0,1]
	v_pk_fma_f32 v[136:137], v[132:133], s[78:79], v[136:137] op_sel_hi:[1,0,1]
	global_store_dwordx4 v[218:219], v[136:139], off
	s_nop 1
	v_sub_f32_e32 v137, v197, v204
	v_sub_f32_e32 v136, v196, v204
	v_sub_f32_e32 v139, v199, v204
	v_sub_f32_e32 v138, v198, v204
	v_pk_mul_f32 v[138:139], v[204:205], v[138:139] op_sel:[1,0]
	v_pk_mul_f32 v[136:137], v[204:205], v[136:137] op_sel:[1,0]
	v_pk_fma_f32 v[138:139], v[148:149], v[138:139], v[106:107]
	v_pk_fma_f32 v[136:137], v[150:151], v[136:137], v[104:105]
	v_add_u32_e32 v196, 0x10010, v194
	v_mov_b32_e32 v197, v159
	v_pk_fma_f32 v[138:139], v[130:131], s[78:79], v[138:139] op_sel_hi:[1,0,1]
	v_pk_fma_f32 v[136:137], v[128:129], s[78:79], v[136:137] op_sel_hi:[1,0,1]
	v_lshl_add_u64 v[196:197], v[196:197], 2, s[90:91]
	global_store_dwordx4 v[196:197], v[136:139], off
	v_add_u32_e32 v196, 0x18000, v194
	v_mov_b32_e32 v197, v159
	v_sub_f32_e32 v137, v209, v216
	v_sub_f32_e32 v136, v208, v216
	v_sub_f32_e32 v139, v211, v216
	v_sub_f32_e32 v138, v210, v216
	v_pk_mul_f32 v[138:139], v[216:217], v[138:139] op_sel:[1,0]
	v_pk_mul_f32 v[136:137], v[216:217], v[136:137] op_sel:[1,0]
	v_pk_fma_f32 v[138:139], v[152:153], v[138:139], v[102:103]
	v_pk_fma_f32 v[136:137], v[154:155], v[136:137], v[100:101]
	v_pk_fma_f32 v[138:139], v[134:135], s[78:79], v[138:139] op_sel_hi:[1,0,1]
	v_pk_fma_f32 v[136:137], v[132:133], s[78:79], v[136:137] op_sel_hi:[1,0,1]
	v_lshl_add_u64 v[196:197], v[196:197], 2, s[90:91]
	global_store_dwordx4 v[196:197], v[136:139], off
	v_add_u32_e32 v196, 0x18010, v194
	v_mov_b32_e32 v197, v159
	v_sub_f32_e32 v137, v213, v216
	v_sub_f32_e32 v136, v212, v216
	v_sub_f32_e32 v139, v215, v216
	v_sub_f32_e32 v138, v214, v216
	v_pk_mul_f32 v[138:139], v[216:217], v[138:139] op_sel:[1,0]
	v_pk_mul_f32 v[136:137], v[216:217], v[136:137] op_sel:[1,0]
	v_pk_fma_f32 v[138:139], v[148:149], v[138:139], v[98:99]
	v_pk_fma_f32 v[136:137], v[150:151], v[136:137], v[96:97]
	v_pk_fma_f32 v[138:139], v[130:131], s[78:79], v[138:139] op_sel_hi:[1,0,1]
	v_pk_fma_f32 v[136:137], v[128:129], s[78:79], v[136:137] op_sel_hi:[1,0,1]
	v_lshl_add_u64 v[196:197], v[196:197], 2, s[90:91]
	global_store_dwordx4 v[196:197], v[136:139], off
	s_nop 1
	v_add_u32_e32 v138, 0x80, v206
	v_lshlrev_b32_e32 v136, 1, v138
	v_mov_b32_e32 v137, v159
	v_lshlrev_b32_e32 v233, 11, v138
	v_lshl_add_u64 v[196:197], v[136:137], 2, s[2:3]
	v_add_u32_e32 v136, v233, v158
	v_lshl_add_u64 v[136:137], v[136:137], 2, s[88:89]
	global_load_dwordx2 v[204:205], v[196:197], off
	v_add_u32_e32 v198, v233, v231
	global_load_dwordx4 v[136:139], v[136:137], off
	v_mov_b32_e32 v199, v159
	v_add_u32_e32 v207, 0x90, v206
	v_lshl_add_u64 v[198:199], v[198:199], 2, s[88:89]
	v_lshlrev_b32_e32 v234, 11, v207
	global_load_dwordx4 v[208:211], v[198:199], off
	v_add_u32_e32 v212, v234, v158
	v_mov_b32_e32 v213, v159
	v_lshl_add_u64 v[212:213], v[212:213], 2, s[88:89]
	global_load_dwordx4 v[212:215], v[212:213], off
	v_lshlrev_b32_e32 v198, 1, v207
	v_mov_b32_e32 v199, v159
	v_lshl_add_u64 v[198:199], v[198:199], 2, s[2:3]
	global_load_dwordx2 v[238:239], v[198:199], off
	v_add_u32_e32 v216, v234, v231
	v_mov_b32_e32 v217, v159
	v_lshl_add_u64 v[216:217], v[216:217], 2, s[88:89]
	global_load_dwordx4 v[216:219], v[216:217], off
	v_add_u32_e32 v240, 0x40000, v194
	v_mov_b32_e32 v241, v159
	v_lshl_add_u64 v[240:241], v[240:241], 2, s[90:91]
	s_waitcnt vmcnt(0)
;     template <bool LN, int BJ, int LO, int HI> DI void batch(const f32x4 (&acc)[2][2][4][2], unsigned row0, unsigned col0, const f32x4 (&gv)[2], const f32x4 (&bv)[2]) const {
;         f32x4 r[HI - LO]; float mean[(HI - LO) / 2], rstd[(HI - LO) / 2];
; #pragma unroll
;         for (int i = LO; i < HI; ++i) { const int ai = i >> 3, m = (i >> 1) & 3, n = i & 1; const unsigned row = row0 + ai * HALF + m * 16;
;             if (n == 0) { mean[(i - LO) >> 1] = 0.f; rstd[(i - LO) >> 1] = 1.f;
;                 if (LN) { const float2 st = *(const float2*)(stats + row * 2u); mean[(i - LO) >> 1] = st.x; rstd[(i - LO) >> 1] = st.y; } }
;             r[i - LO] = *(const f32x4*)(src + (row * (unsigned)DM + col0 + BJ * HALF + n * 16)); }
; #pragma unroll
;         for (int i = LO; i < HI; ++i) { const int ai = i >> 3, m = (i >> 1) & 3, n = i & 1; const unsigned row = row0 + ai * HALF + m * 16;
;             *(f32x4*)(Y + (row * (unsigned)DM + col0 + BJ * HALF + n * 16)) = acc[ai][BJ][m][n] + ((r[i - LO] - mean[(i - LO) >> 1]) * rstd[(i - LO) >> 1]) * gv[n] + bv[n]; }
;         __builtin_amdgcn_sched_barrier(0);
;     }
;     template <bool LN, int BJ> DI void load_gb(unsigned col0, f32x4 (&gv)[2], f32x4 (&bv)[2]) const {
; #pragma unroll
;         for (int n = 0; n < 2; ++n) {
;             if (LN) { gv[n] = *(const f32x4*)(gam + col0 + BJ * HALF + n * 16) * ALPHA; bv[n] = *(const f32x4*)(bet + col0 + BJ * HALF + n * 16) * ALPHA; }
;             else { gv[n] = (f32x4){ALPHA, ALPHA, ALPHA, ALPHA}; bv[n] = (f32x4){0.f, 0.f, 0.f, 0.f}; }
;         }
;     }
;     template <bool LN> DI void run(const f32x4 (&acc)[2][2][4][2], const Unit& u, int wr, int wc, int fr, int fq) const {
;         const unsigned row0 = u.pm * BM + wr * 64 + fr, col0 = u.pn * BM + wc * 32 + 4 * fq;
;         f32x4 gv[2], bv[2];
;         load_gb<LN, 0>(col0, gv, bv);
;         batch<LN, 0, 0, 4>(acc, row0, col0, gv, bv);
;         batch<LN, 0, 4, 8>(acc, row0, col0, gv, bv);
;         batch<LN, 0, 8, 12>(acc, row0, col0, gv, bv);
;         batch<LN, 0, 12, 16>(acc, row0, col0, gv, bv);
;         load_gb<LN, 1>(col0, gv, bv);
;         batch<LN, 1, 0, 8>(acc, row0, col0, gv, bv);
;         batch<LN, 1, 8, 16>(acc, row0, col0, gv, bv);
	v_sub_f32_e32 v137, v137, v204
	v_sub_f32_e32 v136, v136, v204
	v_sub_f32_e32 v139, v139, v204
	v_sub_f32_e32 v138, v138, v204
	v_pk_mul_f32 v[138:139], v[204:205], v[138:139] op_sel:[1,0]
	v_pk_mul_f32 v[136:137], v[204:205], v[136:137] op_sel:[1,0]
	v_pk_fma_f32 v[138:139], v[152:153], v[138:139], v[94:95]
	v_pk_fma_f32 v[136:137], v[154:155], v[136:137], v[92:93]
	v_pk_fma_f32 v[138:139], v[134:135], s[78:79], v[138:139] op_sel_hi:[1,0,1]
	v_pk_fma_f32 v[136:137], v[132:133], s[78:79], v[136:137] op_sel_hi:[1,0,1]
	global_store_dwordx4 v[240:241], v[136:139], off
	s_nop 1
	v_sub_f32_e32 v137, v209, v204
	v_sub_f32_e32 v136, v208, v204
	v_sub_f32_e32 v139, v211, v204
	v_sub_f32_e32 v138, v210, v204
	v_pk_mul_f32 v[138:139], v[204:205], v[138:139] op_sel:[1,0]
	v_pk_mul_f32 v[136:137], v[204:205], v[136:137] op_sel:[1,0]
	v_pk_fma_f32 v[138:139], v[148:149], v[138:139], v[90:91]
	v_pk_fma_f32 v[136:137], v[150:151], v[136:137], v[88:89]
	v_add_u32_e32 v204, 0x40010, v194
	v_mov_b32_e32 v205, v159
	v_pk_fma_f32 v[138:139], v[130:131], s[78:79], v[138:139] op_sel_hi:[1,0,1]
	v_pk_fma_f32 v[136:137], v[128:129], s[78:79], v[136:137] op_sel_hi:[1,0,1]
	v_lshl_add_u64 v[204:205], v[204:205], 2, s[90:91]
	global_store_dwordx4 v[204:205], v[136:139], off
	v_add_u32_e32 v204, 0x48000, v194
	v_mov_b32_e32 v205, v159
	v_sub_f32_e32 v137, v213, v238
	v_sub_f32_e32 v136, v212, v238
	v_sub_f32_e32 v139, v215, v238
	v_sub_f32_e32 v138, v214, v238
	v_pk_mul_f32 v[138:139], v[238:239], v[138:139] op_sel:[1,0]
	v_pk_mul_f32 v[136:137], v[238:239], v[136:137] op_sel:[1,0]
	v_pk_fma_f32 v[138:139], v[152:153], v[138:139], v[86:87]
	v_pk_fma_f32 v[136:137], v[154:155], v[136:137], v[84:85]
	v_pk_fma_f32 v[138:139], v[134:135], s[78:79], v[138:139] op_sel_hi:[1,0,1]
	v_pk_fma_f32 v[136:137], v[132:133], s[78:79], v[136:137] op_sel_hi:[1,0,1]
	v_lshl_add_u64 v[204:205], v[204:205], 2, s[90:91]
	global_store_dwordx4 v[204:205], v[136:139], off
	v_add_u32_e32 v204, 0x48010, v194
	v_mov_b32_e32 v205, v159
	v_sub_f32_e32 v137, v217, v238
	v_sub_f32_e32 v136, v216, v238
	v_sub_f32_e32 v139, v219, v238
	v_sub_f32_e32 v138, v218, v238
	v_pk_mul_f32 v[138:139], v[238:239], v[138:139] op_sel:[1,0]
	v_pk_mul_f32 v[136:137], v[238:239], v[136:137] op_sel:[1,0]
	v_pk_fma_f32 v[138:139], v[148:149], v[138:139], v[82:83]
	v_pk_fma_f32 v[136:137], v[150:151], v[136:137], v[80:81]
	v_pk_fma_f32 v[138:139], v[130:131], s[78:79], v[138:139] op_sel_hi:[1,0,1]
	v_pk_fma_f32 v[136:137], v[128:129], s[78:79], v[136:137] op_sel_hi:[1,0,1]
	v_lshl_add_u64 v[204:205], v[204:205], 2, s[90:91]
	global_store_dwordx4 v[204:205], v[136:139], off
	s_nop 1
	v_add_u32_e32 v138, 0xa0, v206
	v_lshlrev_b32_e32 v136, 1, v138
	v_mov_b32_e32 v137, v159
	v_lshlrev_b32_e32 v237, 11, v138
	v_lshl_add_u64 v[204:205], v[136:137], 2, s[2:3]
	v_add_u32_e32 v136, v237, v158
	v_lshl_add_u64 v[136:137], v[136:137], 2, s[88:89]
	global_load_dwordx2 v[240:241], v[204:205], off
	v_add_u32_e32 v208, v237, v231
	global_load_dwordx4 v[136:139], v[136:137], off
	v_mov_b32_e32 v209, v159
	v_lshl_add_u64 v[208:209], v[208:209], 2, s[88:89]
	global_load_dwordx4 v[212:215], v[208:209], off
	v_add_u32_e32 v208, 0xb0, v206
	v_lshlrev_b32_e32 v206, 1, v208
	v_mov_b32_e32 v207, v159
	v_lshlrev_b32_e32 v238, 11, v208
	v_lshl_add_u64 v[210:211], v[206:207], 2, s[2:3]
	v_add_u32_e32 v206, v238, v158
	v_lshl_add_u64 v[206:207], v[206:207], 2, s[88:89]
	global_load_dwordx2 v[242:243], v[210:211], off
	v_add_u32_e32 v216, v238, v231
	global_load_dwordx4 v[206:209], v[206:207], off
	v_mov_b32_e32 v217, v159
	v_lshl_add_u64 v[216:217], v[216:217], 2, s[88:89]
	global_load_dwordx4 v[216:219], v[216:217], off
	v_add_u32_e32 v244, 0x50000, v194
	v_mov_b32_e32 v245, v159
	v_lshl_add_u64 v[244:245], v[244:245], 2, s[90:91]
	s_waitcnt vmcnt(0)
	v_sub_f32_e32 v137, v137, v240
	v_sub_f32_e32 v136, v136, v240
	v_sub_f32_e32 v139, v139, v240
	v_sub_f32_e32 v138, v138, v240
	v_pk_mul_f32 v[138:139], v[240:241], v[138:139] op_sel:[1,0]
	v_pk_mul_f32 v[136:137], v[240:241], v[136:137] op_sel:[1,0]
	v_pk_fma_f32 v[138:139], v[152:153], v[138:139], v[78:79]
	v_pk_fma_f32 v[136:137], v[154:155], v[136:137], v[76:77]
	v_pk_fma_f32 v[138:139], v[134:135], s[78:79], v[138:139] op_sel_hi:[1,0,1]
	v_pk_fma_f32 v[136:137], v[132:133], s[78:79], v[136:137] op_sel_hi:[1,0,1]
	global_store_dwordx4 v[244:245], v[136:139], off
	s_nop 1
	v_sub_f32_e32 v137, v213, v240
	v_sub_f32_e32 v136, v212, v240
	v_sub_f32_e32 v139, v215, v240
	v_sub_f32_e32 v138, v214, v240
	v_pk_mul_f32 v[138:139], v[240:241], v[138:139] op_sel:[1,0]
	v_pk_mul_f32 v[136:137], v[240:241], v[136:137] op_sel:[1,0]
	v_pk_fma_f32 v[138:139], v[148:149], v[138:139], v[74:75]
	v_pk_fma_f32 v[136:137], v[150:151], v[136:137], v[72:73]
	v_add_u32_e32 v212, 0x50010, v194
	v_mov_b32_e32 v213, v159
	v_pk_fma_f32 v[138:139], v[130:131], s[78:79], v[138:139] op_sel_hi:[1,0,1]
	v_pk_fma_f32 v[136:137], v[128:129], s[78:79], v[136:137] op_sel_hi:[1,0,1]
	v_lshl_add_u64 v[212:213], v[212:213], 2, s[90:91]
	global_store_dwordx4 v[212:213], v[136:139], off
	s_nop 1
	v_sub_f32_e32 v137, v207, v242
	v_sub_f32_e32 v136, v206, v242
	v_sub_f32_e32 v139, v209, v242
	v_sub_f32_e32 v138, v208, v242
	v_pk_mul_f32 v[136:137], v[242:243], v[136:137] op_sel:[1,0]
	v_pk_mul_f32 v[138:139], v[242:243], v[138:139] op_sel:[1,0]
	v_pk_fma_f32 v[136:137], v[154:155], v[136:137], v[68:69]
	v_pk_fma_f32 v[138:139], v[152:153], v[138:139], v[70:71]
	v_pk_fma_f32 v[132:133], v[132:133], s[78:79], v[136:137] op_sel_hi:[1,0,1]
	v_add_u32_e32 v136, 0x58000, v194
	v_mov_b32_e32 v137, v159
	v_pk_fma_f32 v[134:135], v[134:135], s[78:79], v[138:139] op_sel_hi:[1,0,1]
	v_lshl_add_u64 v[136:137], v[136:137], 2, s[90:91]
	global_store_dwordx4 v[136:137], v[132:135], off
	s_nop 1
	v_sub_f32_e32 v133, v217, v242
	v_sub_f32_e32 v132, v216, v242
	v_sub_f32_e32 v135, v219, v242
	v_sub_f32_e32 v134, v218, v242
	v_pk_mul_f32 v[132:133], v[242:243], v[132:133] op_sel:[1,0]
	v_pk_mul_f32 v[134:135], v[242:243], v[134:135] op_sel:[1,0]
	v_pk_fma_f32 v[132:133], v[150:151], v[132:133], v[64:65]
	v_pk_fma_f32 v[134:135], v[148:149], v[134:135], v[66:67]
	v_pk_fma_f32 v[128:129], v[128:129], s[78:79], v[132:133] op_sel_hi:[1,0,1]
	v_add_u32_e32 v132, 0x58010, v194
	v_mov_b32_e32 v133, v159
	v_pk_fma_f32 v[130:131], v[130:131], s[78:79], v[134:135] op_sel_hi:[1,0,1]
	v_lshl_add_u64 v[132:133], v[132:133], 2, s[90:91]
	global_store_dwordx4 v[132:133], v[128:131], off
	global_load_dwordx4 v[128:131], v[140:141], off offset:512
	v_add_u32_e32 v136, v232, v230
	v_mov_b32_e32 v137, v159
	v_lshl_add_u64 v[136:137], v[136:137], 2, s[88:89]
	s_waitcnt vmcnt(0)
;     template <bool LN, int BJ, int LO, int HI> DI void batch(const f32x4 (&acc)[2][2][4][2], unsigned row0, unsigned col0, const f32x4 (&gv)[2], const f32x4 (&bv)[2]) const {
;         f32x4 r[HI - LO]; float mean[(HI - LO) / 2], rstd[(HI - LO) / 2];
; #pragma unroll
;         for (int i = LO; i < HI; ++i) { const int ai = i >> 3, m = (i >> 1) & 3, n = i & 1; const unsigned row = row0 + ai * HALF + m * 16;
;             if (n == 0) { mean[(i - LO) >> 1] = 0.f; rstd[(i - LO) >> 1] = 1.f;
;                 if (LN) { const float2 st = *(const float2*)(stats + row * 2u); mean[(i - LO) >> 1] = st.x; rstd[(i - LO) >> 1] = st.y; } }
;             r[i - LO] = *(const f32x4*)(src + (row * (unsigned)DM + col0 + BJ * HALF + n * 16)); }
; #pragma unroll
;         for (int i = LO; i < HI; ++i) { const int ai = i >> 3, m = (i >> 1) & 3, n = i & 1; const unsigned row = row0 + ai * HALF + m * 16;
;             *(f32x4*)(Y + (row * (unsigned)DM + col0 + BJ * HALF + n * 16)) = acc[ai][BJ][m][n] + ((r[i - LO] - mean[(i - LO) >> 1]) * rstd[(i - LO) >> 1]) * gv[n] + bv[n]; }
;         __builtin_amdgcn_sched_barrier(0);
;     }
;     template <bool LN, int BJ> DI void load_gb(unsigned col0, f32x4 (&gv)[2], f32x4 (&bv)[2]) const {
; #pragma unroll
;         for (int n = 0; n < 2; ++n) {
;             if (LN) { gv[n] = *(const f32x4*)(gam + col0 + BJ * HALF + n * 16) * ALPHA; bv[n] = *(const f32x4*)(bet + col0 + BJ * HALF + n * 16) * ALPHA; }
;             else { gv[n] = (f32x4){ALPHA, ALPHA, ALPHA, ALPHA}; bv[n] = (f32x4){0.f, 0.f, 0.f, 0.f}; }
;         }
;     }
;     template <bool LN> DI void run(const f32x4 (&acc)[2][2][4][2], const Unit& u, int wr, int wc, int fr, int fq) const {
;         const unsigned row0 = u.pm * BM + wr * 64 + fr, col0 = u.pn * BM + wc * 32 + 4 * fq;
;         f32x4 gv[2], bv[2];
;         load_gb<LN, 0>(col0, gv, bv);
;         batch<LN, 0, 0, 4>(acc, row0, col0, gv, bv);
;         batch<LN, 0, 4, 8>(acc, row0, col0, gv, bv);
;         batch<LN, 0, 8, 12>(acc, row0, col0, gv, bv);
;         batch<LN, 0, 12, 16>(acc, row0, col0, gv, bv);
;         load_gb<LN, 1>(col0, gv, bv);
;         batch<LN, 1, 0, 8>(acc, row0, col0, gv, bv);
;         batch<LN, 1, 8, 16>(acc, row0, col0, gv, bv);
	v_pk_mul_f32 v[212:213], v[130:131], s[78:79] op_sel_hi:[1,0]
	v_pk_mul_f32 v[214:215], v[128:129], s[78:79] op_sel_hi:[1,0]
	global_load_dwordx4 v[132:135], v[142:143], off offset:512
	global_load_dwordx4 v[128:131], v[140:141], off offset:576
	s_waitcnt vmcnt(0)
	v_pk_mul_f32 v[206:207], v[130:131], s[78:79] op_sel_hi:[1,0]
	v_pk_mul_f32 v[208:209], v[128:129], s[78:79] op_sel_hi:[1,0]
	global_load_dwordx4 v[128:131], v[142:143], off offset:576
	global_load_dwordx2 v[220:221], v[144:145], off
	global_load_dwordx4 v[240:243], v[136:137], off
	v_add_u32_e32 v136, v232, v229
	v_mov_b32_e32 v137, v159
	v_lshl_add_u64 v[136:137], v[136:137], 2, s[88:89]
	global_load_dwordx4 v[244:247], v[136:137], off
	global_load_dwordx2 v[218:219], v[146:147], off
	v_add_u32_e32 v136, v195, v230
	v_mov_b32_e32 v137, v159
	v_lshl_add_u64 v[136:137], v[136:137], 2, s[88:89]
	global_load_dwordx4 v[248:251], v[136:137], off
	v_add_u32_e32 v136, v195, v229
	v_mov_b32_e32 v137, v159
	v_lshl_add_u64 v[136:137], v[136:137], 2, s[88:89]
	global_load_dwordx4 v[152:155], v[136:137], off
	global_load_dwordx2 v[216:217], v[200:201], off
	v_add_u32_e32 v136, v236, v230
	v_mov_b32_e32 v137, v159
	v_lshl_add_u64 v[136:137], v[136:137], 2, s[88:89]
	global_load_dwordx4 v[148:151], v[136:137], off
	v_add_u32_e32 v136, v236, v229
	v_mov_b32_e32 v137, v159
	v_lshl_add_u64 v[136:137], v[136:137], 2, s[88:89]
	global_load_dwordx4 v[144:147], v[136:137], off
	global_load_dwordx2 v[200:201], v[202:203], off
	v_add_u32_e32 v136, v235, v230
	v_mov_b32_e32 v137, v159
	v_lshl_add_u64 v[136:137], v[136:137], 2, s[88:89]
	global_load_dwordx4 v[140:143], v[136:137], off
	v_add_u32_e32 v136, v235, v229
	v_mov_b32_e32 v137, v159
	v_lshl_add_u64 v[136:137], v[136:137], 2, s[88:89]
	global_load_dwordx4 v[136:139], v[136:137], off
	v_add_u32_e32 v202, 0x80, v194
	v_mov_b32_e32 v203, v159
	v_lshl_add_u64 v[202:203], v[202:203], 2, s[90:91]
	s_waitcnt vmcnt(0)
	v_sub_f32_e32 v241, v241, v220
	v_sub_f32_e32 v240, v240, v220
	v_sub_f32_e32 v243, v243, v220
	v_sub_f32_e32 v242, v242, v220
	v_pk_mul_f32 v[242:243], v[220:221], v[242:243] op_sel:[1,0]
	v_pk_mul_f32 v[240:241], v[220:221], v[240:241] op_sel:[1,0]
	v_pk_fma_f32 v[242:243], v[212:213], v[242:243], v[62:63]
	v_pk_fma_f32 v[240:241], v[214:215], v[240:241], v[60:61]
	v_pk_fma_f32 v[242:243], v[134:135], s[78:79], v[242:243] op_sel_hi:[1,0,1]
	v_pk_fma_f32 v[240:241], v[132:133], s[78:79], v[240:241] op_sel_hi:[1,0,1]
	global_store_dwordx4 v[202:203], v[240:243], off
	v_sub_f32_e32 v203, v245, v220
	v_sub_f32_e32 v202, v244, v220
	v_sub_f32_e32 v241, v247, v220
	v_sub_f32_e32 v240, v246, v220
	v_pk_mul_f32 v[202:203], v[220:221], v[202:203] op_sel:[1,0]
	v_pk_mul_f32 v[240:241], v[220:221], v[240:241] op_sel:[1,0]
	v_pk_fma_f32 v[202:203], v[208:209], v[202:203], v[56:57]
	v_pk_fma_f32 v[220:221], v[206:207], v[240:241], v[58:59]
	v_pk_fma_f32 v[240:241], v[128:129], s[78:79], v[202:203] op_sel_hi:[1,0,1]
	v_add_u32_e32 v202, 0x90, v194
	v_mov_b32_e32 v203, v159
	v_pk_fma_f32 v[242:243], v[130:131], s[78:79], v[220:221] op_sel_hi:[1,0,1]
	v_lshl_add_u64 v[202:203], v[202:203], 2, s[90:91]
	global_store_dwordx4 v[202:203], v[240:243], off
	v_sub_f32_e32 v203, v249, v218
	v_sub_f32_e32 v202, v248, v218
	v_sub_f32_e32 v221, v251, v218
	v_sub_f32_e32 v220, v250, v218
	v_pk_mul_f32 v[202:203], v[218:219], v[202:203] op_sel:[1,0]
	v_pk_mul_f32 v[220:221], v[218:219], v[220:221] op_sel:[1,0]
	v_pk_fma_f32 v[202:203], v[214:215], v[202:203], v[52:53]
	v_pk_fma_f32 v[220:221], v[212:213], v[220:221], v[54:55]
	v_pk_fma_f32 v[240:241], v[132:133], s[78:79], v[202:203] op_sel_hi:[1,0,1]
	v_add_u32_e32 v202, 0x8080, v194
	v_mov_b32_e32 v203, v159
	v_sub_f32_e32 v153, v153, v218
	v_sub_f32_e32 v152, v152, v218
	v_sub_f32_e32 v155, v155, v218
	v_sub_f32_e32 v154, v154, v218
	v_pk_fma_f32 v[242:243], v[134:135], s[78:79], v[220:221] op_sel_hi:[1,0,1]
	v_lshl_add_u64 v[202:203], v[202:203], 2, s[90:91]
	v_pk_mul_f32 v[154:155], v[218:219], v[154:155] op_sel:[1,0]
	v_pk_mul_f32 v[152:153], v[218:219], v[152:153] op_sel:[1,0]
	global_store_dwordx4 v[202:203], v[240:243], off
	v_pk_fma_f32 v[152:153], v[208:209], v[152:153], v[48:49]
	v_pk_fma_f32 v[154:155], v[206:207], v[154:155], v[50:51]
	v_add_u32_e32 v202, 0x8090, v194
	v_mov_b32_e32 v203, v159
	v_sub_f32_e32 v149, v149, v216
	v_sub_f32_e32 v148, v148, v216
	v_sub_f32_e32 v151, v151, v216
	v_sub_f32_e32 v150, v150, v216
	v_pk_fma_f32 v[154:155], v[130:131], s[78:79], v[154:155] op_sel_hi:[1,0,1]
	v_pk_fma_f32 v[152:153], v[128:129], s[78:79], v[152:153] op_sel_hi:[1,0,1]
	v_lshl_add_u64 v[202:203], v[202:203], 2, s[90:91]
	v_pk_mul_f32 v[150:151], v[216:217], v[150:151] op_sel:[1,0]
	v_pk_mul_f32 v[148:149], v[216:217], v[148:149] op_sel:[1,0]
	global_store_dwordx4 v[202:203], v[152:155], off
	v_pk_fma_f32 v[148:149], v[214:215], v[148:149], v[44:45]
	v_pk_fma_f32 v[150:151], v[212:213], v[150:151], v[46:47]
	v_add_u32_e32 v152, 0x10080, v194
	v_mov_b32_e32 v153, v159
	v_sub_f32_e32 v145, v145, v216
	v_sub_f32_e32 v144, v144, v216
	v_sub_f32_e32 v147, v147, v216
	v_sub_f32_e32 v146, v146, v216
	v_pk_fma_f32 v[150:151], v[134:135], s[78:79], v[150:151] op_sel_hi:[1,0,1]
	v_pk_fma_f32 v[148:149], v[132:133], s[78:79], v[148:149] op_sel_hi:[1,0,1]
	v_lshl_add_u64 v[152:153], v[152:153], 2, s[90:91]
	v_pk_mul_f32 v[146:147], v[216:217], v[146:147] op_sel:[1,0]
	v_pk_mul_f32 v[144:145], v[216:217], v[144:145] op_sel:[1,0]
	global_store_dwordx4 v[152:153], v[148:151], off
	v_pk_fma_f32 v[144:145], v[208:209], v[144:145], v[40:41]
	v_pk_fma_f32 v[146:147], v[206:207], v[146:147], v[42:43]
;     template <bool LN, int BJ, int LO, int HI> DI void batch(const f32x4 (&acc)[2][2][4][2], unsigned row0, unsigned col0, const f32x4 (&gv)[2], const f32x4 (&bv)[2]) const {
;         f32x4 r[HI - LO]; float mean[(HI - LO) / 2], rstd[(HI - LO) / 2];
; #pragma unroll
;         for (int i = LO; i < HI; ++i) { const int ai = i >> 3, m = (i >> 1) & 3, n = i & 1; const unsigned row = row0 + ai * HALF + m * 16;
;             if (n == 0) { mean[(i - LO) >> 1] = 0.f; rstd[(i - LO) >> 1] = 1.f;
;                 if (LN) { const float2 st = *(const float2*)(stats + row * 2u); mean[(i - LO) >> 1] = st.x; rstd[(i - LO) >> 1] = st.y; } }
;             r[i - LO] = *(const f32x4*)(src + (row * (unsigned)DM + col0 + BJ * HALF + n * 16)); }
; #pragma unroll
;         for (int i = LO; i < HI; ++i) { const int ai = i >> 3, m = (i >> 1) & 3, n = i & 1; const unsigned row = row0 + ai * HALF + m * 16;
;             *(f32x4*)(Y + (row * (unsigned)DM + col0 + BJ * HALF + n * 16)) = acc[ai][BJ][m][n] + ((r[i - LO] - mean[(i - LO) >> 1]) * rstd[(i - LO) >> 1]) * gv[n] + bv[n]; }
	v_add_u32_e32 v148, 0x10090, v194
	v_mov_b32_e32 v149, v159
	v_sub_f32_e32 v141, v141, v200
	v_sub_f32_e32 v140, v140, v200
	v_sub_f32_e32 v143, v143, v200
	v_sub_f32_e32 v142, v142, v200
	v_pk_fma_f32 v[146:147], v[130:131], s[78:79], v[146:147] op_sel_hi:[1,0,1]
	v_pk_fma_f32 v[144:145], v[128:129], s[78:79], v[144:145] op_sel_hi:[1,0,1]
	v_lshl_add_u64 v[148:149], v[148:149], 2, s[90:91]
	v_pk_mul_f32 v[142:143], v[200:201], v[142:143] op_sel:[1,0]
	v_pk_mul_f32 v[140:141], v[200:201], v[140:141] op_sel:[1,0]
	global_store_dwordx4 v[148:149], v[144:147], off
	v_pk_fma_f32 v[140:141], v[214:215], v[140:141], v[36:37]
	v_pk_fma_f32 v[142:143], v[212:213], v[142:143], v[38:39]
	v_add_u32_e32 v144, 0x18080, v194
	v_mov_b32_e32 v145, v159
	v_sub_f32_e32 v137, v137, v200
	v_sub_f32_e32 v136, v136, v200
	v_sub_f32_e32 v139, v139, v200
	v_sub_f32_e32 v138, v138, v200
	v_pk_fma_f32 v[142:143], v[134:135], s[78:79], v[142:143] op_sel_hi:[1,0,1]
	v_pk_fma_f32 v[140:141], v[132:133], s[78:79], v[140:141] op_sel_hi:[1,0,1]
	v_lshl_add_u64 v[144:145], v[144:145], 2, s[90:91]
	v_pk_mul_f32 v[138:139], v[200:201], v[138:139] op_sel:[1,0]
	v_pk_mul_f32 v[136:137], v[200:201], v[136:137] op_sel:[1,0]
	global_store_dwordx4 v[144:145], v[140:143], off
	v_pk_fma_f32 v[136:137], v[208:209], v[136:137], v[32:33]
	v_pk_fma_f32 v[138:139], v[206:207], v[138:139], v[34:35]
	v_add_u32_e32 v140, 0x18090, v194
	v_mov_b32_e32 v141, v159
	v_pk_fma_f32 v[138:139], v[130:131], s[78:79], v[138:139] op_sel_hi:[1,0,1]
	v_pk_fma_f32 v[136:137], v[128:129], s[78:79], v[136:137] op_sel_hi:[1,0,1]
	v_lshl_add_u64 v[140:141], v[140:141], 2, s[90:91]
	global_store_dwordx4 v[140:141], v[136:139], off
	s_nop 1
	v_add_u32_e32 v136, v233, v230
	v_mov_b32_e32 v137, v159
	v_lshl_add_u64 v[136:137], v[136:137], 2, s[88:89]
	global_load_dwordx2 v[220:221], v[196:197], off
	global_load_dwordx4 v[216:219], v[136:137], off
	v_add_u32_e32 v136, v233, v229
	v_mov_b32_e32 v137, v159
	v_lshl_add_u64 v[136:137], v[136:137], 2, s[88:89]
	global_load_dwordx4 v[240:243], v[136:137], off
	global_load_dwordx2 v[200:201], v[198:199], off
	v_add_u32_e32 v136, v234, v230
	v_mov_b32_e32 v137, v159
	v_lshl_add_u64 v[136:137], v[136:137], 2, s[88:89]
	global_load_dwordx4 v[244:247], v[136:137], off
	v_add_u32_e32 v136, v234, v229
	v_mov_b32_e32 v137, v159
	v_lshl_add_u64 v[136:137], v[136:137], 2, s[88:89]
	global_load_dwordx4 v[152:155], v[136:137], off
	global_load_dwordx2 v[198:199], v[204:205], off
	v_add_u32_e32 v136, v237, v230
	v_mov_b32_e32 v137, v159
	v_lshl_add_u64 v[136:137], v[136:137], 2, s[88:89]
	global_load_dwordx4 v[148:151], v[136:137], off
	v_add_u32_e32 v136, v237, v229
	v_mov_b32_e32 v137, v159
	v_lshl_add_u64 v[136:137], v[136:137], 2, s[88:89]
	global_load_dwordx4 v[144:147], v[136:137], off
	global_load_dwordx2 v[196:197], v[210:211], off
	v_add_u32_e32 v136, v238, v230
	v_mov_b32_e32 v137, v159
	v_lshl_add_u64 v[136:137], v[136:137], 2, s[88:89]
	global_load_dwordx4 v[140:143], v[136:137], off
	v_add_u32_e32 v136, v238, v229
	v_mov_b32_e32 v137, v159
	v_lshl_add_u64 v[136:137], v[136:137], 2, s[88:89]
	global_load_dwordx4 v[136:139], v[136:137], off
	v_add_u32_e32 v210, 0x40080, v194
	v_mov_b32_e32 v211, v159
	v_lshl_add_u64 v[210:211], v[210:211], 2, s[90:91]
	s_waitcnt vmcnt(0)
;     template <bool LN, int BJ, int LO, int HI> DI void batch(const f32x4 (&acc)[2][2][4][2], unsigned row0, unsigned col0, const f32x4 (&gv)[2], const f32x4 (&bv)[2]) const {
;         f32x4 r[HI - LO]; float mean[(HI - LO) / 2], rstd[(HI - LO) / 2];
; #pragma unroll
;         for (int i = LO; i < HI; ++i) { const int ai = i >> 3, m = (i >> 1) & 3, n = i & 1; const unsigned row = row0 + ai * HALF + m * 16;
;             if (n == 0) { mean[(i - LO) >> 1] = 0.f; rstd[(i - LO) >> 1] = 1.f;
;                 if (LN) { const float2 st = *(const float2*)(stats + row * 2u); mean[(i - LO) >> 1] = st.x; rstd[(i - LO) >> 1] = st.y; } }
;             r[i - LO] = *(const f32x4*)(src + (row * (unsigned)DM + col0 + BJ * HALF + n * 16)); }
; #pragma unroll
;         for (int i = LO; i < HI; ++i) { const int ai = i >> 3, m = (i >> 1) & 3, n = i & 1; const unsigned row = row0 + ai * HALF + m * 16;
;             *(f32x4*)(Y + (row * (unsigned)DM + col0 + BJ * HALF + n * 16)) = acc[ai][BJ][m][n] + ((r[i - LO] - mean[(i - LO) >> 1]) * rstd[(i - LO) >> 1]) * gv[n] + bv[n]; }
	v_sub_f32_e32 v203, v217, v220
	v_sub_f32_e32 v202, v216, v220
	v_sub_f32_e32 v205, v219, v220
	v_sub_f32_e32 v204, v218, v220
	v_pk_mul_f32 v[204:205], v[220:221], v[204:205] op_sel:[1,0]
	v_pk_mul_f32 v[202:203], v[220:221], v[202:203] op_sel:[1,0]
	v_pk_fma_f32 v[204:205], v[212:213], v[204:205], v[30:31]
	v_pk_fma_f32 v[202:203], v[214:215], v[202:203], v[28:29]
	v_pk_fma_f32 v[204:205], v[134:135], s[78:79], v[204:205] op_sel_hi:[1,0,1]
	v_pk_fma_f32 v[202:203], v[132:133], s[78:79], v[202:203] op_sel_hi:[1,0,1]
	global_store_dwordx4 v[210:211], v[202:205], off
	v_add_u32_e32 v210, 0x40090, v194
	v_mov_b32_e32 v211, v159
	v_sub_f32_e32 v203, v241, v220
	v_sub_f32_e32 v202, v240, v220
	v_sub_f32_e32 v205, v243, v220
	v_sub_f32_e32 v204, v242, v220
	v_pk_mul_f32 v[204:205], v[220:221], v[204:205] op_sel:[1,0]
	v_pk_mul_f32 v[202:203], v[220:221], v[202:203] op_sel:[1,0]
	v_pk_fma_f32 v[204:205], v[206:207], v[204:205], v[26:27]
	v_pk_fma_f32 v[202:203], v[208:209], v[202:203], v[24:25]
	v_pk_fma_f32 v[204:205], v[130:131], s[78:79], v[204:205] op_sel_hi:[1,0,1]
	v_pk_fma_f32 v[202:203], v[128:129], s[78:79], v[202:203] op_sel_hi:[1,0,1]
	v_lshl_add_u64 v[210:211], v[210:211], 2, s[90:91]
	global_store_dwordx4 v[210:211], v[202:205], off
	v_sub_f32_e32 v149, v149, v198
	v_sub_f32_e32 v148, v148, v198
	v_sub_f32_e32 v203, v245, v200
	v_sub_f32_e32 v202, v244, v200
	v_sub_f32_e32 v141, v141, v196
	v_sub_f32_e32 v140, v140, v196
	v_sub_f32_e32 v205, v247, v200
	v_sub_f32_e32 v204, v246, v200
	v_pk_mul_f32 v[202:203], v[200:201], v[202:203] op_sel:[1,0]
	v_sub_f32_e32 v151, v151, v198
	v_sub_f32_e32 v150, v150, v198
	v_pk_mul_f32 v[148:149], v[198:199], v[148:149] op_sel:[1,0]
	v_sub_f32_e32 v143, v143, v196
	v_sub_f32_e32 v142, v142, v196
	v_pk_mul_f32 v[140:141], v[196:197], v[140:141] op_sel:[1,0]
	v_pk_mul_f32 v[204:205], v[200:201], v[204:205] op_sel:[1,0]
	v_pk_fma_f32 v[202:203], v[214:215], v[202:203], v[20:21]
	v_sub_f32_e32 v153, v153, v200
	v_sub_f32_e32 v152, v152, v200
	v_sub_f32_e32 v155, v155, v200
	v_sub_f32_e32 v154, v154, v200
	v_pk_mul_f32 v[150:151], v[198:199], v[150:151] op_sel:[1,0]
	v_pk_fma_f32 v[148:149], v[214:215], v[148:149], v[12:13]
	v_pk_mul_f32 v[142:143], v[196:197], v[142:143] op_sel:[1,0]
	v_pk_fma_f32 v[140:141], v[214:215], v[140:141], v[4:5]
	v_pk_fma_f32 v[204:205], v[212:213], v[204:205], v[22:23]
	v_pk_fma_f32 v[202:203], v[132:133], s[78:79], v[202:203] op_sel_hi:[1,0,1]
	v_pk_mul_f32 v[154:155], v[200:201], v[154:155] op_sel:[1,0]
	v_pk_mul_f32 v[152:153], v[200:201], v[152:153] op_sel:[1,0]
	v_pk_fma_f32 v[150:151], v[212:213], v[150:151], v[14:15]
	v_pk_fma_f32 v[148:149], v[132:133], s[78:79], v[148:149] op_sel_hi:[1,0,1]
	v_pk_fma_f32 v[142:143], v[212:213], v[142:143], v[6:7]
	v_pk_fma_f32 v[132:133], v[132:133], s[78:79], v[140:141] op_sel_hi:[1,0,1]
	v_add_u32_e32 v140, 0x58080, v194
	v_mov_b32_e32 v141, v159
	v_pk_fma_f32 v[204:205], v[134:135], s[78:79], v[204:205] op_sel_hi:[1,0,1]
	v_pk_fma_f32 v[152:153], v[208:209], v[152:153], v[16:17]
	v_pk_fma_f32 v[154:155], v[206:207], v[154:155], v[18:19]
	v_add_u32_e32 v200, 0x48090, v194
	v_mov_b32_e32 v201, v159
	v_pk_fma_f32 v[150:151], v[134:135], s[78:79], v[150:151] op_sel_hi:[1,0,1]
	v_pk_fma_f32 v[134:135], v[134:135], s[78:79], v[142:143] op_sel_hi:[1,0,1]
	v_lshl_add_u64 v[140:141], v[140:141], 2, s[90:91]
	v_pk_fma_f32 v[154:155], v[130:131], s[78:79], v[154:155] op_sel_hi:[1,0,1]
	v_pk_fma_f32 v[152:153], v[128:129], s[78:79], v[152:153] op_sel_hi:[1,0,1]
	v_lshl_add_u64 v[200:201], v[200:201], 2, s[90:91]
	v_sub_f32_e32 v145, v145, v198
	v_sub_f32_e32 v144, v144, v198
	global_store_dwordx4 v[140:141], v[132:135], off
	global_store_dwordx4 v[200:201], v[152:155], off
	v_sub_f32_e32 v147, v147, v198
	v_sub_f32_e32 v133, v137, v196
	v_sub_f32_e32 v132, v136, v196
	v_add_u32_e32 v152, 0x50080, v194
	v_mov_b32_e32 v153, v159
	v_sub_f32_e32 v146, v146, v198
	v_pk_mul_f32 v[144:145], v[198:199], v[144:145] op_sel:[1,0]
	v_sub_f32_e32 v135, v139, v196
	v_sub_f32_e32 v134, v138, v196
	v_pk_mul_f32 v[132:133], v[196:197], v[132:133] op_sel:[1,0]
	v_lshl_add_u64 v[152:153], v[152:153], 2, s[90:91]
	v_pk_mul_f32 v[146:147], v[198:199], v[146:147] op_sel:[1,0]
	v_pk_fma_f32 v[144:145], v[208:209], v[144:145], v[8:9]
	v_pk_mul_f32 v[134:135], v[196:197], v[134:135] op_sel:[1,0]
	v_pk_fma_f32 v[132:133], v[208:209], v[132:133], v[0:1]
	v_add_u32_e32 v210, 0x48080, v194
	v_mov_b32_e32 v211, v159
	global_store_dwordx4 v[152:153], v[148:151], off
	v_pk_fma_f32 v[146:147], v[206:207], v[146:147], v[10:11]
	v_pk_fma_f32 v[144:145], v[128:129], s[78:79], v[144:145] op_sel_hi:[1,0,1]
	v_add_u32_e32 v148, 0x50090, v194
	v_mov_b32_e32 v149, v159
	v_pk_fma_f32 v[134:135], v[206:207], v[134:135], v[2:3]
	v_pk_fma_f32 v[128:129], v[128:129], s[78:79], v[132:133] op_sel_hi:[1,0,1]
	v_add_u32_e32 v132, 0x58090, v194
	v_mov_b32_e32 v133, v159
	v_lshl_add_u64 v[210:211], v[210:211], 2, s[90:91]
	v_pk_fma_f32 v[146:147], v[130:131], s[78:79], v[146:147] op_sel_hi:[1,0,1]
	v_lshl_add_u64 v[148:149], v[148:149], 2, s[90:91]
	v_pk_fma_f32 v[130:131], v[130:131], s[78:79], v[134:135] op_sel_hi:[1,0,1]
	v_lshl_add_u64 v[132:133], v[132:133], 2, s[90:91]
	global_store_dwordx4 v[210:211], v[202:205], off
	global_store_dwordx4 v[148:149], v[144:147], off
	global_store_dwordx4 v[132:133], v[128:131], off
	s_mov_b64 s[24:25], 0
	s_branch .LBB0_324
